# K-loop load segments: s_setprio 1 doubles as the m0-write wait state before the second DMA (s_nop removed), one issue slot less per load segment
# baseline (speedup 1.0000x reference)
; #define PG8_STAGE(bufoff, gbase, voff) do { _Pragma("unroll") for (int _i = 0; _i < 2; ++_i) \
;         __builtin_amdgcn_global_load_lds((const unsigned*)((const char*)(gbase) + (voff)[_i]), (LAS unsigned*)(lds + (bufoff) + ldsw + _i * 8192), 16, 0, 0); } while (0)
; #define PG8_LDA(dst, b, h) do { _Pragma("unroll") for (int m = 0; m < 4; ++m) _Pragma("unroll") for (int k = 0; k < 2; ++k) dst[m][k] = *(const LAS bf16x8*)(lds + PG8_SA(b, h) + aoff + m * 2048 + k * 1024); } while (0)
; #define PG8_LDB(dst, b, h) do { _Pragma("unroll") for (int n = 0; n < 2; ++n) _Pragma("unroll") for (int k = 0; k < 2; ++k) dst[n][k] = *(const LAS bf16x8*)(lds + PG8_SB(b, h) + boff + n * 2048 + k * 1024); } while (0)
; #define PG8_WAIT_V(n) asm volatile("s_waitcnt vmcnt(" #n ")" ::: "memory")
; #define PG8_WAIT_L(n) asm volatile("s_waitcnt lgkmcnt(" #n ")" ::: "memory")
; #define PG8_BAR __builtin_amdgcn_s_barrier()
; #define PG8_SCHED __builtin_amdgcn_sched_barrier(0)
; template <class Epi>
; __device__ __forceinline__ void gemm_phase(LAS unsigned char* lds, const bf16_t* A, int lda, const bf16_t* Bt, int ldb, int M, int N, int K, int asel, const Epi& E, const int fixed_round = -1) {
;     ...
;         const char* nA = has_next ? PG8_ABASE(nxt) : cA; const char* nB = has_next ? (const char*)Bt + (size_t)nxt.pn * tstepB : cB;
;         for (int t = 0; t < nt; t += 2) {
;             const bool last = (t == nt - 2);
;             const char* a1 = cA + (size_t)(t + 1) * kstep;
;             const char* a2 = last ? nA : cA + (size_t)(t + 2) * kstep; const char* b2 = last ? nB : cB + (size_t)(t + 2) * kstep;
;             const char* a3 = a2 + kstep; const char* b3 = b2 + kstep;
;             PG8_LDB(B0, 0, 0); PG8_SCHED; PG8_LDA(At, 0, 0); PG8_STAGE(PG8_SA(1, 1), a1 + hstepA, voffA);
;             PG8_WAIT_L(8); PG8_BAR; PG8_WAIT_L(0); PG8_MMA(0, 0, At, B0); PG8_BAR; PG8_SCHED;
;             PG8_LDB(B1, 0, 1); PG8_STAGE(PG8_SB(0, 0), b2, voffB);
;             PG8_BAR; PG8_WAIT_L(0); PG8_MMA(0, 1, At, B1); PG8_BAR;
;             PG8_LDA(At, 0, 1); PG8_STAGE(PG8_SA(0, 0), a2, voffA);
;             PG8_BAR; PG8_WAIT_L(0); PG8_MMA(1, 0, At, B0); PG8_BAR; PG8_SCHED;
;             PG8_STAGE(PG8_SB(0, 1), b2 + hstepB, voffB);
;             PG8_WAIT_V(6); PG8_BAR; PG8_MMA(1, 1, At, B1); PG8_BAR;
.LBB0_199:
	ds_read_b128 v[148:151], v161
	ds_read_b128 v[152:155], v161 offset:1024
	ds_read_b128 v[156:159], v161 offset:2048
	ds_read_b128 v[166:169], v161 offset:3072
	s_add_i32 m0, s39, 0xc000
	ds_read_b128 v[170:173], v162
	ds_read_b128 v[174:177], v162 offset:1024
	ds_read_b128 v[178:181], v162 offset:2048
	ds_read_b128 v[182:185], v162 offset:3072
	ds_read_b128 v[186:189], v162 offset:4096
	ds_read_b128 v[190:193], v162 offset:5120
	ds_read_b128 v[196:199], v162 offset:6144
	ds_read_b128 v[202:205], v162 offset:7168
	global_load_lds_dwordx4 v140, s[28:29]
	s_add_i32 m0, s39, 0xe000
	s_setprio 1
	global_load_lds_dwordx4 v142, s[28:29]
	s_waitcnt lgkmcnt(8)
	s_barrier
	s_waitcnt lgkmcnt(0)
	v_mfma_f32_16x16x32_bf16 v[124:127], v[148:151], v[170:173], v[124:127]
	v_mfma_f32_16x16x32_bf16 v[120:123], v[156:159], v[170:173], v[120:123]
	v_mfma_f32_16x16x32_bf16 v[112:115], v[148:151], v[178:181], v[112:115]
	v_mfma_f32_16x16x32_bf16 v[108:111], v[156:159], v[178:181], v[108:111]
	v_mfma_f32_16x16x32_bf16 v[100:103], v[148:151], v[186:189], v[100:103]
	v_mfma_f32_16x16x32_bf16 v[92:95], v[156:159], v[186:189], v[92:95]
	v_mfma_f32_16x16x32_bf16 v[84:87], v[148:151], v[196:199], v[84:87]
	v_mfma_f32_16x16x32_bf16 v[76:79], v[156:159], v[196:199], v[76:79]
	v_mfma_f32_16x16x32_bf16 v[124:127], v[152:155], v[174:177], v[124:127]
	v_mfma_f32_16x16x32_bf16 v[120:123], v[166:169], v[174:177], v[120:123]
	v_mfma_f32_16x16x32_bf16 v[112:115], v[152:155], v[182:185], v[112:115]
	v_mfma_f32_16x16x32_bf16 v[108:111], v[166:169], v[182:185], v[108:111]
	v_mfma_f32_16x16x32_bf16 v[100:103], v[152:155], v[190:193], v[100:103]
	v_mfma_f32_16x16x32_bf16 v[92:95], v[166:169], v[190:193], v[92:95]
	v_mfma_f32_16x16x32_bf16 v[84:87], v[152:155], v[202:205], v[84:87]
	v_mfma_f32_16x16x32_bf16 v[76:79], v[166:169], v[202:205], v[76:79]
	s_barrier
	s_setprio 0
	s_add_u32 s30, s28, 0xfff80080
	s_addc_u32 s31, s29, -1
	s_cmp_eq_u32 s58, 28
	s_cselect_b32 s35, s4, s31
	s_cselect_b32 s34, s21, s30
	s_cselect_b32 s31, s19, s57
	s_cselect_b32 s30, s55, s56
	s_add_i32 s59, s46, s38
	s_add_u32 s98, s30, s6
	s_addc_u32 s99, s31, s7
	s_mov_b32 m0, s59
	ds_read_b128 v[206:209], v163
	ds_read_b128 v[210:213], v163 offset:1024
	ds_read_b128 v[214:217], v163 offset:2048
	ds_read_b128 v[218:221], v163 offset:3072
	global_load_lds_dwordx4 v130, s[30:31]
	s_add_i32 m0, s59, 0x2000
	s_setprio 1
	global_load_lds_dwordx4 v134, s[30:31]
	s_barrier
	s_waitcnt lgkmcnt(0)
	v_mfma_f32_16x16x32_bf16 v[116:119], v[206:209], v[170:173], v[116:119]
	v_mfma_f32_16x16x32_bf16 v[104:107], v[214:217], v[170:173], v[104:107]
	v_mfma_f32_16x16x32_bf16 v[96:99], v[206:209], v[178:181], v[96:99]
	v_mfma_f32_16x16x32_bf16 v[88:91], v[214:217], v[178:181], v[88:91]
	v_mfma_f32_16x16x32_bf16 v[80:83], v[206:209], v[186:189], v[80:83]
	v_mfma_f32_16x16x32_bf16 v[72:75], v[214:217], v[186:189], v[72:75]
	v_mfma_f32_16x16x32_bf16 v[68:71], v[206:209], v[196:199], v[68:71]
	v_mfma_f32_16x16x32_bf16 v[64:67], v[214:217], v[196:199], v[64:67]
	v_mfma_f32_16x16x32_bf16 v[116:119], v[210:213], v[174:177], v[116:119]
	v_mfma_f32_16x16x32_bf16 v[104:107], v[218:221], v[174:177], v[104:107]
	v_mfma_f32_16x16x32_bf16 v[96:99], v[210:213], v[182:185], v[96:99]
	v_mfma_f32_16x16x32_bf16 v[88:91], v[218:221], v[182:185], v[88:91]
	v_mfma_f32_16x16x32_bf16 v[80:83], v[210:213], v[190:193], v[80:83]
	v_mfma_f32_16x16x32_bf16 v[72:75], v[218:221], v[190:193], v[72:75]
	v_mfma_f32_16x16x32_bf16 v[68:71], v[210:213], v[202:205], v[68:71]
	v_mfma_f32_16x16x32_bf16 v[64:67], v[218:221], v[202:205], v[64:67]
	s_barrier
	s_setprio 0
	s_mov_b32 m0, s39
	s_add_u32 s100, s34, s6
	s_addc_u32 s101, s35, s7
	ds_read_b128 v[170:173], v162 offset:16384
	ds_read_b128 v[174:177], v162 offset:17408
	ds_read_b128 v[178:181], v162 offset:18432
	ds_read_b128 v[182:185], v162 offset:19456
	ds_read_b128 v[186:189], v162 offset:20480
	ds_read_b128 v[190:193], v162 offset:21504
	ds_read_b128 v[196:199], v162 offset:22528
	ds_read_b128 v[202:205], v162 offset:23552
	global_load_lds_dwordx4 v128, s[34:35]
	s_mov_b32 m0, s40
	s_setprio 1
	global_load_lds_dwordx4 v132, s[34:35]
	s_barrier
	s_waitcnt lgkmcnt(0)
	v_mfma_f32_16x16x32_bf16 v[60:63], v[148:151], v[170:173], v[60:63]
	v_mfma_f32_16x16x32_bf16 v[56:59], v[156:159], v[170:173], v[56:59]
	v_mfma_f32_16x16x32_bf16 v[52:55], v[148:151], v[178:181], v[52:55]
	v_mfma_f32_16x16x32_bf16 v[44:47], v[156:159], v[178:181], v[44:47]
	v_mfma_f32_16x16x32_bf16 v[36:39], v[148:151], v[186:189], v[36:39]
	v_mfma_f32_16x16x32_bf16 v[28:31], v[156:159], v[186:189], v[28:31]
	v_mfma_f32_16x16x32_bf16 v[20:23], v[148:151], v[196:199], v[20:23]
	v_mfma_f32_16x16x32_bf16 v[12:15], v[156:159], v[196:199], v[12:15]
	v_mfma_f32_16x16x32_bf16 v[60:63], v[152:155], v[174:177], v[60:63]
	v_mfma_f32_16x16x32_bf16 v[56:59], v[166:169], v[174:177], v[56:59]
	v_mfma_f32_16x16x32_bf16 v[52:55], v[152:155], v[182:185], v[52:55]
	v_mfma_f32_16x16x32_bf16 v[44:47], v[166:169], v[182:185], v[44:47]
	v_mfma_f32_16x16x32_bf16 v[36:39], v[152:155], v[190:193], v[36:39]
	v_mfma_f32_16x16x32_bf16 v[28:31], v[166:169], v[190:193], v[28:31]
	v_mfma_f32_16x16x32_bf16 v[20:23], v[152:155], v[202:205], v[20:23]
	v_mfma_f32_16x16x32_bf16 v[12:15], v[166:169], v[202:205], v[12:15]
	s_barrier
	s_setprio 0
	s_add_u32 s60, s30, 0x80000
	s_addc_u32 s61, s31, 0
	s_add_i32 s59, s47, s38
	s_mov_b32 m0, s59
	s_nop 0
	global_load_lds_dwordx4 v130, s[60:61]
	s_add_i32 m0, s59, 0x2000
	s_setprio 1
	global_load_lds_dwordx4 v134, s[60:61]
	s_waitcnt vmcnt(6)
	s_barrier
; #define PG8_STAGE(bufoff, gbase, voff) do { _Pragma("unroll") for (int _i = 0; _i < 2; ++_i) \
;         __builtin_amdgcn_global_load_lds((const unsigned*)((const char*)(gbase) + (voff)[_i]), (LAS unsigned*)(lds + (bufoff) + ldsw + _i * 8192), 16, 0, 0); } while (0)
; #define PG8_LDA(dst, b, h) do { _Pragma("unroll") for (int m = 0; m < 4; ++m) _Pragma("unroll") for (int k = 0; k < 2; ++k) dst[m][k] = *(const LAS bf16x8*)(lds + PG8_SA(b, h) + aoff + m * 2048 + k * 1024); } while (0)
; #define PG8_LDB(dst, b, h) do { _Pragma("unroll") for (int n = 0; n < 2; ++n) _Pragma("unroll") for (int k = 0; k < 2; ++k) dst[n][k] = *(const LAS bf16x8*)(lds + PG8_SB(b, h) + boff + n * 2048 + k * 1024); } while (0)
; #define PG8_WAIT_V(n) asm volatile("s_waitcnt vmcnt(" #n ")" ::: "memory")
; #define PG8_WAIT_L(n) asm volatile("s_waitcnt lgkmcnt(" #n ")" ::: "memory")
; #define PG8_BAR __builtin_amdgcn_s_barrier()
; #define PG8_SCHED __builtin_amdgcn_sched_barrier(0)
; template <class Epi>
; __device__ __forceinline__ void gemm_phase(LAS unsigned char* lds, const bf16_t* A, int lda, const bf16_t* Bt, int ldb, int M, int N, int K, int asel, const Epi& E, const int fixed_round = -1) {
;     ...
;             PG8_WAIT_V(6); PG8_BAR; PG8_MMA(1, 1, At, B1); PG8_BAR;
;             PG8_LDB(B0, 1, 0); PG8_SCHED; PG8_LDA(At, 1, 0); PG8_STAGE(PG8_SA(0, 1), a2 + hstepA, voffA);
;             PG8_WAIT_L(8); PG8_BAR; PG8_WAIT_L(0); PG8_MMA(0, 0, At, B0); PG8_BAR; PG8_SCHED;
;             PG8_LDB(B1, 1, 1); PG8_STAGE(PG8_SB(1, 0), b3, voffB);
;             PG8_BAR; PG8_WAIT_L(0); PG8_MMA(0, 1, At, B1); PG8_BAR;
;             PG8_LDA(At, 1, 1); PG8_STAGE(PG8_SA(1, 0), a3, voffA);
;             PG8_BAR; PG8_WAIT_L(0); PG8_MMA(1, 0, At, B0); PG8_BAR; PG8_SCHED;
	v_mfma_f32_16x16x32_bf16 v[48:51], v[206:209], v[170:173], v[48:51]
	v_mfma_f32_16x16x32_bf16 v[40:43], v[214:217], v[170:173], v[40:43]
	v_mfma_f32_16x16x32_bf16 v[32:35], v[206:209], v[178:181], v[32:35]
	v_mfma_f32_16x16x32_bf16 v[24:27], v[214:217], v[178:181], v[24:27]
	v_mfma_f32_16x16x32_bf16 v[16:19], v[206:209], v[186:189], v[16:19]
	v_mfma_f32_16x16x32_bf16 v[8:11], v[214:217], v[186:189], v[8:11]
	v_mfma_f32_16x16x32_bf16 v[4:7], v[206:209], v[196:199], v[4:7]
	v_mfma_f32_16x16x32_bf16 v[0:3], v[214:217], v[196:199], v[0:3]
	v_mfma_f32_16x16x32_bf16 v[48:51], v[210:213], v[174:177], v[48:51]
	v_mfma_f32_16x16x32_bf16 v[40:43], v[218:221], v[174:177], v[40:43]
	v_mfma_f32_16x16x32_bf16 v[32:35], v[210:213], v[182:185], v[32:35]
	v_mfma_f32_16x16x32_bf16 v[24:27], v[218:221], v[182:185], v[24:27]
	v_mfma_f32_16x16x32_bf16 v[16:19], v[210:213], v[190:193], v[16:19]
	v_mfma_f32_16x16x32_bf16 v[8:11], v[218:221], v[190:193], v[8:11]
	v_mfma_f32_16x16x32_bf16 v[4:7], v[210:213], v[202:205], v[4:7]
	v_mfma_f32_16x16x32_bf16 v[0:3], v[218:221], v[202:205], v[0:3]
	s_barrier
	s_setprio 0
	s_add_i32 s59, 0, 0x18000
	v_add_u32_e32 v136, s59, v160
	ds_read_b128 v[148:151], v136
	ds_read_b128 v[152:155], v136 offset:1024
	ds_read_b128 v[156:159], v136 offset:2048
	ds_read_b128 v[166:169], v136 offset:3072
	s_add_u32 s34, s34, 0x80000
	s_addc_u32 s35, s35, 0
	s_mov_b32 m0, s41
	ds_read_b128 v[170:173], v162 offset:32768
	ds_read_b128 v[174:177], v162 offset:33792
	ds_read_b128 v[178:181], v162 offset:34816
	ds_read_b128 v[182:185], v162 offset:35840
	ds_read_b128 v[186:189], v162 offset:36864
	ds_read_b128 v[190:193], v162 offset:37888
	ds_read_b128 v[196:199], v162 offset:38912
	ds_read_b128 v[202:205], v162 offset:39936
	global_load_lds_dwordx4 v128, s[34:35]
	s_mov_b32 m0, s42
	s_setprio 1
	global_load_lds_dwordx4 v132, s[34:35]
	s_waitcnt lgkmcnt(8)
	s_barrier
	s_waitcnt lgkmcnt(0)
	v_mfma_f32_16x16x32_bf16 v[124:127], v[148:151], v[170:173], v[124:127]
	v_mfma_f32_16x16x32_bf16 v[120:123], v[156:159], v[170:173], v[120:123]
	v_mfma_f32_16x16x32_bf16 v[112:115], v[148:151], v[178:181], v[112:115]
	v_mfma_f32_16x16x32_bf16 v[108:111], v[156:159], v[178:181], v[108:111]
	v_mfma_f32_16x16x32_bf16 v[100:103], v[148:151], v[186:189], v[100:103]
	v_mfma_f32_16x16x32_bf16 v[92:95], v[156:159], v[186:189], v[92:95]
	v_mfma_f32_16x16x32_bf16 v[84:87], v[148:151], v[196:199], v[84:87]
	v_mfma_f32_16x16x32_bf16 v[76:79], v[156:159], v[196:199], v[76:79]
	v_mfma_f32_16x16x32_bf16 v[124:127], v[152:155], v[174:177], v[124:127]
	v_mfma_f32_16x16x32_bf16 v[120:123], v[166:169], v[174:177], v[120:123]
	v_mfma_f32_16x16x32_bf16 v[112:115], v[152:155], v[182:185], v[112:115]
	v_mfma_f32_16x16x32_bf16 v[108:111], v[166:169], v[182:185], v[108:111]
	v_mfma_f32_16x16x32_bf16 v[100:103], v[152:155], v[190:193], v[100:103]
	v_mfma_f32_16x16x32_bf16 v[92:95], v[166:169], v[190:193], v[92:95]
	v_mfma_f32_16x16x32_bf16 v[84:87], v[152:155], v[202:205], v[84:87]
	v_mfma_f32_16x16x32_bf16 v[76:79], v[166:169], v[202:205], v[76:79]
	s_barrier
	s_setprio 0
	s_add_i32 s34, 0, 0x1c000
	s_add_i32 s35, s59, s38
	v_add_u32_e32 v136, s34, v160
	s_mov_b32 m0, s35
	ds_read_b128 v[206:209], v136
	ds_read_b128 v[210:213], v136 offset:1024
	ds_read_b128 v[214:217], v136 offset:2048
	ds_read_b128 v[218:221], v136 offset:3072
	global_load_lds_dwordx4 v130, s[98:99]
	s_add_i32 m0, s35, 0x2000
	s_setprio 1
	global_load_lds_dwordx4 v134, s[98:99]
	s_barrier
	s_waitcnt lgkmcnt(0)
	v_mfma_f32_16x16x32_bf16 v[116:119], v[206:209], v[170:173], v[116:119]
	v_mfma_f32_16x16x32_bf16 v[104:107], v[214:217], v[170:173], v[104:107]
	v_mfma_f32_16x16x32_bf16 v[96:99], v[206:209], v[178:181], v[96:99]
	v_mfma_f32_16x16x32_bf16 v[88:91], v[214:217], v[178:181], v[88:91]
	v_mfma_f32_16x16x32_bf16 v[80:83], v[206:209], v[186:189], v[80:83]
	v_mfma_f32_16x16x32_bf16 v[72:75], v[214:217], v[186:189], v[72:75]
	v_mfma_f32_16x16x32_bf16 v[68:71], v[206:209], v[196:199], v[68:71]
	v_mfma_f32_16x16x32_bf16 v[64:67], v[214:217], v[196:199], v[64:67]
	v_mfma_f32_16x16x32_bf16 v[116:119], v[210:213], v[174:177], v[116:119]
	v_mfma_f32_16x16x32_bf16 v[104:107], v[218:221], v[174:177], v[104:107]
	v_mfma_f32_16x16x32_bf16 v[96:99], v[210:213], v[182:185], v[96:99]
	v_mfma_f32_16x16x32_bf16 v[88:91], v[218:221], v[182:185], v[88:91]
	v_mfma_f32_16x16x32_bf16 v[80:83], v[210:213], v[190:193], v[80:83]
	v_mfma_f32_16x16x32_bf16 v[72:75], v[218:221], v[190:193], v[72:75]
	v_mfma_f32_16x16x32_bf16 v[68:71], v[210:213], v[202:205], v[68:71]
	v_mfma_f32_16x16x32_bf16 v[64:67], v[218:221], v[202:205], v[64:67]
	s_barrier
	s_setprio 0
	s_mov_b32 m0, s43
	ds_read_b128 v[170:173], v162 offset:49152
	ds_read_b128 v[174:177], v162 offset:50176
	ds_read_b128 v[178:181], v162 offset:51200
	ds_read_b128 v[182:185], v162 offset:52224
	ds_read_b128 v[186:189], v162 offset:53248
	ds_read_b128 v[190:193], v162 offset:54272
	ds_read_b128 v[196:199], v162 offset:55296
	ds_read_b128 v[202:205], v162 offset:56320
	global_load_lds_dwordx4 v128, s[100:101]
	s_mov_b32 m0, s44
	s_setprio 1
	global_load_lds_dwordx4 v132, s[100:101]
	s_barrier
; __device__ __forceinline__ unsigned cvt_pk_bf16(float lo, float hi) { const bf16x2_t r = __builtin_convertvector((f32x2){lo, hi}, bf16x2_t); return __builtin_bit_cast(unsigned, r); }
; #define PG8_STAGE(bufoff, gbase, voff) do { _Pragma("unroll") for (int _i = 0; _i < 2; ++_i) \
;         __builtin_amdgcn_global_load_lds((const unsigned*)((const char*)(gbase) + (voff)[_i]), (LAS unsigned*)(lds + (bufoff) + ldsw + _i * 8192), 16, 0, 0); } while (0)
; #define PG8_WAIT_V(n) asm volatile("s_waitcnt vmcnt(" #n ")" ::: "memory")
; #define PG8_BAR __builtin_amdgcn_s_barrier()
; template <class Epi>
; __device__ __forceinline__ void gemm_phase(LAS unsigned char* lds, const bf16_t* A, int lda, const bf16_t* Bt, int ldb, int M, int N, int K, int asel, const Epi& E, const int fixed_round = -1) {
;     ...
;             PG8_STAGE(PG8_SB(1, 1), b3 + hstepB, voffB);
;             PG8_WAIT_V(6); PG8_BAR; PG8_MMA(1, 1, At, B1); PG8_BAR;
;     __device__ __forceinline__ void operator()(const AccT& acc, const Unit& u, int wr, int wc, int fr, int fq) const {
;         const int row0 = u.pm * BM + wr * 64 + fr;
;         const int pn = u.pn + pn_off;
;         const int cl = wc * 32 + 8 * fq;
;         if (pn < 8) {
;             bf16_t* base = pn < 4 ? Q : Kn; const int colt = (pn & 3) * BM; const float sc = pn < 4 ? 0.08838834764831845f : 1.0f;
; #pragma unroll
;             for (int ai = 0; ai < 2; ++ai)
; #pragma unroll
;                 for (int m = 0; m < 4; ++m) { bf16_t* rowp = base + (size_t)(row0 + ai * HALF + m * 16) * 1024 + colt + cl;
; #pragma unroll
;                     for (int bj = 0; bj < 2; ++bj) { const f32x4 v0 = acc[ai][bj][m][0] * sc, v1 = acc[ai][bj][m][1] * sc;
;                         u32x4 w; w.x = cvt_pk_bf16(v0[0], v0[1]); w.y = cvt_pk_bf16(v0[2], v0[3]); w.z = cvt_pk_bf16(v1[0], v1[1]); w.w = cvt_pk_bf16(v1[2], v1[3]);
;                         *(u32x4*)(rowp + bj * HALF) = w; } }
	s_waitcnt lgkmcnt(0)
	v_mfma_f32_16x16x32_bf16 v[60:63], v[148:151], v[170:173], v[60:63]
	v_mfma_f32_16x16x32_bf16 v[56:59], v[156:159], v[170:173], v[56:59]
	v_mfma_f32_16x16x32_bf16 v[52:55], v[148:151], v[178:181], v[52:55]
	v_mfma_f32_16x16x32_bf16 v[44:47], v[156:159], v[178:181], v[44:47]
	v_mfma_f32_16x16x32_bf16 v[36:39], v[148:151], v[186:189], v[36:39]
	v_mfma_f32_16x16x32_bf16 v[28:31], v[156:159], v[186:189], v[28:31]
	v_mfma_f32_16x16x32_bf16 v[20:23], v[148:151], v[196:199], v[20:23]
	v_mfma_f32_16x16x32_bf16 v[12:15], v[156:159], v[196:199], v[12:15]
	v_mfma_f32_16x16x32_bf16 v[60:63], v[152:155], v[174:177], v[60:63]
	v_mfma_f32_16x16x32_bf16 v[56:59], v[166:169], v[174:177], v[56:59]
	v_mfma_f32_16x16x32_bf16 v[52:55], v[152:155], v[182:185], v[52:55]
	v_mfma_f32_16x16x32_bf16 v[44:47], v[166:169], v[182:185], v[44:47]
	v_mfma_f32_16x16x32_bf16 v[36:39], v[152:155], v[190:193], v[36:39]
	v_mfma_f32_16x16x32_bf16 v[28:31], v[166:169], v[190:193], v[28:31]
	v_mfma_f32_16x16x32_bf16 v[20:23], v[152:155], v[202:205], v[20:23]
	v_mfma_f32_16x16x32_bf16 v[12:15], v[166:169], v[202:205], v[12:15]
	s_barrier
	s_setprio 0
	s_add_u32 s30, s30, 0x80080
	s_addc_u32 s31, s31, 0
	s_add_i32 s34, s34, s38
	s_mov_b32 m0, s34
	s_nop 0
	global_load_lds_dwordx4 v130, s[30:31]
	s_add_i32 m0, s34, 0x2000
	s_setprio 1
	global_load_lds_dwordx4 v134, s[30:31]
	s_waitcnt vmcnt(6)
	s_barrier
	v_mfma_f32_16x16x32_bf16 v[48:51], v[206:209], v[170:173], v[48:51]
	v_mfma_f32_16x16x32_bf16 v[40:43], v[214:217], v[170:173], v[40:43]
	v_mfma_f32_16x16x32_bf16 v[32:35], v[206:209], v[178:181], v[32:35]
	v_mfma_f32_16x16x32_bf16 v[24:27], v[214:217], v[178:181], v[24:27]
	v_mfma_f32_16x16x32_bf16 v[16:19], v[206:209], v[186:189], v[16:19]
	v_mfma_f32_16x16x32_bf16 v[8:11], v[214:217], v[186:189], v[8:11]
	v_mfma_f32_16x16x32_bf16 v[4:7], v[206:209], v[196:199], v[4:7]
	v_mfma_f32_16x16x32_bf16 v[0:3], v[214:217], v[196:199], v[0:3]
	v_mfma_f32_16x16x32_bf16 v[48:51], v[210:213], v[174:177], v[48:51]
	v_mfma_f32_16x16x32_bf16 v[40:43], v[218:221], v[174:177], v[40:43]
	v_mfma_f32_16x16x32_bf16 v[32:35], v[210:213], v[182:185], v[32:35]
	v_mfma_f32_16x16x32_bf16 v[24:27], v[218:221], v[182:185], v[24:27]
	v_mfma_f32_16x16x32_bf16 v[16:19], v[210:213], v[190:193], v[16:19]
	v_mfma_f32_16x16x32_bf16 v[8:11], v[218:221], v[190:193], v[8:11]
	v_mfma_f32_16x16x32_bf16 v[4:7], v[210:213], v[202:205], v[4:7]
	v_mfma_f32_16x16x32_bf16 v[0:3], v[218:221], v[202:205], v[0:3]
	s_setprio 0
	s_add_i32 s58, s58, 2
	s_add_u32 s28, s28, 0x100
	s_addc_u32 s29, s29, 0
	s_add_u32 s56, s56, 0x100
	s_addc_u32 s57, s57, 0
	s_cmp_gt_u32 s58, 29
	s_cbranch_scc0 .Lrot_1
	s_barrier
	s_lshl_b32 s19, s26, 8
	v_add_u32_e32 v154, s19, v139
	s_cmp_lt_i32 s27, 8
	v_or_b32_e32 v152, 16, v154
	v_or_b32_e32 v150, 32, v154
	v_or_b32_e32 v148, 48, v154
	s_cselect_b64 s[28:29], -1, 0
	s_cmp_gt_i32 s27, 7
	v_ashrrev_i32_e32 v155, 31, v154
	v_lshlrev_b32_e32 v136, 1, v138
	v_ashrrev_i32_e32 v153, 31, v152
	v_ashrrev_i32_e32 v151, 31, v150
	v_ashrrev_i32_e32 v149, 31, v148
	s_cbranch_scc1 .LBB0_203
	s_cmp_lt_i32 s27, 4
	s_cselect_b64 vcc, -1, 0
	s_and_b64 s[30:31], vcc, exec
	s_cselect_b32 s4, s89, s81
	s_cselect_b32 s21, s88, s91
	s_lshl_b32 s30, s27, 9
	s_and_b32 s30, s30, 0x600
	s_add_u32 s30, s21, s30
	v_cndmask_b32_e32 v156, 1.0, v164, vcc
	s_addc_u32 s31, s4, 0
	v_lshl_add_u64 v[170:171], s[30:31], 0, v[136:137]
	v_lshlrev_b64 v[158:159], 11, v[154:155]
	v_pk_mul_f32 v[168:169], v[156:157], v[126:127] op_sel_hi:[0,1]
	v_pk_mul_f32 v[166:167], v[156:157], v[124:125] op_sel_hi:[0,1]
	v_pk_mul_f32 v[172:173], v[156:157], v[122:123] op_sel_hi:[0,1]
	v_pk_mul_f32 v[174:175], v[156:157], v[120:121] op_sel_hi:[0,1]
	v_lshl_add_u64 v[158:159], v[170:171], 0, v[158:159]
	v_cvt_pk_bf16_f32 v166, v166, v167
	v_cvt_pk_bf16_f32 v167, v168, v169
	v_cvt_pk_bf16_f32 v168, v174, v175
	v_cvt_pk_bf16_f32 v169, v172, v173
	global_store_dwordx4 v[158:159], v[166:169], off
	v_pk_mul_f32 v[172:173], v[156:157], v[106:107] op_sel_hi:[0,1]
	v_pk_mul_f32 v[174:175], v[156:157], v[104:105] op_sel_hi:[0,1]
	v_pk_mul_f32 v[168:169], v[156:157], v[118:119] op_sel_hi:[0,1]
	v_pk_mul_f32 v[166:167], v[156:157], v[116:117] op_sel_hi:[0,1]
	v_cvt_pk_bf16_f32 v166, v166, v167
	v_cvt_pk_bf16_f32 v167, v168, v169
	v_cvt_pk_bf16_f32 v168, v174, v175
	v_cvt_pk_bf16_f32 v169, v172, v173
	global_store_dwordx4 v[158:159], v[166:169], off offset:256
	v_pk_mul_f32 v[174:175], v[156:157], v[110:111] op_sel_hi:[0,1]
	v_pk_mul_f32 v[176:177], v[156:157], v[108:109] op_sel_hi:[0,1]
	v_lshlrev_b64 v[166:167], 11, v[152:153]
	v_lshl_add_u64 v[172:173], v[170:171], 0, v[166:167]
	v_pk_mul_f32 v[168:169], v[156:157], v[114:115] op_sel_hi:[0,1]
	v_pk_mul_f32 v[166:167], v[156:157], v[112:113] op_sel_hi:[0,1]
	v_cvt_pk_bf16_f32 v166, v166, v167
	v_cvt_pk_bf16_f32 v167, v168, v169
	v_cvt_pk_bf16_f32 v168, v176, v177
	v_cvt_pk_bf16_f32 v169, v174, v175
	global_store_dwordx4 v[172:173], v[166:169], off
	v_pk_mul_f32 v[174:175], v[156:157], v[90:91] op_sel_hi:[0,1]
	v_pk_mul_f32 v[176:177], v[156:157], v[88:89] op_sel_hi:[0,1]
	v_pk_mul_f32 v[168:169], v[156:157], v[98:99] op_sel_hi:[0,1]
	v_pk_mul_f32 v[166:167], v[156:157], v[96:97] op_sel_hi:[0,1]
	v_cvt_pk_bf16_f32 v166, v166, v167
	v_cvt_pk_bf16_f32 v167, v168, v169
	v_cvt_pk_bf16_f32 v168, v176, v177
	v_cvt_pk_bf16_f32 v169, v174, v175
	global_store_dwordx4 v[172:173], v[166:169], off offset:256
	v_pk_mul_f32 v[174:175], v[156:157], v[94:95] op_sel_hi:[0,1]
	v_pk_mul_f32 v[176:177], v[156:157], v[92:93] op_sel_hi:[0,1]
	v_lshlrev_b64 v[166:167], 11, v[150:151]
	v_lshl_add_u64 v[172:173], v[170:171], 0, v[166:167]
; __device__ __forceinline__ unsigned cvt_pk_bf16(float lo, float hi) { const bf16x2_t r = __builtin_convertvector((f32x2){lo, hi}, bf16x2_t); return __builtin_bit_cast(unsigned, r); }
;     __device__ __forceinline__ void operator()(const AccT& acc, const Unit& u, int wr, int wc, int fr, int fq) const {
;     ...
;         if (pn < 8) {
;             bf16_t* base = pn < 4 ? Q : Kn; const int colt = (pn & 3) * BM; const float sc = pn < 4 ? 0.08838834764831845f : 1.0f;
; #pragma unroll
;             for (int ai = 0; ai < 2; ++ai)
; #pragma unroll
;                 for (int m = 0; m < 4; ++m) { bf16_t* rowp = base + (size_t)(row0 + ai * HALF + m * 16) * 1024 + colt + cl;
; #pragma unroll
;                     for (int bj = 0; bj < 2; ++bj) { const f32x4 v0 = acc[ai][bj][m][0] * sc, v1 = acc[ai][bj][m][1] * sc;
;                         u32x4 w; w.x = cvt_pk_bf16(v0[0], v0[1]); w.y = cvt_pk_bf16(v0[2], v0[3]); w.z = cvt_pk_bf16(v1[0], v1[1]); w.w = cvt_pk_bf16(v1[2], v1[3]);
;                         *(u32x4*)(rowp + bj * HALF) = w; } }
;         }
;         if (pn >= 16) {
	v_pk_mul_f32 v[168:169], v[156:157], v[102:103] op_sel_hi:[0,1]
	v_pk_mul_f32 v[166:167], v[156:157], v[100:101] op_sel_hi:[0,1]
	v_cvt_pk_bf16_f32 v166, v166, v167
	v_cvt_pk_bf16_f32 v167, v168, v169
	v_cvt_pk_bf16_f32 v168, v176, v177
	v_cvt_pk_bf16_f32 v169, v174, v175
	global_store_dwordx4 v[172:173], v[166:169], off
	v_pk_mul_f32 v[174:175], v[156:157], v[74:75] op_sel_hi:[0,1]
	v_pk_mul_f32 v[176:177], v[156:157], v[72:73] op_sel_hi:[0,1]
	v_pk_mul_f32 v[168:169], v[156:157], v[82:83] op_sel_hi:[0,1]
	v_pk_mul_f32 v[166:167], v[156:157], v[80:81] op_sel_hi:[0,1]
	v_cvt_pk_bf16_f32 v166, v166, v167
	v_cvt_pk_bf16_f32 v167, v168, v169
	v_cvt_pk_bf16_f32 v168, v176, v177
	v_cvt_pk_bf16_f32 v169, v174, v175
	global_store_dwordx4 v[172:173], v[166:169], off offset:256
	v_pk_mul_f32 v[172:173], v[156:157], v[78:79] op_sel_hi:[0,1]
	v_pk_mul_f32 v[174:175], v[156:157], v[76:77] op_sel_hi:[0,1]
	v_lshlrev_b64 v[166:167], 11, v[148:149]
	v_lshl_add_u64 v[170:171], v[170:171], 0, v[166:167]
	v_pk_mul_f32 v[168:169], v[156:157], v[86:87] op_sel_hi:[0,1]
	v_pk_mul_f32 v[166:167], v[156:157], v[84:85] op_sel_hi:[0,1]
	v_cvt_pk_bf16_f32 v166, v166, v167
	v_cvt_pk_bf16_f32 v167, v168, v169
	v_cvt_pk_bf16_f32 v168, v174, v175
	v_cvt_pk_bf16_f32 v169, v172, v173
	global_store_dwordx4 v[170:171], v[166:169], off
	v_pk_mul_f32 v[172:173], v[156:157], v[66:67] op_sel_hi:[0,1]
	v_pk_mul_f32 v[174:175], v[156:157], v[64:65] op_sel_hi:[0,1]
	v_pk_mul_f32 v[168:169], v[156:157], v[70:71] op_sel_hi:[0,1]
	v_pk_mul_f32 v[166:167], v[156:157], v[68:69] op_sel_hi:[0,1]
	v_cvt_pk_bf16_f32 v166, v166, v167
	v_cvt_pk_bf16_f32 v167, v168, v169
	v_cvt_pk_bf16_f32 v168, v174, v175
	v_cvt_pk_bf16_f32 v169, v172, v173
	global_store_dwordx4 v[170:171], v[166:169], off offset:256
	v_pk_mul_f32 v[172:173], v[156:157], v[58:59] op_sel_hi:[0,1]
	s_mov_b32 s4, 0x40000
	v_pk_mul_f32 v[168:169], v[156:157], v[62:63] op_sel_hi:[0,1]
	v_pk_mul_f32 v[166:167], v[156:157], v[60:61] op_sel_hi:[0,1]
	v_pk_mul_f32 v[174:175], v[156:157], v[56:57] op_sel_hi:[0,1]
	v_cvt_pk_bf16_f32 v166, v166, v167
	v_cvt_pk_bf16_f32 v167, v168, v169
	v_cvt_pk_bf16_f32 v169, v172, v173
	v_add_co_u32_e32 v172, vcc, s4, v158
	v_cvt_pk_bf16_f32 v168, v174, v175
	s_nop 0
	v_addc_co_u32_e32 v173, vcc, 0, v159, vcc
	s_mov_b64 s[30:31], 0x40000
	global_store_dwordx4 v[172:173], v[166:169], off
	v_pk_mul_f32 v[172:173], v[156:157], v[42:43] op_sel_hi:[0,1]
	v_pk_mul_f32 v[174:175], v[156:157], v[40:41] op_sel_hi:[0,1]
	v_pk_mul_f32 v[168:169], v[156:157], v[50:51] op_sel_hi:[0,1]
	v_pk_mul_f32 v[166:167], v[156:157], v[48:49] op_sel_hi:[0,1]
	v_lshl_add_u64 v[170:171], v[158:159], 0, s[30:31]
	v_cvt_pk_bf16_f32 v166, v166, v167
	v_cvt_pk_bf16_f32 v167, v168, v169
	v_cvt_pk_bf16_f32 v168, v174, v175
	v_cvt_pk_bf16_f32 v169, v172, v173
	global_store_dwordx4 v[170:171], v[166:169], off offset:256
	v_pk_mul_f32 v[172:173], v[156:157], v[46:47] op_sel_hi:[0,1]
	s_mov_b32 s4, 0x48000
	v_pk_mul_f32 v[168:169], v[156:157], v[54:55] op_sel_hi:[0,1]
	v_pk_mul_f32 v[166:167], v[156:157], v[52:53] op_sel_hi:[0,1]
	v_pk_mul_f32 v[174:175], v[156:157], v[44:45] op_sel_hi:[0,1]
	v_cvt_pk_bf16_f32 v166, v166, v167
	v_cvt_pk_bf16_f32 v167, v168, v169
	v_cvt_pk_bf16_f32 v169, v172, v173
	v_add_co_u32_e32 v172, vcc, s4, v158
	v_cvt_pk_bf16_f32 v168, v174, v175
	s_nop 0
	v_addc_co_u32_e32 v173, vcc, 0, v159, vcc
	s_mov_b64 s[30:31], 0x48000
	global_store_dwordx4 v[172:173], v[166:169], off
	v_pk_mul_f32 v[172:173], v[156:157], v[26:27] op_sel_hi:[0,1]
	v_pk_mul_f32 v[174:175], v[156:157], v[24:25] op_sel_hi:[0,1]
	v_pk_mul_f32 v[168:169], v[156:157], v[34:35] op_sel_hi:[0,1]
	v_pk_mul_f32 v[166:167], v[156:157], v[32:33] op_sel_hi:[0,1]
	v_lshl_add_u64 v[170:171], v[158:159], 0, s[30:31]
	v_cvt_pk_bf16_f32 v166, v166, v167
	v_cvt_pk_bf16_f32 v167, v168, v169
	v_cvt_pk_bf16_f32 v168, v174, v175
	v_cvt_pk_bf16_f32 v169, v172, v173
	global_store_dwordx4 v[170:171], v[166:169], off offset:256
	v_pk_mul_f32 v[172:173], v[156:157], v[30:31] op_sel_hi:[0,1]
	v_pk_mul_f32 v[174:175], v[156:157], v[28:29] op_sel_hi:[0,1]
	v_pk_mul_f32 v[168:169], v[156:157], v[38:39] op_sel_hi:[0,1]
	v_pk_mul_f32 v[166:167], v[156:157], v[36:37] op_sel_hi:[0,1]
	v_cvt_pk_bf16_f32 v166, v166, v167
	v_cvt_pk_bf16_f32 v167, v168, v169
	v_cvt_pk_bf16_f32 v169, v172, v173
	v_add_co_u32_e32 v172, vcc, s48, v158
	v_cvt_pk_bf16_f32 v168, v174, v175
	s_nop 0
	v_addc_co_u32_e32 v173, vcc, 0, v159, vcc
	global_store_dwordx4 v[172:173], v[166:169], off
	v_pk_mul_f32 v[172:173], v[156:157], v[10:11] op_sel_hi:[0,1]
	v_pk_mul_f32 v[174:175], v[156:157], v[8:9] op_sel_hi:[0,1]
	v_pk_mul_f32 v[168:169], v[156:157], v[18:19] op_sel_hi:[0,1]
	v_pk_mul_f32 v[166:167], v[156:157], v[16:17] op_sel_hi:[0,1]
	v_lshl_add_u64 v[170:171], v[158:159], 0, s[8:9]
	v_cvt_pk_bf16_f32 v166, v166, v167
	v_cvt_pk_bf16_f32 v167, v168, v169
	v_cvt_pk_bf16_f32 v168, v174, v175
	v_cvt_pk_bf16_f32 v169, v172, v173
	global_store_dwordx4 v[170:171], v[166:169], off offset:256
	v_lshl_add_u64 v[170:171], v[158:159], 0, s[10:11]
	v_pk_mul_f32 v[172:173], v[156:157], v[14:15] op_sel_hi:[0,1]
	v_pk_mul_f32 v[168:169], v[156:157], v[22:23] op_sel_hi:[0,1]
	v_pk_mul_f32 v[166:167], v[156:157], v[20:21] op_sel_hi:[0,1]
	v_pk_mul_f32 v[174:175], v[156:157], v[12:13] op_sel_hi:[0,1]
	v_add_co_u32_e32 v158, vcc, s49, v158
	v_cvt_pk_bf16_f32 v166, v166, v167
	v_cvt_pk_bf16_f32 v167, v168, v169
	v_cvt_pk_bf16_f32 v168, v174, v175
	v_cvt_pk_bf16_f32 v169, v172, v173
	v_addc_co_u32_e32 v159, vcc, 0, v159, vcc
	global_store_dwordx4 v[158:159], v[166:169], off
	v_pk_mul_f32 v[158:159], v[156:157], v[6:7] op_sel_hi:[0,1]
	v_pk_mul_f32 v[172:173], v[156:157], v[0:1] op_sel_hi:[0,1]
	v_pk_mul_f32 v[166:167], v[156:157], v[4:5] op_sel_hi:[0,1]
	v_pk_mul_f32 v[168:169], v[156:157], v[2:3] op_sel_hi:[0,1]
	v_cvt_pk_bf16_f32 v156, v166, v167
	v_cvt_pk_bf16_f32 v157, v158, v159
	v_cvt_pk_bf16_f32 v158, v172, v173
	v_cvt_pk_bf16_f32 v159, v168, v169
	global_store_dwordx4 v[170:171], v[156:159], off offset:256
	s_cmp_lt_i32 s27, 16
	s_cbranch_scc0 .LBB0_204

; #define PG8_STAGE(bufoff, gbase, voff) do { _Pragma("unroll") for (int _i = 0; _i < 2; ++_i) \
;         __builtin_amdgcn_global_load_lds((const unsigned*)((const char*)(gbase) + (voff)[_i]), (LAS unsigned*)(lds + (bufoff) + ldsw + _i * 8192), 16, 0, 0); } while (0)
; #define PG8_LDA(dst, b, h) do { _Pragma("unroll") for (int m = 0; m < 4; ++m) _Pragma("unroll") for (int k = 0; k < 2; ++k) dst[m][k] = *(const LAS bf16x8*)(lds + PG8_SA(b, h) + aoff + m * 2048 + k * 1024); } while (0)
; #define PG8_LDB(dst, b, h) do { _Pragma("unroll") for (int n = 0; n < 2; ++n) _Pragma("unroll") for (int k = 0; k < 2; ++k) dst[n][k] = *(const LAS bf16x8*)(lds + PG8_SB(b, h) + boff + n * 2048 + k * 1024); } while (0)
; #define PG8_WAIT_V(n) asm volatile("s_waitcnt vmcnt(" #n ")" ::: "memory")
; #define PG8_WAIT_L(n) asm volatile("s_waitcnt lgkmcnt(" #n ")" ::: "memory")
; #define PG8_BAR __builtin_amdgcn_s_barrier()
; #define PG8_SCHED __builtin_amdgcn_sched_barrier(0)
; template <class Epi>
; __device__ __forceinline__ void gemm_phase(LAS unsigned char* lds, const bf16_t* A, int lda, const bf16_t* Bt, int ldb, int M, int N, int K, int asel, const Epi& E, const int fixed_round = -1) {
;     ...
;         const char* nA = has_next ? PG8_ABASE(nxt) : cA; const char* nB = has_next ? (const char*)Bt + (size_t)nxt.pn * tstepB : cB;
;         for (int t = 0; t < nt; t += 2) {
;             const bool last = (t == nt - 2);
;             const char* a1 = cA + (size_t)(t + 1) * kstep;
;             const char* a2 = last ? nA : cA + (size_t)(t + 2) * kstep; const char* b2 = last ? nB : cB + (size_t)(t + 2) * kstep;
;             const char* a3 = a2 + kstep; const char* b3 = b2 + kstep;
;             PG8_LDB(B0, 0, 0); PG8_SCHED; PG8_LDA(At, 0, 0); PG8_STAGE(PG8_SA(1, 1), a1 + hstepA, voffA);
;             PG8_WAIT_L(8); PG8_BAR; PG8_WAIT_L(0); PG8_MMA(0, 0, At, B0); PG8_BAR; PG8_SCHED;
;             PG8_LDB(B1, 0, 1); PG8_STAGE(PG8_SB(0, 0), b2, voffB);
;             PG8_BAR; PG8_WAIT_L(0); PG8_MMA(0, 1, At, B1); PG8_BAR;
;             PG8_LDA(At, 0, 1); PG8_STAGE(PG8_SA(0, 0), a2, voffA);
;             PG8_BAR; PG8_WAIT_L(0); PG8_MMA(1, 0, At, B0); PG8_BAR; PG8_SCHED;
;             PG8_STAGE(PG8_SB(0, 1), b2 + hstepB, voffB);
;             PG8_WAIT_V(6); PG8_BAR; PG8_MMA(1, 1, At, B1); PG8_BAR;
.LBB0_224:
	ds_read_b128 v[146:149], v143
	ds_read_b128 v[150:153], v143 offset:1024
	ds_read_b128 v[154:157], v143 offset:2048
	ds_read_b128 v[158:161], v143 offset:3072
	s_add_i32 m0, s7, 0xc000
	ds_read_b128 v[162:165], v144
	ds_read_b128 v[166:169], v144 offset:1024
	ds_read_b128 v[170:173], v144 offset:2048
	ds_read_b128 v[174:177], v144 offset:3072
	ds_read_b128 v[178:181], v144 offset:4096
	ds_read_b128 v[182:185], v144 offset:5120
	ds_read_b128 v[186:189], v144 offset:6144
	ds_read_b128 v[190:193], v144 offset:7168
	global_load_lds_dwordx4 v132, s[16:17]
	s_add_i32 m0, s7, 0xe000
	s_setprio 1
	global_load_lds_dwordx4 v134, s[16:17]
	s_waitcnt lgkmcnt(8)
	s_barrier
	s_waitcnt lgkmcnt(0)
	v_mfma_f32_16x16x32_bf16 v[124:127], v[162:165], v[146:149], v[124:127]
	v_mfma_f32_16x16x32_bf16 v[108:111], v[162:165], v[154:157], v[108:111]
	v_mfma_f32_16x16x32_bf16 v[120:123], v[170:173], v[146:149], v[120:123]
	v_mfma_f32_16x16x32_bf16 v[104:107], v[170:173], v[154:157], v[104:107]
	v_mfma_f32_16x16x32_bf16 v[116:119], v[178:181], v[146:149], v[116:119]
	v_mfma_f32_16x16x32_bf16 v[100:103], v[178:181], v[154:157], v[100:103]
	v_mfma_f32_16x16x32_bf16 v[112:115], v[186:189], v[146:149], v[112:115]
	v_mfma_f32_16x16x32_bf16 v[92:95], v[186:189], v[154:157], v[92:95]
	v_mfma_f32_16x16x32_bf16 v[124:127], v[166:169], v[150:153], v[124:127]
	v_mfma_f32_16x16x32_bf16 v[108:111], v[166:169], v[158:161], v[108:111]
	v_mfma_f32_16x16x32_bf16 v[120:123], v[174:177], v[150:153], v[120:123]
	v_mfma_f32_16x16x32_bf16 v[104:107], v[174:177], v[158:161], v[104:107]
	v_mfma_f32_16x16x32_bf16 v[116:119], v[182:185], v[150:153], v[116:119]
	v_mfma_f32_16x16x32_bf16 v[100:103], v[182:185], v[158:161], v[100:103]
	v_mfma_f32_16x16x32_bf16 v[112:115], v[190:193], v[150:153], v[112:115]
	v_mfma_f32_16x16x32_bf16 v[92:95], v[190:193], v[158:161], v[92:95]
	s_barrier
	s_setprio 0
	s_add_u32 s18, s16, 0xfff80080
	s_addc_u32 s19, s17, -1
	s_cmp_eq_u32 s41, 28
	s_cselect_b32 s21, s11, s19
	s_cselect_b32 s20, s37, s18
	s_cselect_b32 s19, s9, s40
	s_cselect_b32 s18, s38, s39
	s_add_i32 s42, s34, s25
	s_add_u32 s98, s18, s2
	s_addc_u32 s99, s19, s3
	s_mov_b32 m0, s42
	ds_read_b128 v[196:199], v145
	ds_read_b128 v[202:205], v145 offset:1024
	ds_read_b128 v[206:209], v145 offset:2048
	ds_read_b128 v[210:213], v145 offset:3072
	global_load_lds_dwordx4 v128, s[18:19]
	s_add_i32 m0, s42, 0x2000
	s_setprio 1
	global_load_lds_dwordx4 v130, s[18:19]
	s_barrier
	s_waitcnt lgkmcnt(0)
	v_mfma_f32_16x16x32_bf16 v[80:83], v[162:165], v[196:199], v[80:83]
	v_mfma_f32_16x16x32_bf16 v[48:51], v[162:165], v[206:209], v[48:51]
	v_mfma_f32_16x16x32_bf16 v[68:71], v[170:173], v[196:199], v[68:71]
	v_mfma_f32_16x16x32_bf16 v[40:43], v[170:173], v[206:209], v[40:43]
	v_mfma_f32_16x16x32_bf16 v[60:63], v[178:181], v[196:199], v[60:63]
	v_mfma_f32_16x16x32_bf16 v[36:39], v[178:181], v[206:209], v[36:39]
	v_mfma_f32_16x16x32_bf16 v[52:55], v[186:189], v[196:199], v[52:55]
	v_mfma_f32_16x16x32_bf16 v[28:31], v[186:189], v[206:209], v[28:31]
	v_mfma_f32_16x16x32_bf16 v[80:83], v[166:169], v[202:205], v[80:83]
	v_mfma_f32_16x16x32_bf16 v[48:51], v[166:169], v[210:213], v[48:51]
	v_mfma_f32_16x16x32_bf16 v[68:71], v[174:177], v[202:205], v[68:71]
	v_mfma_f32_16x16x32_bf16 v[40:43], v[174:177], v[210:213], v[40:43]
	v_mfma_f32_16x16x32_bf16 v[60:63], v[182:185], v[202:205], v[60:63]
	v_mfma_f32_16x16x32_bf16 v[36:39], v[182:185], v[210:213], v[36:39]
	v_mfma_f32_16x16x32_bf16 v[52:55], v[190:193], v[202:205], v[52:55]
	v_mfma_f32_16x16x32_bf16 v[28:31], v[190:193], v[210:213], v[28:31]
	s_barrier
	s_setprio 0
	s_mov_b32 m0, s7
	s_add_u32 s100, s20, s2
	s_addc_u32 s101, s21, s3
	ds_read_b128 v[162:165], v144 offset:16384
	ds_read_b128 v[166:169], v144 offset:17408
	ds_read_b128 v[170:173], v144 offset:18432
	ds_read_b128 v[174:177], v144 offset:19456
	ds_read_b128 v[178:181], v144 offset:20480
	ds_read_b128 v[182:185], v144 offset:21504
	ds_read_b128 v[186:189], v144 offset:22528
	ds_read_b128 v[190:193], v144 offset:23552
	global_load_lds_dwordx4 v128, s[20:21]
	s_mov_b32 m0, s26
	s_setprio 1
	global_load_lds_dwordx4 v130, s[20:21]
	s_barrier
	s_waitcnt lgkmcnt(0)
	v_mfma_f32_16x16x32_bf16 v[96:99], v[162:165], v[146:149], v[96:99]
	v_mfma_f32_16x16x32_bf16 v[72:75], v[162:165], v[154:157], v[72:75]
	v_mfma_f32_16x16x32_bf16 v[88:91], v[170:173], v[146:149], v[88:91]
	v_mfma_f32_16x16x32_bf16 v[64:67], v[170:173], v[154:157], v[64:67]
	v_mfma_f32_16x16x32_bf16 v[84:87], v[178:181], v[146:149], v[84:87]
	v_mfma_f32_16x16x32_bf16 v[56:59], v[178:181], v[154:157], v[56:59]
	v_mfma_f32_16x16x32_bf16 v[76:79], v[186:189], v[146:149], v[76:79]
	v_mfma_f32_16x16x32_bf16 v[44:47], v[186:189], v[154:157], v[44:47]
	v_mfma_f32_16x16x32_bf16 v[96:99], v[166:169], v[150:153], v[96:99]
	v_mfma_f32_16x16x32_bf16 v[72:75], v[166:169], v[158:161], v[72:75]
	v_mfma_f32_16x16x32_bf16 v[88:91], v[174:177], v[150:153], v[88:91]
	v_mfma_f32_16x16x32_bf16 v[64:67], v[174:177], v[158:161], v[64:67]
	v_mfma_f32_16x16x32_bf16 v[84:87], v[182:185], v[150:153], v[84:87]
	v_mfma_f32_16x16x32_bf16 v[56:59], v[182:185], v[158:161], v[56:59]
	v_mfma_f32_16x16x32_bf16 v[76:79], v[190:193], v[150:153], v[76:79]
	v_mfma_f32_16x16x32_bf16 v[44:47], v[190:193], v[158:161], v[44:47]
	s_barrier
	s_setprio 0
	s_add_u32 s42, s18, 0x80000
	s_addc_u32 s43, s19, 0
	s_add_i32 s44, s35, s25
	s_mov_b32 m0, s44
	s_nop 0
	global_load_lds_dwordx4 v128, s[42:43]
	s_add_i32 m0, s44, 0x2000
	s_setprio 1
	global_load_lds_dwordx4 v130, s[42:43]
	s_waitcnt vmcnt(6)
	s_barrier
; #define PG8_STAGE(bufoff, gbase, voff) do { _Pragma("unroll") for (int _i = 0; _i < 2; ++_i) \
;         __builtin_amdgcn_global_load_lds((const unsigned*)((const char*)(gbase) + (voff)[_i]), (LAS unsigned*)(lds + (bufoff) + ldsw + _i * 8192), 16, 0, 0); } while (0)
; #define PG8_LDA(dst, b, h) do { _Pragma("unroll") for (int m = 0; m < 4; ++m) _Pragma("unroll") for (int k = 0; k < 2; ++k) dst[m][k] = *(const LAS bf16x8*)(lds + PG8_SA(b, h) + aoff + m * 2048 + k * 1024); } while (0)
; #define PG8_LDB(dst, b, h) do { _Pragma("unroll") for (int n = 0; n < 2; ++n) _Pragma("unroll") for (int k = 0; k < 2; ++k) dst[n][k] = *(const LAS bf16x8*)(lds + PG8_SB(b, h) + boff + n * 2048 + k * 1024); } while (0)
; #define PG8_WAIT_V(n) asm volatile("s_waitcnt vmcnt(" #n ")" ::: "memory")
; #define PG8_WAIT_L(n) asm volatile("s_waitcnt lgkmcnt(" #n ")" ::: "memory")
; #define PG8_BAR __builtin_amdgcn_s_barrier()
; #define PG8_SCHED __builtin_amdgcn_sched_barrier(0)
; template <class Epi>
; __device__ __forceinline__ void gemm_phase(LAS unsigned char* lds, const bf16_t* A, int lda, const bf16_t* Bt, int ldb, int M, int N, int K, int asel, const Epi& E, const int fixed_round = -1) {
;     ...
;             PG8_WAIT_V(6); PG8_BAR; PG8_MMA(1, 1, At, B1); PG8_BAR;
;             PG8_LDB(B0, 1, 0); PG8_SCHED; PG8_LDA(At, 1, 0); PG8_STAGE(PG8_SA(0, 1), a2 + hstepA, voffA);
;             PG8_WAIT_L(8); PG8_BAR; PG8_WAIT_L(0); PG8_MMA(0, 0, At, B0); PG8_BAR; PG8_SCHED;
;             PG8_LDB(B1, 1, 1); PG8_STAGE(PG8_SB(1, 0), b3, voffB);
;             PG8_BAR; PG8_WAIT_L(0); PG8_MMA(0, 1, At, B1); PG8_BAR;
;             PG8_LDA(At, 1, 1); PG8_STAGE(PG8_SA(1, 0), a3, voffA);
;             PG8_BAR; PG8_WAIT_L(0); PG8_MMA(1, 0, At, B0); PG8_BAR; PG8_SCHED;
	v_mfma_f32_16x16x32_bf16 v[32:35], v[162:165], v[196:199], v[32:35]
	v_mfma_f32_16x16x32_bf16 v[12:15], v[162:165], v[206:209], v[12:15]
	v_mfma_f32_16x16x32_bf16 v[24:27], v[170:173], v[196:199], v[24:27]
	v_mfma_f32_16x16x32_bf16 v[8:11], v[170:173], v[206:209], v[8:11]
	v_mfma_f32_16x16x32_bf16 v[20:23], v[178:181], v[196:199], v[20:23]
	v_mfma_f32_16x16x32_bf16 v[4:7], v[178:181], v[206:209], v[4:7]
	v_mfma_f32_16x16x32_bf16 v[16:19], v[186:189], v[196:199], v[16:19]
	v_mfma_f32_16x16x32_bf16 v[0:3], v[186:189], v[206:209], v[0:3]
	v_mfma_f32_16x16x32_bf16 v[32:35], v[166:169], v[202:205], v[32:35]
	v_mfma_f32_16x16x32_bf16 v[12:15], v[166:169], v[210:213], v[12:15]
	v_mfma_f32_16x16x32_bf16 v[24:27], v[174:177], v[202:205], v[24:27]
	v_mfma_f32_16x16x32_bf16 v[8:11], v[174:177], v[210:213], v[8:11]
	v_mfma_f32_16x16x32_bf16 v[20:23], v[182:185], v[202:205], v[20:23]
	v_mfma_f32_16x16x32_bf16 v[4:7], v[182:185], v[210:213], v[4:7]
	v_mfma_f32_16x16x32_bf16 v[16:19], v[190:193], v[202:205], v[16:19]
	v_mfma_f32_16x16x32_bf16 v[0:3], v[190:193], v[210:213], v[0:3]
	s_barrier
	s_setprio 0
	s_add_i32 s42, 0, 0x18000
	v_add_u32_e32 v158, s42, v140
	ds_read_b128 v[146:149], v158
	ds_read_b128 v[150:153], v158 offset:1024
	ds_read_b128 v[154:157], v158 offset:2048
	ds_read_b128 v[158:161], v158 offset:3072
	s_add_u32 s20, s20, 0x80000
	s_addc_u32 s21, s21, 0
	s_mov_b32 m0, s27
	ds_read_b128 v[162:165], v144 offset:32768
	ds_read_b128 v[166:169], v144 offset:33792
	ds_read_b128 v[170:173], v144 offset:34816
	ds_read_b128 v[174:177], v144 offset:35840
	ds_read_b128 v[178:181], v144 offset:36864
	ds_read_b128 v[182:185], v144 offset:37888
	ds_read_b128 v[186:189], v144 offset:38912
	ds_read_b128 v[190:193], v144 offset:39936
	global_load_lds_dwordx4 v128, s[20:21]
	s_mov_b32 m0, s28
	s_setprio 1
	global_load_lds_dwordx4 v130, s[20:21]
	s_waitcnt lgkmcnt(8)
	s_barrier
	s_waitcnt lgkmcnt(0)
	v_mfma_f32_16x16x32_bf16 v[124:127], v[162:165], v[146:149], v[124:127]
	v_mfma_f32_16x16x32_bf16 v[108:111], v[162:165], v[154:157], v[108:111]
	v_mfma_f32_16x16x32_bf16 v[120:123], v[170:173], v[146:149], v[120:123]
	v_mfma_f32_16x16x32_bf16 v[104:107], v[170:173], v[154:157], v[104:107]
	v_mfma_f32_16x16x32_bf16 v[116:119], v[178:181], v[146:149], v[116:119]
	v_mfma_f32_16x16x32_bf16 v[100:103], v[178:181], v[154:157], v[100:103]
	v_mfma_f32_16x16x32_bf16 v[112:115], v[186:189], v[146:149], v[112:115]
	v_mfma_f32_16x16x32_bf16 v[92:95], v[186:189], v[154:157], v[92:95]
	v_mfma_f32_16x16x32_bf16 v[124:127], v[166:169], v[150:153], v[124:127]
	v_mfma_f32_16x16x32_bf16 v[108:111], v[166:169], v[158:161], v[108:111]
	v_mfma_f32_16x16x32_bf16 v[120:123], v[174:177], v[150:153], v[120:123]
	v_mfma_f32_16x16x32_bf16 v[104:107], v[174:177], v[158:161], v[104:107]
	v_mfma_f32_16x16x32_bf16 v[116:119], v[182:185], v[150:153], v[116:119]
	v_mfma_f32_16x16x32_bf16 v[100:103], v[182:185], v[158:161], v[100:103]
	v_mfma_f32_16x16x32_bf16 v[112:115], v[190:193], v[150:153], v[112:115]
	v_mfma_f32_16x16x32_bf16 v[92:95], v[190:193], v[158:161], v[92:95]
	s_barrier
	s_setprio 0
	s_add_i32 s20, 0, 0x1c000
	s_add_i32 s21, s42, s25
	v_add_u32_e32 v195, s20, v140
	s_mov_b32 m0, s21
	ds_read_b128 v[196:199], v195
	ds_read_b128 v[202:205], v195 offset:1024
	ds_read_b128 v[206:209], v195 offset:2048
	ds_read_b128 v[210:213], v195 offset:3072
	global_load_lds_dwordx4 v128, s[98:99]
	s_add_i32 m0, s21, 0x2000
	s_setprio 1
	global_load_lds_dwordx4 v130, s[98:99]
	s_barrier
	s_waitcnt lgkmcnt(0)
	v_mfma_f32_16x16x32_bf16 v[80:83], v[162:165], v[196:199], v[80:83]
	v_mfma_f32_16x16x32_bf16 v[48:51], v[162:165], v[206:209], v[48:51]
	v_mfma_f32_16x16x32_bf16 v[68:71], v[170:173], v[196:199], v[68:71]
	v_mfma_f32_16x16x32_bf16 v[40:43], v[170:173], v[206:209], v[40:43]
	v_mfma_f32_16x16x32_bf16 v[60:63], v[178:181], v[196:199], v[60:63]
	v_mfma_f32_16x16x32_bf16 v[36:39], v[178:181], v[206:209], v[36:39]
	v_mfma_f32_16x16x32_bf16 v[52:55], v[186:189], v[196:199], v[52:55]
	v_mfma_f32_16x16x32_bf16 v[28:31], v[186:189], v[206:209], v[28:31]
	v_mfma_f32_16x16x32_bf16 v[80:83], v[166:169], v[202:205], v[80:83]
	v_mfma_f32_16x16x32_bf16 v[48:51], v[166:169], v[210:213], v[48:51]
	v_mfma_f32_16x16x32_bf16 v[68:71], v[174:177], v[202:205], v[68:71]
	v_mfma_f32_16x16x32_bf16 v[40:43], v[174:177], v[210:213], v[40:43]
	v_mfma_f32_16x16x32_bf16 v[60:63], v[182:185], v[202:205], v[60:63]
	v_mfma_f32_16x16x32_bf16 v[36:39], v[182:185], v[210:213], v[36:39]
	v_mfma_f32_16x16x32_bf16 v[52:55], v[190:193], v[202:205], v[52:55]
	v_mfma_f32_16x16x32_bf16 v[28:31], v[190:193], v[210:213], v[28:31]
	s_barrier
	s_setprio 0
	s_mov_b32 m0, s30
	ds_read_b128 v[162:165], v144 offset:49152
	ds_read_b128 v[166:169], v144 offset:50176
	ds_read_b128 v[170:173], v144 offset:51200
	ds_read_b128 v[174:177], v144 offset:52224
	ds_read_b128 v[178:181], v144 offset:53248
	ds_read_b128 v[182:185], v144 offset:54272
	ds_read_b128 v[186:189], v144 offset:55296
	ds_read_b128 v[190:193], v144 offset:56320
	global_load_lds_dwordx4 v128, s[100:101]
	s_mov_b32 m0, s31
	s_setprio 1
	global_load_lds_dwordx4 v130, s[100:101]
	s_barrier
; #define PG8_STAGE(bufoff, gbase, voff) do { _Pragma("unroll") for (int _i = 0; _i < 2; ++_i) \
;         __builtin_amdgcn_global_load_lds((const unsigned*)((const char*)(gbase) + (voff)[_i]), (LAS unsigned*)(lds + (bufoff) + ldsw + _i * 8192), 16, 0, 0); } while (0)
; #define PG8_WAIT_V(n) asm volatile("s_waitcnt vmcnt(" #n ")" ::: "memory")
; #define PG8_WAIT_L(n) asm volatile("s_waitcnt lgkmcnt(" #n ")" ::: "memory")
; #define PG8_BAR __builtin_amdgcn_s_barrier()
; #define PG8_SCHED __builtin_amdgcn_sched_barrier(0)
; template <class Epi>
; __device__ __forceinline__ void gemm_phase(LAS unsigned char* lds, const bf16_t* A, int lda, const bf16_t* Bt, int ldb, int M, int N, int K, int asel, const Epi& E, const int fixed_round = -1) {
;     ...
;             PG8_BAR; PG8_WAIT_L(0); PG8_MMA(1, 0, At, B0); PG8_BAR; PG8_SCHED;
;             PG8_STAGE(PG8_SB(1, 1), b3 + hstepB, voffB);
;             PG8_WAIT_V(6); PG8_BAR; PG8_MMA(1, 1, At, B1); PG8_BAR;
	s_waitcnt lgkmcnt(0)
	v_mfma_f32_16x16x32_bf16 v[96:99], v[162:165], v[146:149], v[96:99]
	v_mfma_f32_16x16x32_bf16 v[72:75], v[162:165], v[154:157], v[72:75]
	v_mfma_f32_16x16x32_bf16 v[88:91], v[170:173], v[146:149], v[88:91]
	v_mfma_f32_16x16x32_bf16 v[64:67], v[170:173], v[154:157], v[64:67]
	v_mfma_f32_16x16x32_bf16 v[84:87], v[178:181], v[146:149], v[84:87]
	v_mfma_f32_16x16x32_bf16 v[56:59], v[178:181], v[154:157], v[56:59]
	v_mfma_f32_16x16x32_bf16 v[76:79], v[186:189], v[146:149], v[76:79]
	v_mfma_f32_16x16x32_bf16 v[44:47], v[186:189], v[154:157], v[44:47]
	v_mfma_f32_16x16x32_bf16 v[96:99], v[166:169], v[150:153], v[96:99]
	v_mfma_f32_16x16x32_bf16 v[72:75], v[166:169], v[158:161], v[72:75]
	v_mfma_f32_16x16x32_bf16 v[88:91], v[174:177], v[150:153], v[88:91]
	v_mfma_f32_16x16x32_bf16 v[64:67], v[174:177], v[158:161], v[64:67]
	v_mfma_f32_16x16x32_bf16 v[84:87], v[182:185], v[150:153], v[84:87]
	v_mfma_f32_16x16x32_bf16 v[56:59], v[182:185], v[158:161], v[56:59]
	v_mfma_f32_16x16x32_bf16 v[76:79], v[190:193], v[150:153], v[76:79]
	v_mfma_f32_16x16x32_bf16 v[44:47], v[190:193], v[158:161], v[44:47]
	s_barrier
	s_setprio 0
	s_add_u32 s18, s18, 0x80080
	s_addc_u32 s19, s19, 0
	s_add_i32 s20, s20, s25
	s_mov_b32 m0, s20
	s_nop 0
	global_load_lds_dwordx4 v128, s[18:19]
	s_add_i32 m0, s20, 0x2000
	s_setprio 1
	global_load_lds_dwordx4 v130, s[18:19]
	s_waitcnt vmcnt(6)
	s_barrier
	v_mfma_f32_16x16x32_bf16 v[32:35], v[162:165], v[196:199], v[32:35]
	v_mfma_f32_16x16x32_bf16 v[12:15], v[162:165], v[206:209], v[12:15]
	v_mfma_f32_16x16x32_bf16 v[24:27], v[170:173], v[196:199], v[24:27]
	v_mfma_f32_16x16x32_bf16 v[8:11], v[170:173], v[206:209], v[8:11]
	v_mfma_f32_16x16x32_bf16 v[20:23], v[178:181], v[196:199], v[20:23]
	v_mfma_f32_16x16x32_bf16 v[4:7], v[178:181], v[206:209], v[4:7]
	v_mfma_f32_16x16x32_bf16 v[16:19], v[186:189], v[196:199], v[16:19]
	v_mfma_f32_16x16x32_bf16 v[0:3], v[186:189], v[206:209], v[0:3]
	v_mfma_f32_16x16x32_bf16 v[32:35], v[166:169], v[202:205], v[32:35]
	v_mfma_f32_16x16x32_bf16 v[12:15], v[166:169], v[210:213], v[12:15]
	v_mfma_f32_16x16x32_bf16 v[24:27], v[174:177], v[202:205], v[24:27]
	v_mfma_f32_16x16x32_bf16 v[8:11], v[174:177], v[210:213], v[8:11]
	v_mfma_f32_16x16x32_bf16 v[20:23], v[182:185], v[202:205], v[20:23]
	v_mfma_f32_16x16x32_bf16 v[4:7], v[182:185], v[210:213], v[4:7]
	v_mfma_f32_16x16x32_bf16 v[16:19], v[190:193], v[202:205], v[16:19]
	v_mfma_f32_16x16x32_bf16 v[0:3], v[190:193], v[210:213], v[0:3]
	s_setprio 0
	s_add_i32 s41, s41, 2
	s_add_u32 s16, s16, 0x100
	s_addc_u32 s17, s17, 0
	s_add_u32 s39, s39, 0x100
	s_addc_u32 s40, s40, 0
	s_cmp_gt_u32 s41, 29
	s_cbranch_scc0 .Lrot_2
	s_barrier
; __device__ __forceinline__ unsigned cvt_pk_bf16(float lo, float hi) { const bf16x2_t r = __builtin_convertvector((f32x2){lo, hi}, bf16x2_t); return __builtin_bit_cast(unsigned, r); }
; #define PG8_WAIT_V(n) asm volatile("s_waitcnt vmcnt(" #n ")" ::: "memory")
; #define PG8_BAR __builtin_amdgcn_s_barrier()
; template <class Epi>
; __device__ __forceinline__ void gemm_phase(LAS unsigned char* lds, const bf16_t* A, int lda, const bf16_t* Bt, int ldb, int M, int N, int K, int asel, const Epi& E, const int fixed_round = -1) {
;     ...
;         if (!has_next) break;
; #pragma unroll
;         for (int a = 0; a < 2; ++a)
; #pragma unroll
;             for (int b = 0; b < 2; ++b)
; #pragma unroll
;                 for (int m = 0; m < 4; ++m)
; #pragma unroll
;                     for (int n = 0; n < 2; ++n) acc[a][b][m][n] = (f32x4){0.f, 0.f, 0.f, 0.f};
;         cur = nxt; cA = nA; cB = nB; ++ui;
;     }
;     PG8_WAIT_V(0);
;     if (wr == 0) PG8_BAR;
;     PG8_BAR;
;     __device__ __forceinline__ void operator()(const AccT& acc, const Unit& u, int wr, int wc, int fr, int fq) const {
;         const int bb = u.pm >> 4, s0 = (u.pm & 15) * BM + wr * 64 + 4 * fq, feat0 = u.pn * BM + wc * 32 + fr;
; #pragma unroll
;         for (int bj = 0; bj < 2; ++bj)
; #pragma unroll
;             for (int n = 0; n < 2; ++n) { bf16_t* fp = VT + ((size_t)bb * 2048 + feat0 + bj * HALF + n * 16) * SEQ + s0;
; #pragma unroll
;                 for (int ai = 0; ai < 2; ++ai)
; #pragma unroll
;                     for (int m = 0; m < 4; ++m) { const f32x4 v = acc[ai][bj][m][n]; u32x2 w; w.x = cvt_pk_bf16(v[0], v[1]); w.y = cvt_pk_bf16(v[2], v[3]);
;                         *(u32x2*)(fp + ai * HALF + m * 16) = w; } }
;     }
	s_ashr_i32 s16, s6, 4
	v_lshl_or_b32 v148, s36, 8, v142
	s_lshl_b32 s6, s6, 8
	s_ashr_i32 s17, s16, 31
	v_ashrrev_i32_e32 v149, 31, v148
	s_and_b32 s6, s6, 0xf00
	s_lshl_b64 s[16:17], s[16:17], 24
	v_lshlrev_b64 v[148:149], 13, v[148:149]
	v_add_u32_e32 v146, s6, v141
	v_lshl_add_u64 v[148:149], v[148:149], 0, s[16:17]
	v_readlane_b32 s16, v254, 47
	v_ashrrev_i32_e32 v147, 31, v146
	v_readlane_b32 s17, v254, 48
	v_lshlrev_b64 v[146:147], 1, v[146:147]
	v_cvt_pk_bf16_f32 v76, v76, v77
	v_lshl_add_u64 v[150:151], s[16:17], 0, v[148:149]
	v_lshl_add_u64 v[150:151], v[150:151], 0, v[146:147]
	v_cvt_pk_bf16_f32 v77, v78, v79
	global_store_dwordx2 v[150:151], v[76:77], off offset:352
	v_or_b32_e32 v76, 0x20000, v148
	v_mov_b32_e32 v77, v149
	v_lshl_add_u64 v[76:77], s[16:17], 0, v[76:77]
	v_cvt_pk_bf16_f32 v124, v124, v125
	v_cvt_pk_bf16_f32 v125, v126, v127
	v_cvt_pk_bf16_f32 v120, v120, v121
	v_cvt_pk_bf16_f32 v121, v122, v123
	v_cvt_pk_bf16_f32 v116, v116, v117
	v_cvt_pk_bf16_f32 v117, v118, v119
	v_cvt_pk_bf16_f32 v112, v112, v113
	v_cvt_pk_bf16_f32 v113, v114, v115
	v_cvt_pk_bf16_f32 v96, v96, v97
	v_cvt_pk_bf16_f32 v97, v98, v99
	v_cvt_pk_bf16_f32 v88, v88, v89
	v_cvt_pk_bf16_f32 v89, v90, v91
	v_cvt_pk_bf16_f32 v84, v84, v85
	v_cvt_pk_bf16_f32 v85, v86, v87
	v_lshl_add_u64 v[76:77], v[76:77], 0, v[146:147]
	v_cvt_pk_bf16_f32 v78, v108, v109
	v_cvt_pk_bf16_f32 v79, v110, v111
	v_cvt_pk_bf16_f32 v44, v44, v45
	v_cvt_pk_bf16_f32 v45, v46, v47
	global_store_dwordx2 v[150:151], v[124:125], off
	global_store_dwordx2 v[150:151], v[120:121], off offset:32
	global_store_dwordx2 v[150:151], v[116:117], off offset:64
	global_store_dwordx2 v[150:151], v[112:113], off offset:96
	global_store_dwordx2 v[150:151], v[96:97], off offset:256
	global_store_dwordx2 v[150:151], v[88:89], off offset:288
	global_store_dwordx2 v[150:151], v[84:85], off offset:320
	global_store_dwordx2 v[76:77], v[78:79], off
	v_cvt_pk_bf16_f32 v78, v104, v105
	v_cvt_pk_bf16_f32 v79, v106, v107
	global_store_dwordx2 v[76:77], v[44:45], off offset:352
	v_or_b32_e32 v44, 0x100000, v148
	v_mov_b32_e32 v45, v149
	global_store_dwordx2 v[76:77], v[78:79], off offset:32
	v_cvt_pk_bf16_f32 v78, v100, v101
	v_cvt_pk_bf16_f32 v79, v102, v103
	v_lshl_add_u64 v[44:45], s[16:17], 0, v[44:45]
	global_store_dwordx2 v[76:77], v[78:79], off offset:64
	v_cvt_pk_bf16_f32 v78, v92, v93
	v_cvt_pk_bf16_f32 v79, v94, v95
	v_cvt_pk_bf16_f32 v72, v72, v73
	v_cvt_pk_bf16_f32 v73, v74, v75
	v_cvt_pk_bf16_f32 v64, v64, v65
	v_cvt_pk_bf16_f32 v65, v66, v67
	v_cvt_pk_bf16_f32 v56, v56, v57
	v_cvt_pk_bf16_f32 v57, v58, v59
	v_lshl_add_u64 v[44:45], v[44:45], 0, v[146:147]
	v_cvt_pk_bf16_f32 v46, v80, v81
	v_cvt_pk_bf16_f32 v47, v82, v83
	global_store_dwordx2 v[76:77], v[78:79], off offset:96
	global_store_dwordx2 v[76:77], v[72:73], off offset:256
	global_store_dwordx2 v[76:77], v[64:65], off offset:288
	global_store_dwordx2 v[76:77], v[56:57], off offset:320
	global_store_dwordx2 v[44:45], v[46:47], off
	v_cvt_pk_bf16_f32 v46, v68, v69
	v_cvt_pk_bf16_f32 v47, v70, v71
	v_cvt_pk_bf16_f32 v16, v16, v17
	v_cvt_pk_bf16_f32 v17, v18, v19
	v_or_b32_e32 v148, 0x120000, v148
	global_store_dwordx2 v[44:45], v[46:47], off offset:32
	v_cvt_pk_bf16_f32 v46, v60, v61
	v_cvt_pk_bf16_f32 v47, v62, v63
	global_store_dwordx2 v[44:45], v[16:17], off offset:352
	v_lshl_add_u64 v[16:17], s[16:17], 0, v[148:149]
	global_store_dwordx2 v[44:45], v[46:47], off offset:64
	v_cvt_pk_bf16_f32 v46, v52, v53
	v_cvt_pk_bf16_f32 v47, v54, v55
	v_cvt_pk_bf16_f32 v32, v32, v33
	v_cvt_pk_bf16_f32 v33, v34, v35
	v_cvt_pk_bf16_f32 v24, v24, v25
	v_cvt_pk_bf16_f32 v25, v26, v27
	v_cvt_pk_bf16_f32 v20, v20, v21
	v_cvt_pk_bf16_f32 v21, v22, v23
	v_lshl_add_u64 v[16:17], v[16:17], 0, v[146:147]
	v_cvt_pk_bf16_f32 v18, v48, v49
	v_cvt_pk_bf16_f32 v19, v50, v51
	global_store_dwordx2 v[44:45], v[46:47], off offset:96
	global_store_dwordx2 v[44:45], v[32:33], off offset:256
	global_store_dwordx2 v[44:45], v[24:25], off offset:288
	global_store_dwordx2 v[44:45], v[20:21], off offset:320
	global_store_dwordx2 v[16:17], v[18:19], off
	v_cvt_pk_bf16_f32 v18, v40, v41
	v_cvt_pk_bf16_f32 v19, v42, v43
	global_store_dwordx2 v[16:17], v[18:19], off offset:32
	v_cvt_pk_bf16_f32 v18, v36, v37
	v_cvt_pk_bf16_f32 v19, v38, v39
	global_store_dwordx2 v[16:17], v[18:19], off offset:64
	v_cvt_pk_bf16_f32 v18, v28, v29
	v_cvt_pk_bf16_f32 v19, v30, v31
	v_cvt_pk_bf16_f32 v12, v12, v13
	v_cvt_pk_bf16_f32 v13, v14, v15
	v_cvt_pk_bf16_f32 v8, v8, v9
	v_cvt_pk_bf16_f32 v9, v10, v11
	v_cvt_pk_bf16_f32 v4, v4, v5
	v_cvt_pk_bf16_f32 v5, v6, v7
	v_cvt_pk_bf16_f32 v0, v0, v1
	v_cvt_pk_bf16_f32 v1, v2, v3
	s_and_b64 vcc, exec, s[4:5]
	s_mov_b32 s36, s8
	s_mov_b32 s6, s10
	s_mov_b64 s[18:19], s[14:15]
	s_mov_b64 s[16:17], s[12:13]
	global_store_dwordx2 v[16:17], v[18:19], off offset:96
	global_store_dwordx2 v[16:17], v[12:13], off offset:256
	global_store_dwordx2 v[16:17], v[8:9], off offset:288
	global_store_dwordx2 v[16:17], v[4:5], off offset:320
	global_store_dwordx2 v[16:17], v[0:1], off offset:352
	s_cbranch_vccz .LBB0_217
	s_waitcnt vmcnt(0)
	s_cmpk_gt_u32 s22, 0xff
	s_cbranch_scc1 .LBB0_228
	s_barrier

; #define PG8_STAGE(bufoff, gbase, voff) do { _Pragma("unroll") for (int _i = 0; _i < 2; ++_i) \
;         __builtin_amdgcn_global_load_lds((const unsigned*)((const char*)(gbase) + (voff)[_i]), (LAS unsigned*)(lds + (bufoff) + ldsw + _i * 8192), 16, 0, 0); } while (0)
; #define PG8_LDA(dst, b, h) do { _Pragma("unroll") for (int m = 0; m < 4; ++m) _Pragma("unroll") for (int k = 0; k < 2; ++k) dst[m][k] = *(const LAS bf16x8*)(lds + PG8_SA(b, h) + aoff + m * 2048 + k * 1024); } while (0)
; #define PG8_LDB(dst, b, h) do { _Pragma("unroll") for (int n = 0; n < 2; ++n) _Pragma("unroll") for (int k = 0; k < 2; ++k) dst[n][k] = *(const LAS bf16x8*)(lds + PG8_SB(b, h) + boff + n * 2048 + k * 1024); } while (0)
; #define PG8_WAIT_V(n) asm volatile("s_waitcnt vmcnt(" #n ")" ::: "memory")
; #define PG8_WAIT_L(n) asm volatile("s_waitcnt lgkmcnt(" #n ")" ::: "memory")
; #define PG8_BAR __builtin_amdgcn_s_barrier()
; #define PG8_SCHED __builtin_amdgcn_sched_barrier(0)
; template <class Epi>
; __device__ __forceinline__ void gemm_phase(LAS unsigned char* lds, const bf16_t* A, int lda, const bf16_t* Bt, int ldb, int M, int N, int K, int asel, const Epi& E, const int fixed_round = -1) {
;     ...
;         const char* nA = has_next ? PG8_ABASE(nxt) : cA; const char* nB = has_next ? (const char*)Bt + (size_t)nxt.pn * tstepB : cB;
;         for (int t = 0; t < nt; t += 2) {
;             const bool last = (t == nt - 2);
;             const char* a1 = cA + (size_t)(t + 1) * kstep;
;             const char* a2 = last ? nA : cA + (size_t)(t + 2) * kstep; const char* b2 = last ? nB : cB + (size_t)(t + 2) * kstep;
;             const char* a3 = a2 + kstep; const char* b3 = b2 + kstep;
;             PG8_LDB(B0, 0, 0); PG8_SCHED; PG8_LDA(At, 0, 0); PG8_STAGE(PG8_SA(1, 1), a1 + hstepA, voffA);
;             PG8_WAIT_L(8); PG8_BAR; PG8_WAIT_L(0); PG8_MMA(0, 0, At, B0); PG8_BAR; PG8_SCHED;
;             PG8_LDB(B1, 0, 1); PG8_STAGE(PG8_SB(0, 0), b2, voffB);
;             PG8_BAR; PG8_WAIT_L(0); PG8_MMA(0, 1, At, B1); PG8_BAR;
;             PG8_LDA(At, 0, 1); PG8_STAGE(PG8_SA(0, 0), a2, voffA);
;             PG8_BAR; PG8_WAIT_L(0); PG8_MMA(1, 0, At, B0); PG8_BAR; PG8_SCHED;
;             PG8_STAGE(PG8_SB(0, 1), b2 + hstepB, voffB);
;             PG8_WAIT_V(6); PG8_BAR; PG8_MMA(1, 1, At, B1); PG8_BAR;
.LBB0_245:
	ds_read_b128 v[148:151], v161
	ds_read_b128 v[152:155], v161 offset:1024
	ds_read_b128 v[156:159], v161 offset:2048
	ds_read_b128 v[166:169], v161 offset:3072
	s_add_i32 m0, s37, 0xc000
	ds_read_b128 v[170:173], v162
	ds_read_b128 v[174:177], v162 offset:1024
	ds_read_b128 v[178:181], v162 offset:2048
	ds_read_b128 v[182:185], v162 offset:3072
	ds_read_b128 v[186:189], v162 offset:4096
	ds_read_b128 v[190:193], v162 offset:5120
	ds_read_b128 v[196:199], v162 offset:6144
	ds_read_b128 v[202:205], v162 offset:7168
	global_load_lds_dwordx4 v140, s[26:27]
	s_add_i32 m0, s37, 0xe000
	s_setprio 1
	global_load_lds_dwordx4 v142, s[26:27]
	s_waitcnt lgkmcnt(8)
	s_barrier
	s_waitcnt lgkmcnt(0)
	v_mfma_f32_16x16x32_bf16 v[124:127], v[148:151], v[170:173], v[124:127]
	v_mfma_f32_16x16x32_bf16 v[120:123], v[156:159], v[170:173], v[120:123]
	v_mfma_f32_16x16x32_bf16 v[112:115], v[148:151], v[178:181], v[112:115]
	v_mfma_f32_16x16x32_bf16 v[108:111], v[156:159], v[178:181], v[108:111]
	v_mfma_f32_16x16x32_bf16 v[100:103], v[148:151], v[186:189], v[100:103]
	v_mfma_f32_16x16x32_bf16 v[92:95], v[156:159], v[186:189], v[92:95]
	v_mfma_f32_16x16x32_bf16 v[84:87], v[148:151], v[196:199], v[84:87]
	v_mfma_f32_16x16x32_bf16 v[76:79], v[156:159], v[196:199], v[76:79]
	v_mfma_f32_16x16x32_bf16 v[124:127], v[152:155], v[174:177], v[124:127]
	v_mfma_f32_16x16x32_bf16 v[120:123], v[166:169], v[174:177], v[120:123]
	v_mfma_f32_16x16x32_bf16 v[112:115], v[152:155], v[182:185], v[112:115]
	v_mfma_f32_16x16x32_bf16 v[108:111], v[166:169], v[182:185], v[108:111]
	v_mfma_f32_16x16x32_bf16 v[100:103], v[152:155], v[190:193], v[100:103]
	v_mfma_f32_16x16x32_bf16 v[92:95], v[166:169], v[190:193], v[92:95]
	v_mfma_f32_16x16x32_bf16 v[84:87], v[152:155], v[202:205], v[84:87]
	v_mfma_f32_16x16x32_bf16 v[76:79], v[166:169], v[202:205], v[76:79]
	s_barrier
	s_setprio 0
	s_add_u32 s28, s26, 0xfff80080
	s_addc_u32 s29, s27, -1
	s_cmp_eq_u32 s57, 28
	s_cselect_b32 s31, s2, s29
	s_cselect_b32 s30, s19, s28
	s_cselect_b32 s29, s17, s56
	s_cselect_b32 s28, s54, s55
	s_add_i32 s58, s44, s36
	s_add_u32 s98, s28, s4
	s_addc_u32 s99, s29, s5
	s_mov_b32 m0, s58
	ds_read_b128 v[206:209], v163
	ds_read_b128 v[210:213], v163 offset:1024
	ds_read_b128 v[214:217], v163 offset:2048
	ds_read_b128 v[218:221], v163 offset:3072
	global_load_lds_dwordx4 v130, s[28:29]
	s_add_i32 m0, s58, 0x2000
	s_setprio 1
	global_load_lds_dwordx4 v134, s[28:29]
	s_barrier
	s_waitcnt lgkmcnt(0)
	v_mfma_f32_16x16x32_bf16 v[116:119], v[206:209], v[170:173], v[116:119]
	v_mfma_f32_16x16x32_bf16 v[104:107], v[214:217], v[170:173], v[104:107]
	v_mfma_f32_16x16x32_bf16 v[96:99], v[206:209], v[178:181], v[96:99]
	v_mfma_f32_16x16x32_bf16 v[88:91], v[214:217], v[178:181], v[88:91]
	v_mfma_f32_16x16x32_bf16 v[80:83], v[206:209], v[186:189], v[80:83]
	v_mfma_f32_16x16x32_bf16 v[72:75], v[214:217], v[186:189], v[72:75]
	v_mfma_f32_16x16x32_bf16 v[68:71], v[206:209], v[196:199], v[68:71]
	v_mfma_f32_16x16x32_bf16 v[64:67], v[214:217], v[196:199], v[64:67]
	v_mfma_f32_16x16x32_bf16 v[116:119], v[210:213], v[174:177], v[116:119]
	v_mfma_f32_16x16x32_bf16 v[104:107], v[218:221], v[174:177], v[104:107]
	v_mfma_f32_16x16x32_bf16 v[96:99], v[210:213], v[182:185], v[96:99]
	v_mfma_f32_16x16x32_bf16 v[88:91], v[218:221], v[182:185], v[88:91]
	v_mfma_f32_16x16x32_bf16 v[80:83], v[210:213], v[190:193], v[80:83]
	v_mfma_f32_16x16x32_bf16 v[72:75], v[218:221], v[190:193], v[72:75]
	v_mfma_f32_16x16x32_bf16 v[68:71], v[210:213], v[202:205], v[68:71]
	v_mfma_f32_16x16x32_bf16 v[64:67], v[218:221], v[202:205], v[64:67]
	s_barrier
	s_setprio 0
	s_mov_b32 m0, s37
	s_add_u32 s100, s30, s4
	s_addc_u32 s101, s31, s5
	ds_read_b128 v[170:173], v162 offset:16384
	ds_read_b128 v[174:177], v162 offset:17408
	ds_read_b128 v[178:181], v162 offset:18432
	ds_read_b128 v[182:185], v162 offset:19456
	ds_read_b128 v[186:189], v162 offset:20480
	ds_read_b128 v[190:193], v162 offset:21504
	ds_read_b128 v[196:199], v162 offset:22528
	ds_read_b128 v[202:205], v162 offset:23552
	global_load_lds_dwordx4 v128, s[30:31]
	s_mov_b32 m0, s38
	s_setprio 1
	global_load_lds_dwordx4 v132, s[30:31]
	s_barrier
	s_waitcnt lgkmcnt(0)
	v_mfma_f32_16x16x32_bf16 v[60:63], v[148:151], v[170:173], v[60:63]
	v_mfma_f32_16x16x32_bf16 v[56:59], v[156:159], v[170:173], v[56:59]
	v_mfma_f32_16x16x32_bf16 v[52:55], v[148:151], v[178:181], v[52:55]
	v_mfma_f32_16x16x32_bf16 v[44:47], v[156:159], v[178:181], v[44:47]
	v_mfma_f32_16x16x32_bf16 v[36:39], v[148:151], v[186:189], v[36:39]
	v_mfma_f32_16x16x32_bf16 v[28:31], v[156:159], v[186:189], v[28:31]
	v_mfma_f32_16x16x32_bf16 v[20:23], v[148:151], v[196:199], v[20:23]
	v_mfma_f32_16x16x32_bf16 v[12:15], v[156:159], v[196:199], v[12:15]
	v_mfma_f32_16x16x32_bf16 v[60:63], v[152:155], v[174:177], v[60:63]
	v_mfma_f32_16x16x32_bf16 v[56:59], v[166:169], v[174:177], v[56:59]
	v_mfma_f32_16x16x32_bf16 v[52:55], v[152:155], v[182:185], v[52:55]
	v_mfma_f32_16x16x32_bf16 v[44:47], v[166:169], v[182:185], v[44:47]
	v_mfma_f32_16x16x32_bf16 v[36:39], v[152:155], v[190:193], v[36:39]
	v_mfma_f32_16x16x32_bf16 v[28:31], v[166:169], v[190:193], v[28:31]
	v_mfma_f32_16x16x32_bf16 v[20:23], v[152:155], v[202:205], v[20:23]
	v_mfma_f32_16x16x32_bf16 v[12:15], v[166:169], v[202:205], v[12:15]
	s_barrier
	s_setprio 0
	s_add_u32 s58, s28, 0x80000
	s_addc_u32 s59, s29, 0
	s_add_i32 s60, s45, s36
	s_mov_b32 m0, s60
	s_nop 0
	global_load_lds_dwordx4 v130, s[58:59]
	s_add_i32 m0, s60, 0x2000
	s_setprio 1
	global_load_lds_dwordx4 v134, s[58:59]
	s_waitcnt vmcnt(6)
	s_barrier
; #define PG8_STAGE(bufoff, gbase, voff) do { _Pragma("unroll") for (int _i = 0; _i < 2; ++_i) \
;         __builtin_amdgcn_global_load_lds((const unsigned*)((const char*)(gbase) + (voff)[_i]), (LAS unsigned*)(lds + (bufoff) + ldsw + _i * 8192), 16, 0, 0); } while (0)
; #define PG8_LDA(dst, b, h) do { _Pragma("unroll") for (int m = 0; m < 4; ++m) _Pragma("unroll") for (int k = 0; k < 2; ++k) dst[m][k] = *(const LAS bf16x8*)(lds + PG8_SA(b, h) + aoff + m * 2048 + k * 1024); } while (0)
; #define PG8_LDB(dst, b, h) do { _Pragma("unroll") for (int n = 0; n < 2; ++n) _Pragma("unroll") for (int k = 0; k < 2; ++k) dst[n][k] = *(const LAS bf16x8*)(lds + PG8_SB(b, h) + boff + n * 2048 + k * 1024); } while (0)
; #define PG8_WAIT_V(n) asm volatile("s_waitcnt vmcnt(" #n ")" ::: "memory")
; #define PG8_WAIT_L(n) asm volatile("s_waitcnt lgkmcnt(" #n ")" ::: "memory")
; #define PG8_BAR __builtin_amdgcn_s_barrier()
; #define PG8_SCHED __builtin_amdgcn_sched_barrier(0)
; template <class Epi>
; __device__ __forceinline__ void gemm_phase(LAS unsigned char* lds, const bf16_t* A, int lda, const bf16_t* Bt, int ldb, int M, int N, int K, int asel, const Epi& E, const int fixed_round = -1) {
;     ...
;             PG8_WAIT_V(6); PG8_BAR; PG8_MMA(1, 1, At, B1); PG8_BAR;
;             PG8_LDB(B0, 1, 0); PG8_SCHED; PG8_LDA(At, 1, 0); PG8_STAGE(PG8_SA(0, 1), a2 + hstepA, voffA);
;             PG8_WAIT_L(8); PG8_BAR; PG8_WAIT_L(0); PG8_MMA(0, 0, At, B0); PG8_BAR; PG8_SCHED;
;             PG8_LDB(B1, 1, 1); PG8_STAGE(PG8_SB(1, 0), b3, voffB);
;             PG8_BAR; PG8_WAIT_L(0); PG8_MMA(0, 1, At, B1); PG8_BAR;
;             PG8_LDA(At, 1, 1); PG8_STAGE(PG8_SA(1, 0), a3, voffA);
;             PG8_BAR; PG8_WAIT_L(0); PG8_MMA(1, 0, At, B0); PG8_BAR; PG8_SCHED;
	v_mfma_f32_16x16x32_bf16 v[48:51], v[206:209], v[170:173], v[48:51]
	v_mfma_f32_16x16x32_bf16 v[40:43], v[214:217], v[170:173], v[40:43]
	v_mfma_f32_16x16x32_bf16 v[32:35], v[206:209], v[178:181], v[32:35]
	v_mfma_f32_16x16x32_bf16 v[24:27], v[214:217], v[178:181], v[24:27]
	v_mfma_f32_16x16x32_bf16 v[16:19], v[206:209], v[186:189], v[16:19]
	v_mfma_f32_16x16x32_bf16 v[8:11], v[214:217], v[186:189], v[8:11]
	v_mfma_f32_16x16x32_bf16 v[4:7], v[206:209], v[196:199], v[4:7]
	v_mfma_f32_16x16x32_bf16 v[0:3], v[214:217], v[196:199], v[0:3]
	v_mfma_f32_16x16x32_bf16 v[48:51], v[210:213], v[174:177], v[48:51]
	v_mfma_f32_16x16x32_bf16 v[40:43], v[218:221], v[174:177], v[40:43]
	v_mfma_f32_16x16x32_bf16 v[32:35], v[210:213], v[182:185], v[32:35]
	v_mfma_f32_16x16x32_bf16 v[24:27], v[218:221], v[182:185], v[24:27]
	v_mfma_f32_16x16x32_bf16 v[16:19], v[210:213], v[190:193], v[16:19]
	v_mfma_f32_16x16x32_bf16 v[8:11], v[218:221], v[190:193], v[8:11]
	v_mfma_f32_16x16x32_bf16 v[4:7], v[210:213], v[202:205], v[4:7]
	v_mfma_f32_16x16x32_bf16 v[0:3], v[218:221], v[202:205], v[0:3]
	s_barrier
	s_setprio 0
	s_add_i32 s58, 0, 0x18000
	v_add_u32_e32 v136, s58, v160
	ds_read_b128 v[148:151], v136
	ds_read_b128 v[152:155], v136 offset:1024
	ds_read_b128 v[156:159], v136 offset:2048
	ds_read_b128 v[166:169], v136 offset:3072
	s_add_u32 s30, s30, 0x80000
	s_addc_u32 s31, s31, 0
	s_mov_b32 m0, s39
	ds_read_b128 v[170:173], v162 offset:32768
	ds_read_b128 v[174:177], v162 offset:33792
	ds_read_b128 v[178:181], v162 offset:34816
	ds_read_b128 v[182:185], v162 offset:35840
	ds_read_b128 v[186:189], v162 offset:36864
	ds_read_b128 v[190:193], v162 offset:37888
	ds_read_b128 v[196:199], v162 offset:38912
	ds_read_b128 v[202:205], v162 offset:39936
	global_load_lds_dwordx4 v128, s[30:31]
	s_mov_b32 m0, s40
	s_setprio 1
	global_load_lds_dwordx4 v132, s[30:31]
	s_waitcnt lgkmcnt(8)
	s_barrier
	s_waitcnt lgkmcnt(0)
	v_mfma_f32_16x16x32_bf16 v[124:127], v[148:151], v[170:173], v[124:127]
	v_mfma_f32_16x16x32_bf16 v[120:123], v[156:159], v[170:173], v[120:123]
	v_mfma_f32_16x16x32_bf16 v[112:115], v[148:151], v[178:181], v[112:115]
	v_mfma_f32_16x16x32_bf16 v[108:111], v[156:159], v[178:181], v[108:111]
	v_mfma_f32_16x16x32_bf16 v[100:103], v[148:151], v[186:189], v[100:103]
	v_mfma_f32_16x16x32_bf16 v[92:95], v[156:159], v[186:189], v[92:95]
	v_mfma_f32_16x16x32_bf16 v[84:87], v[148:151], v[196:199], v[84:87]
	v_mfma_f32_16x16x32_bf16 v[76:79], v[156:159], v[196:199], v[76:79]
	v_mfma_f32_16x16x32_bf16 v[124:127], v[152:155], v[174:177], v[124:127]
	v_mfma_f32_16x16x32_bf16 v[120:123], v[166:169], v[174:177], v[120:123]
	v_mfma_f32_16x16x32_bf16 v[112:115], v[152:155], v[182:185], v[112:115]
	v_mfma_f32_16x16x32_bf16 v[108:111], v[166:169], v[182:185], v[108:111]
	v_mfma_f32_16x16x32_bf16 v[100:103], v[152:155], v[190:193], v[100:103]
	v_mfma_f32_16x16x32_bf16 v[92:95], v[166:169], v[190:193], v[92:95]
	v_mfma_f32_16x16x32_bf16 v[84:87], v[152:155], v[202:205], v[84:87]
	v_mfma_f32_16x16x32_bf16 v[76:79], v[166:169], v[202:205], v[76:79]
	s_barrier
	s_setprio 0
	s_add_i32 s30, 0, 0x1c000
	s_add_i32 s31, s58, s36
	v_add_u32_e32 v136, s30, v160
	s_mov_b32 m0, s31
	ds_read_b128 v[206:209], v136
	ds_read_b128 v[210:213], v136 offset:1024
	ds_read_b128 v[214:217], v136 offset:2048
	ds_read_b128 v[218:221], v136 offset:3072
	global_load_lds_dwordx4 v130, s[98:99]
	s_add_i32 m0, s31, 0x2000
	s_setprio 1
	global_load_lds_dwordx4 v134, s[98:99]
	s_barrier
	s_waitcnt lgkmcnt(0)
	v_mfma_f32_16x16x32_bf16 v[116:119], v[206:209], v[170:173], v[116:119]
	v_mfma_f32_16x16x32_bf16 v[104:107], v[214:217], v[170:173], v[104:107]
	v_mfma_f32_16x16x32_bf16 v[96:99], v[206:209], v[178:181], v[96:99]
	v_mfma_f32_16x16x32_bf16 v[88:91], v[214:217], v[178:181], v[88:91]
	v_mfma_f32_16x16x32_bf16 v[80:83], v[206:209], v[186:189], v[80:83]
	v_mfma_f32_16x16x32_bf16 v[72:75], v[214:217], v[186:189], v[72:75]
	v_mfma_f32_16x16x32_bf16 v[68:71], v[206:209], v[196:199], v[68:71]
	v_mfma_f32_16x16x32_bf16 v[64:67], v[214:217], v[196:199], v[64:67]
	v_mfma_f32_16x16x32_bf16 v[116:119], v[210:213], v[174:177], v[116:119]
	v_mfma_f32_16x16x32_bf16 v[104:107], v[218:221], v[174:177], v[104:107]
	v_mfma_f32_16x16x32_bf16 v[96:99], v[210:213], v[182:185], v[96:99]
	v_mfma_f32_16x16x32_bf16 v[88:91], v[218:221], v[182:185], v[88:91]
	v_mfma_f32_16x16x32_bf16 v[80:83], v[210:213], v[190:193], v[80:83]
	v_mfma_f32_16x16x32_bf16 v[72:75], v[218:221], v[190:193], v[72:75]
	v_mfma_f32_16x16x32_bf16 v[68:71], v[210:213], v[202:205], v[68:71]
	v_mfma_f32_16x16x32_bf16 v[64:67], v[218:221], v[202:205], v[64:67]
	s_barrier
	s_setprio 0
	s_mov_b32 m0, s41
	ds_read_b128 v[170:173], v162 offset:49152
	ds_read_b128 v[174:177], v162 offset:50176
	ds_read_b128 v[178:181], v162 offset:51200
	ds_read_b128 v[182:185], v162 offset:52224
	ds_read_b128 v[186:189], v162 offset:53248
	ds_read_b128 v[190:193], v162 offset:54272
	ds_read_b128 v[196:199], v162 offset:55296
	ds_read_b128 v[202:205], v162 offset:56320
	global_load_lds_dwordx4 v128, s[100:101]
	s_mov_b32 m0, s42
	s_setprio 1
	global_load_lds_dwordx4 v132, s[100:101]
	s_barrier
; __device__ __forceinline__ unsigned cvt_pk_bf16(float lo, float hi) { const bf16x2_t r = __builtin_convertvector((f32x2){lo, hi}, bf16x2_t); return __builtin_bit_cast(unsigned, r); }
; #define PG8_STAGE(bufoff, gbase, voff) do { _Pragma("unroll") for (int _i = 0; _i < 2; ++_i) \
;         __builtin_amdgcn_global_load_lds((const unsigned*)((const char*)(gbase) + (voff)[_i]), (LAS unsigned*)(lds + (bufoff) + ldsw + _i * 8192), 16, 0, 0); } while (0)
; #define PG8_WAIT_V(n) asm volatile("s_waitcnt vmcnt(" #n ")" ::: "memory")
; #define PG8_BAR __builtin_amdgcn_s_barrier()
; template <class Epi>
; __device__ __forceinline__ void gemm_phase(LAS unsigned char* lds, const bf16_t* A, int lda, const bf16_t* Bt, int ldb, int M, int N, int K, int asel, const Epi& E, const int fixed_round = -1) {
;     ...
;             PG8_STAGE(PG8_SB(1, 1), b3 + hstepB, voffB);
;             PG8_WAIT_V(6); PG8_BAR; PG8_MMA(1, 1, At, B1); PG8_BAR;
;     __device__ __forceinline__ void operator()(const AccT& acc, const Unit& u, int wr, int wc, int fr, int fq) const {
;         const int row0 = u.pm * BM + wr * 64 + fr;
;         const int pn = u.pn + pn_off;
;         const int cl = wc * 32 + 8 * fq;
;         if (pn < 8) {
;             bf16_t* base = pn < 4 ? Q : Kn; const int colt = (pn & 3) * BM; const float sc = pn < 4 ? 0.08838834764831845f : 1.0f;
; #pragma unroll
;             for (int ai = 0; ai < 2; ++ai)
; #pragma unroll
;                 for (int m = 0; m < 4; ++m) { bf16_t* rowp = base + (size_t)(row0 + ai * HALF + m * 16) * 1024 + colt + cl;
; #pragma unroll
;                     for (int bj = 0; bj < 2; ++bj) { const f32x4 v0 = acc[ai][bj][m][0] * sc, v1 = acc[ai][bj][m][1] * sc;
;                         u32x4 w; w.x = cvt_pk_bf16(v0[0], v0[1]); w.y = cvt_pk_bf16(v0[2], v0[3]); w.z = cvt_pk_bf16(v1[0], v1[1]); w.w = cvt_pk_bf16(v1[2], v1[3]);
;                         *(u32x4*)(rowp + bj * HALF) = w; } }
	s_waitcnt lgkmcnt(0)
	v_mfma_f32_16x16x32_bf16 v[60:63], v[148:151], v[170:173], v[60:63]
	v_mfma_f32_16x16x32_bf16 v[56:59], v[156:159], v[170:173], v[56:59]
	v_mfma_f32_16x16x32_bf16 v[52:55], v[148:151], v[178:181], v[52:55]
	v_mfma_f32_16x16x32_bf16 v[44:47], v[156:159], v[178:181], v[44:47]
	v_mfma_f32_16x16x32_bf16 v[36:39], v[148:151], v[186:189], v[36:39]
	v_mfma_f32_16x16x32_bf16 v[28:31], v[156:159], v[186:189], v[28:31]
	v_mfma_f32_16x16x32_bf16 v[20:23], v[148:151], v[196:199], v[20:23]
	v_mfma_f32_16x16x32_bf16 v[12:15], v[156:159], v[196:199], v[12:15]
	v_mfma_f32_16x16x32_bf16 v[60:63], v[152:155], v[174:177], v[60:63]
	v_mfma_f32_16x16x32_bf16 v[56:59], v[166:169], v[174:177], v[56:59]
	v_mfma_f32_16x16x32_bf16 v[52:55], v[152:155], v[182:185], v[52:55]
	v_mfma_f32_16x16x32_bf16 v[44:47], v[166:169], v[182:185], v[44:47]
	v_mfma_f32_16x16x32_bf16 v[36:39], v[152:155], v[190:193], v[36:39]
	v_mfma_f32_16x16x32_bf16 v[28:31], v[166:169], v[190:193], v[28:31]
	v_mfma_f32_16x16x32_bf16 v[20:23], v[152:155], v[202:205], v[20:23]
	v_mfma_f32_16x16x32_bf16 v[12:15], v[166:169], v[202:205], v[12:15]
	s_barrier
	s_setprio 0
	s_add_u32 s28, s28, 0x80080
	s_addc_u32 s29, s29, 0
	s_add_i32 s30, s30, s36
	s_mov_b32 m0, s30
	s_nop 0
	global_load_lds_dwordx4 v130, s[28:29]
	s_add_i32 m0, s30, 0x2000
	s_setprio 1
	global_load_lds_dwordx4 v134, s[28:29]
	s_waitcnt vmcnt(6)
	s_barrier
	v_mfma_f32_16x16x32_bf16 v[48:51], v[206:209], v[170:173], v[48:51]
	v_mfma_f32_16x16x32_bf16 v[40:43], v[214:217], v[170:173], v[40:43]
	v_mfma_f32_16x16x32_bf16 v[32:35], v[206:209], v[178:181], v[32:35]
	v_mfma_f32_16x16x32_bf16 v[24:27], v[214:217], v[178:181], v[24:27]
	v_mfma_f32_16x16x32_bf16 v[16:19], v[206:209], v[186:189], v[16:19]
	v_mfma_f32_16x16x32_bf16 v[8:11], v[214:217], v[186:189], v[8:11]
	v_mfma_f32_16x16x32_bf16 v[4:7], v[206:209], v[196:199], v[4:7]
	v_mfma_f32_16x16x32_bf16 v[0:3], v[214:217], v[196:199], v[0:3]
	v_mfma_f32_16x16x32_bf16 v[48:51], v[210:213], v[174:177], v[48:51]
	v_mfma_f32_16x16x32_bf16 v[40:43], v[218:221], v[174:177], v[40:43]
	v_mfma_f32_16x16x32_bf16 v[32:35], v[210:213], v[182:185], v[32:35]
	v_mfma_f32_16x16x32_bf16 v[24:27], v[218:221], v[182:185], v[24:27]
	v_mfma_f32_16x16x32_bf16 v[16:19], v[210:213], v[190:193], v[16:19]
	v_mfma_f32_16x16x32_bf16 v[8:11], v[218:221], v[190:193], v[8:11]
	v_mfma_f32_16x16x32_bf16 v[4:7], v[210:213], v[202:205], v[4:7]
	v_mfma_f32_16x16x32_bf16 v[0:3], v[218:221], v[202:205], v[0:3]
	s_setprio 0
	s_add_i32 s57, s57, 2
	s_add_u32 s26, s26, 0x100
	s_addc_u32 s27, s27, 0
	s_add_u32 s55, s55, 0x100
	s_addc_u32 s56, s56, 0
	s_cmp_gt_u32 s57, 29
	s_cbranch_scc0 .Lrot_3
	s_barrier
	s_lshl_b32 s17, s24, 8
	v_add_u32_e32 v154, s17, v139
	s_cmp_lt_i32 s25, -8
	v_or_b32_e32 v152, 16, v154
	v_or_b32_e32 v150, 32, v154
	v_or_b32_e32 v148, 48, v154
	s_cselect_b64 s[26:27], -1, 0
	s_cmp_gt_i32 s25, -9
	v_ashrrev_i32_e32 v155, 31, v154
	v_lshlrev_b32_e32 v136, 1, v138
	v_ashrrev_i32_e32 v153, 31, v152
	v_ashrrev_i32_e32 v151, 31, v150
	v_ashrrev_i32_e32 v149, 31, v148
	s_cbranch_scc1 .LBB0_248
	s_cmp_lt_u32 s25, -12
	s_cselect_b64 vcc, -1, 0
	s_and_b64 s[28:29], vcc, exec
	s_cselect_b32 s2, s89, s81
	s_cselect_b32 s19, s88, s91
	s_lshl_b32 s28, s25, 9
	s_and_b32 s28, s28, 0x600
	s_add_u32 s28, s19, s28
	v_cndmask_b32_e32 v156, 1.0, v164, vcc
	s_addc_u32 s29, s2, 0
	v_lshl_add_u64 v[170:171], s[28:29], 0, v[136:137]
	v_lshlrev_b64 v[158:159], 11, v[154:155]
	v_pk_mul_f32 v[168:169], v[156:157], v[126:127] op_sel_hi:[0,1]
	v_pk_mul_f32 v[166:167], v[156:157], v[124:125] op_sel_hi:[0,1]
	v_pk_mul_f32 v[172:173], v[156:157], v[122:123] op_sel_hi:[0,1]
	v_pk_mul_f32 v[174:175], v[156:157], v[120:121] op_sel_hi:[0,1]
	v_lshl_add_u64 v[158:159], v[170:171], 0, v[158:159]
	v_cvt_pk_bf16_f32 v166, v166, v167
	v_cvt_pk_bf16_f32 v167, v168, v169
	v_cvt_pk_bf16_f32 v168, v174, v175
	v_cvt_pk_bf16_f32 v169, v172, v173
	global_store_dwordx4 v[158:159], v[166:169], off
	v_pk_mul_f32 v[172:173], v[156:157], v[106:107] op_sel_hi:[0,1]
	v_pk_mul_f32 v[174:175], v[156:157], v[104:105] op_sel_hi:[0,1]
	v_pk_mul_f32 v[168:169], v[156:157], v[118:119] op_sel_hi:[0,1]
	v_pk_mul_f32 v[166:167], v[156:157], v[116:117] op_sel_hi:[0,1]
	v_cvt_pk_bf16_f32 v166, v166, v167
	v_cvt_pk_bf16_f32 v167, v168, v169
	v_cvt_pk_bf16_f32 v168, v174, v175
	v_cvt_pk_bf16_f32 v169, v172, v173
	global_store_dwordx4 v[158:159], v[166:169], off offset:256
	v_pk_mul_f32 v[174:175], v[156:157], v[110:111] op_sel_hi:[0,1]
	v_pk_mul_f32 v[176:177], v[156:157], v[108:109] op_sel_hi:[0,1]
	v_lshlrev_b64 v[166:167], 11, v[152:153]
	v_lshl_add_u64 v[172:173], v[170:171], 0, v[166:167]
	v_pk_mul_f32 v[168:169], v[156:157], v[114:115] op_sel_hi:[0,1]
	v_pk_mul_f32 v[166:167], v[156:157], v[112:113] op_sel_hi:[0,1]
	v_cvt_pk_bf16_f32 v166, v166, v167
	v_cvt_pk_bf16_f32 v167, v168, v169
	v_cvt_pk_bf16_f32 v168, v176, v177
	v_cvt_pk_bf16_f32 v169, v174, v175
	global_store_dwordx4 v[172:173], v[166:169], off
	v_pk_mul_f32 v[174:175], v[156:157], v[90:91] op_sel_hi:[0,1]
	v_pk_mul_f32 v[176:177], v[156:157], v[88:89] op_sel_hi:[0,1]
	v_pk_mul_f32 v[168:169], v[156:157], v[98:99] op_sel_hi:[0,1]
	v_pk_mul_f32 v[166:167], v[156:157], v[96:97] op_sel_hi:[0,1]
	v_cvt_pk_bf16_f32 v166, v166, v167
	v_cvt_pk_bf16_f32 v167, v168, v169
	v_cvt_pk_bf16_f32 v168, v176, v177
	v_cvt_pk_bf16_f32 v169, v174, v175
	global_store_dwordx4 v[172:173], v[166:169], off offset:256
	v_pk_mul_f32 v[174:175], v[156:157], v[94:95] op_sel_hi:[0,1]
	v_pk_mul_f32 v[176:177], v[156:157], v[92:93] op_sel_hi:[0,1]
	v_lshlrev_b64 v[166:167], 11, v[150:151]
; __device__ __forceinline__ unsigned cvt_pk_bf16(float lo, float hi) { const bf16x2_t r = __builtin_convertvector((f32x2){lo, hi}, bf16x2_t); return __builtin_bit_cast(unsigned, r); }
;     __device__ __forceinline__ void operator()(const AccT& acc, const Unit& u, int wr, int wc, int fr, int fq) const {
;     ...
;         if (pn < 8) {
;             bf16_t* base = pn < 4 ? Q : Kn; const int colt = (pn & 3) * BM; const float sc = pn < 4 ? 0.08838834764831845f : 1.0f;
; #pragma unroll
;             for (int ai = 0; ai < 2; ++ai)
; #pragma unroll
;                 for (int m = 0; m < 4; ++m) { bf16_t* rowp = base + (size_t)(row0 + ai * HALF + m * 16) * 1024 + colt + cl;
; #pragma unroll
;                     for (int bj = 0; bj < 2; ++bj) { const f32x4 v0 = acc[ai][bj][m][0] * sc, v1 = acc[ai][bj][m][1] * sc;
;                         u32x4 w; w.x = cvt_pk_bf16(v0[0], v0[1]); w.y = cvt_pk_bf16(v0[2], v0[3]); w.z = cvt_pk_bf16(v1[0], v1[1]); w.w = cvt_pk_bf16(v1[2], v1[3]);
;                         *(u32x4*)(rowp + bj * HALF) = w; } }
	v_lshl_add_u64 v[172:173], v[170:171], 0, v[166:167]
	v_pk_mul_f32 v[168:169], v[156:157], v[102:103] op_sel_hi:[0,1]
	v_pk_mul_f32 v[166:167], v[156:157], v[100:101] op_sel_hi:[0,1]
	v_cvt_pk_bf16_f32 v166, v166, v167
	v_cvt_pk_bf16_f32 v167, v168, v169
	v_cvt_pk_bf16_f32 v168, v176, v177
	v_cvt_pk_bf16_f32 v169, v174, v175
	global_store_dwordx4 v[172:173], v[166:169], off
	v_pk_mul_f32 v[174:175], v[156:157], v[74:75] op_sel_hi:[0,1]
	v_pk_mul_f32 v[176:177], v[156:157], v[72:73] op_sel_hi:[0,1]
	v_pk_mul_f32 v[168:169], v[156:157], v[82:83] op_sel_hi:[0,1]
	v_pk_mul_f32 v[166:167], v[156:157], v[80:81] op_sel_hi:[0,1]
	v_cvt_pk_bf16_f32 v166, v166, v167
	v_cvt_pk_bf16_f32 v167, v168, v169
	v_cvt_pk_bf16_f32 v168, v176, v177
	v_cvt_pk_bf16_f32 v169, v174, v175
	global_store_dwordx4 v[172:173], v[166:169], off offset:256
	v_pk_mul_f32 v[172:173], v[156:157], v[78:79] op_sel_hi:[0,1]
	v_pk_mul_f32 v[174:175], v[156:157], v[76:77] op_sel_hi:[0,1]
	v_lshlrev_b64 v[166:167], 11, v[148:149]
	v_lshl_add_u64 v[170:171], v[170:171], 0, v[166:167]
	v_pk_mul_f32 v[168:169], v[156:157], v[86:87] op_sel_hi:[0,1]
	v_pk_mul_f32 v[166:167], v[156:157], v[84:85] op_sel_hi:[0,1]
	v_cvt_pk_bf16_f32 v166, v166, v167
	v_cvt_pk_bf16_f32 v167, v168, v169
	v_cvt_pk_bf16_f32 v168, v174, v175
	v_cvt_pk_bf16_f32 v169, v172, v173
	global_store_dwordx4 v[170:171], v[166:169], off
	v_pk_mul_f32 v[172:173], v[156:157], v[66:67] op_sel_hi:[0,1]
	v_pk_mul_f32 v[174:175], v[156:157], v[64:65] op_sel_hi:[0,1]
	v_pk_mul_f32 v[168:169], v[156:157], v[70:71] op_sel_hi:[0,1]
	v_pk_mul_f32 v[166:167], v[156:157], v[68:69] op_sel_hi:[0,1]
	v_cvt_pk_bf16_f32 v166, v166, v167
	v_cvt_pk_bf16_f32 v167, v168, v169
	v_cvt_pk_bf16_f32 v168, v174, v175
	v_cvt_pk_bf16_f32 v169, v172, v173
	global_store_dwordx4 v[170:171], v[166:169], off offset:256
	v_pk_mul_f32 v[172:173], v[156:157], v[58:59] op_sel_hi:[0,1]
	s_mov_b32 s2, 0x40000
	v_pk_mul_f32 v[168:169], v[156:157], v[62:63] op_sel_hi:[0,1]
	v_pk_mul_f32 v[166:167], v[156:157], v[60:61] op_sel_hi:[0,1]
	v_pk_mul_f32 v[174:175], v[156:157], v[56:57] op_sel_hi:[0,1]
	v_cvt_pk_bf16_f32 v166, v166, v167
	v_cvt_pk_bf16_f32 v167, v168, v169
	v_cvt_pk_bf16_f32 v169, v172, v173
	v_add_co_u32_e32 v172, vcc, s2, v158
	v_cvt_pk_bf16_f32 v168, v174, v175
	s_nop 0
	v_addc_co_u32_e32 v173, vcc, 0, v159, vcc
	s_mov_b64 s[28:29], 0x40000
	global_store_dwordx4 v[172:173], v[166:169], off
	v_pk_mul_f32 v[172:173], v[156:157], v[42:43] op_sel_hi:[0,1]
	v_pk_mul_f32 v[174:175], v[156:157], v[40:41] op_sel_hi:[0,1]
	v_pk_mul_f32 v[168:169], v[156:157], v[50:51] op_sel_hi:[0,1]
	v_pk_mul_f32 v[166:167], v[156:157], v[48:49] op_sel_hi:[0,1]
	v_lshl_add_u64 v[170:171], v[158:159], 0, s[28:29]
	v_cvt_pk_bf16_f32 v166, v166, v167
	v_cvt_pk_bf16_f32 v167, v168, v169
	v_cvt_pk_bf16_f32 v168, v174, v175
	v_cvt_pk_bf16_f32 v169, v172, v173
	global_store_dwordx4 v[170:171], v[166:169], off offset:256
	v_pk_mul_f32 v[172:173], v[156:157], v[46:47] op_sel_hi:[0,1]
	v_pk_mul_f32 v[174:175], v[156:157], v[44:45] op_sel_hi:[0,1]
	v_pk_mul_f32 v[168:169], v[156:157], v[54:55] op_sel_hi:[0,1]
	v_pk_mul_f32 v[166:167], v[156:157], v[52:53] op_sel_hi:[0,1]
	v_cvt_pk_bf16_f32 v166, v166, v167
	v_cvt_pk_bf16_f32 v167, v168, v169
	v_cvt_pk_bf16_f32 v169, v172, v173
	v_add_co_u32_e32 v172, vcc, s46, v158
	v_cvt_pk_bf16_f32 v168, v174, v175
	s_nop 0
	v_addc_co_u32_e32 v173, vcc, 0, v159, vcc
	s_mov_b64 s[28:29], 0x48000
	global_store_dwordx4 v[172:173], v[166:169], off
	v_pk_mul_f32 v[172:173], v[156:157], v[26:27] op_sel_hi:[0,1]
	v_pk_mul_f32 v[174:175], v[156:157], v[24:25] op_sel_hi:[0,1]
	v_pk_mul_f32 v[168:169], v[156:157], v[34:35] op_sel_hi:[0,1]
	v_pk_mul_f32 v[166:167], v[156:157], v[32:33] op_sel_hi:[0,1]
	v_lshl_add_u64 v[170:171], v[158:159], 0, s[28:29]
	v_cvt_pk_bf16_f32 v166, v166, v167
	v_cvt_pk_bf16_f32 v167, v168, v169
	v_cvt_pk_bf16_f32 v168, v174, v175
	v_cvt_pk_bf16_f32 v169, v172, v173
	global_store_dwordx4 v[170:171], v[166:169], off offset:256
	v_pk_mul_f32 v[172:173], v[156:157], v[30:31] op_sel_hi:[0,1]
	v_pk_mul_f32 v[174:175], v[156:157], v[28:29] op_sel_hi:[0,1]
	v_pk_mul_f32 v[168:169], v[156:157], v[38:39] op_sel_hi:[0,1]
	v_pk_mul_f32 v[166:167], v[156:157], v[36:37] op_sel_hi:[0,1]
	v_cvt_pk_bf16_f32 v166, v166, v167
	v_cvt_pk_bf16_f32 v167, v168, v169
	v_cvt_pk_bf16_f32 v169, v172, v173
	v_add_co_u32_e32 v172, vcc, s47, v158
	v_cvt_pk_bf16_f32 v168, v174, v175
	s_nop 0
	v_addc_co_u32_e32 v173, vcc, 0, v159, vcc
	global_store_dwordx4 v[172:173], v[166:169], off
	v_pk_mul_f32 v[172:173], v[156:157], v[10:11] op_sel_hi:[0,1]
	v_pk_mul_f32 v[174:175], v[156:157], v[8:9] op_sel_hi:[0,1]
	v_pk_mul_f32 v[168:169], v[156:157], v[18:19] op_sel_hi:[0,1]
	v_pk_mul_f32 v[166:167], v[156:157], v[16:17] op_sel_hi:[0,1]
	v_lshl_add_u64 v[170:171], v[158:159], 0, s[6:7]
	v_cvt_pk_bf16_f32 v166, v166, v167
	v_cvt_pk_bf16_f32 v167, v168, v169
	v_cvt_pk_bf16_f32 v168, v174, v175
	v_cvt_pk_bf16_f32 v169, v172, v173
	global_store_dwordx4 v[170:171], v[166:169], off offset:256
	v_lshl_add_u64 v[170:171], v[158:159], 0, s[8:9]
	v_pk_mul_f32 v[172:173], v[156:157], v[14:15] op_sel_hi:[0,1]
	v_pk_mul_f32 v[168:169], v[156:157], v[22:23] op_sel_hi:[0,1]
	v_pk_mul_f32 v[166:167], v[156:157], v[20:21] op_sel_hi:[0,1]
	v_pk_mul_f32 v[174:175], v[156:157], v[12:13] op_sel_hi:[0,1]
	v_add_co_u32_e32 v158, vcc, s48, v158
	v_cvt_pk_bf16_f32 v166, v166, v167
	v_cvt_pk_bf16_f32 v167, v168, v169
	v_cvt_pk_bf16_f32 v168, v174, v175
	v_cvt_pk_bf16_f32 v169, v172, v173
	v_addc_co_u32_e32 v159, vcc, 0, v159, vcc
	global_store_dwordx4 v[158:159], v[166:169], off
	v_pk_mul_f32 v[158:159], v[156:157], v[6:7] op_sel_hi:[0,1]
	v_pk_mul_f32 v[172:173], v[156:157], v[0:1] op_sel_hi:[0,1]
	v_pk_mul_f32 v[166:167], v[156:157], v[4:5] op_sel_hi:[0,1]
	v_pk_mul_f32 v[168:169], v[156:157], v[2:3] op_sel_hi:[0,1]
	v_cvt_pk_bf16_f32 v156, v166, v167
	v_cvt_pk_bf16_f32 v157, v158, v159
	v_cvt_pk_bf16_f32 v158, v172, v173
	v_cvt_pk_bf16_f32 v159, v168, v169
	global_store_dwordx4 v[170:171], v[156:159], off offset:256

; #define PG8_STAGE(bufoff, gbase, voff) do { _Pragma("unroll") for (int _i = 0; _i < 2; ++_i) \
;         __builtin_amdgcn_global_load_lds((const unsigned*)((const char*)(gbase) + (voff)[_i]), (LAS unsigned*)(lds + (bufoff) + ldsw + _i * 8192), 16, 0, 0); } while (0)
; #define PG8_LDA(dst, b, h) do { _Pragma("unroll") for (int m = 0; m < 4; ++m) _Pragma("unroll") for (int k = 0; k < 2; ++k) dst[m][k] = *(const LAS bf16x8*)(lds + PG8_SA(b, h) + aoff + m * 2048 + k * 1024); } while (0)
; #define PG8_LDB(dst, b, h) do { _Pragma("unroll") for (int n = 0; n < 2; ++n) _Pragma("unroll") for (int k = 0; k < 2; ++k) dst[n][k] = *(const LAS bf16x8*)(lds + PG8_SB(b, h) + boff + n * 2048 + k * 1024); } while (0)
; #define PG8_WAIT_V(n) asm volatile("s_waitcnt vmcnt(" #n ")" ::: "memory")
; #define PG8_WAIT_L(n) asm volatile("s_waitcnt lgkmcnt(" #n ")" ::: "memory")
; #define PG8_BAR __builtin_amdgcn_s_barrier()
; #define PG8_SCHED __builtin_amdgcn_sched_barrier(0)
; template <class Epi>
; __device__ __forceinline__ void gemm_phase(LAS unsigned char* lds, const bf16_t* A, int lda, const bf16_t* Bt, int ldb, int M, int N, int K, int asel, const Epi& E, const int fixed_round = -1) {
;     ...
;             const char* a1 = cA + (size_t)(t + 1) * kstep;
;             const char* a2 = last ? nA : cA + (size_t)(t + 2) * kstep; const char* b2 = last ? nB : cB + (size_t)(t + 2) * kstep;
;             const char* a3 = a2 + kstep; const char* b3 = b2 + kstep;
;             PG8_LDB(B0, 0, 0); PG8_SCHED; PG8_LDA(At, 0, 0); PG8_STAGE(PG8_SA(1, 1), a1 + hstepA, voffA);
;             PG8_WAIT_L(8); PG8_BAR; PG8_WAIT_L(0); PG8_MMA(0, 0, At, B0); PG8_BAR; PG8_SCHED;
;             PG8_LDB(B1, 0, 1); PG8_STAGE(PG8_SB(0, 0), b2, voffB);
;             PG8_BAR; PG8_WAIT_L(0); PG8_MMA(0, 1, At, B1); PG8_BAR;
;             PG8_LDA(At, 0, 1); PG8_STAGE(PG8_SA(0, 0), a2, voffA);
;             PG8_BAR; PG8_WAIT_L(0); PG8_MMA(1, 0, At, B0); PG8_BAR; PG8_SCHED;
;             PG8_STAGE(PG8_SB(0, 1), b2 + hstepB, voffB);
;             PG8_WAIT_V(6); PG8_BAR; PG8_MMA(1, 1, At, B1); PG8_BAR;
.LBB0_440:
	s_add_i32 s34, s34, 2
	s_add_u32 s16, s12, s14
	ds_read_b128 v[150:153], v141
	ds_read_b128 v[154:157], v141 offset:1024
	ds_read_b128 v[160:163], v141 offset:2048
	ds_read_b128 v[168:171], v141 offset:3072
	s_addc_u32 s17, s13, s15
	s_add_u32 s16, s16, 0x14500100
	s_addc_u32 s17, s17, 0
	s_add_u32 s46, s26, s14
	s_addc_u32 s47, s27, s15
	s_cmpk_eq_i32 s14, 0xf00
	s_cselect_b32 s19, s1, s17
	s_cselect_b32 s18, s0, s16
	s_cselect_b32 s17, s3, s47
	s_cselect_b32 s16, s2, s46
	s_mov_b32 m0, s36
	v_lshl_add_u64 v[146:147], v[136:137], 0, s[14:15]
	ds_read_b128 v[172:175], v142
	ds_read_b128 v[176:179], v142 offset:1024
	ds_read_b128 v[180:183], v142 offset:2048
	ds_read_b128 v[184:187], v142 offset:3072
	ds_read_b128 v[188:191], v142 offset:4096
	ds_read_b128 v[196:199], v142 offset:5120
	ds_read_b128 v[202:205], v142 offset:6144
	ds_read_b128 v[206:209], v142 offset:7168
	global_load_lds_dwordx4 v[146:147], off
	v_lshl_add_u64 v[146:147], v[138:139], 0, s[14:15]
	s_mov_b32 m0, s37
	s_setprio 1
	global_load_lds_dwordx4 v[146:147], off
	s_waitcnt lgkmcnt(8)
	s_barrier
	s_waitcnt lgkmcnt(0)
	v_mfma_f32_16x16x32_bf16 v[124:127], v[150:153], v[172:175], v[124:127]
	v_mfma_f32_16x16x32_bf16 v[120:123], v[160:163], v[172:175], v[120:123]
	v_mfma_f32_16x16x32_bf16 v[116:119], v[150:153], v[180:183], v[116:119]
	v_mfma_f32_16x16x32_bf16 v[112:115], v[160:163], v[180:183], v[112:115]
	v_mfma_f32_16x16x32_bf16 v[100:103], v[150:153], v[188:191], v[100:103]
	v_mfma_f32_16x16x32_bf16 v[92:95], v[160:163], v[188:191], v[92:95]
	v_mfma_f32_16x16x32_bf16 v[84:87], v[150:153], v[202:205], v[84:87]
	v_mfma_f32_16x16x32_bf16 v[76:79], v[160:163], v[202:205], v[76:79]
	v_mfma_f32_16x16x32_bf16 v[124:127], v[154:157], v[176:179], v[124:127]
	v_mfma_f32_16x16x32_bf16 v[120:123], v[168:171], v[176:179], v[120:123]
	v_mfma_f32_16x16x32_bf16 v[116:119], v[154:157], v[184:187], v[116:119]
	v_mfma_f32_16x16x32_bf16 v[112:115], v[168:171], v[184:187], v[112:115]
	v_mfma_f32_16x16x32_bf16 v[100:103], v[154:157], v[196:199], v[100:103]
	v_mfma_f32_16x16x32_bf16 v[92:95], v[168:171], v[196:199], v[92:95]
	v_mfma_f32_16x16x32_bf16 v[84:87], v[154:157], v[206:209], v[84:87]
	v_mfma_f32_16x16x32_bf16 v[76:79], v[168:171], v[206:209], v[76:79]
	s_barrier
	s_setprio 0
	s_mov_b32 m0, s38
	s_add_u32 s98, s16, s10
	s_addc_u32 s99, s17, s11
	ds_read_b128 v[210:213], v143
	ds_read_b128 v[214:217], v143 offset:1024
	ds_read_b128 v[218:221], v143 offset:2048
	ds_read_b128 v[222:225], v143 offset:3072
	global_load_lds_dwordx4 v130, s[16:17]
	s_mov_b32 m0, s39
	s_setprio 1
	global_load_lds_dwordx4 v134, s[16:17]
	s_barrier
	s_waitcnt lgkmcnt(0)
	v_mfma_f32_16x16x32_bf16 v[108:111], v[210:213], v[172:175], v[108:111]
	v_mfma_f32_16x16x32_bf16 v[104:107], v[218:221], v[172:175], v[104:107]
	v_mfma_f32_16x16x32_bf16 v[96:99], v[210:213], v[180:183], v[96:99]
	v_mfma_f32_16x16x32_bf16 v[88:91], v[218:221], v[180:183], v[88:91]
	v_mfma_f32_16x16x32_bf16 v[80:83], v[210:213], v[188:191], v[80:83]
	v_mfma_f32_16x16x32_bf16 v[72:75], v[218:221], v[188:191], v[72:75]
	v_mfma_f32_16x16x32_bf16 v[68:71], v[210:213], v[202:205], v[68:71]
	v_mfma_f32_16x16x32_bf16 v[64:67], v[218:221], v[202:205], v[64:67]
	v_mfma_f32_16x16x32_bf16 v[108:111], v[214:217], v[176:179], v[108:111]
	v_mfma_f32_16x16x32_bf16 v[104:107], v[222:225], v[176:179], v[104:107]
	v_mfma_f32_16x16x32_bf16 v[96:99], v[214:217], v[184:187], v[96:99]
	v_mfma_f32_16x16x32_bf16 v[88:91], v[222:225], v[184:187], v[88:91]
	v_mfma_f32_16x16x32_bf16 v[80:83], v[214:217], v[196:199], v[80:83]
	v_mfma_f32_16x16x32_bf16 v[72:75], v[222:225], v[196:199], v[72:75]
	v_mfma_f32_16x16x32_bf16 v[68:71], v[214:217], v[206:209], v[68:71]
	v_mfma_f32_16x16x32_bf16 v[64:67], v[222:225], v[206:209], v[64:67]
	s_barrier
	s_setprio 0
	s_mov_b32 m0, s25
	s_add_u32 s100, s18, s10
	s_addc_u32 s101, s19, s11
	ds_read_b128 v[172:175], v142 offset:16384
	ds_read_b128 v[176:179], v142 offset:17408
	ds_read_b128 v[180:183], v142 offset:18432
	ds_read_b128 v[184:187], v142 offset:19456
	ds_read_b128 v[188:191], v142 offset:20480
	ds_read_b128 v[196:199], v142 offset:21504
	ds_read_b128 v[202:205], v142 offset:22528
	ds_read_b128 v[206:209], v142 offset:23552
	global_load_lds_dwordx4 v128, s[18:19]
	s_mov_b32 m0, s28
	s_setprio 1
	global_load_lds_dwordx4 v132, s[18:19]
	s_barrier
	s_waitcnt lgkmcnt(0)
	v_mfma_f32_16x16x32_bf16 v[60:63], v[150:153], v[172:175], v[60:63]
	v_mfma_f32_16x16x32_bf16 v[56:59], v[160:163], v[172:175], v[56:59]
	v_mfma_f32_16x16x32_bf16 v[52:55], v[150:153], v[180:183], v[52:55]
	v_mfma_f32_16x16x32_bf16 v[44:47], v[160:163], v[180:183], v[44:47]
	v_mfma_f32_16x16x32_bf16 v[36:39], v[150:153], v[188:191], v[36:39]
	v_mfma_f32_16x16x32_bf16 v[28:31], v[160:163], v[188:191], v[28:31]
	v_mfma_f32_16x16x32_bf16 v[20:23], v[150:153], v[202:205], v[20:23]
	v_mfma_f32_16x16x32_bf16 v[12:15], v[160:163], v[202:205], v[12:15]
	v_mfma_f32_16x16x32_bf16 v[60:63], v[154:157], v[176:179], v[60:63]
	v_mfma_f32_16x16x32_bf16 v[56:59], v[168:171], v[176:179], v[56:59]
	v_mfma_f32_16x16x32_bf16 v[52:55], v[154:157], v[184:187], v[52:55]
	v_mfma_f32_16x16x32_bf16 v[44:47], v[168:171], v[184:187], v[44:47]
	v_mfma_f32_16x16x32_bf16 v[36:39], v[154:157], v[196:199], v[36:39]
	v_mfma_f32_16x16x32_bf16 v[28:31], v[168:171], v[196:199], v[28:31]
	v_mfma_f32_16x16x32_bf16 v[20:23], v[154:157], v[206:209], v[20:23]
	v_mfma_f32_16x16x32_bf16 v[12:15], v[168:171], v[206:209], v[12:15]
	s_barrier
	s_setprio 0
	s_add_u32 s46, s16, 0x80000
	s_addc_u32 s47, s17, 0
	s_mov_b32 m0, s40
	s_nop 0
	global_load_lds_dwordx4 v130, s[46:47]
	s_mov_b32 m0, s41
	s_setprio 1
	global_load_lds_dwordx4 v134, s[46:47]
	s_waitcnt vmcnt(6)
	s_barrier
; #define PG8_STAGE(bufoff, gbase, voff) do { _Pragma("unroll") for (int _i = 0; _i < 2; ++_i) \
;         __builtin_amdgcn_global_load_lds((const unsigned*)((const char*)(gbase) + (voff)[_i]), (LAS unsigned*)(lds + (bufoff) + ldsw + _i * 8192), 16, 0, 0); } while (0)
; #define PG8_LDA(dst, b, h) do { _Pragma("unroll") for (int m = 0; m < 4; ++m) _Pragma("unroll") for (int k = 0; k < 2; ++k) dst[m][k] = *(const LAS bf16x8*)(lds + PG8_SA(b, h) + aoff + m * 2048 + k * 1024); } while (0)
; #define PG8_LDB(dst, b, h) do { _Pragma("unroll") for (int n = 0; n < 2; ++n) _Pragma("unroll") for (int k = 0; k < 2; ++k) dst[n][k] = *(const LAS bf16x8*)(lds + PG8_SB(b, h) + boff + n * 2048 + k * 1024); } while (0)
; #define PG8_WAIT_V(n) asm volatile("s_waitcnt vmcnt(" #n ")" ::: "memory")
; #define PG8_WAIT_L(n) asm volatile("s_waitcnt lgkmcnt(" #n ")" ::: "memory")
; #define PG8_BAR __builtin_amdgcn_s_barrier()
; template <class Epi>
; __device__ __forceinline__ void gemm_phase(LAS unsigned char* lds, const bf16_t* A, int lda, const bf16_t* Bt, int ldb, int M, int N, int K, int asel, const Epi& E, const int fixed_round = -1) {
;     ...
;             PG8_LDB(B0, 0, 0); PG8_SCHED; PG8_LDA(At, 0, 0); PG8_STAGE(PG8_SA(1, 1), a1 + hstepA, voffA);
;             PG8_WAIT_L(8); PG8_BAR; PG8_WAIT_L(0); PG8_MMA(0, 0, At, B0); PG8_BAR; PG8_SCHED;
;             PG8_LDB(B1, 0, 1); PG8_STAGE(PG8_SB(0, 0), b2, voffB);
;             PG8_BAR; PG8_WAIT_L(0); PG8_MMA(0, 1, At, B1); PG8_BAR;
;             PG8_LDA(At, 0, 1); PG8_STAGE(PG8_SA(0, 0), a2, voffA);
;             PG8_BAR; PG8_WAIT_L(0); PG8_MMA(1, 0, At, B0); PG8_BAR; PG8_SCHED;
;             PG8_STAGE(PG8_SB(0, 1), b2 + hstepB, voffB);
;             PG8_WAIT_V(6); PG8_BAR; PG8_MMA(1, 1, At, B1); PG8_BAR;
;             PG8_LDB(B0, 1, 0); PG8_SCHED; PG8_LDA(At, 1, 0); PG8_STAGE(PG8_SA(0, 1), a2 + hstepA, voffA);
;             PG8_WAIT_L(8); PG8_BAR; PG8_WAIT_L(0); PG8_MMA(0, 0, At, B0); PG8_BAR; PG8_SCHED;
;             PG8_LDB(B1, 1, 1); PG8_STAGE(PG8_SB(1, 0), b3, voffB);
;             PG8_BAR; PG8_WAIT_L(0); PG8_MMA(0, 1, At, B1); PG8_BAR;
;             PG8_LDA(At, 1, 1); PG8_STAGE(PG8_SA(1, 0), a3, voffA);
;             PG8_BAR; PG8_WAIT_L(0); PG8_MMA(1, 0, At, B0); PG8_BAR; PG8_SCHED;
;             PG8_STAGE(PG8_SB(1, 1), b3 + hstepB, voffB);
;             PG8_WAIT_V(6); PG8_BAR; PG8_MMA(1, 1, At, B1); PG8_BAR;
	v_mfma_f32_16x16x32_bf16 v[48:51], v[210:213], v[172:175], v[48:51]
	v_mfma_f32_16x16x32_bf16 v[40:43], v[218:221], v[172:175], v[40:43]
	v_mfma_f32_16x16x32_bf16 v[32:35], v[210:213], v[180:183], v[32:35]
	v_mfma_f32_16x16x32_bf16 v[24:27], v[218:221], v[180:183], v[24:27]
	v_mfma_f32_16x16x32_bf16 v[16:19], v[210:213], v[188:191], v[16:19]
	v_mfma_f32_16x16x32_bf16 v[8:11], v[218:221], v[188:191], v[8:11]
	v_mfma_f32_16x16x32_bf16 v[4:7], v[210:213], v[202:205], v[4:7]
	v_mfma_f32_16x16x32_bf16 v[0:3], v[218:221], v[202:205], v[0:3]
	v_mfma_f32_16x16x32_bf16 v[48:51], v[214:217], v[176:179], v[48:51]
	v_mfma_f32_16x16x32_bf16 v[40:43], v[222:225], v[176:179], v[40:43]
	v_mfma_f32_16x16x32_bf16 v[32:35], v[214:217], v[184:187], v[32:35]
	v_mfma_f32_16x16x32_bf16 v[24:27], v[222:225], v[184:187], v[24:27]
	v_mfma_f32_16x16x32_bf16 v[16:19], v[214:217], v[196:199], v[16:19]
	v_mfma_f32_16x16x32_bf16 v[8:11], v[222:225], v[196:199], v[8:11]
	v_mfma_f32_16x16x32_bf16 v[4:7], v[214:217], v[206:209], v[4:7]
	v_mfma_f32_16x16x32_bf16 v[0:3], v[222:225], v[206:209], v[0:3]
	s_barrier
	s_setprio 0
	ds_read_b128 v[150:153], v144
	ds_read_b128 v[154:157], v144 offset:1024
	ds_read_b128 v[160:163], v144 offset:2048
	ds_read_b128 v[168:171], v144 offset:3072
	s_add_u32 s18, s18, 0x80000
	s_addc_u32 s19, s19, 0
	s_mov_b32 m0, s29
	ds_read_b128 v[172:175], v142 offset:32768
	ds_read_b128 v[176:179], v142 offset:33792
	ds_read_b128 v[180:183], v142 offset:34816
	ds_read_b128 v[184:187], v142 offset:35840
	ds_read_b128 v[188:191], v142 offset:36864
	ds_read_b128 v[196:199], v142 offset:37888
	ds_read_b128 v[202:205], v142 offset:38912
	ds_read_b128 v[206:209], v142 offset:39936
	global_load_lds_dwordx4 v128, s[18:19]
	s_mov_b32 m0, s30
	s_setprio 1
	global_load_lds_dwordx4 v132, s[18:19]
	s_waitcnt lgkmcnt(8)
	s_barrier
	s_waitcnt lgkmcnt(0)
	v_mfma_f32_16x16x32_bf16 v[124:127], v[150:153], v[172:175], v[124:127]
	v_mfma_f32_16x16x32_bf16 v[120:123], v[160:163], v[172:175], v[120:123]
	v_mfma_f32_16x16x32_bf16 v[116:119], v[150:153], v[180:183], v[116:119]
	v_mfma_f32_16x16x32_bf16 v[112:115], v[160:163], v[180:183], v[112:115]
	v_mfma_f32_16x16x32_bf16 v[100:103], v[150:153], v[188:191], v[100:103]
	v_mfma_f32_16x16x32_bf16 v[92:95], v[160:163], v[188:191], v[92:95]
	v_mfma_f32_16x16x32_bf16 v[84:87], v[150:153], v[202:205], v[84:87]
	v_mfma_f32_16x16x32_bf16 v[76:79], v[160:163], v[202:205], v[76:79]
	v_mfma_f32_16x16x32_bf16 v[124:127], v[154:157], v[176:179], v[124:127]
	v_mfma_f32_16x16x32_bf16 v[120:123], v[168:171], v[176:179], v[120:123]
	v_mfma_f32_16x16x32_bf16 v[116:119], v[154:157], v[184:187], v[116:119]
	v_mfma_f32_16x16x32_bf16 v[112:115], v[168:171], v[184:187], v[112:115]
	v_mfma_f32_16x16x32_bf16 v[100:103], v[154:157], v[196:199], v[100:103]
	v_mfma_f32_16x16x32_bf16 v[92:95], v[168:171], v[196:199], v[92:95]
	v_mfma_f32_16x16x32_bf16 v[84:87], v[154:157], v[206:209], v[84:87]
	v_mfma_f32_16x16x32_bf16 v[76:79], v[168:171], v[206:209], v[76:79]
	s_barrier
	s_setprio 0
	s_mov_b32 m0, s42
	ds_read_b128 v[210:213], v145
	ds_read_b128 v[214:217], v145 offset:1024
	ds_read_b128 v[218:221], v145 offset:2048
	ds_read_b128 v[222:225], v145 offset:3072
	global_load_lds_dwordx4 v130, s[98:99]
	s_mov_b32 m0, s43
	s_setprio 1
	global_load_lds_dwordx4 v134, s[98:99]
	s_barrier
	s_waitcnt lgkmcnt(0)
	v_mfma_f32_16x16x32_bf16 v[108:111], v[210:213], v[172:175], v[108:111]
	v_mfma_f32_16x16x32_bf16 v[104:107], v[218:221], v[172:175], v[104:107]
	v_mfma_f32_16x16x32_bf16 v[96:99], v[210:213], v[180:183], v[96:99]
	v_mfma_f32_16x16x32_bf16 v[88:91], v[218:221], v[180:183], v[88:91]
	v_mfma_f32_16x16x32_bf16 v[80:83], v[210:213], v[188:191], v[80:83]
	v_mfma_f32_16x16x32_bf16 v[72:75], v[218:221], v[188:191], v[72:75]
	v_mfma_f32_16x16x32_bf16 v[68:71], v[210:213], v[202:205], v[68:71]
	v_mfma_f32_16x16x32_bf16 v[64:67], v[218:221], v[202:205], v[64:67]
	v_mfma_f32_16x16x32_bf16 v[108:111], v[214:217], v[176:179], v[108:111]
	v_mfma_f32_16x16x32_bf16 v[104:107], v[222:225], v[176:179], v[104:107]
	v_mfma_f32_16x16x32_bf16 v[96:99], v[214:217], v[184:187], v[96:99]
	v_mfma_f32_16x16x32_bf16 v[88:91], v[222:225], v[184:187], v[88:91]
	v_mfma_f32_16x16x32_bf16 v[80:83], v[214:217], v[196:199], v[80:83]
	v_mfma_f32_16x16x32_bf16 v[72:75], v[222:225], v[196:199], v[72:75]
	v_mfma_f32_16x16x32_bf16 v[68:71], v[214:217], v[206:209], v[68:71]
	v_mfma_f32_16x16x32_bf16 v[64:67], v[222:225], v[206:209], v[64:67]
	s_barrier
	s_setprio 0
	s_mov_b32 m0, s31
	ds_read_b128 v[172:175], v142 offset:49152
	ds_read_b128 v[176:179], v142 offset:50176
	ds_read_b128 v[180:183], v142 offset:51200
	ds_read_b128 v[184:187], v142 offset:52224
	ds_read_b128 v[188:191], v142 offset:53248
	ds_read_b128 v[196:199], v142 offset:54272
	ds_read_b128 v[202:205], v142 offset:55296
	ds_read_b128 v[206:209], v142 offset:56320
	global_load_lds_dwordx4 v128, s[100:101]
	s_mov_b32 m0, s33
	s_setprio 1
	global_load_lds_dwordx4 v132, s[100:101]
	s_barrier
	s_waitcnt lgkmcnt(0)
	v_mfma_f32_16x16x32_bf16 v[60:63], v[150:153], v[172:175], v[60:63]
	v_mfma_f32_16x16x32_bf16 v[56:59], v[160:163], v[172:175], v[56:59]
	v_mfma_f32_16x16x32_bf16 v[52:55], v[150:153], v[180:183], v[52:55]
	v_mfma_f32_16x16x32_bf16 v[44:47], v[160:163], v[180:183], v[44:47]
	v_mfma_f32_16x16x32_bf16 v[36:39], v[150:153], v[188:191], v[36:39]
	v_mfma_f32_16x16x32_bf16 v[28:31], v[160:163], v[188:191], v[28:31]
	v_mfma_f32_16x16x32_bf16 v[20:23], v[150:153], v[202:205], v[20:23]
	v_mfma_f32_16x16x32_bf16 v[12:15], v[160:163], v[202:205], v[12:15]
	v_mfma_f32_16x16x32_bf16 v[60:63], v[154:157], v[176:179], v[60:63]
	v_mfma_f32_16x16x32_bf16 v[56:59], v[168:171], v[176:179], v[56:59]
	v_mfma_f32_16x16x32_bf16 v[52:55], v[154:157], v[184:187], v[52:55]
	v_mfma_f32_16x16x32_bf16 v[44:47], v[168:171], v[184:187], v[44:47]
	v_mfma_f32_16x16x32_bf16 v[36:39], v[154:157], v[196:199], v[36:39]
	v_mfma_f32_16x16x32_bf16 v[28:31], v[168:171], v[196:199], v[28:31]
	v_mfma_f32_16x16x32_bf16 v[20:23], v[154:157], v[206:209], v[20:23]
	v_mfma_f32_16x16x32_bf16 v[12:15], v[168:171], v[206:209], v[12:15]
	s_barrier
; #define LAS __attribute__((address_space(3)))
; #define PG8_STAGE(bufoff, gbase, voff) do { _Pragma("unroll") for (int _i = 0; _i < 2; ++_i) \
;         __builtin_amdgcn_global_load_lds((const unsigned*)((const char*)(gbase) + (voff)[_i]), (LAS unsigned*)(lds + (bufoff) + ldsw + _i * 8192), 16, 0, 0); } while (0)
; #define PG8_WAIT_V(n) asm volatile("s_waitcnt vmcnt(" #n ")" ::: "memory")
; #define PG8_BAR __builtin_amdgcn_s_barrier()
; template <class Epi>
; __device__ __forceinline__ void gemm_phase(LAS unsigned char* lds, const bf16_t* A, int lda, const bf16_t* Bt, int ldb, int M, int N, int K, int asel, const Epi& E, const int fixed_round = -1) {
;     ...
;             PG8_STAGE(PG8_SB(1, 1), b3 + hstepB, voffB);
;             PG8_WAIT_V(6); PG8_BAR; PG8_MMA(1, 1, At, B1); PG8_BAR;
;             if constexpr (Epi::HEADSCALE) {
;                 if (t & 2) {
;                     const LAS float* rt = (const LAS float*)(lds + L_RT) + (t >> 2);
; #pragma unroll
;                     for (int ai = 0; ai < 2; ++ai)
; #pragma unroll
;                         for (int m = 0; m < 4; ++m) { const float f = rt[(ai * HALF + wr * 64 + m * 16 + fr) * 8];
; #pragma unroll
;                             for (int bj = 0; bj < 2; ++bj)
; #pragma unroll
;                                 for (int n = 0; n < 2; ++n) acc[ai][bj][m][n] *= f; }
;                 }
	s_setprio 0
	s_add_u32 s16, s16, 0x80080
	s_addc_u32 s17, s17, 0
	s_mov_b32 m0, s44
	s_nop 0
	global_load_lds_dwordx4 v130, s[16:17]
	s_mov_b32 m0, s45
	s_setprio 1
	global_load_lds_dwordx4 v134, s[16:17]
	s_waitcnt vmcnt(6)
	s_barrier
	v_mfma_f32_16x16x32_bf16 v[48:51], v[210:213], v[172:175], v[48:51]
	v_mfma_f32_16x16x32_bf16 v[40:43], v[218:221], v[172:175], v[40:43]
	v_mfma_f32_16x16x32_bf16 v[32:35], v[210:213], v[180:183], v[32:35]
	v_mfma_f32_16x16x32_bf16 v[24:27], v[218:221], v[180:183], v[24:27]
	v_mfma_f32_16x16x32_bf16 v[16:19], v[210:213], v[188:191], v[16:19]
	v_mfma_f32_16x16x32_bf16 v[8:11], v[218:221], v[188:191], v[8:11]
	v_mfma_f32_16x16x32_bf16 v[4:7], v[210:213], v[202:205], v[4:7]
	v_mfma_f32_16x16x32_bf16 v[0:3], v[218:221], v[202:205], v[0:3]
	v_mfma_f32_16x16x32_bf16 v[48:51], v[214:217], v[176:179], v[48:51]
	v_mfma_f32_16x16x32_bf16 v[40:43], v[222:225], v[176:179], v[40:43]
	v_mfma_f32_16x16x32_bf16 v[32:35], v[214:217], v[184:187], v[32:35]
	v_mfma_f32_16x16x32_bf16 v[24:27], v[222:225], v[184:187], v[24:27]
	v_mfma_f32_16x16x32_bf16 v[16:19], v[214:217], v[196:199], v[16:19]
	v_mfma_f32_16x16x32_bf16 v[8:11], v[222:225], v[196:199], v[8:11]
	v_mfma_f32_16x16x32_bf16 v[4:7], v[214:217], v[206:209], v[4:7]
	v_mfma_f32_16x16x32_bf16 v[0:3], v[222:225], v[206:209], v[0:3]
	s_setprio 0
	s_bitcmp0_b32 s34, 1
	s_barrier
	s_cbranch_scc1 .LBB0_439
	s_and_b32 s16, s34, -4
	v_add_u32_e32 v148, s16, v140
	ds_read2st64_b32 v[146:147], v148 offset1:2
	ds_read2st64_b32 v[150:151], v148 offset0:4 offset1:6
	s_waitcnt lgkmcnt(0)
	v_pk_mul_f32 v[126:127], v[126:127], v[146:147] op_sel_hi:[1,0]
	v_pk_mul_f32 v[124:125], v[124:125], v[146:147] op_sel_hi:[1,0]
	v_pk_mul_f32 v[122:123], v[122:123], v[146:147] op_sel_hi:[1,0]
	v_pk_mul_f32 v[120:121], v[120:121], v[146:147] op_sel_hi:[1,0]
	v_pk_mul_f32 v[110:111], v[110:111], v[146:147] op_sel_hi:[1,0]
	v_pk_mul_f32 v[108:109], v[108:109], v[146:147] op_sel_hi:[1,0]
	v_pk_mul_f32 v[106:107], v[106:107], v[146:147] op_sel_hi:[1,0]
	v_pk_mul_f32 v[104:105], v[104:105], v[146:147] op_sel_hi:[1,0]
	v_mov_b32_e32 v146, v147
	v_pk_mul_f32 v[118:119], v[118:119], v[146:147] op_sel_hi:[1,0]
	v_pk_mul_f32 v[116:117], v[116:117], v[146:147] op_sel_hi:[1,0]
	v_pk_mul_f32 v[114:115], v[114:115], v[146:147] op_sel_hi:[1,0]
	v_pk_mul_f32 v[112:113], v[112:113], v[146:147] op_sel_hi:[1,0]
	v_pk_mul_f32 v[98:99], v[98:99], v[146:147] op_sel_hi:[1,0]
	v_pk_mul_f32 v[96:97], v[96:97], v[146:147] op_sel_hi:[1,0]
	v_pk_mul_f32 v[90:91], v[90:91], v[146:147] op_sel_hi:[1,0]
	v_pk_mul_f32 v[88:89], v[88:89], v[146:147] op_sel_hi:[1,0]
	v_pk_mul_f32 v[102:103], v[102:103], v[150:151] op_sel_hi:[1,0]
	v_pk_mul_f32 v[100:101], v[100:101], v[150:151] op_sel_hi:[1,0]
	v_pk_mul_f32 v[94:95], v[94:95], v[150:151] op_sel_hi:[1,0]
	v_pk_mul_f32 v[92:93], v[92:93], v[150:151] op_sel_hi:[1,0]
	v_pk_mul_f32 v[82:83], v[82:83], v[150:151] op_sel_hi:[1,0]
	v_pk_mul_f32 v[80:81], v[80:81], v[150:151] op_sel_hi:[1,0]
	v_pk_mul_f32 v[74:75], v[74:75], v[150:151] op_sel_hi:[1,0]
	v_pk_mul_f32 v[72:73], v[72:73], v[150:151] op_sel_hi:[1,0]
	v_mov_b32_e32 v146, v151
	ds_read2st64_b32 v[150:151], v148 offset0:16 offset1:18
	v_pk_mul_f32 v[86:87], v[86:87], v[146:147] op_sel_hi:[1,0]
	v_pk_mul_f32 v[84:85], v[84:85], v[146:147] op_sel_hi:[1,0]
	v_pk_mul_f32 v[78:79], v[78:79], v[146:147] op_sel_hi:[1,0]
	v_pk_mul_f32 v[76:77], v[76:77], v[146:147] op_sel_hi:[1,0]
	v_pk_mul_f32 v[70:71], v[70:71], v[146:147] op_sel_hi:[1,0]
	v_pk_mul_f32 v[68:69], v[68:69], v[146:147] op_sel_hi:[1,0]
	v_pk_mul_f32 v[66:67], v[66:67], v[146:147] op_sel_hi:[1,0]
	v_pk_mul_f32 v[64:65], v[64:65], v[146:147] op_sel_hi:[1,0]
	s_waitcnt lgkmcnt(0)
	v_pk_mul_f32 v[62:63], v[62:63], v[150:151] op_sel_hi:[1,0]
	v_pk_mul_f32 v[60:61], v[60:61], v[150:151] op_sel_hi:[1,0]
	v_pk_mul_f32 v[58:59], v[58:59], v[150:151] op_sel_hi:[1,0]
	v_pk_mul_f32 v[56:57], v[56:57], v[150:151] op_sel_hi:[1,0]
	v_pk_mul_f32 v[50:51], v[50:51], v[150:151] op_sel_hi:[1,0]
	v_pk_mul_f32 v[48:49], v[48:49], v[150:151] op_sel_hi:[1,0]
	v_pk_mul_f32 v[42:43], v[42:43], v[150:151] op_sel_hi:[1,0]
	v_pk_mul_f32 v[40:41], v[40:41], v[150:151] op_sel_hi:[1,0]
	v_mov_b32_e32 v146, v151
	ds_read2st64_b32 v[150:151], v148 offset0:20 offset1:22
	v_pk_mul_f32 v[54:55], v[54:55], v[146:147] op_sel_hi:[1,0]
	v_pk_mul_f32 v[52:53], v[52:53], v[146:147] op_sel_hi:[1,0]
	v_pk_mul_f32 v[46:47], v[46:47], v[146:147] op_sel_hi:[1,0]
	v_pk_mul_f32 v[44:45], v[44:45], v[146:147] op_sel_hi:[1,0]
	v_pk_mul_f32 v[34:35], v[34:35], v[146:147] op_sel_hi:[1,0]
	v_pk_mul_f32 v[32:33], v[32:33], v[146:147] op_sel_hi:[1,0]
	v_pk_mul_f32 v[26:27], v[26:27], v[146:147] op_sel_hi:[1,0]
	v_pk_mul_f32 v[24:25], v[24:25], v[146:147] op_sel_hi:[1,0]
	s_waitcnt lgkmcnt(0)
	v_mov_b32_e32 v146, v151
	v_pk_mul_f32 v[38:39], v[38:39], v[150:151] op_sel_hi:[1,0]
	v_pk_mul_f32 v[36:37], v[36:37], v[150:151] op_sel_hi:[1,0]
	v_pk_mul_f32 v[30:31], v[30:31], v[150:151] op_sel_hi:[1,0]
	v_pk_mul_f32 v[28:29], v[28:29], v[150:151] op_sel_hi:[1,0]
	v_pk_mul_f32 v[18:19], v[18:19], v[150:151] op_sel_hi:[1,0]
	v_pk_mul_f32 v[16:17], v[16:17], v[150:151] op_sel_hi:[1,0]
	v_pk_mul_f32 v[10:11], v[10:11], v[150:151] op_sel_hi:[1,0]
	v_pk_mul_f32 v[8:9], v[8:9], v[150:151] op_sel_hi:[1,0]
	v_pk_mul_f32 v[22:23], v[22:23], v[146:147] op_sel_hi:[1,0]
	v_pk_mul_f32 v[20:21], v[20:21], v[146:147] op_sel_hi:[1,0]
	v_pk_mul_f32 v[14:15], v[14:15], v[146:147] op_sel_hi:[1,0]
	v_pk_mul_f32 v[12:13], v[12:13], v[146:147] op_sel_hi:[1,0]
	v_pk_mul_f32 v[6:7], v[6:7], v[146:147] op_sel_hi:[1,0]
	v_pk_mul_f32 v[4:5], v[4:5], v[146:147] op_sel_hi:[1,0]
	v_pk_mul_f32 v[2:3], v[2:3], v[146:147] op_sel_hi:[1,0]
	v_pk_mul_f32 v[0:1], v[0:1], v[146:147] op_sel_hi:[1,0]
	s_branch .LBB0_439

; #define PG8_STAGE(bufoff, gbase, voff) do { _Pragma("unroll") for (int _i = 0; _i < 2; ++_i) \
;         __builtin_amdgcn_global_load_lds((const unsigned*)((const char*)(gbase) + (voff)[_i]), (LAS unsigned*)(lds + (bufoff) + ldsw + _i * 8192), 16, 0, 0); } while (0)
; #define PG8_LDA(dst, b, h) do { _Pragma("unroll") for (int m = 0; m < 4; ++m) _Pragma("unroll") for (int k = 0; k < 2; ++k) dst[m][k] = *(const LAS bf16x8*)(lds + PG8_SA(b, h) + aoff + m * 2048 + k * 1024); } while (0)
; #define PG8_LDB(dst, b, h) do { _Pragma("unroll") for (int n = 0; n < 2; ++n) _Pragma("unroll") for (int k = 0; k < 2; ++k) dst[n][k] = *(const LAS bf16x8*)(lds + PG8_SB(b, h) + boff + n * 2048 + k * 1024); } while (0)
; #define PG8_WAIT_V(n) asm volatile("s_waitcnt vmcnt(" #n ")" ::: "memory")
; #define PG8_WAIT_L(n) asm volatile("s_waitcnt lgkmcnt(" #n ")" ::: "memory")
; #define PG8_BAR __builtin_amdgcn_s_barrier()
; #define PG8_SCHED __builtin_amdgcn_sched_barrier(0)
; template <class Epi>
; __device__ __forceinline__ void gemm_phase(LAS unsigned char* lds, const bf16_t* A, int lda, const bf16_t* Bt, int ldb, int M, int N, int K, int asel, const Epi& E, const int fixed_round = -1) {
;     ...
;         for (int t = 0; t < nt; t += 2) {
;             const bool last = (t == nt - 2);
;             const char* a1 = cA + (size_t)(t + 1) * kstep;
;             const char* a2 = last ? nA : cA + (size_t)(t + 2) * kstep; const char* b2 = last ? nB : cB + (size_t)(t + 2) * kstep;
;             const char* a3 = a2 + kstep; const char* b3 = b2 + kstep;
;             PG8_LDB(B0, 0, 0); PG8_SCHED; PG8_LDA(At, 0, 0); PG8_STAGE(PG8_SA(1, 1), a1 + hstepA, voffA);
;             PG8_WAIT_L(8); PG8_BAR; PG8_WAIT_L(0); PG8_MMA(0, 0, At, B0); PG8_BAR; PG8_SCHED;
;             PG8_LDB(B1, 0, 1); PG8_STAGE(PG8_SB(0, 0), b2, voffB);
;             PG8_BAR; PG8_WAIT_L(0); PG8_MMA(0, 1, At, B1); PG8_BAR;
;             PG8_LDA(At, 0, 1); PG8_STAGE(PG8_SA(0, 0), a2, voffA);
;             PG8_BAR; PG8_WAIT_L(0); PG8_MMA(1, 0, At, B0); PG8_BAR; PG8_SCHED;
;             PG8_STAGE(PG8_SB(0, 1), b2 + hstepB, voffB);
;             PG8_WAIT_V(6); PG8_BAR; PG8_MMA(1, 1, At, B1); PG8_BAR;
.LBB0_487:
	s_add_i32 s35, s35, 2
	s_add_u32 s18, s6, s14
	ds_read_b128 v[150:153], v141
	ds_read_b128 v[154:157], v141 offset:1024
	ds_read_b128 v[160:163], v141 offset:2048
	ds_read_b128 v[168:171], v141 offset:3072
	s_addc_u32 s19, s7, s15
	s_add_u32 s18, s18, 0x14500100
	s_addc_u32 s19, s19, 0
	s_add_u32 s59, s26, s14
	s_addc_u32 s60, s27, s15
	s_cmpk_eq_i32 s14, 0xf00
	s_cselect_b32 s21, s1, s19
	s_cselect_b32 s20, s0, s18
	s_cselect_b32 s19, s3, s60
	s_cselect_b32 s18, s2, s59
	s_mov_b32 m0, s49
	v_lshl_add_u64 v[146:147], v[136:137], 0, s[14:15]
	ds_read_b128 v[172:175], v142
	ds_read_b128 v[176:179], v142 offset:1024
	ds_read_b128 v[180:183], v142 offset:2048
	ds_read_b128 v[184:187], v142 offset:3072
	ds_read_b128 v[188:191], v142 offset:4096
	ds_read_b128 v[192:195], v142 offset:5120
	ds_read_b128 v[196:199], v142 offset:6144
	ds_read_b128 v[202:205], v142 offset:7168
	global_load_lds_dwordx4 v[146:147], off
	v_lshl_add_u64 v[146:147], v[138:139], 0, s[14:15]
	s_mov_b32 m0, s50
	s_setprio 1
	global_load_lds_dwordx4 v[146:147], off
	s_waitcnt lgkmcnt(8)
	s_barrier
	s_waitcnt lgkmcnt(0)
	v_mfma_f32_16x16x32_bf16 v[124:127], v[150:153], v[172:175], v[124:127]
	v_mfma_f32_16x16x32_bf16 v[120:123], v[160:163], v[172:175], v[120:123]
	v_mfma_f32_16x16x32_bf16 v[116:119], v[150:153], v[180:183], v[116:119]
	v_mfma_f32_16x16x32_bf16 v[112:115], v[160:163], v[180:183], v[112:115]
	v_mfma_f32_16x16x32_bf16 v[100:103], v[150:153], v[188:191], v[100:103]
	v_mfma_f32_16x16x32_bf16 v[92:95], v[160:163], v[188:191], v[92:95]
	v_mfma_f32_16x16x32_bf16 v[84:87], v[150:153], v[196:199], v[84:87]
	v_mfma_f32_16x16x32_bf16 v[76:79], v[160:163], v[196:199], v[76:79]
	v_mfma_f32_16x16x32_bf16 v[124:127], v[154:157], v[176:179], v[124:127]
	v_mfma_f32_16x16x32_bf16 v[120:123], v[168:171], v[176:179], v[120:123]
	v_mfma_f32_16x16x32_bf16 v[116:119], v[154:157], v[184:187], v[116:119]
	v_mfma_f32_16x16x32_bf16 v[112:115], v[168:171], v[184:187], v[112:115]
	v_mfma_f32_16x16x32_bf16 v[100:103], v[154:157], v[192:195], v[100:103]
	v_mfma_f32_16x16x32_bf16 v[92:95], v[168:171], v[192:195], v[92:95]
	v_mfma_f32_16x16x32_bf16 v[84:87], v[154:157], v[202:205], v[84:87]
	v_mfma_f32_16x16x32_bf16 v[76:79], v[168:171], v[202:205], v[76:79]
	s_barrier
	s_setprio 0
	s_mov_b32 m0, s51
	s_add_u32 s98, s18, s4
	s_addc_u32 s99, s19, s5
	ds_read_b128 v[206:209], v143
	ds_read_b128 v[210:213], v143 offset:1024
	ds_read_b128 v[214:217], v143 offset:2048
	ds_read_b128 v[218:221], v143 offset:3072
	global_load_lds_dwordx4 v130, s[18:19]
	s_mov_b32 m0, s52
	s_setprio 1
	global_load_lds_dwordx4 v134, s[18:19]
	s_barrier
	s_waitcnt lgkmcnt(0)
	v_mfma_f32_16x16x32_bf16 v[108:111], v[206:209], v[172:175], v[108:111]
	v_mfma_f32_16x16x32_bf16 v[104:107], v[214:217], v[172:175], v[104:107]
	v_mfma_f32_16x16x32_bf16 v[96:99], v[206:209], v[180:183], v[96:99]
	v_mfma_f32_16x16x32_bf16 v[88:91], v[214:217], v[180:183], v[88:91]
	v_mfma_f32_16x16x32_bf16 v[80:83], v[206:209], v[188:191], v[80:83]
	v_mfma_f32_16x16x32_bf16 v[72:75], v[214:217], v[188:191], v[72:75]
	v_mfma_f32_16x16x32_bf16 v[68:71], v[206:209], v[196:199], v[68:71]
	v_mfma_f32_16x16x32_bf16 v[64:67], v[214:217], v[196:199], v[64:67]
	v_mfma_f32_16x16x32_bf16 v[108:111], v[210:213], v[176:179], v[108:111]
	v_mfma_f32_16x16x32_bf16 v[104:107], v[218:221], v[176:179], v[104:107]
	v_mfma_f32_16x16x32_bf16 v[96:99], v[210:213], v[184:187], v[96:99]
	v_mfma_f32_16x16x32_bf16 v[88:91], v[218:221], v[184:187], v[88:91]
	v_mfma_f32_16x16x32_bf16 v[80:83], v[210:213], v[192:195], v[80:83]
	v_mfma_f32_16x16x32_bf16 v[72:75], v[218:221], v[192:195], v[72:75]
	v_mfma_f32_16x16x32_bf16 v[68:71], v[210:213], v[202:205], v[68:71]
	v_mfma_f32_16x16x32_bf16 v[64:67], v[218:221], v[202:205], v[64:67]
	s_barrier
	s_setprio 0
	s_mov_b32 m0, s43
	s_add_u32 s100, s20, s4
	s_addc_u32 s101, s21, s5
	ds_read_b128 v[172:175], v142 offset:16384
	ds_read_b128 v[176:179], v142 offset:17408
	ds_read_b128 v[180:183], v142 offset:18432
	ds_read_b128 v[184:187], v142 offset:19456
	ds_read_b128 v[188:191], v142 offset:20480
	ds_read_b128 v[192:195], v142 offset:21504
	ds_read_b128 v[196:199], v142 offset:22528
	ds_read_b128 v[202:205], v142 offset:23552
	global_load_lds_dwordx4 v128, s[20:21]
	s_mov_b32 m0, s44
	s_setprio 1
	global_load_lds_dwordx4 v132, s[20:21]
	s_barrier
	s_waitcnt lgkmcnt(0)
	v_mfma_f32_16x16x32_bf16 v[60:63], v[150:153], v[172:175], v[60:63]
	v_mfma_f32_16x16x32_bf16 v[56:59], v[160:163], v[172:175], v[56:59]
	v_mfma_f32_16x16x32_bf16 v[52:55], v[150:153], v[180:183], v[52:55]
	v_mfma_f32_16x16x32_bf16 v[44:47], v[160:163], v[180:183], v[44:47]
	v_mfma_f32_16x16x32_bf16 v[36:39], v[150:153], v[188:191], v[36:39]
	v_mfma_f32_16x16x32_bf16 v[28:31], v[160:163], v[188:191], v[28:31]
	v_mfma_f32_16x16x32_bf16 v[20:23], v[150:153], v[196:199], v[20:23]
	v_mfma_f32_16x16x32_bf16 v[12:15], v[160:163], v[196:199], v[12:15]
	v_mfma_f32_16x16x32_bf16 v[60:63], v[154:157], v[176:179], v[60:63]
	v_mfma_f32_16x16x32_bf16 v[56:59], v[168:171], v[176:179], v[56:59]
	v_mfma_f32_16x16x32_bf16 v[52:55], v[154:157], v[184:187], v[52:55]
	v_mfma_f32_16x16x32_bf16 v[44:47], v[168:171], v[184:187], v[44:47]
	v_mfma_f32_16x16x32_bf16 v[36:39], v[154:157], v[192:195], v[36:39]
	v_mfma_f32_16x16x32_bf16 v[28:31], v[168:171], v[192:195], v[28:31]
	v_mfma_f32_16x16x32_bf16 v[20:23], v[154:157], v[202:205], v[20:23]
	v_mfma_f32_16x16x32_bf16 v[12:15], v[168:171], v[202:205], v[12:15]
	s_barrier
	s_setprio 0
	s_add_u32 s60, s18, 0x80000
	s_addc_u32 s61, s19, 0
	s_mov_b32 m0, s53
	s_nop 0
	global_load_lds_dwordx4 v130, s[60:61]
	s_mov_b32 m0, s54
	s_setprio 1
	global_load_lds_dwordx4 v134, s[60:61]
	s_waitcnt vmcnt(6)
	s_barrier
; #define PG8_STAGE(bufoff, gbase, voff) do { _Pragma("unroll") for (int _i = 0; _i < 2; ++_i) \
;         __builtin_amdgcn_global_load_lds((const unsigned*)((const char*)(gbase) + (voff)[_i]), (LAS unsigned*)(lds + (bufoff) + ldsw + _i * 8192), 16, 0, 0); } while (0)
; #define PG8_LDA(dst, b, h) do { _Pragma("unroll") for (int m = 0; m < 4; ++m) _Pragma("unroll") for (int k = 0; k < 2; ++k) dst[m][k] = *(const LAS bf16x8*)(lds + PG8_SA(b, h) + aoff + m * 2048 + k * 1024); } while (0)
; #define PG8_LDB(dst, b, h) do { _Pragma("unroll") for (int n = 0; n < 2; ++n) _Pragma("unroll") for (int k = 0; k < 2; ++k) dst[n][k] = *(const LAS bf16x8*)(lds + PG8_SB(b, h) + boff + n * 2048 + k * 1024); } while (0)
; #define PG8_WAIT_V(n) asm volatile("s_waitcnt vmcnt(" #n ")" ::: "memory")
; #define PG8_WAIT_L(n) asm volatile("s_waitcnt lgkmcnt(" #n ")" ::: "memory")
; #define PG8_BAR __builtin_amdgcn_s_barrier()
; #define PG8_SCHED __builtin_amdgcn_sched_barrier(0)
; template <class Epi>
; __device__ __forceinline__ void gemm_phase(LAS unsigned char* lds, const bf16_t* A, int lda, const bf16_t* Bt, int ldb, int M, int N, int K, int asel, const Epi& E, const int fixed_round = -1) {
;     ...
;             PG8_WAIT_V(6); PG8_BAR; PG8_MMA(1, 1, At, B1); PG8_BAR;
;             PG8_LDB(B0, 1, 0); PG8_SCHED; PG8_LDA(At, 1, 0); PG8_STAGE(PG8_SA(0, 1), a2 + hstepA, voffA);
;             PG8_WAIT_L(8); PG8_BAR; PG8_WAIT_L(0); PG8_MMA(0, 0, At, B0); PG8_BAR; PG8_SCHED;
;             PG8_LDB(B1, 1, 1); PG8_STAGE(PG8_SB(1, 0), b3, voffB);
;             PG8_BAR; PG8_WAIT_L(0); PG8_MMA(0, 1, At, B1); PG8_BAR;
;             PG8_LDA(At, 1, 1); PG8_STAGE(PG8_SA(1, 0), a3, voffA);
;             PG8_BAR; PG8_WAIT_L(0); PG8_MMA(1, 0, At, B0); PG8_BAR; PG8_SCHED;
;             PG8_STAGE(PG8_SB(1, 1), b3 + hstepB, voffB);
;             PG8_WAIT_V(6); PG8_BAR; PG8_MMA(1, 1, At, B1); PG8_BAR;
	v_mfma_f32_16x16x32_bf16 v[48:51], v[206:209], v[172:175], v[48:51]
	v_mfma_f32_16x16x32_bf16 v[40:43], v[214:217], v[172:175], v[40:43]
	v_mfma_f32_16x16x32_bf16 v[32:35], v[206:209], v[180:183], v[32:35]
	v_mfma_f32_16x16x32_bf16 v[24:27], v[214:217], v[180:183], v[24:27]
	v_mfma_f32_16x16x32_bf16 v[16:19], v[206:209], v[188:191], v[16:19]
	v_mfma_f32_16x16x32_bf16 v[8:11], v[214:217], v[188:191], v[8:11]
	v_mfma_f32_16x16x32_bf16 v[4:7], v[206:209], v[196:199], v[4:7]
	v_mfma_f32_16x16x32_bf16 v[0:3], v[214:217], v[196:199], v[0:3]
	v_mfma_f32_16x16x32_bf16 v[48:51], v[210:213], v[176:179], v[48:51]
	v_mfma_f32_16x16x32_bf16 v[40:43], v[218:221], v[176:179], v[40:43]
	v_mfma_f32_16x16x32_bf16 v[32:35], v[210:213], v[184:187], v[32:35]
	v_mfma_f32_16x16x32_bf16 v[24:27], v[218:221], v[184:187], v[24:27]
	v_mfma_f32_16x16x32_bf16 v[16:19], v[210:213], v[192:195], v[16:19]
	v_mfma_f32_16x16x32_bf16 v[8:11], v[218:221], v[192:195], v[8:11]
	v_mfma_f32_16x16x32_bf16 v[4:7], v[210:213], v[202:205], v[4:7]
	v_mfma_f32_16x16x32_bf16 v[0:3], v[218:221], v[202:205], v[0:3]
	s_barrier
	s_setprio 0
	ds_read_b128 v[150:153], v144
	ds_read_b128 v[154:157], v144 offset:1024
	ds_read_b128 v[160:163], v144 offset:2048
	ds_read_b128 v[168:171], v144 offset:3072
	s_add_u32 s20, s20, 0x80000
	s_addc_u32 s21, s21, 0
	s_mov_b32 m0, s45
	ds_read_b128 v[172:175], v142 offset:32768
	ds_read_b128 v[176:179], v142 offset:33792
	ds_read_b128 v[180:183], v142 offset:34816
	ds_read_b128 v[184:187], v142 offset:35840
	ds_read_b128 v[188:191], v142 offset:36864
	ds_read_b128 v[192:195], v142 offset:37888
	ds_read_b128 v[196:199], v142 offset:38912
	ds_read_b128 v[202:205], v142 offset:39936
	global_load_lds_dwordx4 v128, s[20:21]
	s_mov_b32 m0, s46
	s_setprio 1
	global_load_lds_dwordx4 v132, s[20:21]
	s_waitcnt lgkmcnt(8)
	s_barrier
	s_waitcnt lgkmcnt(0)
	v_mfma_f32_16x16x32_bf16 v[124:127], v[150:153], v[172:175], v[124:127]
	v_mfma_f32_16x16x32_bf16 v[120:123], v[160:163], v[172:175], v[120:123]
	v_mfma_f32_16x16x32_bf16 v[116:119], v[150:153], v[180:183], v[116:119]
	v_mfma_f32_16x16x32_bf16 v[112:115], v[160:163], v[180:183], v[112:115]
	v_mfma_f32_16x16x32_bf16 v[100:103], v[150:153], v[188:191], v[100:103]
	v_mfma_f32_16x16x32_bf16 v[92:95], v[160:163], v[188:191], v[92:95]
	v_mfma_f32_16x16x32_bf16 v[84:87], v[150:153], v[196:199], v[84:87]
	v_mfma_f32_16x16x32_bf16 v[76:79], v[160:163], v[196:199], v[76:79]
	v_mfma_f32_16x16x32_bf16 v[124:127], v[154:157], v[176:179], v[124:127]
	v_mfma_f32_16x16x32_bf16 v[120:123], v[168:171], v[176:179], v[120:123]
	v_mfma_f32_16x16x32_bf16 v[116:119], v[154:157], v[184:187], v[116:119]
	v_mfma_f32_16x16x32_bf16 v[112:115], v[168:171], v[184:187], v[112:115]
	v_mfma_f32_16x16x32_bf16 v[100:103], v[154:157], v[192:195], v[100:103]
	v_mfma_f32_16x16x32_bf16 v[92:95], v[168:171], v[192:195], v[92:95]
	v_mfma_f32_16x16x32_bf16 v[84:87], v[154:157], v[202:205], v[84:87]
	v_mfma_f32_16x16x32_bf16 v[76:79], v[168:171], v[202:205], v[76:79]
	s_barrier
	s_setprio 0
	s_mov_b32 m0, s55
	ds_read_b128 v[206:209], v145
	ds_read_b128 v[210:213], v145 offset:1024
	ds_read_b128 v[214:217], v145 offset:2048
	ds_read_b128 v[218:221], v145 offset:3072
	global_load_lds_dwordx4 v130, s[98:99]
	s_mov_b32 m0, s56
	s_setprio 1
	global_load_lds_dwordx4 v134, s[98:99]
	s_barrier
	s_waitcnt lgkmcnt(0)
	v_mfma_f32_16x16x32_bf16 v[108:111], v[206:209], v[172:175], v[108:111]
	v_mfma_f32_16x16x32_bf16 v[104:107], v[214:217], v[172:175], v[104:107]
	v_mfma_f32_16x16x32_bf16 v[96:99], v[206:209], v[180:183], v[96:99]
	v_mfma_f32_16x16x32_bf16 v[88:91], v[214:217], v[180:183], v[88:91]
	v_mfma_f32_16x16x32_bf16 v[80:83], v[206:209], v[188:191], v[80:83]
	v_mfma_f32_16x16x32_bf16 v[72:75], v[214:217], v[188:191], v[72:75]
	v_mfma_f32_16x16x32_bf16 v[68:71], v[206:209], v[196:199], v[68:71]
	v_mfma_f32_16x16x32_bf16 v[64:67], v[214:217], v[196:199], v[64:67]
	v_mfma_f32_16x16x32_bf16 v[108:111], v[210:213], v[176:179], v[108:111]
	v_mfma_f32_16x16x32_bf16 v[104:107], v[218:221], v[176:179], v[104:107]
	v_mfma_f32_16x16x32_bf16 v[96:99], v[210:213], v[184:187], v[96:99]
	v_mfma_f32_16x16x32_bf16 v[88:91], v[218:221], v[184:187], v[88:91]
	v_mfma_f32_16x16x32_bf16 v[80:83], v[210:213], v[192:195], v[80:83]
	v_mfma_f32_16x16x32_bf16 v[72:75], v[218:221], v[192:195], v[72:75]
	v_mfma_f32_16x16x32_bf16 v[68:71], v[210:213], v[202:205], v[68:71]
	v_mfma_f32_16x16x32_bf16 v[64:67], v[218:221], v[202:205], v[64:67]
	s_barrier
	s_setprio 0
	s_mov_b32 m0, s47
	ds_read_b128 v[172:175], v142 offset:49152
	ds_read_b128 v[176:179], v142 offset:50176
	ds_read_b128 v[180:183], v142 offset:51200
	ds_read_b128 v[184:187], v142 offset:52224
	ds_read_b128 v[188:191], v142 offset:53248
	ds_read_b128 v[192:195], v142 offset:54272
	ds_read_b128 v[196:199], v142 offset:55296
	ds_read_b128 v[202:205], v142 offset:56320
	global_load_lds_dwordx4 v128, s[100:101]
	s_mov_b32 m0, s48
	s_setprio 1
	global_load_lds_dwordx4 v132, s[100:101]
	s_barrier
	s_waitcnt lgkmcnt(0)
	v_mfma_f32_16x16x32_bf16 v[60:63], v[150:153], v[172:175], v[60:63]
	v_mfma_f32_16x16x32_bf16 v[56:59], v[160:163], v[172:175], v[56:59]
	v_mfma_f32_16x16x32_bf16 v[52:55], v[150:153], v[180:183], v[52:55]
	v_mfma_f32_16x16x32_bf16 v[44:47], v[160:163], v[180:183], v[44:47]
	v_mfma_f32_16x16x32_bf16 v[36:39], v[150:153], v[188:191], v[36:39]
	v_mfma_f32_16x16x32_bf16 v[28:31], v[160:163], v[188:191], v[28:31]
	v_mfma_f32_16x16x32_bf16 v[20:23], v[150:153], v[196:199], v[20:23]
	v_mfma_f32_16x16x32_bf16 v[12:15], v[160:163], v[196:199], v[12:15]
	v_mfma_f32_16x16x32_bf16 v[60:63], v[154:157], v[176:179], v[60:63]
	v_mfma_f32_16x16x32_bf16 v[56:59], v[168:171], v[176:179], v[56:59]
	v_mfma_f32_16x16x32_bf16 v[52:55], v[154:157], v[184:187], v[52:55]
	v_mfma_f32_16x16x32_bf16 v[44:47], v[168:171], v[184:187], v[44:47]
	v_mfma_f32_16x16x32_bf16 v[36:39], v[154:157], v[192:195], v[36:39]
	v_mfma_f32_16x16x32_bf16 v[28:31], v[168:171], v[192:195], v[28:31]
	v_mfma_f32_16x16x32_bf16 v[20:23], v[154:157], v[202:205], v[20:23]
	v_mfma_f32_16x16x32_bf16 v[12:15], v[168:171], v[202:205], v[12:15]
	s_barrier
; #define LAS __attribute__((address_space(3)))
; #define PG8_STAGE(bufoff, gbase, voff) do { _Pragma("unroll") for (int _i = 0; _i < 2; ++_i) \
;         __builtin_amdgcn_global_load_lds((const unsigned*)((const char*)(gbase) + (voff)[_i]), (LAS unsigned*)(lds + (bufoff) + ldsw + _i * 8192), 16, 0, 0); } while (0)
; #define PG8_WAIT_V(n) asm volatile("s_waitcnt vmcnt(" #n ")" ::: "memory")
; #define PG8_BAR __builtin_amdgcn_s_barrier()
; template <class Epi>
; __device__ __forceinline__ void gemm_phase(LAS unsigned char* lds, const bf16_t* A, int lda, const bf16_t* Bt, int ldb, int M, int N, int K, int asel, const Epi& E, const int fixed_round = -1) {
;     ...
;             PG8_STAGE(PG8_SB(1, 1), b3 + hstepB, voffB);
;             PG8_WAIT_V(6); PG8_BAR; PG8_MMA(1, 1, At, B1); PG8_BAR;
;             if constexpr (Epi::HEADSCALE) {
;                 if (t & 2) {
;                     const LAS float* rt = (const LAS float*)(lds + L_RT) + (t >> 2);
; #pragma unroll
;                     for (int ai = 0; ai < 2; ++ai)
; #pragma unroll
;                         for (int m = 0; m < 4; ++m) { const float f = rt[(ai * HALF + wr * 64 + m * 16 + fr) * 8];
; #pragma unroll
;                             for (int bj = 0; bj < 2; ++bj)
; #pragma unroll
;                                 for (int n = 0; n < 2; ++n) acc[ai][bj][m][n] *= f; }
;                 }
	s_setprio 0
	s_add_u32 s18, s18, 0x80080
	s_addc_u32 s19, s19, 0
	s_mov_b32 m0, s57
	s_nop 0
	global_load_lds_dwordx4 v130, s[18:19]
	s_mov_b32 m0, s58
	s_setprio 1
	global_load_lds_dwordx4 v134, s[18:19]
	s_waitcnt vmcnt(6)
	s_barrier
	v_mfma_f32_16x16x32_bf16 v[48:51], v[206:209], v[172:175], v[48:51]
	v_mfma_f32_16x16x32_bf16 v[40:43], v[214:217], v[172:175], v[40:43]
	v_mfma_f32_16x16x32_bf16 v[32:35], v[206:209], v[180:183], v[32:35]
	v_mfma_f32_16x16x32_bf16 v[24:27], v[214:217], v[180:183], v[24:27]
	v_mfma_f32_16x16x32_bf16 v[16:19], v[206:209], v[188:191], v[16:19]
	v_mfma_f32_16x16x32_bf16 v[8:11], v[214:217], v[188:191], v[8:11]
	v_mfma_f32_16x16x32_bf16 v[4:7], v[206:209], v[196:199], v[4:7]
	v_mfma_f32_16x16x32_bf16 v[0:3], v[214:217], v[196:199], v[0:3]
	v_mfma_f32_16x16x32_bf16 v[48:51], v[210:213], v[176:179], v[48:51]
	v_mfma_f32_16x16x32_bf16 v[40:43], v[218:221], v[176:179], v[40:43]
	v_mfma_f32_16x16x32_bf16 v[32:35], v[210:213], v[184:187], v[32:35]
	v_mfma_f32_16x16x32_bf16 v[24:27], v[218:221], v[184:187], v[24:27]
	v_mfma_f32_16x16x32_bf16 v[16:19], v[210:213], v[192:195], v[16:19]
	v_mfma_f32_16x16x32_bf16 v[8:11], v[218:221], v[192:195], v[8:11]
	v_mfma_f32_16x16x32_bf16 v[4:7], v[210:213], v[202:205], v[4:7]
	v_mfma_f32_16x16x32_bf16 v[0:3], v[218:221], v[202:205], v[0:3]
	s_setprio 0
	s_bitcmp0_b32 s35, 1
	s_barrier
	s_cbranch_scc1 .LBB0_486
	s_and_b32 s18, s35, -4
	v_add_u32_e32 v148, s18, v140
	ds_read2st64_b32 v[146:147], v148 offset1:2
	ds_read2st64_b32 v[150:151], v148 offset0:4 offset1:6
	s_waitcnt lgkmcnt(0)
	v_pk_mul_f32 v[126:127], v[126:127], v[146:147] op_sel_hi:[1,0]
	v_pk_mul_f32 v[124:125], v[124:125], v[146:147] op_sel_hi:[1,0]
	v_pk_mul_f32 v[122:123], v[122:123], v[146:147] op_sel_hi:[1,0]
	v_pk_mul_f32 v[120:121], v[120:121], v[146:147] op_sel_hi:[1,0]
	v_pk_mul_f32 v[110:111], v[110:111], v[146:147] op_sel_hi:[1,0]
	v_pk_mul_f32 v[108:109], v[108:109], v[146:147] op_sel_hi:[1,0]
	v_pk_mul_f32 v[106:107], v[106:107], v[146:147] op_sel_hi:[1,0]
	v_pk_mul_f32 v[104:105], v[104:105], v[146:147] op_sel_hi:[1,0]
	v_mov_b32_e32 v146, v147
	v_pk_mul_f32 v[118:119], v[118:119], v[146:147] op_sel_hi:[1,0]
	v_pk_mul_f32 v[116:117], v[116:117], v[146:147] op_sel_hi:[1,0]
	v_pk_mul_f32 v[114:115], v[114:115], v[146:147] op_sel_hi:[1,0]
	v_pk_mul_f32 v[112:113], v[112:113], v[146:147] op_sel_hi:[1,0]
	v_pk_mul_f32 v[98:99], v[98:99], v[146:147] op_sel_hi:[1,0]
	v_pk_mul_f32 v[96:97], v[96:97], v[146:147] op_sel_hi:[1,0]
	v_pk_mul_f32 v[90:91], v[90:91], v[146:147] op_sel_hi:[1,0]
	v_pk_mul_f32 v[88:89], v[88:89], v[146:147] op_sel_hi:[1,0]
	v_pk_mul_f32 v[102:103], v[102:103], v[150:151] op_sel_hi:[1,0]
	v_pk_mul_f32 v[100:101], v[100:101], v[150:151] op_sel_hi:[1,0]
	v_pk_mul_f32 v[94:95], v[94:95], v[150:151] op_sel_hi:[1,0]
	v_pk_mul_f32 v[92:93], v[92:93], v[150:151] op_sel_hi:[1,0]
	v_pk_mul_f32 v[82:83], v[82:83], v[150:151] op_sel_hi:[1,0]
	v_pk_mul_f32 v[80:81], v[80:81], v[150:151] op_sel_hi:[1,0]
	v_pk_mul_f32 v[74:75], v[74:75], v[150:151] op_sel_hi:[1,0]
	v_pk_mul_f32 v[72:73], v[72:73], v[150:151] op_sel_hi:[1,0]
	v_mov_b32_e32 v146, v151
	ds_read2st64_b32 v[150:151], v148 offset0:16 offset1:18
	v_pk_mul_f32 v[86:87], v[86:87], v[146:147] op_sel_hi:[1,0]
	v_pk_mul_f32 v[84:85], v[84:85], v[146:147] op_sel_hi:[1,0]
	v_pk_mul_f32 v[78:79], v[78:79], v[146:147] op_sel_hi:[1,0]
	v_pk_mul_f32 v[76:77], v[76:77], v[146:147] op_sel_hi:[1,0]
	v_pk_mul_f32 v[70:71], v[70:71], v[146:147] op_sel_hi:[1,0]
	v_pk_mul_f32 v[68:69], v[68:69], v[146:147] op_sel_hi:[1,0]
	v_pk_mul_f32 v[66:67], v[66:67], v[146:147] op_sel_hi:[1,0]
	v_pk_mul_f32 v[64:65], v[64:65], v[146:147] op_sel_hi:[1,0]
	s_waitcnt lgkmcnt(0)
	v_pk_mul_f32 v[62:63], v[62:63], v[150:151] op_sel_hi:[1,0]
	v_pk_mul_f32 v[60:61], v[60:61], v[150:151] op_sel_hi:[1,0]
	v_pk_mul_f32 v[58:59], v[58:59], v[150:151] op_sel_hi:[1,0]
	v_pk_mul_f32 v[56:57], v[56:57], v[150:151] op_sel_hi:[1,0]
	v_pk_mul_f32 v[50:51], v[50:51], v[150:151] op_sel_hi:[1,0]
	v_pk_mul_f32 v[48:49], v[48:49], v[150:151] op_sel_hi:[1,0]
	v_pk_mul_f32 v[42:43], v[42:43], v[150:151] op_sel_hi:[1,0]
	v_pk_mul_f32 v[40:41], v[40:41], v[150:151] op_sel_hi:[1,0]
	v_mov_b32_e32 v146, v151
	ds_read2st64_b32 v[150:151], v148 offset0:20 offset1:22
	v_pk_mul_f32 v[54:55], v[54:55], v[146:147] op_sel_hi:[1,0]
	v_pk_mul_f32 v[52:53], v[52:53], v[146:147] op_sel_hi:[1,0]
	v_pk_mul_f32 v[46:47], v[46:47], v[146:147] op_sel_hi:[1,0]
	v_pk_mul_f32 v[44:45], v[44:45], v[146:147] op_sel_hi:[1,0]
	v_pk_mul_f32 v[34:35], v[34:35], v[146:147] op_sel_hi:[1,0]
	v_pk_mul_f32 v[32:33], v[32:33], v[146:147] op_sel_hi:[1,0]
	v_pk_mul_f32 v[26:27], v[26:27], v[146:147] op_sel_hi:[1,0]
	v_pk_mul_f32 v[24:25], v[24:25], v[146:147] op_sel_hi:[1,0]
	s_waitcnt lgkmcnt(0)
	v_mov_b32_e32 v146, v151
	v_pk_mul_f32 v[38:39], v[38:39], v[150:151] op_sel_hi:[1,0]
	v_pk_mul_f32 v[36:37], v[36:37], v[150:151] op_sel_hi:[1,0]
	v_pk_mul_f32 v[30:31], v[30:31], v[150:151] op_sel_hi:[1,0]
	v_pk_mul_f32 v[28:29], v[28:29], v[150:151] op_sel_hi:[1,0]
	v_pk_mul_f32 v[18:19], v[18:19], v[150:151] op_sel_hi:[1,0]
	v_pk_mul_f32 v[16:17], v[16:17], v[150:151] op_sel_hi:[1,0]
	v_pk_mul_f32 v[10:11], v[10:11], v[150:151] op_sel_hi:[1,0]
	v_pk_mul_f32 v[8:9], v[8:9], v[150:151] op_sel_hi:[1,0]
	v_pk_mul_f32 v[22:23], v[22:23], v[146:147] op_sel_hi:[1,0]
	v_pk_mul_f32 v[20:21], v[20:21], v[146:147] op_sel_hi:[1,0]
	v_pk_mul_f32 v[14:15], v[14:15], v[146:147] op_sel_hi:[1,0]
	v_pk_mul_f32 v[12:13], v[12:13], v[146:147] op_sel_hi:[1,0]
	v_pk_mul_f32 v[6:7], v[6:7], v[146:147] op_sel_hi:[1,0]
	v_pk_mul_f32 v[4:5], v[4:5], v[146:147] op_sel_hi:[1,0]
	v_pk_mul_f32 v[2:3], v[2:3], v[146:147] op_sel_hi:[1,0]
	v_pk_mul_f32 v[0:1], v[0:1], v[146:147] op_sel_hi:[1,0]
	s_branch .LBB0_486

; #define PG8_STAGE(bufoff, gbase, voff) do { _Pragma("unroll") for (int _i = 0; _i < 2; ++_i) \
;         __builtin_amdgcn_global_load_lds((const unsigned*)((const char*)(gbase) + (voff)[_i]), (LAS unsigned*)(lds + (bufoff) + ldsw + _i * 8192), 16, 0, 0); } while (0)
; #define PG8_LDA(dst, b, h) do { _Pragma("unroll") for (int m = 0; m < 4; ++m) _Pragma("unroll") for (int k = 0; k < 2; ++k) dst[m][k] = *(const LAS bf16x8*)(lds + PG8_SA(b, h) + aoff + m * 2048 + k * 1024); } while (0)
; #define PG8_LDB(dst, b, h) do { _Pragma("unroll") for (int n = 0; n < 2; ++n) _Pragma("unroll") for (int k = 0; k < 2; ++k) dst[n][k] = *(const LAS bf16x8*)(lds + PG8_SB(b, h) + boff + n * 2048 + k * 1024); } while (0)
; #define PG8_WAIT_V(n) asm volatile("s_waitcnt vmcnt(" #n ")" ::: "memory")
; #define PG8_WAIT_L(n) asm volatile("s_waitcnt lgkmcnt(" #n ")" ::: "memory")
; #define PG8_BAR __builtin_amdgcn_s_barrier()
; #define PG8_SCHED __builtin_amdgcn_sched_barrier(0)
; template <class Epi>
; __device__ __forceinline__ void gemm_phase(LAS unsigned char* lds, const bf16_t* A, int lda, const bf16_t* Bt, int ldb, int M, int N, int K, int asel, const Epi& E, const int fixed_round = -1) {
;     ...
;         for (int t = 0; t < nt; t += 2) {
;             const bool last = (t == nt - 2);
;             const char* a1 = cA + (size_t)(t + 1) * kstep;
;             const char* a2 = last ? nA : cA + (size_t)(t + 2) * kstep; const char* b2 = last ? nB : cB + (size_t)(t + 2) * kstep;
;             const char* a3 = a2 + kstep; const char* b3 = b2 + kstep;
;             PG8_LDB(B0, 0, 0); PG8_SCHED; PG8_LDA(At, 0, 0); PG8_STAGE(PG8_SA(1, 1), a1 + hstepA, voffA);
;             PG8_WAIT_L(8); PG8_BAR; PG8_WAIT_L(0); PG8_MMA(0, 0, At, B0); PG8_BAR; PG8_SCHED;
;             PG8_LDB(B1, 0, 1); PG8_STAGE(PG8_SB(0, 0), b2, voffB);
;             PG8_BAR; PG8_WAIT_L(0); PG8_MMA(0, 1, At, B1); PG8_BAR;
;             PG8_LDA(At, 0, 1); PG8_STAGE(PG8_SA(0, 0), a2, voffA);
;             PG8_BAR; PG8_WAIT_L(0); PG8_MMA(1, 0, At, B0); PG8_BAR; PG8_SCHED;
;             PG8_STAGE(PG8_SB(0, 1), b2 + hstepB, voffB);
;             PG8_WAIT_V(6); PG8_BAR; PG8_MMA(1, 1, At, B1); PG8_BAR;
.LBB0_591:
	ds_read_b128 v[152:155], v149
	ds_read_b128 v[156:159], v149 offset:1024
	ds_read_b128 v[160:163], v149 offset:2048
	ds_read_b128 v[164:167], v149 offset:3072
	s_add_i32 m0, s27, 0xc000
	ds_read_b128 v[168:171], v150
	ds_read_b128 v[172:175], v150 offset:1024
	ds_read_b128 v[176:179], v150 offset:2048
	ds_read_b128 v[180:183], v150 offset:3072
	ds_read_b128 v[184:187], v150 offset:4096
	ds_read_b128 v[188:191], v150 offset:5120
	ds_read_b128 v[192:195], v150 offset:6144
	ds_read_b128 v[196:199], v150 offset:7168
	global_load_lds_dwordx4 v136, s[30:31]
	s_add_i32 m0, s27, 0xe000
	s_setprio 1
	global_load_lds_dwordx4 v138, s[30:31]
	s_waitcnt lgkmcnt(8)
	s_barrier
	s_waitcnt lgkmcnt(0)
	v_mfma_f32_16x16x32_bf16 v[124:127], v[152:155], v[168:171], v[124:127]
	v_mfma_f32_16x16x32_bf16 v[120:123], v[160:163], v[168:171], v[120:123]
	v_mfma_f32_16x16x32_bf16 v[108:111], v[152:155], v[176:179], v[108:111]
	v_mfma_f32_16x16x32_bf16 v[104:107], v[160:163], v[176:179], v[104:107]
	v_mfma_f32_16x16x32_bf16 v[92:95], v[152:155], v[184:187], v[92:95]
	v_mfma_f32_16x16x32_bf16 v[88:91], v[160:163], v[184:187], v[88:91]
	v_mfma_f32_16x16x32_bf16 v[76:79], v[152:155], v[192:195], v[76:79]
	v_mfma_f32_16x16x32_bf16 v[72:75], v[160:163], v[192:195], v[72:75]
	v_mfma_f32_16x16x32_bf16 v[124:127], v[156:159], v[172:175], v[124:127]
	v_mfma_f32_16x16x32_bf16 v[120:123], v[164:167], v[172:175], v[120:123]
	v_mfma_f32_16x16x32_bf16 v[108:111], v[156:159], v[180:183], v[108:111]
	v_mfma_f32_16x16x32_bf16 v[104:107], v[164:167], v[180:183], v[104:107]
	v_mfma_f32_16x16x32_bf16 v[92:95], v[156:159], v[188:191], v[92:95]
	v_mfma_f32_16x16x32_bf16 v[88:91], v[164:167], v[188:191], v[88:91]
	v_mfma_f32_16x16x32_bf16 v[76:79], v[156:159], v[196:199], v[76:79]
	v_mfma_f32_16x16x32_bf16 v[72:75], v[164:167], v[196:199], v[72:75]
	s_barrier
	s_setprio 0
	s_add_u32 s28, s30, 0xfff80080
	s_addc_u32 s29, s31, -1
	s_cmp_eq_u32 s56, 28
	s_cselect_b32 s37, s7, s29
	s_cselect_b32 s36, s52, s28
	s_cselect_b32 s35, s5, s55
	s_cselect_b32 s34, s53, s54
	s_add_i32 s28, s81, s42
	s_add_u32 s98, s34, s2
	s_addc_u32 s99, s35, s3
	s_mov_b32 m0, s28
	ds_read_b128 v[202:205], v151
	ds_read_b128 v[206:209], v151 offset:1024
	ds_read_b128 v[210:213], v151 offset:2048
	ds_read_b128 v[214:217], v151 offset:3072
	global_load_lds_dwordx4 v130, s[34:35]
	s_add_i32 m0, s28, 0x2000
	s_setprio 1
	global_load_lds_dwordx4 v134, s[34:35]
	s_barrier
	s_waitcnt lgkmcnt(0)
	v_mfma_f32_16x16x32_bf16 v[116:119], v[202:205], v[168:171], v[116:119]
	v_mfma_f32_16x16x32_bf16 v[112:115], v[210:213], v[168:171], v[112:115]
	v_mfma_f32_16x16x32_bf16 v[100:103], v[202:205], v[176:179], v[100:103]
	v_mfma_f32_16x16x32_bf16 v[96:99], v[210:213], v[176:179], v[96:99]
	v_mfma_f32_16x16x32_bf16 v[84:87], v[202:205], v[184:187], v[84:87]
	v_mfma_f32_16x16x32_bf16 v[80:83], v[210:213], v[184:187], v[80:83]
	v_mfma_f32_16x16x32_bf16 v[68:71], v[202:205], v[192:195], v[68:71]
	v_mfma_f32_16x16x32_bf16 v[64:67], v[210:213], v[192:195], v[64:67]
	v_mfma_f32_16x16x32_bf16 v[116:119], v[206:209], v[172:175], v[116:119]
	v_mfma_f32_16x16x32_bf16 v[112:115], v[214:217], v[172:175], v[112:115]
	v_mfma_f32_16x16x32_bf16 v[100:103], v[206:209], v[180:183], v[100:103]
	v_mfma_f32_16x16x32_bf16 v[96:99], v[214:217], v[180:183], v[96:99]
	v_mfma_f32_16x16x32_bf16 v[84:87], v[206:209], v[188:191], v[84:87]
	v_mfma_f32_16x16x32_bf16 v[80:83], v[214:217], v[188:191], v[80:83]
	v_mfma_f32_16x16x32_bf16 v[68:71], v[206:209], v[196:199], v[68:71]
	v_mfma_f32_16x16x32_bf16 v[64:67], v[214:217], v[196:199], v[64:67]
	s_barrier
	s_setprio 0
	s_mov_b32 m0, s27
	s_add_u32 s100, s36, s2
	s_addc_u32 s101, s37, s3
	ds_read_b128 v[168:171], v150 offset:16384
	ds_read_b128 v[172:175], v150 offset:17408
	ds_read_b128 v[176:179], v150 offset:18432
	ds_read_b128 v[180:183], v150 offset:19456
	ds_read_b128 v[184:187], v150 offset:20480
	ds_read_b128 v[188:191], v150 offset:21504
	ds_read_b128 v[192:195], v150 offset:22528
	ds_read_b128 v[196:199], v150 offset:23552
	global_load_lds_dwordx4 v128, s[36:37]
	s_mov_b32 m0, s43
	s_setprio 1
	global_load_lds_dwordx4 v132, s[36:37]
	s_barrier
	s_waitcnt lgkmcnt(0)
	v_mfma_f32_16x16x32_bf16 v[60:63], v[152:155], v[168:171], v[60:63]
	v_mfma_f32_16x16x32_bf16 v[56:59], v[160:163], v[168:171], v[56:59]
	v_mfma_f32_16x16x32_bf16 v[44:47], v[152:155], v[176:179], v[44:47]
	v_mfma_f32_16x16x32_bf16 v[40:43], v[160:163], v[176:179], v[40:43]
	v_mfma_f32_16x16x32_bf16 v[28:31], v[152:155], v[184:187], v[28:31]
	v_mfma_f32_16x16x32_bf16 v[24:27], v[160:163], v[184:187], v[24:27]
	v_mfma_f32_16x16x32_bf16 v[12:15], v[152:155], v[192:195], v[12:15]
	v_mfma_f32_16x16x32_bf16 v[8:11], v[160:163], v[192:195], v[8:11]
	v_mfma_f32_16x16x32_bf16 v[60:63], v[156:159], v[172:175], v[60:63]
	v_mfma_f32_16x16x32_bf16 v[56:59], v[164:167], v[172:175], v[56:59]
	v_mfma_f32_16x16x32_bf16 v[44:47], v[156:159], v[180:183], v[44:47]
	v_mfma_f32_16x16x32_bf16 v[40:43], v[164:167], v[180:183], v[40:43]
	v_mfma_f32_16x16x32_bf16 v[28:31], v[156:159], v[188:191], v[28:31]
	v_mfma_f32_16x16x32_bf16 v[24:27], v[164:167], v[188:191], v[24:27]
	v_mfma_f32_16x16x32_bf16 v[12:15], v[156:159], v[196:199], v[12:15]
	v_mfma_f32_16x16x32_bf16 v[8:11], v[164:167], v[196:199], v[8:11]
	s_barrier
	s_setprio 0
	s_add_u32 s28, s34, 0x80000
	s_addc_u32 s29, s35, 0
	s_add_i32 s57, s82, s42
	s_mov_b32 m0, s57
	s_nop 0
	global_load_lds_dwordx4 v130, s[28:29]
	s_add_i32 m0, s57, 0x2000
	s_setprio 1
	global_load_lds_dwordx4 v134, s[28:29]
	s_waitcnt vmcnt(6)
	s_barrier
; #define PG8_STAGE(bufoff, gbase, voff) do { _Pragma("unroll") for (int _i = 0; _i < 2; ++_i) \
;         __builtin_amdgcn_global_load_lds((const unsigned*)((const char*)(gbase) + (voff)[_i]), (LAS unsigned*)(lds + (bufoff) + ldsw + _i * 8192), 16, 0, 0); } while (0)
; #define PG8_LDA(dst, b, h) do { _Pragma("unroll") for (int m = 0; m < 4; ++m) _Pragma("unroll") for (int k = 0; k < 2; ++k) dst[m][k] = *(const LAS bf16x8*)(lds + PG8_SA(b, h) + aoff + m * 2048 + k * 1024); } while (0)
; #define PG8_LDB(dst, b, h) do { _Pragma("unroll") for (int n = 0; n < 2; ++n) _Pragma("unroll") for (int k = 0; k < 2; ++k) dst[n][k] = *(const LAS bf16x8*)(lds + PG8_SB(b, h) + boff + n * 2048 + k * 1024); } while (0)
; #define PG8_WAIT_V(n) asm volatile("s_waitcnt vmcnt(" #n ")" ::: "memory")
; #define PG8_WAIT_L(n) asm volatile("s_waitcnt lgkmcnt(" #n ")" ::: "memory")
; #define PG8_BAR __builtin_amdgcn_s_barrier()
; #define PG8_SCHED __builtin_amdgcn_sched_barrier(0)
; template <class Epi>
; __device__ __forceinline__ void gemm_phase(LAS unsigned char* lds, const bf16_t* A, int lda, const bf16_t* Bt, int ldb, int M, int N, int K, int asel, const Epi& E, const int fixed_round = -1) {
;     ...
;             PG8_WAIT_V(6); PG8_BAR; PG8_MMA(1, 1, At, B1); PG8_BAR;
;             PG8_LDB(B0, 1, 0); PG8_SCHED; PG8_LDA(At, 1, 0); PG8_STAGE(PG8_SA(0, 1), a2 + hstepA, voffA);
;             PG8_WAIT_L(8); PG8_BAR; PG8_WAIT_L(0); PG8_MMA(0, 0, At, B0); PG8_BAR; PG8_SCHED;
;             PG8_LDB(B1, 1, 1); PG8_STAGE(PG8_SB(1, 0), b3, voffB);
;             PG8_BAR; PG8_WAIT_L(0); PG8_MMA(0, 1, At, B1); PG8_BAR;
;             PG8_LDA(At, 1, 1); PG8_STAGE(PG8_SA(1, 0), a3, voffA);
;             PG8_BAR; PG8_WAIT_L(0); PG8_MMA(1, 0, At, B0); PG8_BAR; PG8_SCHED;
	v_mfma_f32_16x16x32_bf16 v[52:55], v[202:205], v[168:171], v[52:55]
	v_mfma_f32_16x16x32_bf16 v[48:51], v[210:213], v[168:171], v[48:51]
	v_mfma_f32_16x16x32_bf16 v[36:39], v[202:205], v[176:179], v[36:39]
	v_mfma_f32_16x16x32_bf16 v[32:35], v[210:213], v[176:179], v[32:35]
	v_mfma_f32_16x16x32_bf16 v[20:23], v[202:205], v[184:187], v[20:23]
	v_mfma_f32_16x16x32_bf16 v[16:19], v[210:213], v[184:187], v[16:19]
	v_mfma_f32_16x16x32_bf16 v[4:7], v[202:205], v[192:195], v[4:7]
	v_mfma_f32_16x16x32_bf16 v[0:3], v[210:213], v[192:195], v[0:3]
	v_mfma_f32_16x16x32_bf16 v[52:55], v[206:209], v[172:175], v[52:55]
	v_mfma_f32_16x16x32_bf16 v[48:51], v[214:217], v[172:175], v[48:51]
	v_mfma_f32_16x16x32_bf16 v[36:39], v[206:209], v[180:183], v[36:39]
	v_mfma_f32_16x16x32_bf16 v[32:35], v[214:217], v[180:183], v[32:35]
	v_mfma_f32_16x16x32_bf16 v[20:23], v[206:209], v[188:191], v[20:23]
	v_mfma_f32_16x16x32_bf16 v[16:19], v[214:217], v[188:191], v[16:19]
	v_mfma_f32_16x16x32_bf16 v[4:7], v[206:209], v[196:199], v[4:7]
	v_mfma_f32_16x16x32_bf16 v[0:3], v[214:217], v[196:199], v[0:3]
	s_barrier
	s_setprio 0
	v_add_u32_e32 v164, s83, v147
	ds_read_b128 v[152:155], v164
	ds_read_b128 v[156:159], v164 offset:1024
	ds_read_b128 v[160:163], v164 offset:2048
	ds_read_b128 v[164:167], v164 offset:3072
	s_add_u32 s28, s36, 0x80000
	s_addc_u32 s29, s37, 0
	s_mov_b32 m0, s44
	ds_read_b128 v[168:171], v150 offset:32768
	ds_read_b128 v[172:175], v150 offset:33792
	ds_read_b128 v[176:179], v150 offset:34816
	ds_read_b128 v[180:183], v150 offset:35840
	ds_read_b128 v[184:187], v150 offset:36864
	ds_read_b128 v[188:191], v150 offset:37888
	ds_read_b128 v[192:195], v150 offset:38912
	ds_read_b128 v[196:199], v150 offset:39936
	global_load_lds_dwordx4 v128, s[28:29]
	s_mov_b32 m0, s45
	s_setprio 1
	global_load_lds_dwordx4 v132, s[28:29]
	s_waitcnt lgkmcnt(8)
	s_barrier
	s_waitcnt lgkmcnt(0)
	v_mfma_f32_16x16x32_bf16 v[124:127], v[152:155], v[168:171], v[124:127]
	v_mfma_f32_16x16x32_bf16 v[120:123], v[160:163], v[168:171], v[120:123]
	v_mfma_f32_16x16x32_bf16 v[108:111], v[152:155], v[176:179], v[108:111]
	v_mfma_f32_16x16x32_bf16 v[104:107], v[160:163], v[176:179], v[104:107]
	v_mfma_f32_16x16x32_bf16 v[92:95], v[152:155], v[184:187], v[92:95]
	v_mfma_f32_16x16x32_bf16 v[88:91], v[160:163], v[184:187], v[88:91]
	v_mfma_f32_16x16x32_bf16 v[76:79], v[152:155], v[192:195], v[76:79]
	v_mfma_f32_16x16x32_bf16 v[72:75], v[160:163], v[192:195], v[72:75]
	v_mfma_f32_16x16x32_bf16 v[124:127], v[156:159], v[172:175], v[124:127]
	v_mfma_f32_16x16x32_bf16 v[120:123], v[164:167], v[172:175], v[120:123]
	v_mfma_f32_16x16x32_bf16 v[108:111], v[156:159], v[180:183], v[108:111]
	v_mfma_f32_16x16x32_bf16 v[104:107], v[164:167], v[180:183], v[104:107]
	v_mfma_f32_16x16x32_bf16 v[92:95], v[156:159], v[188:191], v[92:95]
	v_mfma_f32_16x16x32_bf16 v[88:91], v[164:167], v[188:191], v[88:91]
	v_mfma_f32_16x16x32_bf16 v[76:79], v[156:159], v[196:199], v[76:79]
	v_mfma_f32_16x16x32_bf16 v[72:75], v[164:167], v[196:199], v[72:75]
	s_barrier
	s_setprio 0
	s_add_i32 s28, s83, s42
	v_add_u32_e32 v214, s84, v147
	s_mov_b32 m0, s28
	ds_read_b128 v[202:205], v214
	ds_read_b128 v[206:209], v214 offset:1024
	ds_read_b128 v[210:213], v214 offset:2048
	ds_read_b128 v[214:217], v214 offset:3072
	global_load_lds_dwordx4 v130, s[98:99]
	s_add_i32 m0, s28, 0x2000
	s_setprio 1
	global_load_lds_dwordx4 v134, s[98:99]
	s_barrier
	s_waitcnt lgkmcnt(0)
	v_mfma_f32_16x16x32_bf16 v[116:119], v[202:205], v[168:171], v[116:119]
	v_mfma_f32_16x16x32_bf16 v[112:115], v[210:213], v[168:171], v[112:115]
	v_mfma_f32_16x16x32_bf16 v[100:103], v[202:205], v[176:179], v[100:103]
	v_mfma_f32_16x16x32_bf16 v[96:99], v[210:213], v[176:179], v[96:99]
	v_mfma_f32_16x16x32_bf16 v[84:87], v[202:205], v[184:187], v[84:87]
	v_mfma_f32_16x16x32_bf16 v[80:83], v[210:213], v[184:187], v[80:83]
	v_mfma_f32_16x16x32_bf16 v[68:71], v[202:205], v[192:195], v[68:71]
	v_mfma_f32_16x16x32_bf16 v[64:67], v[210:213], v[192:195], v[64:67]
	v_mfma_f32_16x16x32_bf16 v[116:119], v[206:209], v[172:175], v[116:119]
	v_mfma_f32_16x16x32_bf16 v[112:115], v[214:217], v[172:175], v[112:115]
	v_mfma_f32_16x16x32_bf16 v[100:103], v[206:209], v[180:183], v[100:103]
	v_mfma_f32_16x16x32_bf16 v[96:99], v[214:217], v[180:183], v[96:99]
	v_mfma_f32_16x16x32_bf16 v[84:87], v[206:209], v[188:191], v[84:87]
	v_mfma_f32_16x16x32_bf16 v[80:83], v[214:217], v[188:191], v[80:83]
	v_mfma_f32_16x16x32_bf16 v[68:71], v[206:209], v[196:199], v[68:71]
	v_mfma_f32_16x16x32_bf16 v[64:67], v[214:217], v[196:199], v[64:67]
	s_barrier
	s_setprio 0
	s_mov_b32 m0, s47
	ds_read_b128 v[168:171], v150 offset:49152
	ds_read_b128 v[172:175], v150 offset:50176
	ds_read_b128 v[176:179], v150 offset:51200
	ds_read_b128 v[180:183], v150 offset:52224
	ds_read_b128 v[184:187], v150 offset:53248
	ds_read_b128 v[188:191], v150 offset:54272
	ds_read_b128 v[192:195], v150 offset:55296
	ds_read_b128 v[196:199], v150 offset:56320
	global_load_lds_dwordx4 v128, s[100:101]
	s_mov_b32 m0, s48
	s_setprio 1
	global_load_lds_dwordx4 v132, s[100:101]
	s_barrier
; __device__ __forceinline__ unsigned cvt_pk_bf16(float lo, float hi) { const bf16x2_t r = __builtin_convertvector((f32x2){lo, hi}, bf16x2_t); return __builtin_bit_cast(unsigned, r); }
; #define PG8_STAGE(bufoff, gbase, voff) do { _Pragma("unroll") for (int _i = 0; _i < 2; ++_i) \
;         __builtin_amdgcn_global_load_lds((const unsigned*)((const char*)(gbase) + (voff)[_i]), (LAS unsigned*)(lds + (bufoff) + ldsw + _i * 8192), 16, 0, 0); } while (0)
; #define PG8_WAIT_V(n) asm volatile("s_waitcnt vmcnt(" #n ")" ::: "memory")
; #define PG8_WAIT_L(n) asm volatile("s_waitcnt lgkmcnt(" #n ")" ::: "memory")
; #define PG8_BAR __builtin_amdgcn_s_barrier()
; #define PG8_SCHED __builtin_amdgcn_sched_barrier(0)
; template <class Epi>
; __device__ __forceinline__ void gemm_phase(LAS unsigned char* lds, const bf16_t* A, int lda, const bf16_t* Bt, int ldb, int M, int N, int K, int asel, const Epi& E, const int fixed_round = -1) {
;     ...
;             PG8_BAR; PG8_WAIT_L(0); PG8_MMA(1, 0, At, B0); PG8_BAR; PG8_SCHED;
;             PG8_STAGE(PG8_SB(1, 1), b3 + hstepB, voffB);
;             PG8_WAIT_V(6); PG8_BAR; PG8_MMA(1, 1, At, B1); PG8_BAR;
;     __device__ __forceinline__ void operator()(const AccT& acc, const Unit& u, int wr, int wc, int fr, int fq) const {
;         const int row0 = u.pm * BM + wr * 64 + fr, col0 = u.pn * BM + wc * 32 + 8 * fq;
; #pragma unroll
;         for (int ai = 0; ai < 2; ++ai)
; #pragma unroll
;             for (int m = 0; m < 4; ++m) { bf16_t* rowp = O + (size_t)(row0 + ai * HALF + m * 16) * DFF + col0;
; #pragma unroll
;                 for (int bj = 0; bj < 2; ++bj) { f32x4 v0 = acc[ai][bj][m][0], v1 = acc[ai][bj][m][1];
; #pragma unroll
;                     for (int j = 0; j < 4; ++j) { float a = fmaxf(v0[j], 0.f), b = fmaxf(v1[j], 0.f); v0[j] = a * a; v1[j] = b * b; }
;                     u32x4 w; w.x = cvt_pk_bf16(v0[0], v0[1]); w.y = cvt_pk_bf16(v0[2], v0[3]); w.z = cvt_pk_bf16(v1[0], v1[1]); w.w = cvt_pk_bf16(v1[2], v1[3]);
;                     *(u32x4*)(rowp + bj * HALF) = w; } }
;     }
	s_waitcnt lgkmcnt(0)
	v_mfma_f32_16x16x32_bf16 v[60:63], v[152:155], v[168:171], v[60:63]
	v_mfma_f32_16x16x32_bf16 v[56:59], v[160:163], v[168:171], v[56:59]
	v_mfma_f32_16x16x32_bf16 v[44:47], v[152:155], v[176:179], v[44:47]
	v_mfma_f32_16x16x32_bf16 v[40:43], v[160:163], v[176:179], v[40:43]
	v_mfma_f32_16x16x32_bf16 v[28:31], v[152:155], v[184:187], v[28:31]
	v_mfma_f32_16x16x32_bf16 v[24:27], v[160:163], v[184:187], v[24:27]
	v_mfma_f32_16x16x32_bf16 v[12:15], v[152:155], v[192:195], v[12:15]
	v_mfma_f32_16x16x32_bf16 v[8:11], v[160:163], v[192:195], v[8:11]
	v_mfma_f32_16x16x32_bf16 v[60:63], v[156:159], v[172:175], v[60:63]
	v_mfma_f32_16x16x32_bf16 v[56:59], v[164:167], v[172:175], v[56:59]
	v_mfma_f32_16x16x32_bf16 v[44:47], v[156:159], v[180:183], v[44:47]
	v_mfma_f32_16x16x32_bf16 v[40:43], v[164:167], v[180:183], v[40:43]
	v_mfma_f32_16x16x32_bf16 v[28:31], v[156:159], v[188:191], v[28:31]
	v_mfma_f32_16x16x32_bf16 v[24:27], v[164:167], v[188:191], v[24:27]
	v_mfma_f32_16x16x32_bf16 v[12:15], v[156:159], v[196:199], v[12:15]
	v_mfma_f32_16x16x32_bf16 v[8:11], v[164:167], v[196:199], v[8:11]
	s_barrier
	s_setprio 0
	s_add_u32 s28, s34, 0x80080
	s_addc_u32 s29, s35, 0
	s_add_i32 s34, s84, s42
	s_mov_b32 m0, s34
	s_nop 0
	global_load_lds_dwordx4 v130, s[28:29]
	s_add_i32 m0, s34, 0x2000
	s_setprio 1
	global_load_lds_dwordx4 v134, s[28:29]
	s_waitcnt vmcnt(6)
	s_barrier
	v_mfma_f32_16x16x32_bf16 v[52:55], v[202:205], v[168:171], v[52:55]
	v_mfma_f32_16x16x32_bf16 v[48:51], v[210:213], v[168:171], v[48:51]
	v_mfma_f32_16x16x32_bf16 v[36:39], v[202:205], v[176:179], v[36:39]
	v_mfma_f32_16x16x32_bf16 v[32:35], v[210:213], v[176:179], v[32:35]
	v_mfma_f32_16x16x32_bf16 v[20:23], v[202:205], v[184:187], v[20:23]
	v_mfma_f32_16x16x32_bf16 v[16:19], v[210:213], v[184:187], v[16:19]
	v_mfma_f32_16x16x32_bf16 v[4:7], v[202:205], v[192:195], v[4:7]
	v_mfma_f32_16x16x32_bf16 v[0:3], v[210:213], v[192:195], v[0:3]
	v_mfma_f32_16x16x32_bf16 v[52:55], v[206:209], v[172:175], v[52:55]
	v_mfma_f32_16x16x32_bf16 v[48:51], v[214:217], v[172:175], v[48:51]
	v_mfma_f32_16x16x32_bf16 v[36:39], v[206:209], v[180:183], v[36:39]
	v_mfma_f32_16x16x32_bf16 v[32:35], v[214:217], v[180:183], v[32:35]
	v_mfma_f32_16x16x32_bf16 v[20:23], v[206:209], v[188:191], v[20:23]
	v_mfma_f32_16x16x32_bf16 v[16:19], v[214:217], v[188:191], v[16:19]
	v_mfma_f32_16x16x32_bf16 v[4:7], v[206:209], v[196:199], v[4:7]
	v_mfma_f32_16x16x32_bf16 v[0:3], v[214:217], v[196:199], v[0:3]
	s_setprio 0
	s_add_i32 s56, s56, 2
	s_add_u32 s30, s30, 0x100
	s_addc_u32 s31, s31, 0
	s_add_u32 s54, s54, 0x100
	s_addc_u32 s55, s55, 0
	s_cmp_gt_u32 s56, 29
	s_cbranch_scc0 .Lrot_4
	s_barrier
	v_lshl_add_u32 v152, s26, 8, v146
	v_lshl_or_b32 v144, s51, 8, v148
	v_ashrrev_i32_e32 v153, 31, v152
	v_ashrrev_i32_e32 v145, 31, v144
	v_lshlrev_b64 v[154:155], 14, v[152:153]
	v_lshl_add_u64 v[154:155], s[88:89], 0, v[154:155]
	v_lshlrev_b64 v[156:157], 1, v[144:145]
	v_max_f32_e32 v120, 0, v120
	v_max_f32_e32 v121, 0, v121
	v_lshl_add_u64 v[144:145], v[154:155], 0, v[156:157]
	v_pk_mul_f32 v[154:155], v[120:121], v[120:121]
	v_max_f32_e32 v121, v122, v122
	v_max_f32_e32 v120, v126, v126
	v_max_f32_e32 v122, 0, v121
	v_max_f32_e32 v121, v127, v127
	v_max_f32_e32 v124, 0, v124
	v_max_f32_e32 v125, 0, v125
	v_max_f32_e32 v120, 0, v120
	v_max_f32_e32 v121, 0, v121
	v_max_f32_e32 v123, 0, v123
	v_pk_mul_f32 v[124:125], v[124:125], v[124:125]
	v_pk_mul_f32 v[126:127], v[120:121], v[120:121]
	v_pk_mul_f32 v[158:159], v[122:123], v[122:123]
	v_cvt_pk_bf16_f32 v120, v124, v125
	v_cvt_pk_bf16_f32 v121, v126, v127
	v_cvt_pk_bf16_f32 v122, v154, v155
	v_cvt_pk_bf16_f32 v123, v158, v159
	v_max_f32_e32 v112, 0, v112
	v_max_f32_e32 v113, 0, v113
	global_store_dwordx4 v[144:145], v[120:123], off
	s_nop 1
	v_pk_mul_f32 v[120:121], v[112:113], v[112:113]
	v_max_f32_e32 v113, v114, v114
	v_max_f32_e32 v112, v118, v118
	v_max_f32_e32 v114, 0, v113
	v_max_f32_e32 v113, v119, v119
	v_max_f32_e32 v116, 0, v116
	v_max_f32_e32 v117, 0, v117
	v_max_f32_e32 v112, 0, v112
	v_max_f32_e32 v113, 0, v113
	v_max_f32_e32 v115, 0, v115
	v_pk_mul_f32 v[116:117], v[116:117], v[116:117]
	v_pk_mul_f32 v[118:119], v[112:113], v[112:113]
	v_pk_mul_f32 v[122:123], v[114:115], v[114:115]
	v_cvt_pk_bf16_f32 v112, v116, v117
	v_cvt_pk_bf16_f32 v113, v118, v119
	v_cvt_pk_bf16_f32 v114, v120, v121
	v_cvt_pk_bf16_f32 v115, v122, v123
	v_max_f32_e32 v104, 0, v104
	v_max_f32_e32 v105, 0, v105
	global_store_dwordx4 v[144:145], v[112:115], off offset:256
	s_nop 1
	v_or_b32_e32 v112, 16, v152
	v_pk_mul_f32 v[114:115], v[104:105], v[104:105]
	v_max_f32_e32 v105, v106, v106
	v_ashrrev_i32_e32 v113, 31, v112
	v_max_f32_e32 v104, v110, v110
	v_max_f32_e32 v106, 0, v105
	v_max_f32_e32 v105, v111, v111
	v_lshlrev_b64 v[112:113], 14, v[112:113]
	v_max_f32_e32 v108, 0, v108
	v_max_f32_e32 v109, 0, v109
	v_max_f32_e32 v104, 0, v104
	v_max_f32_e32 v105, 0, v105
	v_max_f32_e32 v107, 0, v107
	v_lshl_add_u64 v[112:113], s[88:89], 0, v[112:113]
	v_pk_mul_f32 v[108:109], v[108:109], v[108:109]
	v_pk_mul_f32 v[110:111], v[104:105], v[104:105]
	v_pk_mul_f32 v[116:117], v[106:107], v[106:107]
	v_lshl_add_u64 v[112:113], v[112:113], 0, v[156:157]
	v_cvt_pk_bf16_f32 v104, v108, v109
	v_cvt_pk_bf16_f32 v105, v110, v111
	v_cvt_pk_bf16_f32 v106, v114, v115
	v_cvt_pk_bf16_f32 v107, v116, v117
	v_max_f32_e32 v96, 0, v96
	v_max_f32_e32 v97, 0, v97
	global_store_dwordx4 v[112:113], v[104:107], off
	s_nop 1
	v_pk_mul_f32 v[104:105], v[96:97], v[96:97]
	v_max_f32_e32 v97, v98, v98
	v_max_f32_e32 v96, v102, v102
	v_max_f32_e32 v98, 0, v97
	v_max_f32_e32 v97, v103, v103
; __device__ __forceinline__ unsigned cvt_pk_bf16(float lo, float hi) { const bf16x2_t r = __builtin_convertvector((f32x2){lo, hi}, bf16x2_t); return __builtin_bit_cast(unsigned, r); }
;     __device__ __forceinline__ void operator()(const AccT& acc, const Unit& u, int wr, int wc, int fr, int fq) const {
;         const int row0 = u.pm * BM + wr * 64 + fr, col0 = u.pn * BM + wc * 32 + 8 * fq;
; #pragma unroll
;         for (int ai = 0; ai < 2; ++ai)
; #pragma unroll
;             for (int m = 0; m < 4; ++m) { bf16_t* rowp = O + (size_t)(row0 + ai * HALF + m * 16) * DFF + col0;
; #pragma unroll
;                 for (int bj = 0; bj < 2; ++bj) { f32x4 v0 = acc[ai][bj][m][0], v1 = acc[ai][bj][m][1];
; #pragma unroll
;                     for (int j = 0; j < 4; ++j) { float a = fmaxf(v0[j], 0.f), b = fmaxf(v1[j], 0.f); v0[j] = a * a; v1[j] = b * b; }
;                     u32x4 w; w.x = cvt_pk_bf16(v0[0], v0[1]); w.y = cvt_pk_bf16(v0[2], v0[3]); w.z = cvt_pk_bf16(v1[0], v1[1]); w.w = cvt_pk_bf16(v1[2], v1[3]);
;                     *(u32x4*)(rowp + bj * HALF) = w; } }
;     }
	v_max_f32_e32 v100, 0, v100
	v_max_f32_e32 v101, 0, v101
	v_max_f32_e32 v96, 0, v96
	v_max_f32_e32 v97, 0, v97
	v_max_f32_e32 v99, 0, v99
	v_pk_mul_f32 v[100:101], v[100:101], v[100:101]
	v_pk_mul_f32 v[102:103], v[96:97], v[96:97]
	v_pk_mul_f32 v[106:107], v[98:99], v[98:99]
	v_cvt_pk_bf16_f32 v96, v100, v101
	v_cvt_pk_bf16_f32 v97, v102, v103
	v_cvt_pk_bf16_f32 v98, v104, v105
	v_cvt_pk_bf16_f32 v99, v106, v107
	v_max_f32_e32 v88, 0, v88
	v_max_f32_e32 v89, 0, v89
	global_store_dwordx4 v[112:113], v[96:99], off offset:256
	s_nop 1
	v_or_b32_e32 v96, 32, v152
	v_pk_mul_f32 v[98:99], v[88:89], v[88:89]
	v_max_f32_e32 v89, v90, v90
	v_ashrrev_i32_e32 v97, 31, v96
	v_max_f32_e32 v88, v94, v94
	v_max_f32_e32 v90, 0, v89
	v_max_f32_e32 v89, v95, v95
	v_lshlrev_b64 v[96:97], 14, v[96:97]
	v_max_f32_e32 v92, 0, v92
	v_max_f32_e32 v93, 0, v93
	v_max_f32_e32 v88, 0, v88
	v_max_f32_e32 v89, 0, v89
	v_max_f32_e32 v91, 0, v91
	v_lshl_add_u64 v[96:97], s[88:89], 0, v[96:97]
	v_pk_mul_f32 v[92:93], v[92:93], v[92:93]
	v_pk_mul_f32 v[94:95], v[88:89], v[88:89]
	v_pk_mul_f32 v[100:101], v[90:91], v[90:91]
	v_lshl_add_u64 v[96:97], v[96:97], 0, v[156:157]
	v_cvt_pk_bf16_f32 v88, v92, v93
	v_cvt_pk_bf16_f32 v89, v94, v95
	v_cvt_pk_bf16_f32 v90, v98, v99
	v_cvt_pk_bf16_f32 v91, v100, v101
	v_max_f32_e32 v80, 0, v80
	v_max_f32_e32 v81, 0, v81
	global_store_dwordx4 v[96:97], v[88:91], off
	s_nop 1
	v_pk_mul_f32 v[88:89], v[80:81], v[80:81]
	v_max_f32_e32 v81, v82, v82
	v_max_f32_e32 v80, v86, v86
	v_max_f32_e32 v82, 0, v81
	v_max_f32_e32 v81, v87, v87
	v_max_f32_e32 v84, 0, v84
	v_max_f32_e32 v85, 0, v85
	v_max_f32_e32 v80, 0, v80
	v_max_f32_e32 v81, 0, v81
	v_max_f32_e32 v83, 0, v83
	v_pk_mul_f32 v[84:85], v[84:85], v[84:85]
	v_pk_mul_f32 v[86:87], v[80:81], v[80:81]
	v_pk_mul_f32 v[90:91], v[82:83], v[82:83]
	v_cvt_pk_bf16_f32 v80, v84, v85
	v_cvt_pk_bf16_f32 v81, v86, v87
	v_cvt_pk_bf16_f32 v82, v88, v89
	v_cvt_pk_bf16_f32 v83, v90, v91
	v_max_f32_e32 v72, 0, v72
	v_max_f32_e32 v73, 0, v73
	global_store_dwordx4 v[96:97], v[80:83], off offset:256
	s_nop 1
	v_or_b32_e32 v80, 48, v152
	v_pk_mul_f32 v[82:83], v[72:73], v[72:73]
	v_max_f32_e32 v73, v74, v74
	v_ashrrev_i32_e32 v81, 31, v80
	v_max_f32_e32 v72, v78, v78
	v_max_f32_e32 v74, 0, v73
	v_max_f32_e32 v73, v79, v79
	v_lshlrev_b64 v[80:81], 14, v[80:81]
	v_max_f32_e32 v76, 0, v76
	v_max_f32_e32 v77, 0, v77
	v_max_f32_e32 v72, 0, v72
	v_max_f32_e32 v73, 0, v73
	v_max_f32_e32 v75, 0, v75
	v_lshl_add_u64 v[80:81], s[88:89], 0, v[80:81]
	v_pk_mul_f32 v[76:77], v[76:77], v[76:77]
	v_pk_mul_f32 v[78:79], v[72:73], v[72:73]
	v_pk_mul_f32 v[84:85], v[74:75], v[74:75]
	v_lshl_add_u64 v[80:81], v[80:81], 0, v[156:157]
	v_cvt_pk_bf16_f32 v72, v76, v77
	v_cvt_pk_bf16_f32 v73, v78, v79
	v_cvt_pk_bf16_f32 v74, v82, v83
	v_cvt_pk_bf16_f32 v75, v84, v85
	v_max_f32_e32 v64, 0, v64
	v_max_f32_e32 v65, 0, v65
	global_store_dwordx4 v[80:81], v[72:75], off
	s_nop 1
	v_pk_mul_f32 v[72:73], v[64:65], v[64:65]
	v_max_f32_e32 v65, v66, v66
	v_max_f32_e32 v64, v70, v70
	v_max_f32_e32 v66, 0, v65
	v_max_f32_e32 v65, v71, v71
	v_max_f32_e32 v68, 0, v68
	v_max_f32_e32 v69, 0, v69
	v_max_f32_e32 v64, 0, v64
	v_max_f32_e32 v65, 0, v65
	v_max_f32_e32 v67, 0, v67
	v_pk_mul_f32 v[68:69], v[68:69], v[68:69]
	v_pk_mul_f32 v[70:71], v[64:65], v[64:65]
	v_pk_mul_f32 v[74:75], v[66:67], v[66:67]
	v_cvt_pk_bf16_f32 v64, v68, v69
	v_cvt_pk_bf16_f32 v65, v70, v71
	v_cvt_pk_bf16_f32 v66, v72, v73
	v_cvt_pk_bf16_f32 v67, v74, v75
	v_max_f32_e32 v56, 0, v56
	v_max_f32_e32 v57, 0, v57
	global_store_dwordx4 v[80:81], v[64:67], off offset:256
	s_nop 1
	v_pk_mul_f32 v[66:67], v[56:57], v[56:57]
	v_max_f32_e32 v57, v58, v58
	v_max_f32_e32 v60, 0, v60
	v_max_f32_e32 v61, 0, v61
	v_max_f32_e32 v56, v62, v62
	v_max_f32_e32 v58, 0, v57
	v_max_f32_e32 v57, v63, v63
	v_pk_mul_f32 v[60:61], v[60:61], v[60:61]
	v_max_f32_e32 v56, 0, v56
	v_max_f32_e32 v57, 0, v57
	v_max_f32_e32 v59, 0, v59
	s_mov_b32 s5, 0x200000
	v_pk_mul_f32 v[62:63], v[56:57], v[56:57]
	v_pk_mul_f32 v[68:69], v[58:59], v[58:59]
	v_cvt_pk_bf16_f32 v56, v60, v61
	v_add_co_u32_e32 v60, vcc, s5, v144
	v_cvt_pk_bf16_f32 v57, v62, v63
	v_cvt_pk_bf16_f32 v58, v66, v67
	v_cvt_pk_bf16_f32 v59, v68, v69
	v_addc_co_u32_e32 v61, vcc, 0, v145, vcc
	v_max_f32_e32 v48, 0, v48
	v_max_f32_e32 v49, 0, v49
	global_store_dwordx4 v[60:61], v[56:59], off
	s_nop 1
	v_pk_mul_f32 v[56:57], v[48:49], v[48:49]
	v_max_f32_e32 v49, v50, v50
	v_max_f32_e32 v48, v54, v54
	v_max_f32_e32 v50, 0, v49
	v_max_f32_e32 v49, v55, v55
	v_max_f32_e32 v52, 0, v52
	v_max_f32_e32 v53, 0, v53
	v_max_f32_e32 v48, 0, v48
	v_max_f32_e32 v49, 0, v49
	v_max_f32_e32 v51, 0, v51
	s_mov_b64 s[28:29], 0x200000
	v_pk_mul_f32 v[52:53], v[52:53], v[52:53]
	v_pk_mul_f32 v[54:55], v[48:49], v[48:49]
	v_pk_mul_f32 v[58:59], v[50:51], v[50:51]
	v_lshl_add_u64 v[64:65], v[144:145], 0, s[28:29]
; __device__ __forceinline__ unsigned cvt_pk_bf16(float lo, float hi) { const bf16x2_t r = __builtin_convertvector((f32x2){lo, hi}, bf16x2_t); return __builtin_bit_cast(unsigned, r); }
; #define PG8_WAIT_V(n) asm volatile("s_waitcnt vmcnt(" #n ")" ::: "memory")
; #define PG8_BAR __builtin_amdgcn_s_barrier()
; template <class Epi>
; __device__ __forceinline__ void gemm_phase(LAS unsigned char* lds, const bf16_t* A, int lda, const bf16_t* Bt, int ldb, int M, int N, int K, int asel, const Epi& E, const int fixed_round = -1) {
;     ...
;         if (!has_next) break;
; #pragma unroll
;         for (int a = 0; a < 2; ++a)
; #pragma unroll
;             for (int b = 0; b < 2; ++b)
; #pragma unroll
;                 for (int m = 0; m < 4; ++m)
; #pragma unroll
;                     for (int n = 0; n < 2; ++n) acc[a][b][m][n] = (f32x4){0.f, 0.f, 0.f, 0.f};
;         cur = nxt; cA = nA; cB = nB; ++ui;
;     }
;     PG8_WAIT_V(0);
;     if (wr == 0) PG8_BAR;
;     PG8_BAR;
;     __device__ __forceinline__ void operator()(const AccT& acc, const Unit& u, int wr, int wc, int fr, int fq) const {
;         const int row0 = u.pm * BM + wr * 64 + fr, col0 = u.pn * BM + wc * 32 + 8 * fq;
; #pragma unroll
;         for (int ai = 0; ai < 2; ++ai)
; #pragma unroll
;             for (int m = 0; m < 4; ++m) { bf16_t* rowp = O + (size_t)(row0 + ai * HALF + m * 16) * DFF + col0;
; #pragma unroll
;                 for (int bj = 0; bj < 2; ++bj) { f32x4 v0 = acc[ai][bj][m][0], v1 = acc[ai][bj][m][1];
; #pragma unroll
;                     for (int j = 0; j < 4; ++j) { float a = fmaxf(v0[j], 0.f), b = fmaxf(v1[j], 0.f); v0[j] = a * a; v1[j] = b * b; }
;                     u32x4 w; w.x = cvt_pk_bf16(v0[0], v0[1]); w.y = cvt_pk_bf16(v0[2], v0[3]); w.z = cvt_pk_bf16(v1[0], v1[1]); w.w = cvt_pk_bf16(v1[2], v1[3]);
;                     *(u32x4*)(rowp + bj * HALF) = w; } }
;     }
	v_cvt_pk_bf16_f32 v48, v52, v53
	v_cvt_pk_bf16_f32 v49, v54, v55
	v_cvt_pk_bf16_f32 v50, v56, v57
	v_cvt_pk_bf16_f32 v51, v58, v59
	v_max_f32_e32 v40, 0, v40
	v_max_f32_e32 v41, 0, v41
	global_store_dwordx4 v[64:65], v[48:51], off offset:256
	s_nop 1
	v_pk_mul_f32 v[50:51], v[40:41], v[40:41]
	v_max_f32_e32 v41, v42, v42
	v_max_f32_e32 v44, 0, v44
	v_max_f32_e32 v45, 0, v45
	v_max_f32_e32 v40, v46, v46
	v_max_f32_e32 v42, 0, v41
	v_max_f32_e32 v41, v47, v47
	v_pk_mul_f32 v[44:45], v[44:45], v[44:45]
	v_max_f32_e32 v40, 0, v40
	v_max_f32_e32 v41, 0, v41
	v_max_f32_e32 v43, 0, v43
	s_mov_b32 s5, 0x240000
	v_pk_mul_f32 v[46:47], v[40:41], v[40:41]
	v_pk_mul_f32 v[52:53], v[42:43], v[42:43]
	v_cvt_pk_bf16_f32 v40, v44, v45
	v_add_co_u32_e32 v44, vcc, s5, v144
	v_cvt_pk_bf16_f32 v41, v46, v47
	v_cvt_pk_bf16_f32 v42, v50, v51
	v_cvt_pk_bf16_f32 v43, v52, v53
	v_addc_co_u32_e32 v45, vcc, 0, v145, vcc
	v_max_f32_e32 v32, 0, v32
	v_max_f32_e32 v33, 0, v33
	global_store_dwordx4 v[44:45], v[40:43], off
	s_nop 1
	v_pk_mul_f32 v[40:41], v[32:33], v[32:33]
	v_max_f32_e32 v33, v34, v34
	v_max_f32_e32 v32, v38, v38
	v_max_f32_e32 v34, 0, v33
	v_max_f32_e32 v33, v39, v39
	v_max_f32_e32 v36, 0, v36
	v_max_f32_e32 v37, 0, v37
	v_max_f32_e32 v32, 0, v32
	v_max_f32_e32 v33, 0, v33
	v_max_f32_e32 v35, 0, v35
	s_mov_b64 s[28:29], 0x240000
	v_pk_mul_f32 v[36:37], v[36:37], v[36:37]
	v_pk_mul_f32 v[38:39], v[32:33], v[32:33]
	v_pk_mul_f32 v[42:43], v[34:35], v[34:35]
	v_lshl_add_u64 v[48:49], v[144:145], 0, s[28:29]
	v_cvt_pk_bf16_f32 v32, v36, v37
	v_cvt_pk_bf16_f32 v33, v38, v39
	v_cvt_pk_bf16_f32 v34, v40, v41
	v_cvt_pk_bf16_f32 v35, v42, v43
	v_max_f32_e32 v24, 0, v24
	v_max_f32_e32 v25, 0, v25
	global_store_dwordx4 v[48:49], v[32:35], off offset:256
	s_nop 1
	v_pk_mul_f32 v[34:35], v[24:25], v[24:25]
	v_max_f32_e32 v25, v26, v26
	v_max_f32_e32 v28, 0, v28
	v_max_f32_e32 v29, 0, v29
	v_max_f32_e32 v24, v30, v30
	v_max_f32_e32 v26, 0, v25
	v_max_f32_e32 v25, v31, v31
	v_pk_mul_f32 v[28:29], v[28:29], v[28:29]
	v_max_f32_e32 v24, 0, v24
	v_max_f32_e32 v25, 0, v25
	v_max_f32_e32 v27, 0, v27
	s_mov_b32 s5, 0x280000
	v_pk_mul_f32 v[30:31], v[24:25], v[24:25]
	v_pk_mul_f32 v[36:37], v[26:27], v[26:27]
	v_cvt_pk_bf16_f32 v24, v28, v29
	v_add_co_u32_e32 v28, vcc, s5, v144
	v_cvt_pk_bf16_f32 v25, v30, v31
	v_cvt_pk_bf16_f32 v26, v34, v35
	v_cvt_pk_bf16_f32 v27, v36, v37
	v_addc_co_u32_e32 v29, vcc, 0, v145, vcc
	v_max_f32_e32 v16, 0, v16
	v_max_f32_e32 v17, 0, v17
	global_store_dwordx4 v[28:29], v[24:27], off
	s_nop 1
	v_pk_mul_f32 v[24:25], v[16:17], v[16:17]
	v_max_f32_e32 v17, v18, v18
	v_max_f32_e32 v16, v22, v22
	v_max_f32_e32 v18, 0, v17
	v_max_f32_e32 v17, v23, v23
	v_max_f32_e32 v20, 0, v20
	v_max_f32_e32 v21, 0, v21
	v_max_f32_e32 v16, 0, v16
	v_max_f32_e32 v17, 0, v17
	v_max_f32_e32 v19, 0, v19
	s_mov_b64 s[28:29], 0x280000
	v_pk_mul_f32 v[20:21], v[20:21], v[20:21]
	v_pk_mul_f32 v[22:23], v[16:17], v[16:17]
	v_pk_mul_f32 v[26:27], v[18:19], v[18:19]
	v_lshl_add_u64 v[32:33], v[144:145], 0, s[28:29]
	v_cvt_pk_bf16_f32 v16, v20, v21
	v_cvt_pk_bf16_f32 v17, v22, v23
	v_cvt_pk_bf16_f32 v18, v24, v25
	v_cvt_pk_bf16_f32 v19, v26, v27
	v_max_f32_e32 v8, 0, v8
	v_max_f32_e32 v9, 0, v9
	global_store_dwordx4 v[32:33], v[16:19], off offset:256
	s_nop 1
	v_pk_mul_f32 v[18:19], v[8:9], v[8:9]
	v_max_f32_e32 v9, v10, v10
	v_max_f32_e32 v12, 0, v12
	v_max_f32_e32 v13, 0, v13
	v_max_f32_e32 v8, v14, v14
	v_max_f32_e32 v10, 0, v9
	v_max_f32_e32 v9, v15, v15
	v_pk_mul_f32 v[12:13], v[12:13], v[12:13]
	v_max_f32_e32 v8, 0, v8
	v_max_f32_e32 v9, 0, v9
	v_max_f32_e32 v11, 0, v11
	v_pk_mul_f32 v[14:15], v[8:9], v[8:9]
	v_pk_mul_f32 v[20:21], v[10:11], v[10:11]
	v_cvt_pk_bf16_f32 v8, v12, v13
	v_add_co_u32_e32 v12, vcc, s50, v144
	v_cvt_pk_bf16_f32 v9, v14, v15
	v_cvt_pk_bf16_f32 v10, v18, v19
	v_cvt_pk_bf16_f32 v11, v20, v21
	v_addc_co_u32_e32 v13, vcc, 0, v145, vcc
	v_max_f32_e32 v0, 0, v0
	v_max_f32_e32 v1, 0, v1
	global_store_dwordx4 v[12:13], v[8:11], off
	s_nop 1
	v_pk_mul_f32 v[8:9], v[0:1], v[0:1]
	v_max_f32_e32 v1, v2, v2
	v_max_f32_e32 v0, v6, v6
	v_max_f32_e32 v2, 0, v1
	v_max_f32_e32 v1, v7, v7
	v_max_f32_e32 v4, 0, v4
	v_max_f32_e32 v5, 0, v5
	v_max_f32_e32 v0, 0, v0
	v_max_f32_e32 v1, 0, v1
	v_max_f32_e32 v3, 0, v3
	s_mov_b64 s[28:29], 0x2c0000
	v_pk_mul_f32 v[4:5], v[4:5], v[4:5]
	v_pk_mul_f32 v[6:7], v[0:1], v[0:1]
	v_pk_mul_f32 v[10:11], v[2:3], v[2:3]
	v_lshl_add_u64 v[16:17], v[144:145], 0, s[28:29]
	v_cvt_pk_bf16_f32 v0, v4, v5
	v_cvt_pk_bf16_f32 v1, v6, v7
	v_cvt_pk_bf16_f32 v2, v8, v9
	v_cvt_pk_bf16_f32 v3, v10, v11
	s_and_b64 vcc, exec, s[0:1]
	s_mov_b32 s51, s4
	s_mov_b32 s26, s6
	s_mov_b64 s[34:35], s[20:21]
	s_mov_b64 s[30:31], s[18:19]
	global_store_dwordx4 v[16:17], v[0:3], off offset:256
	s_cbranch_vccz .LBB0_584
	s_waitcnt vmcnt(0)
	s_cmpk_gt_u32 s33, 0xff
	s_cbranch_scc1 .LBB0_595
	s_barrier

; #define PG8_STAGE(bufoff, gbase, voff) do { _Pragma("unroll") for (int _i = 0; _i < 2; ++_i) \
;         __builtin_amdgcn_global_load_lds((const unsigned*)((const char*)(gbase) + (voff)[_i]), (LAS unsigned*)(lds + (bufoff) + ldsw + _i * 8192), 16, 0, 0); } while (0)
; #define PG8_LDA(dst, b, h) do { _Pragma("unroll") for (int m = 0; m < 4; ++m) _Pragma("unroll") for (int k = 0; k < 2; ++k) dst[m][k] = *(const LAS bf16x8*)(lds + PG8_SA(b, h) + aoff + m * 2048 + k * 1024); } while (0)
; #define PG8_LDB(dst, b, h) do { _Pragma("unroll") for (int n = 0; n < 2; ++n) _Pragma("unroll") for (int k = 0; k < 2; ++k) dst[n][k] = *(const LAS bf16x8*)(lds + PG8_SB(b, h) + boff + n * 2048 + k * 1024); } while (0)
; #define PG8_WAIT_V(n) asm volatile("s_waitcnt vmcnt(" #n ")" ::: "memory")
; #define PG8_WAIT_L(n) asm volatile("s_waitcnt lgkmcnt(" #n ")" ::: "memory")
; #define PG8_BAR __builtin_amdgcn_s_barrier()
; #define PG8_SCHED __builtin_amdgcn_sched_barrier(0)
; template <class Epi>
; __device__ __forceinline__ void gemm_phase(LAS unsigned char* lds, const bf16_t* A, int lda, const bf16_t* Bt, int ldb, int M, int N, int K, int asel, const Epi& E, const int fixed_round = -1) {
;     ...
;         for (int t = 0; t < nt; t += 2) {
;             const bool last = (t == nt - 2);
;             const char* a1 = cA + (size_t)(t + 1) * kstep;
;             const char* a2 = last ? nA : cA + (size_t)(t + 2) * kstep; const char* b2 = last ? nB : cB + (size_t)(t + 2) * kstep;
;             const char* a3 = a2 + kstep; const char* b3 = b2 + kstep;
;             PG8_LDB(B0, 0, 0); PG8_SCHED; PG8_LDA(At, 0, 0); PG8_STAGE(PG8_SA(1, 1), a1 + hstepA, voffA);
;             PG8_WAIT_L(8); PG8_BAR; PG8_WAIT_L(0); PG8_MMA(0, 0, At, B0); PG8_BAR; PG8_SCHED;
;             PG8_LDB(B1, 0, 1); PG8_STAGE(PG8_SB(0, 0), b2, voffB);
;             PG8_BAR; PG8_WAIT_L(0); PG8_MMA(0, 1, At, B1); PG8_BAR;
;             PG8_LDA(At, 0, 1); PG8_STAGE(PG8_SA(0, 0), a2, voffA);
;             PG8_BAR; PG8_WAIT_L(0); PG8_MMA(1, 0, At, B0); PG8_BAR; PG8_SCHED;
;             PG8_STAGE(PG8_SB(0, 1), b2 + hstepB, voffB);
;             PG8_WAIT_V(6); PG8_BAR; PG8_MMA(1, 1, At, B1); PG8_BAR;
.LBB0_651:
	ds_read_b128 v[146:149], v140
	ds_read_b128 v[150:153], v140 offset:1024
	ds_read_b128 v[160:163], v140 offset:2048
	ds_read_b128 v[166:169], v140 offset:3072
	s_mov_b32 m0, s49
	v_lshl_add_u64 v[156:157], v[136:137], 0, s[20:21]
	ds_read_b128 v[170:173], v141
	ds_read_b128 v[174:177], v141 offset:1024
	ds_read_b128 v[178:181], v141 offset:2048
	ds_read_b128 v[182:185], v141 offset:3072
	ds_read_b128 v[186:189], v141 offset:4096
	ds_read_b128 v[190:193], v141 offset:5120
	ds_read_b128 v[194:197], v141 offset:6144
	ds_read_b128 v[202:205], v141 offset:7168
	global_load_lds_dwordx4 v[156:157], off
	v_lshl_add_u64 v[156:157], v[138:139], 0, s[20:21]
	s_mov_b32 m0, s50
	s_setprio 1
	global_load_lds_dwordx4 v[156:157], off
	s_waitcnt lgkmcnt(8)
	s_barrier
	s_waitcnt lgkmcnt(0)
	v_mfma_f32_16x16x32_bf16 v[124:127], v[146:149], v[170:173], v[124:127]
	v_mfma_f32_16x16x32_bf16 v[120:123], v[160:163], v[170:173], v[120:123]
	v_mfma_f32_16x16x32_bf16 v[112:115], v[146:149], v[178:181], v[112:115]
	v_mfma_f32_16x16x32_bf16 v[104:107], v[160:163], v[178:181], v[104:107]
	v_mfma_f32_16x16x32_bf16 v[96:99], v[146:149], v[186:189], v[96:99]
	v_mfma_f32_16x16x32_bf16 v[88:91], v[160:163], v[186:189], v[88:91]
	v_mfma_f32_16x16x32_bf16 v[80:83], v[146:149], v[194:197], v[80:83]
	v_mfma_f32_16x16x32_bf16 v[72:75], v[160:163], v[194:197], v[72:75]
	v_mfma_f32_16x16x32_bf16 v[124:127], v[150:153], v[174:177], v[124:127]
	v_mfma_f32_16x16x32_bf16 v[120:123], v[166:169], v[174:177], v[120:123]
	v_mfma_f32_16x16x32_bf16 v[112:115], v[150:153], v[182:185], v[112:115]
	v_mfma_f32_16x16x32_bf16 v[104:107], v[166:169], v[182:185], v[104:107]
	v_mfma_f32_16x16x32_bf16 v[96:99], v[150:153], v[190:193], v[96:99]
	v_mfma_f32_16x16x32_bf16 v[88:91], v[166:169], v[190:193], v[88:91]
	v_mfma_f32_16x16x32_bf16 v[80:83], v[150:153], v[202:205], v[80:83]
	v_mfma_f32_16x16x32_bf16 v[72:75], v[166:169], v[202:205], v[72:75]
	s_barrier
	s_setprio 0
	s_add_u32 s28, s20, 0xe7900080
	s_addc_u32 s29, s21, -1
	s_cmpk_lg_i32 s48, 0x7c
	s_cselect_b32 s28, s28, 0
	s_cselect_b32 s29, s29, 0
	s_add_u32 s36, s86, s28
	s_addc_u32 s37, s87, s29
	s_add_u32 s34, s2, s28
	s_addc_u32 s35, s3, s29
	s_mov_b32 m0, s51
	s_add_u32 s98, s34, s0
	s_addc_u32 s99, s35, s1
	ds_read_b128 v[206:209], v142
	ds_read_b128 v[210:213], v142 offset:1024
	ds_read_b128 v[214:217], v142 offset:2048
	ds_read_b128 v[218:221], v142 offset:3072
	global_load_lds_dwordx4 v130, s[34:35]
	s_mov_b32 m0, s52
	s_setprio 1
	global_load_lds_dwordx4 v134, s[34:35]
	s_barrier
	s_waitcnt lgkmcnt(0)
	v_mfma_f32_16x16x32_bf16 v[116:119], v[206:209], v[170:173], v[116:119]
	v_mfma_f32_16x16x32_bf16 v[108:111], v[214:217], v[170:173], v[108:111]
	v_mfma_f32_16x16x32_bf16 v[100:103], v[206:209], v[178:181], v[100:103]
	v_mfma_f32_16x16x32_bf16 v[92:95], v[214:217], v[178:181], v[92:95]
	v_mfma_f32_16x16x32_bf16 v[84:87], v[206:209], v[186:189], v[84:87]
	v_mfma_f32_16x16x32_bf16 v[76:79], v[214:217], v[186:189], v[76:79]
	v_mfma_f32_16x16x32_bf16 v[68:71], v[206:209], v[194:197], v[68:71]
	v_mfma_f32_16x16x32_bf16 v[64:67], v[214:217], v[194:197], v[64:67]
	v_mfma_f32_16x16x32_bf16 v[116:119], v[210:213], v[174:177], v[116:119]
	v_mfma_f32_16x16x32_bf16 v[108:111], v[218:221], v[174:177], v[108:111]
	v_mfma_f32_16x16x32_bf16 v[100:103], v[210:213], v[182:185], v[100:103]
	v_mfma_f32_16x16x32_bf16 v[92:95], v[218:221], v[182:185], v[92:95]
	v_mfma_f32_16x16x32_bf16 v[84:87], v[210:213], v[190:193], v[84:87]
	v_mfma_f32_16x16x32_bf16 v[76:79], v[218:221], v[190:193], v[76:79]
	v_mfma_f32_16x16x32_bf16 v[68:71], v[210:213], v[202:205], v[68:71]
	v_mfma_f32_16x16x32_bf16 v[64:67], v[218:221], v[202:205], v[64:67]
	s_barrier
	s_setprio 0
	s_mov_b32 m0, s42
	s_add_u32 s100, s36, s0
	s_addc_u32 s101, s37, s1
	ds_read_b128 v[170:173], v141 offset:16384
	ds_read_b128 v[174:177], v141 offset:17408
	ds_read_b128 v[178:181], v141 offset:18432
	ds_read_b128 v[182:185], v141 offset:19456
	ds_read_b128 v[186:189], v141 offset:20480
	ds_read_b128 v[190:193], v141 offset:21504
	ds_read_b128 v[194:197], v141 offset:22528
	ds_read_b128 v[202:205], v141 offset:23552
	global_load_lds_dwordx4 v128, s[36:37]
	s_mov_b32 m0, s43
	s_setprio 1
	global_load_lds_dwordx4 v132, s[36:37]
	s_barrier
	s_waitcnt lgkmcnt(0)
	v_mfma_f32_16x16x32_bf16 v[60:63], v[146:149], v[170:173], v[60:63]
	v_mfma_f32_16x16x32_bf16 v[56:59], v[160:163], v[170:173], v[56:59]
	v_mfma_f32_16x16x32_bf16 v[48:51], v[146:149], v[178:181], v[48:51]
	v_mfma_f32_16x16x32_bf16 v[40:43], v[160:163], v[178:181], v[40:43]
	v_mfma_f32_16x16x32_bf16 v[32:35], v[146:149], v[186:189], v[32:35]
	v_mfma_f32_16x16x32_bf16 v[24:27], v[160:163], v[186:189], v[24:27]
	v_mfma_f32_16x16x32_bf16 v[16:19], v[146:149], v[194:197], v[16:19]
	v_mfma_f32_16x16x32_bf16 v[8:11], v[160:163], v[194:197], v[8:11]
	v_mfma_f32_16x16x32_bf16 v[60:63], v[150:153], v[174:177], v[60:63]
	v_mfma_f32_16x16x32_bf16 v[56:59], v[166:169], v[174:177], v[56:59]
	v_mfma_f32_16x16x32_bf16 v[48:51], v[150:153], v[182:185], v[48:51]
	v_mfma_f32_16x16x32_bf16 v[40:43], v[166:169], v[182:185], v[40:43]
	v_mfma_f32_16x16x32_bf16 v[32:35], v[150:153], v[190:193], v[32:35]
	v_mfma_f32_16x16x32_bf16 v[24:27], v[166:169], v[190:193], v[24:27]
	v_mfma_f32_16x16x32_bf16 v[16:19], v[150:153], v[202:205], v[16:19]
	v_mfma_f32_16x16x32_bf16 v[8:11], v[166:169], v[202:205], v[8:11]
	s_barrier
	s_setprio 0
	s_add_u32 s28, s34, 0x200000
	s_addc_u32 s29, s35, 0
	s_mov_b32 m0, s53
	s_nop 0
	global_load_lds_dwordx4 v130, s[28:29]
	s_mov_b32 m0, s54
	s_setprio 1
	global_load_lds_dwordx4 v134, s[28:29]
	s_waitcnt vmcnt(6)
	s_barrier
; #define PG8_STAGE(bufoff, gbase, voff) do { _Pragma("unroll") for (int _i = 0; _i < 2; ++_i) \
;         __builtin_amdgcn_global_load_lds((const unsigned*)((const char*)(gbase) + (voff)[_i]), (LAS unsigned*)(lds + (bufoff) + ldsw + _i * 8192), 16, 0, 0); } while (0)
; #define PG8_LDA(dst, b, h) do { _Pragma("unroll") for (int m = 0; m < 4; ++m) _Pragma("unroll") for (int k = 0; k < 2; ++k) dst[m][k] = *(const LAS bf16x8*)(lds + PG8_SA(b, h) + aoff + m * 2048 + k * 1024); } while (0)
; #define PG8_LDB(dst, b, h) do { _Pragma("unroll") for (int n = 0; n < 2; ++n) _Pragma("unroll") for (int k = 0; k < 2; ++k) dst[n][k] = *(const LAS bf16x8*)(lds + PG8_SB(b, h) + boff + n * 2048 + k * 1024); } while (0)
; #define PG8_WAIT_V(n) asm volatile("s_waitcnt vmcnt(" #n ")" ::: "memory")
; #define PG8_WAIT_L(n) asm volatile("s_waitcnt lgkmcnt(" #n ")" ::: "memory")
; #define PG8_BAR __builtin_amdgcn_s_barrier()
; #define PG8_SCHED __builtin_amdgcn_sched_barrier(0)
; template <class Epi>
; __device__ __forceinline__ void gemm_phase(LAS unsigned char* lds, const bf16_t* A, int lda, const bf16_t* Bt, int ldb, int M, int N, int K, int asel, const Epi& E, const int fixed_round = -1) {
;     ...
;             PG8_WAIT_V(6); PG8_BAR; PG8_MMA(1, 1, At, B1); PG8_BAR;
;             PG8_LDB(B0, 1, 0); PG8_SCHED; PG8_LDA(At, 1, 0); PG8_STAGE(PG8_SA(0, 1), a2 + hstepA, voffA);
;             PG8_WAIT_L(8); PG8_BAR; PG8_WAIT_L(0); PG8_MMA(0, 0, At, B0); PG8_BAR; PG8_SCHED;
;             PG8_LDB(B1, 1, 1); PG8_STAGE(PG8_SB(1, 0), b3, voffB);
;             PG8_BAR; PG8_WAIT_L(0); PG8_MMA(0, 1, At, B1); PG8_BAR;
	v_mfma_f32_16x16x32_bf16 v[52:55], v[206:209], v[170:173], v[52:55]
	v_mfma_f32_16x16x32_bf16 v[44:47], v[214:217], v[170:173], v[44:47]
	v_mfma_f32_16x16x32_bf16 v[36:39], v[206:209], v[178:181], v[36:39]
	v_mfma_f32_16x16x32_bf16 v[28:31], v[214:217], v[178:181], v[28:31]
	v_mfma_f32_16x16x32_bf16 v[20:23], v[206:209], v[186:189], v[20:23]
	v_mfma_f32_16x16x32_bf16 v[12:15], v[214:217], v[186:189], v[12:15]
	v_mfma_f32_16x16x32_bf16 v[4:7], v[206:209], v[194:197], v[4:7]
	v_mfma_f32_16x16x32_bf16 v[0:3], v[214:217], v[194:197], v[0:3]
	v_mfma_f32_16x16x32_bf16 v[52:55], v[210:213], v[174:177], v[52:55]
	v_mfma_f32_16x16x32_bf16 v[44:47], v[218:221], v[174:177], v[44:47]
	v_mfma_f32_16x16x32_bf16 v[36:39], v[210:213], v[182:185], v[36:39]
	v_mfma_f32_16x16x32_bf16 v[28:31], v[218:221], v[182:185], v[28:31]
	v_mfma_f32_16x16x32_bf16 v[20:23], v[210:213], v[190:193], v[20:23]
	v_mfma_f32_16x16x32_bf16 v[12:15], v[218:221], v[190:193], v[12:15]
	v_mfma_f32_16x16x32_bf16 v[4:7], v[210:213], v[202:205], v[4:7]
	v_mfma_f32_16x16x32_bf16 v[0:3], v[218:221], v[202:205], v[0:3]
	s_barrier
	s_setprio 0
	ds_read_b128 v[146:149], v143
	ds_read_b128 v[150:153], v143 offset:1024
	ds_read_b128 v[160:163], v143 offset:2048
	ds_read_b128 v[166:169], v143 offset:3072
	s_add_u32 s28, s36, 0x200000
	s_addc_u32 s29, s37, 0
	s_mov_b32 m0, s44
	ds_read_b128 v[170:173], v141 offset:32768
	ds_read_b128 v[174:177], v141 offset:33792
	ds_read_b128 v[178:181], v141 offset:34816
	ds_read_b128 v[182:185], v141 offset:35840
	ds_read_b128 v[186:189], v141 offset:36864
	ds_read_b128 v[190:193], v141 offset:37888
	ds_read_b128 v[194:197], v141 offset:38912
	ds_read_b128 v[202:205], v141 offset:39936
	global_load_lds_dwordx4 v128, s[28:29]
	s_mov_b32 m0, s45
	s_setprio 1
	global_load_lds_dwordx4 v132, s[28:29]
	s_waitcnt lgkmcnt(8)
	s_barrier
	s_waitcnt lgkmcnt(0)
	v_mfma_f32_16x16x32_bf16 v[124:127], v[146:149], v[170:173], v[124:127]
	v_mfma_f32_16x16x32_bf16 v[120:123], v[160:163], v[170:173], v[120:123]
	v_mfma_f32_16x16x32_bf16 v[112:115], v[146:149], v[178:181], v[112:115]
	v_mfma_f32_16x16x32_bf16 v[104:107], v[160:163], v[178:181], v[104:107]
	v_mfma_f32_16x16x32_bf16 v[96:99], v[146:149], v[186:189], v[96:99]
	v_mfma_f32_16x16x32_bf16 v[88:91], v[160:163], v[186:189], v[88:91]
	v_mfma_f32_16x16x32_bf16 v[80:83], v[146:149], v[194:197], v[80:83]
	v_mfma_f32_16x16x32_bf16 v[72:75], v[160:163], v[194:197], v[72:75]
	v_mfma_f32_16x16x32_bf16 v[124:127], v[150:153], v[174:177], v[124:127]
	v_mfma_f32_16x16x32_bf16 v[120:123], v[166:169], v[174:177], v[120:123]
	v_mfma_f32_16x16x32_bf16 v[112:115], v[150:153], v[182:185], v[112:115]
	v_mfma_f32_16x16x32_bf16 v[104:107], v[166:169], v[182:185], v[104:107]
	v_mfma_f32_16x16x32_bf16 v[96:99], v[150:153], v[190:193], v[96:99]
	v_mfma_f32_16x16x32_bf16 v[88:91], v[166:169], v[190:193], v[88:91]
	v_mfma_f32_16x16x32_bf16 v[80:83], v[150:153], v[202:205], v[80:83]
	v_mfma_f32_16x16x32_bf16 v[72:75], v[166:169], v[202:205], v[72:75]
	s_barrier
	s_setprio 0
	s_mov_b32 m0, s55
	ds_read_b128 v[206:209], v144
	ds_read_b128 v[210:213], v144 offset:1024
	ds_read_b128 v[214:217], v144 offset:2048
	ds_read_b128 v[218:221], v144 offset:3072
	global_load_lds_dwordx4 v130, s[98:99]
	s_mov_b32 m0, s56
	s_setprio 1
	global_load_lds_dwordx4 v134, s[98:99]
	s_barrier
; #define PG8_STAGE(bufoff, gbase, voff) do { _Pragma("unroll") for (int _i = 0; _i < 2; ++_i) \
;         __builtin_amdgcn_global_load_lds((const unsigned*)((const char*)(gbase) + (voff)[_i]), (LAS unsigned*)(lds + (bufoff) + ldsw + _i * 8192), 16, 0, 0); } while (0)
; #define PG8_LDA(dst, b, h) do { _Pragma("unroll") for (int m = 0; m < 4; ++m) _Pragma("unroll") for (int k = 0; k < 2; ++k) dst[m][k] = *(const LAS bf16x8*)(lds + PG8_SA(b, h) + aoff + m * 2048 + k * 1024); } while (0)
; #define PG8_WAIT_V(n) asm volatile("s_waitcnt vmcnt(" #n ")" ::: "memory")
; #define PG8_WAIT_L(n) asm volatile("s_waitcnt lgkmcnt(" #n ")" ::: "memory")
; #define PG8_BAR __builtin_amdgcn_s_barrier()
; #define PG8_SCHED __builtin_amdgcn_sched_barrier(0)
; template <class Epi>
; __device__ __forceinline__ void gemm_phase(LAS unsigned char* lds, const bf16_t* A, int lda, const bf16_t* Bt, int ldb, int M, int N, int K, int asel, const Epi& E, const int fixed_round = -1) {
;     ...
;             PG8_BAR; PG8_WAIT_L(0); PG8_MMA(0, 1, At, B1); PG8_BAR;
;             PG8_LDA(At, 1, 1); PG8_STAGE(PG8_SA(1, 0), a3, voffA);
;             PG8_BAR; PG8_WAIT_L(0); PG8_MMA(1, 0, At, B0); PG8_BAR; PG8_SCHED;
;             PG8_STAGE(PG8_SB(1, 1), b3 + hstepB, voffB);
;             PG8_WAIT_V(6); PG8_BAR; PG8_MMA(1, 1, At, B1); PG8_BAR;
	s_waitcnt lgkmcnt(0)
	v_mfma_f32_16x16x32_bf16 v[116:119], v[206:209], v[170:173], v[116:119]
	v_mfma_f32_16x16x32_bf16 v[108:111], v[214:217], v[170:173], v[108:111]
	v_mfma_f32_16x16x32_bf16 v[100:103], v[206:209], v[178:181], v[100:103]
	v_mfma_f32_16x16x32_bf16 v[92:95], v[214:217], v[178:181], v[92:95]
	v_mfma_f32_16x16x32_bf16 v[84:87], v[206:209], v[186:189], v[84:87]
	v_mfma_f32_16x16x32_bf16 v[76:79], v[214:217], v[186:189], v[76:79]
	v_mfma_f32_16x16x32_bf16 v[68:71], v[206:209], v[194:197], v[68:71]
	v_mfma_f32_16x16x32_bf16 v[64:67], v[214:217], v[194:197], v[64:67]
	v_mfma_f32_16x16x32_bf16 v[116:119], v[210:213], v[174:177], v[116:119]
	v_mfma_f32_16x16x32_bf16 v[108:111], v[218:221], v[174:177], v[108:111]
	v_mfma_f32_16x16x32_bf16 v[100:103], v[210:213], v[182:185], v[100:103]
	v_mfma_f32_16x16x32_bf16 v[92:95], v[218:221], v[182:185], v[92:95]
	v_mfma_f32_16x16x32_bf16 v[84:87], v[210:213], v[190:193], v[84:87]
	v_mfma_f32_16x16x32_bf16 v[76:79], v[218:221], v[190:193], v[76:79]
	v_mfma_f32_16x16x32_bf16 v[68:71], v[210:213], v[202:205], v[68:71]
	v_mfma_f32_16x16x32_bf16 v[64:67], v[218:221], v[202:205], v[64:67]
	s_barrier
	s_setprio 0
	s_mov_b32 m0, s46
	ds_read_b128 v[170:173], v141 offset:49152
	ds_read_b128 v[174:177], v141 offset:50176
	ds_read_b128 v[178:181], v141 offset:51200
	ds_read_b128 v[182:185], v141 offset:52224
	ds_read_b128 v[186:189], v141 offset:53248
	ds_read_b128 v[190:193], v141 offset:54272
	ds_read_b128 v[194:197], v141 offset:55296
	ds_read_b128 v[202:205], v141 offset:56320
	global_load_lds_dwordx4 v128, s[100:101]
	s_mov_b32 m0, s47
	s_setprio 1
	global_load_lds_dwordx4 v132, s[100:101]
	s_barrier
	s_waitcnt lgkmcnt(0)
	v_mfma_f32_16x16x32_bf16 v[60:63], v[146:149], v[170:173], v[60:63]
	v_mfma_f32_16x16x32_bf16 v[56:59], v[160:163], v[170:173], v[56:59]
	v_mfma_f32_16x16x32_bf16 v[48:51], v[146:149], v[178:181], v[48:51]
	v_mfma_f32_16x16x32_bf16 v[40:43], v[160:163], v[178:181], v[40:43]
	v_mfma_f32_16x16x32_bf16 v[32:35], v[146:149], v[186:189], v[32:35]
	v_mfma_f32_16x16x32_bf16 v[24:27], v[160:163], v[186:189], v[24:27]
	v_mfma_f32_16x16x32_bf16 v[16:19], v[146:149], v[194:197], v[16:19]
	v_mfma_f32_16x16x32_bf16 v[8:11], v[160:163], v[194:197], v[8:11]
	v_mfma_f32_16x16x32_bf16 v[60:63], v[150:153], v[174:177], v[60:63]
	v_mfma_f32_16x16x32_bf16 v[56:59], v[166:169], v[174:177], v[56:59]
	v_mfma_f32_16x16x32_bf16 v[48:51], v[150:153], v[182:185], v[48:51]
	v_mfma_f32_16x16x32_bf16 v[40:43], v[166:169], v[182:185], v[40:43]
	v_mfma_f32_16x16x32_bf16 v[32:35], v[150:153], v[190:193], v[32:35]
	v_mfma_f32_16x16x32_bf16 v[24:27], v[166:169], v[190:193], v[24:27]
	v_mfma_f32_16x16x32_bf16 v[16:19], v[150:153], v[202:205], v[16:19]
	v_mfma_f32_16x16x32_bf16 v[8:11], v[166:169], v[202:205], v[8:11]
	s_barrier
	s_setprio 0
	s_add_u32 s28, s34, 0x200080
	s_addc_u32 s29, s35, 0
	s_mov_b32 m0, s57
	s_nop 0
	global_load_lds_dwordx4 v130, s[28:29]
	s_mov_b32 m0, s58
	s_setprio 1
	global_load_lds_dwordx4 v134, s[28:29]
	s_waitcnt vmcnt(6)
	s_barrier
	v_mfma_f32_16x16x32_bf16 v[52:55], v[206:209], v[170:173], v[52:55]
	v_mfma_f32_16x16x32_bf16 v[44:47], v[214:217], v[170:173], v[44:47]
	v_mfma_f32_16x16x32_bf16 v[36:39], v[206:209], v[178:181], v[36:39]
	v_mfma_f32_16x16x32_bf16 v[28:31], v[214:217], v[178:181], v[28:31]
	v_mfma_f32_16x16x32_bf16 v[20:23], v[206:209], v[186:189], v[20:23]
	v_mfma_f32_16x16x32_bf16 v[12:15], v[214:217], v[186:189], v[12:15]
	v_mfma_f32_16x16x32_bf16 v[4:7], v[206:209], v[194:197], v[4:7]
	v_mfma_f32_16x16x32_bf16 v[0:3], v[214:217], v[194:197], v[0:3]
	v_mfma_f32_16x16x32_bf16 v[52:55], v[210:213], v[174:177], v[52:55]
	v_mfma_f32_16x16x32_bf16 v[44:47], v[218:221], v[174:177], v[44:47]
	v_mfma_f32_16x16x32_bf16 v[36:39], v[210:213], v[182:185], v[36:39]
	v_mfma_f32_16x16x32_bf16 v[28:31], v[218:221], v[182:185], v[28:31]
	v_mfma_f32_16x16x32_bf16 v[20:23], v[210:213], v[190:193], v[20:23]
	v_mfma_f32_16x16x32_bf16 v[12:15], v[218:221], v[190:193], v[12:15]
	v_mfma_f32_16x16x32_bf16 v[4:7], v[210:213], v[202:205], v[4:7]
	v_mfma_f32_16x16x32_bf16 v[0:3], v[218:221], v[202:205], v[0:3]
	s_setprio 0
	s_add_i32 s48, s48, 2
	s_add_u32 s20, s20, 0x100
	s_addc_u32 s21, s21, 0
	s_cmpk_lt_u32 s48, 0x7e
	s_cbranch_scc1 .Lrot_5
	s_barrier
	s_waitcnt vmcnt(0)
	v_writelane_b32 v255, s8, 26
	s_cmpk_gt_u32 s41, 0xff
	s_nop 0
	v_writelane_b32 v255, s9, 27
	s_cbranch_scc1 .LBB0_654
	s_barrier

; #define PG8_STAGE(bufoff, gbase, voff) do { _Pragma("unroll") for (int _i = 0; _i < 2; ++_i) \
;         __builtin_amdgcn_global_load_lds((const unsigned*)((const char*)(gbase) + (voff)[_i]), (LAS unsigned*)(lds + (bufoff) + ldsw + _i * 8192), 16, 0, 0); } while (0)
; #define PG8_LDA(dst, b, h) do { _Pragma("unroll") for (int m = 0; m < 4; ++m) _Pragma("unroll") for (int k = 0; k < 2; ++k) dst[m][k] = *(const LAS bf16x8*)(lds + PG8_SA(b, h) + aoff + m * 2048 + k * 1024); } while (0)
; #define PG8_LDB(dst, b, h) do { _Pragma("unroll") for (int n = 0; n < 2; ++n) _Pragma("unroll") for (int k = 0; k < 2; ++k) dst[n][k] = *(const LAS bf16x8*)(lds + PG8_SB(b, h) + boff + n * 2048 + k * 1024); } while (0)
; #define PG8_WAIT_V(n) asm volatile("s_waitcnt vmcnt(" #n ")" ::: "memory")
; #define PG8_WAIT_L(n) asm volatile("s_waitcnt lgkmcnt(" #n ")" ::: "memory")
; #define PG8_BAR __builtin_amdgcn_s_barrier()
; #define PG8_SCHED __builtin_amdgcn_sched_barrier(0)
; template <class Epi>
; __device__ __forceinline__ void gemm_phase(LAS unsigned char* lds, const bf16_t* A, int lda, const bf16_t* Bt, int ldb, int M, int N, int K, int asel, const Epi& E, const int fixed_round = -1) {
;     ...
;         for (int t = 0; t < nt; t += 2) {
;             const bool last = (t == nt - 2);
;             const char* a1 = cA + (size_t)(t + 1) * kstep;
;             const char* a2 = last ? nA : cA + (size_t)(t + 2) * kstep; const char* b2 = last ? nB : cB + (size_t)(t + 2) * kstep;
;             const char* a3 = a2 + kstep; const char* b3 = b2 + kstep;
;             PG8_LDB(B0, 0, 0); PG8_SCHED; PG8_LDA(At, 0, 0); PG8_STAGE(PG8_SA(1, 1), a1 + hstepA, voffA);
;             PG8_WAIT_L(8); PG8_BAR; PG8_WAIT_L(0); PG8_MMA(0, 0, At, B0); PG8_BAR; PG8_SCHED;
;             PG8_LDB(B1, 0, 1); PG8_STAGE(PG8_SB(0, 0), b2, voffB);
;             PG8_BAR; PG8_WAIT_L(0); PG8_MMA(0, 1, At, B1); PG8_BAR;
;             PG8_LDA(At, 0, 1); PG8_STAGE(PG8_SA(0, 0), a2, voffA);
;             PG8_BAR; PG8_WAIT_L(0); PG8_MMA(1, 0, At, B0); PG8_BAR; PG8_SCHED;
;             PG8_STAGE(PG8_SB(0, 1), b2 + hstepB, voffB);
;             PG8_WAIT_V(6); PG8_BAR; PG8_MMA(1, 1, At, B1); PG8_BAR;
.LBB0_690:
	ds_read_b128 v[146:149], v138
	ds_read_b128 v[150:153], v138 offset:1024
	ds_read_b128 v[160:163], v138 offset:2048
	ds_read_b128 v[166:169], v138 offset:3072
	s_mov_b32 m0, s59
	v_lshl_add_u64 v[156:157], v[134:135], 0, s[4:5]
	ds_read_b128 v[170:173], v139
	ds_read_b128 v[174:177], v139 offset:1024
	ds_read_b128 v[178:181], v139 offset:2048
	ds_read_b128 v[182:185], v139 offset:3072
	ds_read_b128 v[186:189], v139 offset:4096
	ds_read_b128 v[190:193], v139 offset:5120
	ds_read_b128 v[194:197], v139 offset:6144
	ds_read_b128 v[202:205], v139 offset:7168
	global_load_lds_dwordx4 v[156:157], off
	v_lshl_add_u64 v[156:157], v[136:137], 0, s[4:5]
	s_mov_b32 m0, s60
	s_setprio 1
	global_load_lds_dwordx4 v[156:157], off
	s_waitcnt lgkmcnt(8)
	s_barrier
	s_waitcnt lgkmcnt(0)
	v_mfma_f32_16x16x32_bf16 v[124:127], v[146:149], v[170:173], v[124:127]
	v_mfma_f32_16x16x32_bf16 v[120:123], v[160:163], v[170:173], v[120:123]
	v_mfma_f32_16x16x32_bf16 v[112:115], v[146:149], v[178:181], v[112:115]
	v_mfma_f32_16x16x32_bf16 v[104:107], v[160:163], v[178:181], v[104:107]
	v_mfma_f32_16x16x32_bf16 v[96:99], v[146:149], v[186:189], v[96:99]
	v_mfma_f32_16x16x32_bf16 v[88:91], v[160:163], v[186:189], v[88:91]
	v_mfma_f32_16x16x32_bf16 v[80:83], v[146:149], v[194:197], v[80:83]
	v_mfma_f32_16x16x32_bf16 v[72:75], v[160:163], v[194:197], v[72:75]
	v_mfma_f32_16x16x32_bf16 v[124:127], v[150:153], v[174:177], v[124:127]
	v_mfma_f32_16x16x32_bf16 v[120:123], v[166:169], v[174:177], v[120:123]
	v_mfma_f32_16x16x32_bf16 v[112:115], v[150:153], v[182:185], v[112:115]
	v_mfma_f32_16x16x32_bf16 v[104:107], v[166:169], v[182:185], v[104:107]
	v_mfma_f32_16x16x32_bf16 v[96:99], v[150:153], v[190:193], v[96:99]
	v_mfma_f32_16x16x32_bf16 v[88:91], v[166:169], v[190:193], v[88:91]
	v_mfma_f32_16x16x32_bf16 v[80:83], v[150:153], v[202:205], v[80:83]
	v_mfma_f32_16x16x32_bf16 v[72:75], v[166:169], v[202:205], v[72:75]
	s_barrier
	s_setprio 0
	s_add_u32 s6, s4, 0xe7900080
	s_addc_u32 s7, s5, -1
	s_cmpk_lg_i32 s58, 0x7c
	s_cselect_b32 s6, s6, 0
	s_cselect_b32 s7, s7, 0
	s_add_u32 s40, s8, s6
	s_addc_u32 s41, s9, s7
	s_add_u32 s6, s2, s6
	s_addc_u32 s7, s3, s7
	s_mov_b32 m0, s61
	s_add_u32 s98, s6, s0
	s_addc_u32 s99, s7, s1
	ds_read_b128 v[206:209], v140
	ds_read_b128 v[210:213], v140 offset:1024
	ds_read_b128 v[214:217], v140 offset:2048
	ds_read_b128 v[218:221], v140 offset:3072
	global_load_lds_dwordx4 v144, s[6:7]
	s_mov_b32 m0, s62
	s_setprio 1
	global_load_lds_dwordx4 v132, s[6:7]
	s_barrier
	s_waitcnt lgkmcnt(0)
	v_mfma_f32_16x16x32_bf16 v[116:119], v[206:209], v[170:173], v[116:119]
	v_mfma_f32_16x16x32_bf16 v[108:111], v[214:217], v[170:173], v[108:111]
	v_mfma_f32_16x16x32_bf16 v[100:103], v[206:209], v[178:181], v[100:103]
	v_mfma_f32_16x16x32_bf16 v[92:95], v[214:217], v[178:181], v[92:95]
	v_mfma_f32_16x16x32_bf16 v[84:87], v[206:209], v[186:189], v[84:87]
	v_mfma_f32_16x16x32_bf16 v[76:79], v[214:217], v[186:189], v[76:79]
	v_mfma_f32_16x16x32_bf16 v[68:71], v[206:209], v[194:197], v[68:71]
	v_mfma_f32_16x16x32_bf16 v[64:67], v[214:217], v[194:197], v[64:67]
	v_mfma_f32_16x16x32_bf16 v[116:119], v[210:213], v[174:177], v[116:119]
	v_mfma_f32_16x16x32_bf16 v[108:111], v[218:221], v[174:177], v[108:111]
	v_mfma_f32_16x16x32_bf16 v[100:103], v[210:213], v[182:185], v[100:103]
	v_mfma_f32_16x16x32_bf16 v[92:95], v[218:221], v[182:185], v[92:95]
	v_mfma_f32_16x16x32_bf16 v[84:87], v[210:213], v[190:193], v[84:87]
	v_mfma_f32_16x16x32_bf16 v[76:79], v[218:221], v[190:193], v[76:79]
	v_mfma_f32_16x16x32_bf16 v[68:71], v[210:213], v[202:205], v[68:71]
	v_mfma_f32_16x16x32_bf16 v[64:67], v[218:221], v[202:205], v[64:67]
	s_barrier
	s_setprio 0
	s_mov_b32 m0, s52
	s_add_u32 s100, s40, s0
	s_addc_u32 s101, s41, s1
	ds_read_b128 v[170:173], v139 offset:16384
	ds_read_b128 v[174:177], v139 offset:17408
	ds_read_b128 v[178:181], v139 offset:18432
	ds_read_b128 v[182:185], v139 offset:19456
	ds_read_b128 v[186:189], v139 offset:20480
	ds_read_b128 v[190:193], v139 offset:21504
	ds_read_b128 v[194:197], v139 offset:22528
	ds_read_b128 v[202:205], v139 offset:23552
	global_load_lds_dwordx4 v128, s[40:41]
	s_mov_b32 m0, s53
	s_setprio 1
	global_load_lds_dwordx4 v130, s[40:41]
	s_barrier
	s_waitcnt lgkmcnt(0)
	v_mfma_f32_16x16x32_bf16 v[60:63], v[146:149], v[170:173], v[60:63]
	v_mfma_f32_16x16x32_bf16 v[56:59], v[160:163], v[170:173], v[56:59]
	v_mfma_f32_16x16x32_bf16 v[48:51], v[146:149], v[178:181], v[48:51]
	v_mfma_f32_16x16x32_bf16 v[40:43], v[160:163], v[178:181], v[40:43]
	v_mfma_f32_16x16x32_bf16 v[32:35], v[146:149], v[186:189], v[32:35]
	v_mfma_f32_16x16x32_bf16 v[24:27], v[160:163], v[186:189], v[24:27]
	v_mfma_f32_16x16x32_bf16 v[16:19], v[146:149], v[194:197], v[16:19]
	v_mfma_f32_16x16x32_bf16 v[8:11], v[160:163], v[194:197], v[8:11]
	v_mfma_f32_16x16x32_bf16 v[60:63], v[150:153], v[174:177], v[60:63]
	v_mfma_f32_16x16x32_bf16 v[56:59], v[166:169], v[174:177], v[56:59]
	v_mfma_f32_16x16x32_bf16 v[48:51], v[150:153], v[182:185], v[48:51]
	v_mfma_f32_16x16x32_bf16 v[40:43], v[166:169], v[182:185], v[40:43]
	v_mfma_f32_16x16x32_bf16 v[32:35], v[150:153], v[190:193], v[32:35]
	v_mfma_f32_16x16x32_bf16 v[24:27], v[166:169], v[190:193], v[24:27]
	v_mfma_f32_16x16x32_bf16 v[16:19], v[150:153], v[202:205], v[16:19]
	v_mfma_f32_16x16x32_bf16 v[8:11], v[166:169], v[202:205], v[8:11]
	s_barrier
	s_setprio 0
	s_add_u32 s28, s6, 0x200000
	s_addc_u32 s29, s7, 0
	s_mov_b32 m0, s63
	s_nop 0
	global_load_lds_dwordx4 v144, s[28:29]
	s_mov_b32 m0, s64
	s_setprio 1
	global_load_lds_dwordx4 v132, s[28:29]
	s_waitcnt vmcnt(6)
	s_barrier
; #define PG8_STAGE(bufoff, gbase, voff) do { _Pragma("unroll") for (int _i = 0; _i < 2; ++_i) \
;         __builtin_amdgcn_global_load_lds((const unsigned*)((const char*)(gbase) + (voff)[_i]), (LAS unsigned*)(lds + (bufoff) + ldsw + _i * 8192), 16, 0, 0); } while (0)
; #define PG8_LDA(dst, b, h) do { _Pragma("unroll") for (int m = 0; m < 4; ++m) _Pragma("unroll") for (int k = 0; k < 2; ++k) dst[m][k] = *(const LAS bf16x8*)(lds + PG8_SA(b, h) + aoff + m * 2048 + k * 1024); } while (0)
; #define PG8_LDB(dst, b, h) do { _Pragma("unroll") for (int n = 0; n < 2; ++n) _Pragma("unroll") for (int k = 0; k < 2; ++k) dst[n][k] = *(const LAS bf16x8*)(lds + PG8_SB(b, h) + boff + n * 2048 + k * 1024); } while (0)
; #define PG8_WAIT_V(n) asm volatile("s_waitcnt vmcnt(" #n ")" ::: "memory")
; #define PG8_WAIT_L(n) asm volatile("s_waitcnt lgkmcnt(" #n ")" ::: "memory")
; #define PG8_BAR __builtin_amdgcn_s_barrier()
; #define PG8_SCHED __builtin_amdgcn_sched_barrier(0)
; template <class Epi>
; __device__ __forceinline__ void gemm_phase(LAS unsigned char* lds, const bf16_t* A, int lda, const bf16_t* Bt, int ldb, int M, int N, int K, int asel, const Epi& E, const int fixed_round = -1) {
;     ...
;             PG8_WAIT_V(6); PG8_BAR; PG8_MMA(1, 1, At, B1); PG8_BAR;
;             PG8_LDB(B0, 1, 0); PG8_SCHED; PG8_LDA(At, 1, 0); PG8_STAGE(PG8_SA(0, 1), a2 + hstepA, voffA);
;             PG8_WAIT_L(8); PG8_BAR; PG8_WAIT_L(0); PG8_MMA(0, 0, At, B0); PG8_BAR; PG8_SCHED;
;             PG8_LDB(B1, 1, 1); PG8_STAGE(PG8_SB(1, 0), b3, voffB);
;             PG8_BAR; PG8_WAIT_L(0); PG8_MMA(0, 1, At, B1); PG8_BAR;
	v_mfma_f32_16x16x32_bf16 v[52:55], v[206:209], v[170:173], v[52:55]
	v_mfma_f32_16x16x32_bf16 v[44:47], v[214:217], v[170:173], v[44:47]
	v_mfma_f32_16x16x32_bf16 v[36:39], v[206:209], v[178:181], v[36:39]
	v_mfma_f32_16x16x32_bf16 v[28:31], v[214:217], v[178:181], v[28:31]
	v_mfma_f32_16x16x32_bf16 v[20:23], v[206:209], v[186:189], v[20:23]
	v_mfma_f32_16x16x32_bf16 v[12:15], v[214:217], v[186:189], v[12:15]
	v_mfma_f32_16x16x32_bf16 v[4:7], v[206:209], v[194:197], v[4:7]
	v_mfma_f32_16x16x32_bf16 v[0:3], v[214:217], v[194:197], v[0:3]
	v_mfma_f32_16x16x32_bf16 v[52:55], v[210:213], v[174:177], v[52:55]
	v_mfma_f32_16x16x32_bf16 v[44:47], v[218:221], v[174:177], v[44:47]
	v_mfma_f32_16x16x32_bf16 v[36:39], v[210:213], v[182:185], v[36:39]
	v_mfma_f32_16x16x32_bf16 v[28:31], v[218:221], v[182:185], v[28:31]
	v_mfma_f32_16x16x32_bf16 v[20:23], v[210:213], v[190:193], v[20:23]
	v_mfma_f32_16x16x32_bf16 v[12:15], v[218:221], v[190:193], v[12:15]
	v_mfma_f32_16x16x32_bf16 v[4:7], v[210:213], v[202:205], v[4:7]
	v_mfma_f32_16x16x32_bf16 v[0:3], v[218:221], v[202:205], v[0:3]
	s_barrier
	s_setprio 0
	ds_read_b128 v[146:149], v141
	ds_read_b128 v[150:153], v141 offset:1024
	ds_read_b128 v[160:163], v141 offset:2048
	ds_read_b128 v[166:169], v141 offset:3072
	s_add_u32 s28, s40, 0x200000
	s_addc_u32 s29, s41, 0
	s_mov_b32 m0, s54
	ds_read_b128 v[170:173], v139 offset:32768
	ds_read_b128 v[174:177], v139 offset:33792
	ds_read_b128 v[178:181], v139 offset:34816
	ds_read_b128 v[182:185], v139 offset:35840
	ds_read_b128 v[186:189], v139 offset:36864
	ds_read_b128 v[190:193], v139 offset:37888
	ds_read_b128 v[194:197], v139 offset:38912
	ds_read_b128 v[202:205], v139 offset:39936
	global_load_lds_dwordx4 v128, s[28:29]
	s_mov_b32 m0, s55
	s_setprio 1
	global_load_lds_dwordx4 v130, s[28:29]
	s_waitcnt lgkmcnt(8)
	s_barrier
	s_waitcnt lgkmcnt(0)
	v_mfma_f32_16x16x32_bf16 v[124:127], v[146:149], v[170:173], v[124:127]
	v_mfma_f32_16x16x32_bf16 v[120:123], v[160:163], v[170:173], v[120:123]
	v_mfma_f32_16x16x32_bf16 v[112:115], v[146:149], v[178:181], v[112:115]
	v_mfma_f32_16x16x32_bf16 v[104:107], v[160:163], v[178:181], v[104:107]
	v_mfma_f32_16x16x32_bf16 v[96:99], v[146:149], v[186:189], v[96:99]
	v_mfma_f32_16x16x32_bf16 v[88:91], v[160:163], v[186:189], v[88:91]
	v_mfma_f32_16x16x32_bf16 v[80:83], v[146:149], v[194:197], v[80:83]
	v_mfma_f32_16x16x32_bf16 v[72:75], v[160:163], v[194:197], v[72:75]
	v_mfma_f32_16x16x32_bf16 v[124:127], v[150:153], v[174:177], v[124:127]
	v_mfma_f32_16x16x32_bf16 v[120:123], v[166:169], v[174:177], v[120:123]
	v_mfma_f32_16x16x32_bf16 v[112:115], v[150:153], v[182:185], v[112:115]
	v_mfma_f32_16x16x32_bf16 v[104:107], v[166:169], v[182:185], v[104:107]
	v_mfma_f32_16x16x32_bf16 v[96:99], v[150:153], v[190:193], v[96:99]
	v_mfma_f32_16x16x32_bf16 v[88:91], v[166:169], v[190:193], v[88:91]
	v_mfma_f32_16x16x32_bf16 v[80:83], v[150:153], v[202:205], v[80:83]
	v_mfma_f32_16x16x32_bf16 v[72:75], v[166:169], v[202:205], v[72:75]
	s_barrier
	s_setprio 0
	s_mov_b32 m0, s65
	ds_read_b128 v[206:209], v142
	ds_read_b128 v[210:213], v142 offset:1024
	ds_read_b128 v[214:217], v142 offset:2048
	ds_read_b128 v[218:221], v142 offset:3072
	global_load_lds_dwordx4 v144, s[98:99]
	s_mov_b32 m0, s66
	s_setprio 1
	global_load_lds_dwordx4 v132, s[98:99]
	s_barrier
; #define PG8_STAGE(bufoff, gbase, voff) do { _Pragma("unroll") for (int _i = 0; _i < 2; ++_i) \
;         __builtin_amdgcn_global_load_lds((const unsigned*)((const char*)(gbase) + (voff)[_i]), (LAS unsigned*)(lds + (bufoff) + ldsw + _i * 8192), 16, 0, 0); } while (0)
; #define PG8_LDA(dst, b, h) do { _Pragma("unroll") for (int m = 0; m < 4; ++m) _Pragma("unroll") for (int k = 0; k < 2; ++k) dst[m][k] = *(const LAS bf16x8*)(lds + PG8_SA(b, h) + aoff + m * 2048 + k * 1024); } while (0)
; #define PG8_WAIT_V(n) asm volatile("s_waitcnt vmcnt(" #n ")" ::: "memory")
; #define PG8_WAIT_L(n) asm volatile("s_waitcnt lgkmcnt(" #n ")" ::: "memory")
; #define PG8_BAR __builtin_amdgcn_s_barrier()
; #define PG8_SCHED __builtin_amdgcn_sched_barrier(0)
; template <class Epi>
; __device__ __forceinline__ void gemm_phase(LAS unsigned char* lds, const bf16_t* A, int lda, const bf16_t* Bt, int ldb, int M, int N, int K, int asel, const Epi& E, const int fixed_round = -1) {
;     ...
;             PG8_BAR; PG8_WAIT_L(0); PG8_MMA(0, 1, At, B1); PG8_BAR;
;             PG8_LDA(At, 1, 1); PG8_STAGE(PG8_SA(1, 0), a3, voffA);
;             PG8_BAR; PG8_WAIT_L(0); PG8_MMA(1, 0, At, B0); PG8_BAR; PG8_SCHED;
;             PG8_STAGE(PG8_SB(1, 1), b3 + hstepB, voffB);
;             PG8_WAIT_V(6); PG8_BAR; PG8_MMA(1, 1, At, B1); PG8_BAR;
	s_waitcnt lgkmcnt(0)
	v_mfma_f32_16x16x32_bf16 v[116:119], v[206:209], v[170:173], v[116:119]
	v_mfma_f32_16x16x32_bf16 v[108:111], v[214:217], v[170:173], v[108:111]
	v_mfma_f32_16x16x32_bf16 v[100:103], v[206:209], v[178:181], v[100:103]
	v_mfma_f32_16x16x32_bf16 v[92:95], v[214:217], v[178:181], v[92:95]
	v_mfma_f32_16x16x32_bf16 v[84:87], v[206:209], v[186:189], v[84:87]
	v_mfma_f32_16x16x32_bf16 v[76:79], v[214:217], v[186:189], v[76:79]
	v_mfma_f32_16x16x32_bf16 v[68:71], v[206:209], v[194:197], v[68:71]
	v_mfma_f32_16x16x32_bf16 v[64:67], v[214:217], v[194:197], v[64:67]
	v_mfma_f32_16x16x32_bf16 v[116:119], v[210:213], v[174:177], v[116:119]
	v_mfma_f32_16x16x32_bf16 v[108:111], v[218:221], v[174:177], v[108:111]
	v_mfma_f32_16x16x32_bf16 v[100:103], v[210:213], v[182:185], v[100:103]
	v_mfma_f32_16x16x32_bf16 v[92:95], v[218:221], v[182:185], v[92:95]
	v_mfma_f32_16x16x32_bf16 v[84:87], v[210:213], v[190:193], v[84:87]
	v_mfma_f32_16x16x32_bf16 v[76:79], v[218:221], v[190:193], v[76:79]
	v_mfma_f32_16x16x32_bf16 v[68:71], v[210:213], v[202:205], v[68:71]
	v_mfma_f32_16x16x32_bf16 v[64:67], v[218:221], v[202:205], v[64:67]
	s_barrier
	s_setprio 0
	s_mov_b32 m0, s56
	ds_read_b128 v[170:173], v139 offset:49152
	ds_read_b128 v[174:177], v139 offset:50176
	ds_read_b128 v[178:181], v139 offset:51200
	ds_read_b128 v[182:185], v139 offset:52224
	ds_read_b128 v[186:189], v139 offset:53248
	ds_read_b128 v[190:193], v139 offset:54272
	ds_read_b128 v[194:197], v139 offset:55296
	ds_read_b128 v[202:205], v139 offset:56320
	global_load_lds_dwordx4 v128, s[100:101]
	s_mov_b32 m0, s57
	s_setprio 1
	global_load_lds_dwordx4 v130, s[100:101]
	s_barrier
	s_waitcnt lgkmcnt(0)
	v_mfma_f32_16x16x32_bf16 v[60:63], v[146:149], v[170:173], v[60:63]
	v_mfma_f32_16x16x32_bf16 v[56:59], v[160:163], v[170:173], v[56:59]
	v_mfma_f32_16x16x32_bf16 v[48:51], v[146:149], v[178:181], v[48:51]
	v_mfma_f32_16x16x32_bf16 v[40:43], v[160:163], v[178:181], v[40:43]
	v_mfma_f32_16x16x32_bf16 v[32:35], v[146:149], v[186:189], v[32:35]
	v_mfma_f32_16x16x32_bf16 v[24:27], v[160:163], v[186:189], v[24:27]
	v_mfma_f32_16x16x32_bf16 v[16:19], v[146:149], v[194:197], v[16:19]
	v_mfma_f32_16x16x32_bf16 v[8:11], v[160:163], v[194:197], v[8:11]
	v_mfma_f32_16x16x32_bf16 v[60:63], v[150:153], v[174:177], v[60:63]
	v_mfma_f32_16x16x32_bf16 v[56:59], v[166:169], v[174:177], v[56:59]
	v_mfma_f32_16x16x32_bf16 v[48:51], v[150:153], v[182:185], v[48:51]
	v_mfma_f32_16x16x32_bf16 v[40:43], v[166:169], v[182:185], v[40:43]
	v_mfma_f32_16x16x32_bf16 v[32:35], v[150:153], v[190:193], v[32:35]
	v_mfma_f32_16x16x32_bf16 v[24:27], v[166:169], v[190:193], v[24:27]
	v_mfma_f32_16x16x32_bf16 v[16:19], v[150:153], v[202:205], v[16:19]
	v_mfma_f32_16x16x32_bf16 v[8:11], v[166:169], v[202:205], v[8:11]
	s_barrier
	s_setprio 0
	s_add_u32 s6, s6, 0x200080
	s_addc_u32 s7, s7, 0
	s_mov_b32 m0, s67
	s_nop 0
	global_load_lds_dwordx4 v144, s[6:7]
	s_mov_b32 m0, s68
	s_setprio 1
	global_load_lds_dwordx4 v132, s[6:7]
	s_waitcnt vmcnt(6)
	s_barrier
	v_mfma_f32_16x16x32_bf16 v[52:55], v[206:209], v[170:173], v[52:55]
	v_mfma_f32_16x16x32_bf16 v[44:47], v[214:217], v[170:173], v[44:47]
	v_mfma_f32_16x16x32_bf16 v[36:39], v[206:209], v[178:181], v[36:39]
	v_mfma_f32_16x16x32_bf16 v[28:31], v[214:217], v[178:181], v[28:31]
	v_mfma_f32_16x16x32_bf16 v[20:23], v[206:209], v[186:189], v[20:23]
	v_mfma_f32_16x16x32_bf16 v[12:15], v[214:217], v[186:189], v[12:15]
	v_mfma_f32_16x16x32_bf16 v[4:7], v[206:209], v[194:197], v[4:7]
	v_mfma_f32_16x16x32_bf16 v[0:3], v[214:217], v[194:197], v[0:3]
	v_mfma_f32_16x16x32_bf16 v[52:55], v[210:213], v[174:177], v[52:55]
	v_mfma_f32_16x16x32_bf16 v[44:47], v[218:221], v[174:177], v[44:47]
	v_mfma_f32_16x16x32_bf16 v[36:39], v[210:213], v[182:185], v[36:39]
	v_mfma_f32_16x16x32_bf16 v[28:31], v[218:221], v[182:185], v[28:31]
	v_mfma_f32_16x16x32_bf16 v[20:23], v[210:213], v[190:193], v[20:23]
	v_mfma_f32_16x16x32_bf16 v[12:15], v[218:221], v[190:193], v[12:15]
	v_mfma_f32_16x16x32_bf16 v[4:7], v[210:213], v[202:205], v[4:7]
	v_mfma_f32_16x16x32_bf16 v[0:3], v[218:221], v[202:205], v[0:3]
	s_setprio 0
	s_add_i32 s58, s58, 2
	s_add_u32 s4, s4, 0x100
	s_addc_u32 s5, s5, 0
	s_cmpk_lt_u32 s58, 0x7e
	s_cbranch_scc1 .Lrot_6
	s_barrier
	s_waitcnt vmcnt(0)
	s_cmpk_gt_u32 s51, 0xff
	s_cbranch_scc1 .LBB0_693
	s_barrier

; #define PG8_STAGE(bufoff, gbase, voff) do { _Pragma("unroll") for (int _i = 0; _i < 2; ++_i) \
;         __builtin_amdgcn_global_load_lds((const unsigned*)((const char*)(gbase) + (voff)[_i]), (LAS unsigned*)(lds + (bufoff) + ldsw + _i * 8192), 16, 0, 0); } while (0)
; #define PG8_LDA(dst, b, h) do { _Pragma("unroll") for (int m = 0; m < 4; ++m) _Pragma("unroll") for (int k = 0; k < 2; ++k) dst[m][k] = *(const LAS bf16x8*)(lds + PG8_SA(b, h) + aoff + m * 2048 + k * 1024); } while (0)
; #define PG8_LDB(dst, b, h) do { _Pragma("unroll") for (int n = 0; n < 2; ++n) _Pragma("unroll") for (int k = 0; k < 2; ++k) dst[n][k] = *(const LAS bf16x8*)(lds + PG8_SB(b, h) + boff + n * 2048 + k * 1024); } while (0)
; #define PG8_WAIT_V(n) asm volatile("s_waitcnt vmcnt(" #n ")" ::: "memory")
; #define PG8_WAIT_L(n) asm volatile("s_waitcnt lgkmcnt(" #n ")" ::: "memory")
; #define PG8_BAR __builtin_amdgcn_s_barrier()
; #define PG8_SCHED __builtin_amdgcn_sched_barrier(0)
; template <class Epi>
; __device__ __forceinline__ void gemm_phase(LAS unsigned char* lds, const bf16_t* A, int lda, const bf16_t* Bt, int ldb, int M, int N, int K, int asel, const Epi& E, const int fixed_round = -1) {
;     ...
;         for (int t = 0; t < nt; t += 2) {
;             const bool last = (t == nt - 2);
;             const char* a1 = cA + (size_t)(t + 1) * kstep;
;             const char* a2 = last ? nA : cA + (size_t)(t + 2) * kstep; const char* b2 = last ? nB : cB + (size_t)(t + 2) * kstep;
;             const char* a3 = a2 + kstep; const char* b3 = b2 + kstep;
;             PG8_LDB(B0, 0, 0); PG8_SCHED; PG8_LDA(At, 0, 0); PG8_STAGE(PG8_SA(1, 1), a1 + hstepA, voffA);
;             PG8_WAIT_L(8); PG8_BAR; PG8_WAIT_L(0); PG8_MMA(0, 0, At, B0); PG8_BAR; PG8_SCHED;
;             PG8_LDB(B1, 0, 1); PG8_STAGE(PG8_SB(0, 0), b2, voffB);
;             PG8_BAR; PG8_WAIT_L(0); PG8_MMA(0, 1, At, B1); PG8_BAR;
;             PG8_LDA(At, 0, 1); PG8_STAGE(PG8_SA(0, 0), a2, voffA);
;             PG8_BAR; PG8_WAIT_L(0); PG8_MMA(1, 0, At, B0); PG8_BAR; PG8_SCHED;
;             PG8_STAGE(PG8_SB(0, 1), b2 + hstepB, voffB);
;             PG8_WAIT_V(6); PG8_BAR; PG8_MMA(1, 1, At, B1); PG8_BAR;
.LBB0_799:
	ds_read_b128 v[146:149], v155
	ds_read_b128 v[158:161], v155 offset:1024
	ds_read_b128 v[162:165], v155 offset:2048
	ds_read_b128 v[166:169], v155 offset:3072
	s_add_i32 m0, s49, 0xc000
	ds_read_b128 v[170:173], v156
	ds_read_b128 v[174:177], v156 offset:1024
	ds_read_b128 v[178:181], v156 offset:2048
	ds_read_b128 v[182:185], v156 offset:3072
	ds_read_b128 v[186:189], v156 offset:4096
	ds_read_b128 v[190:193], v156 offset:5120
	ds_read_b128 v[194:197], v156 offset:6144
	ds_read_b128 v[202:205], v156 offset:7168
	global_load_lds_dwordx4 v138, s[50:51]
	s_add_i32 m0, s49, 0xe000
	s_setprio 1
	global_load_lds_dwordx4 v140, s[50:51]
	s_waitcnt lgkmcnt(8)
	s_barrier
	s_waitcnt lgkmcnt(0)
	v_mfma_f32_16x16x32_bf16 v[124:127], v[146:149], v[170:173], v[124:127]
	v_mfma_f32_16x16x32_bf16 v[120:123], v[162:165], v[170:173], v[120:123]
	v_mfma_f32_16x16x32_bf16 v[108:111], v[146:149], v[178:181], v[108:111]
	v_mfma_f32_16x16x32_bf16 v[104:107], v[162:165], v[178:181], v[104:107]
	v_mfma_f32_16x16x32_bf16 v[92:95], v[146:149], v[186:189], v[92:95]
	v_mfma_f32_16x16x32_bf16 v[88:91], v[162:165], v[186:189], v[88:91]
	v_mfma_f32_16x16x32_bf16 v[76:79], v[146:149], v[194:197], v[76:79]
	v_mfma_f32_16x16x32_bf16 v[72:75], v[162:165], v[194:197], v[72:75]
	v_mfma_f32_16x16x32_bf16 v[124:127], v[158:161], v[174:177], v[124:127]
	v_mfma_f32_16x16x32_bf16 v[120:123], v[166:169], v[174:177], v[120:123]
	v_mfma_f32_16x16x32_bf16 v[108:111], v[158:161], v[182:185], v[108:111]
	v_mfma_f32_16x16x32_bf16 v[104:107], v[166:169], v[182:185], v[104:107]
	v_mfma_f32_16x16x32_bf16 v[92:95], v[158:161], v[190:193], v[92:95]
	v_mfma_f32_16x16x32_bf16 v[88:91], v[166:169], v[190:193], v[88:91]
	v_mfma_f32_16x16x32_bf16 v[76:79], v[158:161], v[202:205], v[76:79]
	v_mfma_f32_16x16x32_bf16 v[72:75], v[166:169], v[202:205], v[72:75]
	s_barrier
	s_setprio 0
	s_add_u32 s28, s50, 0xfff80080
	s_addc_u32 s29, s51, -1
	s_cmp_eq_u32 s68, 28
	s_cselect_b32 s55, s5, s29
	s_cselect_b32 s54, s41, s28
	s_cselect_b32 s53, s7, s67
	s_cselect_b32 s52, s65, s66
	s_add_i32 s28, s81, s58
	s_add_u32 s98, s52, s2
	s_addc_u32 s99, s53, s3
	s_mov_b32 m0, s28
	ds_read_b128 v[206:209], v157
	ds_read_b128 v[210:213], v157 offset:1024
	ds_read_b128 v[214:217], v157 offset:2048
	ds_read_b128 v[218:221], v157 offset:3072
	global_load_lds_dwordx4 v130, s[52:53]
	s_add_i32 m0, s28, 0x2000
	s_setprio 1
	global_load_lds_dwordx4 v134, s[52:53]
	s_barrier
	s_waitcnt lgkmcnt(0)
	v_mfma_f32_16x16x32_bf16 v[116:119], v[206:209], v[170:173], v[116:119]
	v_mfma_f32_16x16x32_bf16 v[112:115], v[214:217], v[170:173], v[112:115]
	v_mfma_f32_16x16x32_bf16 v[100:103], v[206:209], v[178:181], v[100:103]
	v_mfma_f32_16x16x32_bf16 v[96:99], v[214:217], v[178:181], v[96:99]
	v_mfma_f32_16x16x32_bf16 v[84:87], v[206:209], v[186:189], v[84:87]
	v_mfma_f32_16x16x32_bf16 v[80:83], v[214:217], v[186:189], v[80:83]
	v_mfma_f32_16x16x32_bf16 v[68:71], v[206:209], v[194:197], v[68:71]
	v_mfma_f32_16x16x32_bf16 v[64:67], v[214:217], v[194:197], v[64:67]
	v_mfma_f32_16x16x32_bf16 v[116:119], v[210:213], v[174:177], v[116:119]
	v_mfma_f32_16x16x32_bf16 v[112:115], v[218:221], v[174:177], v[112:115]
	v_mfma_f32_16x16x32_bf16 v[100:103], v[210:213], v[182:185], v[100:103]
	v_mfma_f32_16x16x32_bf16 v[96:99], v[218:221], v[182:185], v[96:99]
	v_mfma_f32_16x16x32_bf16 v[84:87], v[210:213], v[190:193], v[84:87]
	v_mfma_f32_16x16x32_bf16 v[80:83], v[218:221], v[190:193], v[80:83]
	v_mfma_f32_16x16x32_bf16 v[68:71], v[210:213], v[202:205], v[68:71]
	v_mfma_f32_16x16x32_bf16 v[64:67], v[218:221], v[202:205], v[64:67]
	s_barrier
	s_setprio 0
	s_mov_b32 m0, s49
	s_add_u32 s100, s54, s2
	s_addc_u32 s101, s55, s3
	ds_read_b128 v[170:173], v156 offset:16384
	ds_read_b128 v[174:177], v156 offset:17408
	ds_read_b128 v[178:181], v156 offset:18432
	ds_read_b128 v[182:185], v156 offset:19456
	ds_read_b128 v[186:189], v156 offset:20480
	ds_read_b128 v[190:193], v156 offset:21504
	ds_read_b128 v[194:197], v156 offset:22528
	ds_read_b128 v[202:205], v156 offset:23552
	global_load_lds_dwordx4 v128, s[54:55]
	s_mov_b32 m0, s59
	s_setprio 1
	global_load_lds_dwordx4 v132, s[54:55]
	s_barrier
	s_waitcnt lgkmcnt(0)
	v_mfma_f32_16x16x32_bf16 v[60:63], v[146:149], v[170:173], v[60:63]
	v_mfma_f32_16x16x32_bf16 v[56:59], v[162:165], v[170:173], v[56:59]
	v_mfma_f32_16x16x32_bf16 v[44:47], v[146:149], v[178:181], v[44:47]
	v_mfma_f32_16x16x32_bf16 v[40:43], v[162:165], v[178:181], v[40:43]
	v_mfma_f32_16x16x32_bf16 v[28:31], v[146:149], v[186:189], v[28:31]
	v_mfma_f32_16x16x32_bf16 v[24:27], v[162:165], v[186:189], v[24:27]
	v_mfma_f32_16x16x32_bf16 v[12:15], v[146:149], v[194:197], v[12:15]
	v_mfma_f32_16x16x32_bf16 v[8:11], v[162:165], v[194:197], v[8:11]
	v_mfma_f32_16x16x32_bf16 v[60:63], v[158:161], v[174:177], v[60:63]
	v_mfma_f32_16x16x32_bf16 v[56:59], v[166:169], v[174:177], v[56:59]
	v_mfma_f32_16x16x32_bf16 v[44:47], v[158:161], v[182:185], v[44:47]
	v_mfma_f32_16x16x32_bf16 v[40:43], v[166:169], v[182:185], v[40:43]
	v_mfma_f32_16x16x32_bf16 v[28:31], v[158:161], v[190:193], v[28:31]
	v_mfma_f32_16x16x32_bf16 v[24:27], v[166:169], v[190:193], v[24:27]
	v_mfma_f32_16x16x32_bf16 v[12:15], v[158:161], v[202:205], v[12:15]
	v_mfma_f32_16x16x32_bf16 v[8:11], v[166:169], v[202:205], v[8:11]
	s_barrier
	s_setprio 0
	s_add_u32 s28, s52, 0x80000
	s_addc_u32 s29, s53, 0
	s_add_i32 s69, s82, s58
	s_mov_b32 m0, s69
	s_nop 0
	global_load_lds_dwordx4 v130, s[28:29]
	s_add_i32 m0, s69, 0x2000
	s_setprio 1
	global_load_lds_dwordx4 v134, s[28:29]
	s_waitcnt vmcnt(6)
	s_barrier
; #define PG8_STAGE(bufoff, gbase, voff) do { _Pragma("unroll") for (int _i = 0; _i < 2; ++_i) \
;         __builtin_amdgcn_global_load_lds((const unsigned*)((const char*)(gbase) + (voff)[_i]), (LAS unsigned*)(lds + (bufoff) + ldsw + _i * 8192), 16, 0, 0); } while (0)
; #define PG8_LDA(dst, b, h) do { _Pragma("unroll") for (int m = 0; m < 4; ++m) _Pragma("unroll") for (int k = 0; k < 2; ++k) dst[m][k] = *(const LAS bf16x8*)(lds + PG8_SA(b, h) + aoff + m * 2048 + k * 1024); } while (0)
; #define PG8_LDB(dst, b, h) do { _Pragma("unroll") for (int n = 0; n < 2; ++n) _Pragma("unroll") for (int k = 0; k < 2; ++k) dst[n][k] = *(const LAS bf16x8*)(lds + PG8_SB(b, h) + boff + n * 2048 + k * 1024); } while (0)
; #define PG8_WAIT_V(n) asm volatile("s_waitcnt vmcnt(" #n ")" ::: "memory")
; #define PG8_WAIT_L(n) asm volatile("s_waitcnt lgkmcnt(" #n ")" ::: "memory")
; #define PG8_BAR __builtin_amdgcn_s_barrier()
; #define PG8_SCHED __builtin_amdgcn_sched_barrier(0)
; template <class Epi>
; __device__ __forceinline__ void gemm_phase(LAS unsigned char* lds, const bf16_t* A, int lda, const bf16_t* Bt, int ldb, int M, int N, int K, int asel, const Epi& E, const int fixed_round = -1) {
;     ...
;             PG8_WAIT_V(6); PG8_BAR; PG8_MMA(1, 1, At, B1); PG8_BAR;
;             PG8_LDB(B0, 1, 0); PG8_SCHED; PG8_LDA(At, 1, 0); PG8_STAGE(PG8_SA(0, 1), a2 + hstepA, voffA);
;             PG8_WAIT_L(8); PG8_BAR; PG8_WAIT_L(0); PG8_MMA(0, 0, At, B0); PG8_BAR; PG8_SCHED;
;             PG8_LDB(B1, 1, 1); PG8_STAGE(PG8_SB(1, 0), b3, voffB);
;             PG8_BAR; PG8_WAIT_L(0); PG8_MMA(0, 1, At, B1); PG8_BAR;
;             PG8_LDA(At, 1, 1); PG8_STAGE(PG8_SA(1, 0), a3, voffA);
;             PG8_BAR; PG8_WAIT_L(0); PG8_MMA(1, 0, At, B0); PG8_BAR; PG8_SCHED;
	v_mfma_f32_16x16x32_bf16 v[52:55], v[206:209], v[170:173], v[52:55]
	v_mfma_f32_16x16x32_bf16 v[48:51], v[214:217], v[170:173], v[48:51]
	v_mfma_f32_16x16x32_bf16 v[36:39], v[206:209], v[178:181], v[36:39]
	v_mfma_f32_16x16x32_bf16 v[32:35], v[214:217], v[178:181], v[32:35]
	v_mfma_f32_16x16x32_bf16 v[20:23], v[206:209], v[186:189], v[20:23]
	v_mfma_f32_16x16x32_bf16 v[16:19], v[214:217], v[186:189], v[16:19]
	v_mfma_f32_16x16x32_bf16 v[4:7], v[206:209], v[194:197], v[4:7]
	v_mfma_f32_16x16x32_bf16 v[0:3], v[214:217], v[194:197], v[0:3]
	v_mfma_f32_16x16x32_bf16 v[52:55], v[210:213], v[174:177], v[52:55]
	v_mfma_f32_16x16x32_bf16 v[48:51], v[218:221], v[174:177], v[48:51]
	v_mfma_f32_16x16x32_bf16 v[36:39], v[210:213], v[182:185], v[36:39]
	v_mfma_f32_16x16x32_bf16 v[32:35], v[218:221], v[182:185], v[32:35]
	v_mfma_f32_16x16x32_bf16 v[20:23], v[210:213], v[190:193], v[20:23]
	v_mfma_f32_16x16x32_bf16 v[16:19], v[218:221], v[190:193], v[16:19]
	v_mfma_f32_16x16x32_bf16 v[4:7], v[210:213], v[202:205], v[4:7]
	v_mfma_f32_16x16x32_bf16 v[0:3], v[218:221], v[202:205], v[0:3]
	s_barrier
	s_setprio 0
	v_add_u32_e32 v136, s83, v153
	ds_read_b128 v[146:149], v136
	ds_read_b128 v[158:161], v136 offset:1024
	ds_read_b128 v[162:165], v136 offset:2048
	ds_read_b128 v[166:169], v136 offset:3072
	s_add_u32 s28, s54, 0x80000
	s_addc_u32 s29, s55, 0
	s_mov_b32 m0, s60
	ds_read_b128 v[170:173], v156 offset:32768
	ds_read_b128 v[174:177], v156 offset:33792
	ds_read_b128 v[178:181], v156 offset:34816
	ds_read_b128 v[182:185], v156 offset:35840
	ds_read_b128 v[186:189], v156 offset:36864
	ds_read_b128 v[190:193], v156 offset:37888
	ds_read_b128 v[194:197], v156 offset:38912
	ds_read_b128 v[202:205], v156 offset:39936
	global_load_lds_dwordx4 v128, s[28:29]
	s_mov_b32 m0, s61
	s_setprio 1
	global_load_lds_dwordx4 v132, s[28:29]
	s_waitcnt lgkmcnt(8)
	s_barrier
	s_waitcnt lgkmcnt(0)
	v_mfma_f32_16x16x32_bf16 v[124:127], v[146:149], v[170:173], v[124:127]
	v_mfma_f32_16x16x32_bf16 v[120:123], v[162:165], v[170:173], v[120:123]
	v_mfma_f32_16x16x32_bf16 v[108:111], v[146:149], v[178:181], v[108:111]
	v_mfma_f32_16x16x32_bf16 v[104:107], v[162:165], v[178:181], v[104:107]
	v_mfma_f32_16x16x32_bf16 v[92:95], v[146:149], v[186:189], v[92:95]
	v_mfma_f32_16x16x32_bf16 v[88:91], v[162:165], v[186:189], v[88:91]
	v_mfma_f32_16x16x32_bf16 v[76:79], v[146:149], v[194:197], v[76:79]
	v_mfma_f32_16x16x32_bf16 v[72:75], v[162:165], v[194:197], v[72:75]
	v_mfma_f32_16x16x32_bf16 v[124:127], v[158:161], v[174:177], v[124:127]
	v_mfma_f32_16x16x32_bf16 v[120:123], v[166:169], v[174:177], v[120:123]
	v_mfma_f32_16x16x32_bf16 v[108:111], v[158:161], v[182:185], v[108:111]
	v_mfma_f32_16x16x32_bf16 v[104:107], v[166:169], v[182:185], v[104:107]
	v_mfma_f32_16x16x32_bf16 v[92:95], v[158:161], v[190:193], v[92:95]
	v_mfma_f32_16x16x32_bf16 v[88:91], v[166:169], v[190:193], v[88:91]
	v_mfma_f32_16x16x32_bf16 v[76:79], v[158:161], v[202:205], v[76:79]
	v_mfma_f32_16x16x32_bf16 v[72:75], v[166:169], v[202:205], v[72:75]
	s_barrier
	s_setprio 0
	s_add_i32 s28, s83, s58
	v_add_u32_e32 v136, s84, v153
	s_mov_b32 m0, s28
	ds_read_b128 v[206:209], v136
	ds_read_b128 v[210:213], v136 offset:1024
	ds_read_b128 v[214:217], v136 offset:2048
	ds_read_b128 v[218:221], v136 offset:3072
	global_load_lds_dwordx4 v130, s[98:99]
	s_add_i32 m0, s28, 0x2000
	s_setprio 1
	global_load_lds_dwordx4 v134, s[98:99]
	s_barrier
	s_waitcnt lgkmcnt(0)
	v_mfma_f32_16x16x32_bf16 v[116:119], v[206:209], v[170:173], v[116:119]
	v_mfma_f32_16x16x32_bf16 v[112:115], v[214:217], v[170:173], v[112:115]
	v_mfma_f32_16x16x32_bf16 v[100:103], v[206:209], v[178:181], v[100:103]
	v_mfma_f32_16x16x32_bf16 v[96:99], v[214:217], v[178:181], v[96:99]
	v_mfma_f32_16x16x32_bf16 v[84:87], v[206:209], v[186:189], v[84:87]
	v_mfma_f32_16x16x32_bf16 v[80:83], v[214:217], v[186:189], v[80:83]
	v_mfma_f32_16x16x32_bf16 v[68:71], v[206:209], v[194:197], v[68:71]
	v_mfma_f32_16x16x32_bf16 v[64:67], v[214:217], v[194:197], v[64:67]
	v_mfma_f32_16x16x32_bf16 v[116:119], v[210:213], v[174:177], v[116:119]
	v_mfma_f32_16x16x32_bf16 v[112:115], v[218:221], v[174:177], v[112:115]
	v_mfma_f32_16x16x32_bf16 v[100:103], v[210:213], v[182:185], v[100:103]
	v_mfma_f32_16x16x32_bf16 v[96:99], v[218:221], v[182:185], v[96:99]
	v_mfma_f32_16x16x32_bf16 v[84:87], v[210:213], v[190:193], v[84:87]
	v_mfma_f32_16x16x32_bf16 v[80:83], v[218:221], v[190:193], v[80:83]
	v_mfma_f32_16x16x32_bf16 v[68:71], v[210:213], v[202:205], v[68:71]
	v_mfma_f32_16x16x32_bf16 v[64:67], v[218:221], v[202:205], v[64:67]
	s_barrier
	s_setprio 0
	s_mov_b32 m0, s63
	ds_read_b128 v[170:173], v156 offset:49152
	ds_read_b128 v[174:177], v156 offset:50176
	ds_read_b128 v[178:181], v156 offset:51200
	ds_read_b128 v[182:185], v156 offset:52224
	ds_read_b128 v[186:189], v156 offset:53248
	ds_read_b128 v[190:193], v156 offset:54272
	ds_read_b128 v[194:197], v156 offset:55296
	ds_read_b128 v[202:205], v156 offset:56320
	global_load_lds_dwordx4 v128, s[100:101]
	s_mov_b32 m0, s64
	s_setprio 1
	global_load_lds_dwordx4 v132, s[100:101]
	s_barrier
; __device__ __forceinline__ unsigned cvt_pk_bf16(float lo, float hi) { const bf16x2_t r = __builtin_convertvector((f32x2){lo, hi}, bf16x2_t); return __builtin_bit_cast(unsigned, r); }
; #define PG8_STAGE(bufoff, gbase, voff) do { _Pragma("unroll") for (int _i = 0; _i < 2; ++_i) \
;         __builtin_amdgcn_global_load_lds((const unsigned*)((const char*)(gbase) + (voff)[_i]), (LAS unsigned*)(lds + (bufoff) + ldsw + _i * 8192), 16, 0, 0); } while (0)
; #define PG8_WAIT_V(n) asm volatile("s_waitcnt vmcnt(" #n ")" ::: "memory")
; #define PG8_BAR __builtin_amdgcn_s_barrier()
; template <class Epi>
; __device__ __forceinline__ void gemm_phase(LAS unsigned char* lds, const bf16_t* A, int lda, const bf16_t* Bt, int ldb, int M, int N, int K, int asel, const Epi& E, const int fixed_round = -1) {
;     ...
;             PG8_STAGE(PG8_SB(1, 1), b3 + hstepB, voffB);
;             PG8_WAIT_V(6); PG8_BAR; PG8_MMA(1, 1, At, B1); PG8_BAR;
;     __device__ __forceinline__ void operator()(const AccT& acc, const Unit& u, int wr, int wc, int fr, int fq) const {
;         const int row0 = u.pm * BM + wr * 64 + fr; const bool isg = u.pn >= 8;
;         bf16_t* base = isg ? GB : XB; const int col0 = (u.pn & 7) * BM + wc * 32 + 8 * fq;
; #pragma unroll
;         for (int ai = 0; ai < 2; ++ai)
; #pragma unroll
;             for (int m = 0; m < 4; ++m) { bf16_t* rowp = base + (size_t)(row0 + ai * HALF + m * 16) * DM + col0;
; #pragma unroll
;                 for (int bj = 0; bj < 2; ++bj) { f32x4 v0 = acc[ai][bj][m][0], v1 = acc[ai][bj][m][1];
;                     if (isg) {
; #pragma unroll
;                         for (int j = 0; j < 4; ++j) { float a = v0[j], b = v1[j];
;                             const float ta = 1.5957691216057308f * (a + 0.044715f * a * a * a), tb = 1.5957691216057308f * (b + 0.044715f * b * b * b);
;                             v0[j] = a * __builtin_amdgcn_rcpf(1.0f + __expf(-ta)); v1[j] = b * __builtin_amdgcn_rcpf(1.0f + __expf(-tb)); } }
;                     u32x4 w; w.x = cvt_pk_bf16(v0[0], v0[1]); w.y = cvt_pk_bf16(v0[2], v0[3]); w.z = cvt_pk_bf16(v1[0], v1[1]); w.w = cvt_pk_bf16(v1[2], v1[3]);
;                     *(u32x4*)(rowp + bj * HALF) = w; } }
;     }
	s_waitcnt lgkmcnt(0)
	v_mfma_f32_16x16x32_bf16 v[60:63], v[146:149], v[170:173], v[60:63]
	v_mfma_f32_16x16x32_bf16 v[56:59], v[162:165], v[170:173], v[56:59]
	v_mfma_f32_16x16x32_bf16 v[44:47], v[146:149], v[178:181], v[44:47]
	v_mfma_f32_16x16x32_bf16 v[40:43], v[162:165], v[178:181], v[40:43]
	v_mfma_f32_16x16x32_bf16 v[28:31], v[146:149], v[186:189], v[28:31]
	v_mfma_f32_16x16x32_bf16 v[24:27], v[162:165], v[186:189], v[24:27]
	v_mfma_f32_16x16x32_bf16 v[12:15], v[146:149], v[194:197], v[12:15]
	v_mfma_f32_16x16x32_bf16 v[8:11], v[162:165], v[194:197], v[8:11]
	v_mfma_f32_16x16x32_bf16 v[60:63], v[158:161], v[174:177], v[60:63]
	v_mfma_f32_16x16x32_bf16 v[56:59], v[166:169], v[174:177], v[56:59]
	v_mfma_f32_16x16x32_bf16 v[44:47], v[158:161], v[182:185], v[44:47]
	v_mfma_f32_16x16x32_bf16 v[40:43], v[166:169], v[182:185], v[40:43]
	v_mfma_f32_16x16x32_bf16 v[28:31], v[158:161], v[190:193], v[28:31]
	v_mfma_f32_16x16x32_bf16 v[24:27], v[166:169], v[190:193], v[24:27]
	v_mfma_f32_16x16x32_bf16 v[12:15], v[158:161], v[202:205], v[12:15]
	v_mfma_f32_16x16x32_bf16 v[8:11], v[166:169], v[202:205], v[8:11]
	s_barrier
	s_setprio 0
	s_add_u32 s28, s52, 0x80080
	s_addc_u32 s29, s53, 0
	s_add_i32 s52, s84, s58
	s_mov_b32 m0, s52
	s_nop 0
	global_load_lds_dwordx4 v130, s[28:29]
	s_add_i32 m0, s52, 0x2000
	s_setprio 1
	global_load_lds_dwordx4 v134, s[28:29]
	s_waitcnt vmcnt(6)
	s_barrier
	v_mfma_f32_16x16x32_bf16 v[52:55], v[206:209], v[170:173], v[52:55]
	v_mfma_f32_16x16x32_bf16 v[48:51], v[214:217], v[170:173], v[48:51]
	v_mfma_f32_16x16x32_bf16 v[36:39], v[206:209], v[178:181], v[36:39]
	v_mfma_f32_16x16x32_bf16 v[32:35], v[214:217], v[178:181], v[32:35]
	v_mfma_f32_16x16x32_bf16 v[20:23], v[206:209], v[186:189], v[20:23]
	v_mfma_f32_16x16x32_bf16 v[16:19], v[214:217], v[186:189], v[16:19]
	v_mfma_f32_16x16x32_bf16 v[4:7], v[206:209], v[194:197], v[4:7]
	v_mfma_f32_16x16x32_bf16 v[0:3], v[214:217], v[194:197], v[0:3]
	v_mfma_f32_16x16x32_bf16 v[52:55], v[210:213], v[174:177], v[52:55]
	v_mfma_f32_16x16x32_bf16 v[48:51], v[218:221], v[174:177], v[48:51]
	v_mfma_f32_16x16x32_bf16 v[36:39], v[210:213], v[182:185], v[36:39]
	v_mfma_f32_16x16x32_bf16 v[32:35], v[218:221], v[182:185], v[32:35]
	v_mfma_f32_16x16x32_bf16 v[20:23], v[210:213], v[190:193], v[20:23]
	v_mfma_f32_16x16x32_bf16 v[16:19], v[218:221], v[190:193], v[16:19]
	v_mfma_f32_16x16x32_bf16 v[4:7], v[210:213], v[202:205], v[4:7]
	v_mfma_f32_16x16x32_bf16 v[0:3], v[218:221], v[202:205], v[0:3]
	s_setprio 0
	s_add_i32 s68, s68, 2
	s_add_u32 s50, s50, 0x100
	s_addc_u32 s51, s51, 0
	s_add_u32 s66, s66, 0x100
	s_addc_u32 s67, s67, 0
	s_cmp_gt_u32 s68, 29
	s_cbranch_scc0 .Lrot_7
	s_barrier
	s_cmp_gt_i32 s4, 7
	s_cselect_b64 s[50:51], -1, 0
	s_cmp_lt_i32 s4, 8
	s_cbranch_scc1 .LBB0_802
	v_mul_f32_e32 v136, 0x3d372713, v124
	v_mul_f32_e32 v136, v124, v136
	v_mul_f32_e32 v146, 0x3d372713, v120
	v_fma_f32 v136, v124, v136, v124
	v_mul_f32_e32 v146, v120, v146
	v_fma_f32 v146, v120, v146, v120
	v_mul_f32_e32 v136, 0xbfcc422a, v136
	v_mul_f32_e32 v136, 0x3fb8aa3b, v136
	v_mul_f32_e32 v146, 0xbfcc422a, v146
	v_exp_f32_e32 v136, v136
	v_mul_f32_e32 v146, 0x3fb8aa3b, v146
	v_exp_f32_e32 v147, v146
	v_mul_f32_e32 v150, 0x3d372713, v122
	v_add_f32_e32 v136, 1.0, v136
	v_rcp_f32_e32 v146, v136
	v_add_f32_e32 v136, 1.0, v147
	v_rcp_f32_e32 v148, v136
	v_mul_f32_e32 v136, 0x3d372713, v125
	v_mul_f32_e32 v136, v125, v136
	v_fma_f32 v136, v125, v136, v125
	v_mul_f32_e32 v136, 0xbfcc422a, v136
	v_mul_f32_e32 v136, 0x3fb8aa3b, v136
	v_exp_f32_e32 v136, v136
	v_mul_f32_e32 v147, 0x3d372713, v121
	v_mul_f32_e32 v147, v121, v147
	v_fma_f32 v149, v121, v147, v121
	v_add_f32_e32 v136, 1.0, v136
	v_rcp_f32_e32 v147, v136
	v_mul_f32_e32 v136, 0xbfcc422a, v149
	v_mul_f32_e32 v149, 0x3d372713, v126
	v_mul_f32_e32 v149, v126, v149
	v_fma_f32 v149, v126, v149, v126
	v_mul_f32_e32 v150, v122, v150
	v_fma_f32 v150, v122, v150, v122
	v_mul_f32_e32 v149, 0xbfcc422a, v149
	v_mul_f32_e32 v149, 0x3fb8aa3b, v149
	v_mul_f32_e32 v150, 0xbfcc422a, v150
	v_exp_f32_e32 v149, v149
	v_mul_f32_e32 v150, 0x3fb8aa3b, v150
	v_exp_f32_e32 v151, v150
	v_mul_f32_e32 v158, 0x3d372713, v123
	v_add_f32_e32 v149, 1.0, v149
	v_rcp_f32_e32 v150, v149
	v_add_f32_e32 v149, 1.0, v151
	v_mul_f32_e32 v151, 0x3d372713, v127
	v_mul_f32_e32 v151, v127, v151
	v_fma_f32 v151, v127, v151, v127
	v_mul_f32_e32 v158, v123, v158
	v_fma_f32 v158, v123, v158, v123
	v_mul_f32_e32 v151, 0xbfcc422a, v151
	v_mul_f32_e32 v151, 0x3fb8aa3b, v151
	v_mul_f32_e32 v158, 0xbfcc422a, v158
	v_mul_f32_e32 v136, 0x3fb8aa3b, v136
	v_exp_f32_e32 v151, v151
	v_mul_f32_e32 v158, 0x3fb8aa3b, v158
	v_exp_f32_e32 v136, v136
	v_exp_f32_e32 v159, v158
	v_rcp_f32_e32 v158, v149
	v_add_f32_e32 v149, 1.0, v151
	v_add_f32_e32 v136, 1.0, v136
	v_rcp_f32_e32 v151, v149
	v_add_f32_e32 v149, 1.0, v159
	v_rcp_f32_e32 v159, v149
	v_rcp_f32_e32 v149, v136
	v_pk_mul_f32 v[126:127], v[126:127], v[150:151]
	v_pk_mul_f32 v[124:125], v[124:125], v[146:147]
	v_pk_mul_f32 v[122:123], v[122:123], v[158:159]
	v_pk_mul_f32 v[120:121], v[120:121], v[148:149]

; #define PG8_STAGE(bufoff, gbase, voff) do { _Pragma("unroll") for (int _i = 0; _i < 2; ++_i) \
;         __builtin_amdgcn_global_load_lds((const unsigned*)((const char*)(gbase) + (voff)[_i]), (LAS unsigned*)(lds + (bufoff) + ldsw + _i * 8192), 16, 0, 0); } while (0)
; #define PG8_LDA(dst, b, h) do { _Pragma("unroll") for (int m = 0; m < 4; ++m) _Pragma("unroll") for (int k = 0; k < 2; ++k) dst[m][k] = *(const LAS bf16x8*)(lds + PG8_SA(b, h) + aoff + m * 2048 + k * 1024); } while (0)
; #define PG8_LDB(dst, b, h) do { _Pragma("unroll") for (int n = 0; n < 2; ++n) _Pragma("unroll") for (int k = 0; k < 2; ++k) dst[n][k] = *(const LAS bf16x8*)(lds + PG8_SB(b, h) + boff + n * 2048 + k * 1024); } while (0)
; #define PG8_WAIT_V(n) asm volatile("s_waitcnt vmcnt(" #n ")" ::: "memory")
; #define PG8_WAIT_L(n) asm volatile("s_waitcnt lgkmcnt(" #n ")" ::: "memory")
; #define PG8_BAR __builtin_amdgcn_s_barrier()
; #define PG8_SCHED __builtin_amdgcn_sched_barrier(0)
; template <class Epi>
; __device__ __forceinline__ void gemm_phase(LAS unsigned char* lds, const bf16_t* A, int lda, const bf16_t* Bt, int ldb, int M, int N, int K, int asel, const Epi& E, const int fixed_round = -1) {
;     ...
;         for (int t = 0; t < nt; t += 2) {
;             const bool last = (t == nt - 2);
;             const char* a1 = cA + (size_t)(t + 1) * kstep;
;             const char* a2 = last ? nA : cA + (size_t)(t + 2) * kstep; const char* b2 = last ? nB : cB + (size_t)(t + 2) * kstep;
;             const char* a3 = a2 + kstep; const char* b3 = b2 + kstep;
;             PG8_LDB(B0, 0, 0); PG8_SCHED; PG8_LDA(At, 0, 0); PG8_STAGE(PG8_SA(1, 1), a1 + hstepA, voffA);
;             PG8_WAIT_L(8); PG8_BAR; PG8_WAIT_L(0); PG8_MMA(0, 0, At, B0); PG8_BAR; PG8_SCHED;
;             PG8_LDB(B1, 0, 1); PG8_STAGE(PG8_SB(0, 0), b2, voffB);
;             PG8_BAR; PG8_WAIT_L(0); PG8_MMA(0, 1, At, B1); PG8_BAR;
;             PG8_LDA(At, 0, 1); PG8_STAGE(PG8_SA(0, 0), a2, voffA);
;             PG8_BAR; PG8_WAIT_L(0); PG8_MMA(1, 0, At, B0); PG8_BAR; PG8_SCHED;
;             PG8_STAGE(PG8_SB(0, 1), b2 + hstepB, voffB);
;             PG8_WAIT_V(6); PG8_BAR; PG8_MMA(1, 1, At, B1); PG8_BAR;
.LBB0_1081:
	ds_read_b128 v[146:149], v140
	ds_read_b128 v[150:153], v140 offset:1024
	ds_read_b128 v[160:163], v140 offset:2048
	ds_read_b128 v[166:169], v140 offset:3072
	s_mov_b32 m0, s57
	v_lshl_add_u64 v[156:157], v[136:137], 0, s[22:23]
	ds_read_b128 v[170:173], v141
	ds_read_b128 v[174:177], v141 offset:1024
	ds_read_b128 v[178:181], v141 offset:2048
	ds_read_b128 v[182:185], v141 offset:3072
	ds_read_b128 v[186:189], v141 offset:4096
	ds_read_b128 v[190:193], v141 offset:5120
	ds_read_b128 v[194:197], v141 offset:6144
	ds_read_b128 v[202:205], v141 offset:7168
	global_load_lds_dwordx4 v[156:157], off
	v_lshl_add_u64 v[156:157], v[138:139], 0, s[22:23]
	s_mov_b32 m0, s58
	s_setprio 1
	global_load_lds_dwordx4 v[156:157], off
	s_waitcnt lgkmcnt(8)
	s_barrier
	s_waitcnt lgkmcnt(0)
	v_mfma_f32_16x16x32_bf16 v[124:127], v[146:149], v[170:173], v[124:127]
	v_mfma_f32_16x16x32_bf16 v[120:123], v[160:163], v[170:173], v[120:123]
	v_mfma_f32_16x16x32_bf16 v[112:115], v[146:149], v[178:181], v[112:115]
	v_mfma_f32_16x16x32_bf16 v[104:107], v[160:163], v[178:181], v[104:107]
	v_mfma_f32_16x16x32_bf16 v[96:99], v[146:149], v[186:189], v[96:99]
	v_mfma_f32_16x16x32_bf16 v[88:91], v[160:163], v[186:189], v[88:91]
	v_mfma_f32_16x16x32_bf16 v[80:83], v[146:149], v[194:197], v[80:83]
	v_mfma_f32_16x16x32_bf16 v[72:75], v[160:163], v[194:197], v[72:75]
	v_mfma_f32_16x16x32_bf16 v[124:127], v[150:153], v[174:177], v[124:127]
	v_mfma_f32_16x16x32_bf16 v[120:123], v[166:169], v[174:177], v[120:123]
	v_mfma_f32_16x16x32_bf16 v[112:115], v[150:153], v[182:185], v[112:115]
	v_mfma_f32_16x16x32_bf16 v[104:107], v[166:169], v[182:185], v[104:107]
	v_mfma_f32_16x16x32_bf16 v[96:99], v[150:153], v[190:193], v[96:99]
	v_mfma_f32_16x16x32_bf16 v[88:91], v[166:169], v[190:193], v[88:91]
	v_mfma_f32_16x16x32_bf16 v[80:83], v[150:153], v[202:205], v[80:83]
	v_mfma_f32_16x16x32_bf16 v[72:75], v[166:169], v[202:205], v[72:75]
	s_barrier
	s_setprio 0
	s_add_u32 s28, s22, 0xdfa80080
	s_addc_u32 s29, s23, -1
	s_cmp_lg_u32 s56, 28
	s_cselect_b32 s28, s28, 0
	s_cselect_b32 s29, s29, 0
	s_add_u32 s46, s0, s28
	s_addc_u32 s47, s1, s29
	s_add_u32 s44, s2, s28
	s_addc_u32 s45, s3, s29
	s_mov_b32 m0, s59
	s_add_u32 s98, s44, s42
	s_addc_u32 s99, s45, s43
	ds_read_b128 v[206:209], v142
	ds_read_b128 v[210:213], v142 offset:1024
	ds_read_b128 v[214:217], v142 offset:2048
	ds_read_b128 v[218:221], v142 offset:3072
	global_load_lds_dwordx4 v130, s[44:45]
	s_mov_b32 m0, s60
	s_setprio 1
	global_load_lds_dwordx4 v134, s[44:45]
	s_barrier
	s_waitcnt lgkmcnt(0)
	v_mfma_f32_16x16x32_bf16 v[116:119], v[206:209], v[170:173], v[116:119]
	v_mfma_f32_16x16x32_bf16 v[108:111], v[214:217], v[170:173], v[108:111]
	v_mfma_f32_16x16x32_bf16 v[100:103], v[206:209], v[178:181], v[100:103]
	v_mfma_f32_16x16x32_bf16 v[92:95], v[214:217], v[178:181], v[92:95]
	v_mfma_f32_16x16x32_bf16 v[84:87], v[206:209], v[186:189], v[84:87]
	v_mfma_f32_16x16x32_bf16 v[76:79], v[214:217], v[186:189], v[76:79]
	v_mfma_f32_16x16x32_bf16 v[68:71], v[206:209], v[194:197], v[68:71]
	v_mfma_f32_16x16x32_bf16 v[64:67], v[214:217], v[194:197], v[64:67]
	v_mfma_f32_16x16x32_bf16 v[116:119], v[210:213], v[174:177], v[116:119]
	v_mfma_f32_16x16x32_bf16 v[108:111], v[218:221], v[174:177], v[108:111]
	v_mfma_f32_16x16x32_bf16 v[100:103], v[210:213], v[182:185], v[100:103]
	v_mfma_f32_16x16x32_bf16 v[92:95], v[218:221], v[182:185], v[92:95]
	v_mfma_f32_16x16x32_bf16 v[84:87], v[210:213], v[190:193], v[84:87]
	v_mfma_f32_16x16x32_bf16 v[76:79], v[218:221], v[190:193], v[76:79]
	v_mfma_f32_16x16x32_bf16 v[68:71], v[210:213], v[202:205], v[68:71]
	v_mfma_f32_16x16x32_bf16 v[64:67], v[218:221], v[202:205], v[64:67]
	s_barrier
	s_setprio 0
	s_mov_b32 m0, s49
	s_add_u32 s100, s46, s42
	s_addc_u32 s101, s47, s43
	ds_read_b128 v[170:173], v141 offset:16384
	ds_read_b128 v[174:177], v141 offset:17408
	ds_read_b128 v[178:181], v141 offset:18432
	ds_read_b128 v[182:185], v141 offset:19456
	ds_read_b128 v[186:189], v141 offset:20480
	ds_read_b128 v[190:193], v141 offset:21504
	ds_read_b128 v[194:197], v141 offset:22528
	ds_read_b128 v[202:205], v141 offset:23552
	global_load_lds_dwordx4 v128, s[46:47]
	s_mov_b32 m0, s50
	s_setprio 1
	global_load_lds_dwordx4 v132, s[46:47]
	s_barrier
	s_waitcnt lgkmcnt(0)
	v_mfma_f32_16x16x32_bf16 v[60:63], v[146:149], v[170:173], v[60:63]
	v_mfma_f32_16x16x32_bf16 v[56:59], v[160:163], v[170:173], v[56:59]
	v_mfma_f32_16x16x32_bf16 v[48:51], v[146:149], v[178:181], v[48:51]
	v_mfma_f32_16x16x32_bf16 v[40:43], v[160:163], v[178:181], v[40:43]
	v_mfma_f32_16x16x32_bf16 v[32:35], v[146:149], v[186:189], v[32:35]
	v_mfma_f32_16x16x32_bf16 v[24:27], v[160:163], v[186:189], v[24:27]
	v_mfma_f32_16x16x32_bf16 v[16:19], v[146:149], v[194:197], v[16:19]
	v_mfma_f32_16x16x32_bf16 v[8:11], v[160:163], v[194:197], v[8:11]
	v_mfma_f32_16x16x32_bf16 v[60:63], v[150:153], v[174:177], v[60:63]
	v_mfma_f32_16x16x32_bf16 v[56:59], v[166:169], v[174:177], v[56:59]
	v_mfma_f32_16x16x32_bf16 v[48:51], v[150:153], v[182:185], v[48:51]
	v_mfma_f32_16x16x32_bf16 v[40:43], v[166:169], v[182:185], v[40:43]
	v_mfma_f32_16x16x32_bf16 v[32:35], v[150:153], v[190:193], v[32:35]
	v_mfma_f32_16x16x32_bf16 v[24:27], v[166:169], v[190:193], v[24:27]
	v_mfma_f32_16x16x32_bf16 v[16:19], v[150:153], v[202:205], v[16:19]
	v_mfma_f32_16x16x32_bf16 v[8:11], v[166:169], v[202:205], v[8:11]
	s_barrier
	s_setprio 0
	s_add_u32 s28, s44, 0x80000
	s_addc_u32 s29, s45, 0
	s_mov_b32 m0, s61
	s_nop 0
	global_load_lds_dwordx4 v130, s[28:29]
	s_mov_b32 m0, s62
	s_setprio 1
	global_load_lds_dwordx4 v134, s[28:29]
	s_waitcnt vmcnt(6)
	s_barrier
; #define PG8_STAGE(bufoff, gbase, voff) do { _Pragma("unroll") for (int _i = 0; _i < 2; ++_i) \
;         __builtin_amdgcn_global_load_lds((const unsigned*)((const char*)(gbase) + (voff)[_i]), (LAS unsigned*)(lds + (bufoff) + ldsw + _i * 8192), 16, 0, 0); } while (0)
; #define PG8_LDA(dst, b, h) do { _Pragma("unroll") for (int m = 0; m < 4; ++m) _Pragma("unroll") for (int k = 0; k < 2; ++k) dst[m][k] = *(const LAS bf16x8*)(lds + PG8_SA(b, h) + aoff + m * 2048 + k * 1024); } while (0)
; #define PG8_LDB(dst, b, h) do { _Pragma("unroll") for (int n = 0; n < 2; ++n) _Pragma("unroll") for (int k = 0; k < 2; ++k) dst[n][k] = *(const LAS bf16x8*)(lds + PG8_SB(b, h) + boff + n * 2048 + k * 1024); } while (0)
; #define PG8_WAIT_V(n) asm volatile("s_waitcnt vmcnt(" #n ")" ::: "memory")
; #define PG8_WAIT_L(n) asm volatile("s_waitcnt lgkmcnt(" #n ")" ::: "memory")
; #define PG8_BAR __builtin_amdgcn_s_barrier()
; #define PG8_SCHED __builtin_amdgcn_sched_barrier(0)
; template <class Epi>
; __device__ __forceinline__ void gemm_phase(LAS unsigned char* lds, const bf16_t* A, int lda, const bf16_t* Bt, int ldb, int M, int N, int K, int asel, const Epi& E, const int fixed_round = -1) {
;     ...
;             PG8_WAIT_V(6); PG8_BAR; PG8_MMA(1, 1, At, B1); PG8_BAR;
;             PG8_LDB(B0, 1, 0); PG8_SCHED; PG8_LDA(At, 1, 0); PG8_STAGE(PG8_SA(0, 1), a2 + hstepA, voffA);
;             PG8_WAIT_L(8); PG8_BAR; PG8_WAIT_L(0); PG8_MMA(0, 0, At, B0); PG8_BAR; PG8_SCHED;
;             PG8_LDB(B1, 1, 1); PG8_STAGE(PG8_SB(1, 0), b3, voffB);
;             PG8_BAR; PG8_WAIT_L(0); PG8_MMA(0, 1, At, B1); PG8_BAR;
	v_mfma_f32_16x16x32_bf16 v[52:55], v[206:209], v[170:173], v[52:55]
	v_mfma_f32_16x16x32_bf16 v[44:47], v[214:217], v[170:173], v[44:47]
	v_mfma_f32_16x16x32_bf16 v[36:39], v[206:209], v[178:181], v[36:39]
	v_mfma_f32_16x16x32_bf16 v[28:31], v[214:217], v[178:181], v[28:31]
	v_mfma_f32_16x16x32_bf16 v[20:23], v[206:209], v[186:189], v[20:23]
	v_mfma_f32_16x16x32_bf16 v[12:15], v[214:217], v[186:189], v[12:15]
	v_mfma_f32_16x16x32_bf16 v[4:7], v[206:209], v[194:197], v[4:7]
	v_mfma_f32_16x16x32_bf16 v[0:3], v[214:217], v[194:197], v[0:3]
	v_mfma_f32_16x16x32_bf16 v[52:55], v[210:213], v[174:177], v[52:55]
	v_mfma_f32_16x16x32_bf16 v[44:47], v[218:221], v[174:177], v[44:47]
	v_mfma_f32_16x16x32_bf16 v[36:39], v[210:213], v[182:185], v[36:39]
	v_mfma_f32_16x16x32_bf16 v[28:31], v[218:221], v[182:185], v[28:31]
	v_mfma_f32_16x16x32_bf16 v[20:23], v[210:213], v[190:193], v[20:23]
	v_mfma_f32_16x16x32_bf16 v[12:15], v[218:221], v[190:193], v[12:15]
	v_mfma_f32_16x16x32_bf16 v[4:7], v[210:213], v[202:205], v[4:7]
	v_mfma_f32_16x16x32_bf16 v[0:3], v[218:221], v[202:205], v[0:3]
	s_barrier
	s_setprio 0
	ds_read_b128 v[146:149], v143
	ds_read_b128 v[150:153], v143 offset:1024
	ds_read_b128 v[160:163], v143 offset:2048
	ds_read_b128 v[166:169], v143 offset:3072
	s_add_u32 s28, s46, 0x80000
	s_addc_u32 s29, s47, 0
	s_mov_b32 m0, s52
	ds_read_b128 v[170:173], v141 offset:32768
	ds_read_b128 v[174:177], v141 offset:33792
	ds_read_b128 v[178:181], v141 offset:34816
	ds_read_b128 v[182:185], v141 offset:35840
	ds_read_b128 v[186:189], v141 offset:36864
	ds_read_b128 v[190:193], v141 offset:37888
	ds_read_b128 v[194:197], v141 offset:38912
	ds_read_b128 v[202:205], v141 offset:39936
	global_load_lds_dwordx4 v128, s[28:29]
	s_mov_b32 m0, s53
	s_setprio 1
	global_load_lds_dwordx4 v132, s[28:29]
	s_waitcnt lgkmcnt(8)
	s_barrier
	s_waitcnt lgkmcnt(0)
	v_mfma_f32_16x16x32_bf16 v[124:127], v[146:149], v[170:173], v[124:127]
	v_mfma_f32_16x16x32_bf16 v[120:123], v[160:163], v[170:173], v[120:123]
	v_mfma_f32_16x16x32_bf16 v[112:115], v[146:149], v[178:181], v[112:115]
	v_mfma_f32_16x16x32_bf16 v[104:107], v[160:163], v[178:181], v[104:107]
	v_mfma_f32_16x16x32_bf16 v[96:99], v[146:149], v[186:189], v[96:99]
	v_mfma_f32_16x16x32_bf16 v[88:91], v[160:163], v[186:189], v[88:91]
	v_mfma_f32_16x16x32_bf16 v[80:83], v[146:149], v[194:197], v[80:83]
	v_mfma_f32_16x16x32_bf16 v[72:75], v[160:163], v[194:197], v[72:75]
	v_mfma_f32_16x16x32_bf16 v[124:127], v[150:153], v[174:177], v[124:127]
	v_mfma_f32_16x16x32_bf16 v[120:123], v[166:169], v[174:177], v[120:123]
	v_mfma_f32_16x16x32_bf16 v[112:115], v[150:153], v[182:185], v[112:115]
	v_mfma_f32_16x16x32_bf16 v[104:107], v[166:169], v[182:185], v[104:107]
	v_mfma_f32_16x16x32_bf16 v[96:99], v[150:153], v[190:193], v[96:99]
	v_mfma_f32_16x16x32_bf16 v[88:91], v[166:169], v[190:193], v[88:91]
	v_mfma_f32_16x16x32_bf16 v[80:83], v[150:153], v[202:205], v[80:83]
	v_mfma_f32_16x16x32_bf16 v[72:75], v[166:169], v[202:205], v[72:75]
	s_barrier
	s_setprio 0
	s_mov_b32 m0, s63
	ds_read_b128 v[206:209], v144
	ds_read_b128 v[210:213], v144 offset:1024
	ds_read_b128 v[214:217], v144 offset:2048
	ds_read_b128 v[218:221], v144 offset:3072
	global_load_lds_dwordx4 v130, s[98:99]
	s_mov_b32 m0, s64
	s_setprio 1
	global_load_lds_dwordx4 v134, s[98:99]
	s_barrier
; #define PG8_STAGE(bufoff, gbase, voff) do { _Pragma("unroll") for (int _i = 0; _i < 2; ++_i) \
;         __builtin_amdgcn_global_load_lds((const unsigned*)((const char*)(gbase) + (voff)[_i]), (LAS unsigned*)(lds + (bufoff) + ldsw + _i * 8192), 16, 0, 0); } while (0)
; #define PG8_LDA(dst, b, h) do { _Pragma("unroll") for (int m = 0; m < 4; ++m) _Pragma("unroll") for (int k = 0; k < 2; ++k) dst[m][k] = *(const LAS bf16x8*)(lds + PG8_SA(b, h) + aoff + m * 2048 + k * 1024); } while (0)
; #define PG8_WAIT_V(n) asm volatile("s_waitcnt vmcnt(" #n ")" ::: "memory")
; #define PG8_WAIT_L(n) asm volatile("s_waitcnt lgkmcnt(" #n ")" ::: "memory")
; #define PG8_BAR __builtin_amdgcn_s_barrier()
; #define PG8_SCHED __builtin_amdgcn_sched_barrier(0)
; template <class Epi>
; __device__ __forceinline__ void gemm_phase(LAS unsigned char* lds, const bf16_t* A, int lda, const bf16_t* Bt, int ldb, int M, int N, int K, int asel, const Epi& E, const int fixed_round = -1) {
;     ...
;             PG8_BAR; PG8_WAIT_L(0); PG8_MMA(0, 1, At, B1); PG8_BAR;
;             PG8_LDA(At, 1, 1); PG8_STAGE(PG8_SA(1, 0), a3, voffA);
;             PG8_BAR; PG8_WAIT_L(0); PG8_MMA(1, 0, At, B0); PG8_BAR; PG8_SCHED;
;             PG8_STAGE(PG8_SB(1, 1), b3 + hstepB, voffB);
;             PG8_WAIT_V(6); PG8_BAR; PG8_MMA(1, 1, At, B1); PG8_BAR;
	s_waitcnt lgkmcnt(0)
	v_mfma_f32_16x16x32_bf16 v[116:119], v[206:209], v[170:173], v[116:119]
	v_mfma_f32_16x16x32_bf16 v[108:111], v[214:217], v[170:173], v[108:111]
	v_mfma_f32_16x16x32_bf16 v[100:103], v[206:209], v[178:181], v[100:103]
	v_mfma_f32_16x16x32_bf16 v[92:95], v[214:217], v[178:181], v[92:95]
	v_mfma_f32_16x16x32_bf16 v[84:87], v[206:209], v[186:189], v[84:87]
	v_mfma_f32_16x16x32_bf16 v[76:79], v[214:217], v[186:189], v[76:79]
	v_mfma_f32_16x16x32_bf16 v[68:71], v[206:209], v[194:197], v[68:71]
	v_mfma_f32_16x16x32_bf16 v[64:67], v[214:217], v[194:197], v[64:67]
	v_mfma_f32_16x16x32_bf16 v[116:119], v[210:213], v[174:177], v[116:119]
	v_mfma_f32_16x16x32_bf16 v[108:111], v[218:221], v[174:177], v[108:111]
	v_mfma_f32_16x16x32_bf16 v[100:103], v[210:213], v[182:185], v[100:103]
	v_mfma_f32_16x16x32_bf16 v[92:95], v[218:221], v[182:185], v[92:95]
	v_mfma_f32_16x16x32_bf16 v[84:87], v[210:213], v[190:193], v[84:87]
	v_mfma_f32_16x16x32_bf16 v[76:79], v[218:221], v[190:193], v[76:79]
	v_mfma_f32_16x16x32_bf16 v[68:71], v[210:213], v[202:205], v[68:71]
	v_mfma_f32_16x16x32_bf16 v[64:67], v[218:221], v[202:205], v[64:67]
	s_barrier
	s_setprio 0
	s_mov_b32 m0, s54
	ds_read_b128 v[170:173], v141 offset:49152
	ds_read_b128 v[174:177], v141 offset:50176
	ds_read_b128 v[178:181], v141 offset:51200
	ds_read_b128 v[182:185], v141 offset:52224
	ds_read_b128 v[186:189], v141 offset:53248
	ds_read_b128 v[190:193], v141 offset:54272
	ds_read_b128 v[194:197], v141 offset:55296
	ds_read_b128 v[202:205], v141 offset:56320
	global_load_lds_dwordx4 v128, s[100:101]
	s_mov_b32 m0, s55
	s_setprio 1
	global_load_lds_dwordx4 v132, s[100:101]
	s_barrier
	s_waitcnt lgkmcnt(0)
	v_mfma_f32_16x16x32_bf16 v[60:63], v[146:149], v[170:173], v[60:63]
	v_mfma_f32_16x16x32_bf16 v[56:59], v[160:163], v[170:173], v[56:59]
	v_mfma_f32_16x16x32_bf16 v[48:51], v[146:149], v[178:181], v[48:51]
	v_mfma_f32_16x16x32_bf16 v[40:43], v[160:163], v[178:181], v[40:43]
	v_mfma_f32_16x16x32_bf16 v[32:35], v[146:149], v[186:189], v[32:35]
	v_mfma_f32_16x16x32_bf16 v[24:27], v[160:163], v[186:189], v[24:27]
	v_mfma_f32_16x16x32_bf16 v[16:19], v[146:149], v[194:197], v[16:19]
	v_mfma_f32_16x16x32_bf16 v[8:11], v[160:163], v[194:197], v[8:11]
	v_mfma_f32_16x16x32_bf16 v[60:63], v[150:153], v[174:177], v[60:63]
	v_mfma_f32_16x16x32_bf16 v[56:59], v[166:169], v[174:177], v[56:59]
	v_mfma_f32_16x16x32_bf16 v[48:51], v[150:153], v[182:185], v[48:51]
	v_mfma_f32_16x16x32_bf16 v[40:43], v[166:169], v[182:185], v[40:43]
	v_mfma_f32_16x16x32_bf16 v[32:35], v[150:153], v[190:193], v[32:35]
	v_mfma_f32_16x16x32_bf16 v[24:27], v[166:169], v[190:193], v[24:27]
	v_mfma_f32_16x16x32_bf16 v[16:19], v[150:153], v[202:205], v[16:19]
	v_mfma_f32_16x16x32_bf16 v[8:11], v[166:169], v[202:205], v[8:11]
	s_barrier
	s_setprio 0
	s_add_u32 s28, s44, 0x80080
	s_addc_u32 s29, s45, 0
	s_mov_b32 m0, s65
	s_nop 0
	global_load_lds_dwordx4 v130, s[28:29]
	s_mov_b32 m0, s66
	s_setprio 1
	global_load_lds_dwordx4 v134, s[28:29]
	s_waitcnt vmcnt(6)
	s_barrier
	v_mfma_f32_16x16x32_bf16 v[52:55], v[206:209], v[170:173], v[52:55]
	v_mfma_f32_16x16x32_bf16 v[44:47], v[214:217], v[170:173], v[44:47]
	v_mfma_f32_16x16x32_bf16 v[36:39], v[206:209], v[178:181], v[36:39]
	v_mfma_f32_16x16x32_bf16 v[28:31], v[214:217], v[178:181], v[28:31]
	v_mfma_f32_16x16x32_bf16 v[20:23], v[206:209], v[186:189], v[20:23]
	v_mfma_f32_16x16x32_bf16 v[12:15], v[214:217], v[186:189], v[12:15]
	v_mfma_f32_16x16x32_bf16 v[4:7], v[206:209], v[194:197], v[4:7]
	v_mfma_f32_16x16x32_bf16 v[0:3], v[214:217], v[194:197], v[0:3]
	v_mfma_f32_16x16x32_bf16 v[52:55], v[210:213], v[174:177], v[52:55]
	v_mfma_f32_16x16x32_bf16 v[44:47], v[218:221], v[174:177], v[44:47]
	v_mfma_f32_16x16x32_bf16 v[36:39], v[210:213], v[182:185], v[36:39]
	v_mfma_f32_16x16x32_bf16 v[28:31], v[218:221], v[182:185], v[28:31]
	v_mfma_f32_16x16x32_bf16 v[20:23], v[210:213], v[190:193], v[20:23]
	v_mfma_f32_16x16x32_bf16 v[12:15], v[218:221], v[190:193], v[12:15]
	v_mfma_f32_16x16x32_bf16 v[4:7], v[210:213], v[202:205], v[4:7]
	v_mfma_f32_16x16x32_bf16 v[0:3], v[218:221], v[202:205], v[0:3]
	s_setprio 0
	s_add_i32 s56, s56, 2
	s_add_u32 s22, s22, 0x100
	s_addc_u32 s23, s23, 0
	s_cmp_lt_u32 s56, 30
	s_cbranch_scc1 .Lrot_8
	s_barrier
	s_waitcnt vmcnt(0)
	s_cmpk_gt_u32 s48, 0xff
	s_cbranch_scc1 .LBB0_1084
	s_barrier

; #define PG8_STAGE(bufoff, gbase, voff) do { _Pragma("unroll") for (int _i = 0; _i < 2; ++_i) \
;         __builtin_amdgcn_global_load_lds((const unsigned*)((const char*)(gbase) + (voff)[_i]), (LAS unsigned*)(lds + (bufoff) + ldsw + _i * 8192), 16, 0, 0); } while (0)
; #define PG8_LDA(dst, b, h) do { _Pragma("unroll") for (int m = 0; m < 4; ++m) _Pragma("unroll") for (int k = 0; k < 2; ++k) dst[m][k] = *(const LAS bf16x8*)(lds + PG8_SA(b, h) + aoff + m * 2048 + k * 1024); } while (0)
; #define PG8_LDB(dst, b, h) do { _Pragma("unroll") for (int n = 0; n < 2; ++n) _Pragma("unroll") for (int k = 0; k < 2; ++k) dst[n][k] = *(const LAS bf16x8*)(lds + PG8_SB(b, h) + boff + n * 2048 + k * 1024); } while (0)
; #define PG8_WAIT_V(n) asm volatile("s_waitcnt vmcnt(" #n ")" ::: "memory")
; #define PG8_WAIT_L(n) asm volatile("s_waitcnt lgkmcnt(" #n ")" ::: "memory")
; #define PG8_BAR __builtin_amdgcn_s_barrier()
; #define PG8_SCHED __builtin_amdgcn_sched_barrier(0)
; template <class Epi>
; __device__ __forceinline__ void gemm_phase(LAS unsigned char* lds, const bf16_t* A, int lda, const bf16_t* Bt, int ldb, int M, int N, int K, int asel, const Epi& E, const int fixed_round = -1) {
;     ...
;         for (int t = 0; t < nt; t += 2) {
;             const bool last = (t == nt - 2);
;             const char* a1 = cA + (size_t)(t + 1) * kstep;
;             const char* a2 = last ? nA : cA + (size_t)(t + 2) * kstep; const char* b2 = last ? nB : cB + (size_t)(t + 2) * kstep;
;             const char* a3 = a2 + kstep; const char* b3 = b2 + kstep;
;             PG8_LDB(B0, 0, 0); PG8_SCHED; PG8_LDA(At, 0, 0); PG8_STAGE(PG8_SA(1, 1), a1 + hstepA, voffA);
;             PG8_WAIT_L(8); PG8_BAR; PG8_WAIT_L(0); PG8_MMA(0, 0, At, B0); PG8_BAR; PG8_SCHED;
;             PG8_LDB(B1, 0, 1); PG8_STAGE(PG8_SB(0, 0), b2, voffB);
;             PG8_BAR; PG8_WAIT_L(0); PG8_MMA(0, 1, At, B1); PG8_BAR;
;             PG8_LDA(At, 0, 1); PG8_STAGE(PG8_SA(0, 0), a2, voffA);
;             PG8_BAR; PG8_WAIT_L(0); PG8_MMA(1, 0, At, B0); PG8_BAR; PG8_SCHED;
;             PG8_STAGE(PG8_SB(0, 1), b2 + hstepB, voffB);
;             PG8_WAIT_V(6); PG8_BAR; PG8_MMA(1, 1, At, B1); PG8_BAR;
.LBB0_1120:
	ds_read_b128 v[146:149], v138
	ds_read_b128 v[150:153], v138 offset:1024
	ds_read_b128 v[160:163], v138 offset:2048
	ds_read_b128 v[166:169], v138 offset:3072
	s_mov_b32 m0, s41
	v_lshl_add_u64 v[156:157], v[134:135], 0, s[6:7]
	ds_read_b128 v[170:173], v139
	ds_read_b128 v[174:177], v139 offset:1024
	ds_read_b128 v[178:181], v139 offset:2048
	ds_read_b128 v[182:185], v139 offset:3072
	ds_read_b128 v[186:189], v139 offset:4096
	ds_read_b128 v[190:193], v139 offset:5120
	ds_read_b128 v[194:197], v139 offset:6144
	ds_read_b128 v[202:205], v139 offset:7168
	global_load_lds_dwordx4 v[156:157], off
	v_lshl_add_u64 v[156:157], v[136:137], 0, s[6:7]
	s_mov_b32 m0, s58
	s_setprio 1
	global_load_lds_dwordx4 v[156:157], off
	s_waitcnt lgkmcnt(8)
	s_barrier
	s_waitcnt lgkmcnt(0)
	v_mfma_f32_16x16x32_bf16 v[124:127], v[146:149], v[170:173], v[124:127]
	v_mfma_f32_16x16x32_bf16 v[120:123], v[160:163], v[170:173], v[120:123]
	v_mfma_f32_16x16x32_bf16 v[112:115], v[146:149], v[178:181], v[112:115]
	v_mfma_f32_16x16x32_bf16 v[104:107], v[160:163], v[178:181], v[104:107]
	v_mfma_f32_16x16x32_bf16 v[96:99], v[146:149], v[186:189], v[96:99]
	v_mfma_f32_16x16x32_bf16 v[88:91], v[160:163], v[186:189], v[88:91]
	v_mfma_f32_16x16x32_bf16 v[80:83], v[146:149], v[194:197], v[80:83]
	v_mfma_f32_16x16x32_bf16 v[72:75], v[160:163], v[194:197], v[72:75]
	v_mfma_f32_16x16x32_bf16 v[124:127], v[150:153], v[174:177], v[124:127]
	v_mfma_f32_16x16x32_bf16 v[120:123], v[166:169], v[174:177], v[120:123]
	v_mfma_f32_16x16x32_bf16 v[112:115], v[150:153], v[182:185], v[112:115]
	v_mfma_f32_16x16x32_bf16 v[104:107], v[166:169], v[182:185], v[104:107]
	v_mfma_f32_16x16x32_bf16 v[96:99], v[150:153], v[190:193], v[96:99]
	v_mfma_f32_16x16x32_bf16 v[88:91], v[166:169], v[190:193], v[88:91]
	v_mfma_f32_16x16x32_bf16 v[80:83], v[150:153], v[202:205], v[80:83]
	v_mfma_f32_16x16x32_bf16 v[72:75], v[166:169], v[202:205], v[72:75]
	s_barrier
	s_setprio 0
	s_add_u32 s22, s6, 0xdfa80080
	s_addc_u32 s23, s7, -1
	s_cmp_lg_u32 s40, 28
	s_cselect_b32 s22, s22, 0
	s_cselect_b32 s23, s23, 0
	s_add_u32 s24, s0, s22
	s_addc_u32 s25, s1, s23
	s_add_u32 s22, s2, s22
	s_addc_u32 s23, s3, s23
	s_mov_b32 m0, s59
	s_add_u32 s98, s22, s4
	s_addc_u32 s99, s23, s5
	ds_read_b128 v[206:209], v140
	ds_read_b128 v[210:213], v140 offset:1024
	ds_read_b128 v[214:217], v140 offset:2048
	ds_read_b128 v[218:221], v140 offset:3072
	global_load_lds_dwordx4 v144, s[22:23]
	s_mov_b32 m0, s60
	s_setprio 1
	global_load_lds_dwordx4 v132, s[22:23]
	s_barrier
	s_waitcnt lgkmcnt(0)
	v_mfma_f32_16x16x32_bf16 v[116:119], v[206:209], v[170:173], v[116:119]
	v_mfma_f32_16x16x32_bf16 v[108:111], v[214:217], v[170:173], v[108:111]
	v_mfma_f32_16x16x32_bf16 v[100:103], v[206:209], v[178:181], v[100:103]
	v_mfma_f32_16x16x32_bf16 v[92:95], v[214:217], v[178:181], v[92:95]
	v_mfma_f32_16x16x32_bf16 v[84:87], v[206:209], v[186:189], v[84:87]
	v_mfma_f32_16x16x32_bf16 v[76:79], v[214:217], v[186:189], v[76:79]
	v_mfma_f32_16x16x32_bf16 v[68:71], v[206:209], v[194:197], v[68:71]
	v_mfma_f32_16x16x32_bf16 v[64:67], v[214:217], v[194:197], v[64:67]
	v_mfma_f32_16x16x32_bf16 v[116:119], v[210:213], v[174:177], v[116:119]
	v_mfma_f32_16x16x32_bf16 v[108:111], v[218:221], v[174:177], v[108:111]
	v_mfma_f32_16x16x32_bf16 v[100:103], v[210:213], v[182:185], v[100:103]
	v_mfma_f32_16x16x32_bf16 v[92:95], v[218:221], v[182:185], v[92:95]
	v_mfma_f32_16x16x32_bf16 v[84:87], v[210:213], v[190:193], v[84:87]
	v_mfma_f32_16x16x32_bf16 v[76:79], v[218:221], v[190:193], v[76:79]
	v_mfma_f32_16x16x32_bf16 v[68:71], v[210:213], v[202:205], v[68:71]
	v_mfma_f32_16x16x32_bf16 v[64:67], v[218:221], v[202:205], v[64:67]
	s_barrier
	s_setprio 0
	s_mov_b32 m0, s52
	s_add_u32 s100, s24, s4
	s_addc_u32 s101, s25, s5
	ds_read_b128 v[170:173], v139 offset:16384
	ds_read_b128 v[174:177], v139 offset:17408
	ds_read_b128 v[178:181], v139 offset:18432
	ds_read_b128 v[182:185], v139 offset:19456
	ds_read_b128 v[186:189], v139 offset:20480
	ds_read_b128 v[190:193], v139 offset:21504
	ds_read_b128 v[194:197], v139 offset:22528
	ds_read_b128 v[202:205], v139 offset:23552
	global_load_lds_dwordx4 v128, s[24:25]
	s_mov_b32 m0, s53
	s_setprio 1
	global_load_lds_dwordx4 v130, s[24:25]
	s_barrier
	s_waitcnt lgkmcnt(0)
	v_mfma_f32_16x16x32_bf16 v[60:63], v[146:149], v[170:173], v[60:63]
	v_mfma_f32_16x16x32_bf16 v[56:59], v[160:163], v[170:173], v[56:59]
	v_mfma_f32_16x16x32_bf16 v[48:51], v[146:149], v[178:181], v[48:51]
	v_mfma_f32_16x16x32_bf16 v[40:43], v[160:163], v[178:181], v[40:43]
	v_mfma_f32_16x16x32_bf16 v[32:35], v[146:149], v[186:189], v[32:35]
	v_mfma_f32_16x16x32_bf16 v[24:27], v[160:163], v[186:189], v[24:27]
	v_mfma_f32_16x16x32_bf16 v[16:19], v[146:149], v[194:197], v[16:19]
	v_mfma_f32_16x16x32_bf16 v[8:11], v[160:163], v[194:197], v[8:11]
	v_mfma_f32_16x16x32_bf16 v[60:63], v[150:153], v[174:177], v[60:63]
	v_mfma_f32_16x16x32_bf16 v[56:59], v[166:169], v[174:177], v[56:59]
	v_mfma_f32_16x16x32_bf16 v[48:51], v[150:153], v[182:185], v[48:51]
	v_mfma_f32_16x16x32_bf16 v[40:43], v[166:169], v[182:185], v[40:43]
	v_mfma_f32_16x16x32_bf16 v[32:35], v[150:153], v[190:193], v[32:35]
	v_mfma_f32_16x16x32_bf16 v[24:27], v[166:169], v[190:193], v[24:27]
	v_mfma_f32_16x16x32_bf16 v[16:19], v[150:153], v[202:205], v[16:19]
	v_mfma_f32_16x16x32_bf16 v[8:11], v[166:169], v[202:205], v[8:11]
	s_barrier
	s_setprio 0
	s_add_u32 s28, s22, 0x80000
	s_addc_u32 s29, s23, 0
	s_mov_b32 m0, s61
	s_nop 0
	global_load_lds_dwordx4 v144, s[28:29]
	s_mov_b32 m0, s62
	s_setprio 1
	global_load_lds_dwordx4 v132, s[28:29]
	s_waitcnt vmcnt(6)
	s_barrier
; #define PG8_STAGE(bufoff, gbase, voff) do { _Pragma("unroll") for (int _i = 0; _i < 2; ++_i) \
;         __builtin_amdgcn_global_load_lds((const unsigned*)((const char*)(gbase) + (voff)[_i]), (LAS unsigned*)(lds + (bufoff) + ldsw + _i * 8192), 16, 0, 0); } while (0)
; #define PG8_LDA(dst, b, h) do { _Pragma("unroll") for (int m = 0; m < 4; ++m) _Pragma("unroll") for (int k = 0; k < 2; ++k) dst[m][k] = *(const LAS bf16x8*)(lds + PG8_SA(b, h) + aoff + m * 2048 + k * 1024); } while (0)
; #define PG8_LDB(dst, b, h) do { _Pragma("unroll") for (int n = 0; n < 2; ++n) _Pragma("unroll") for (int k = 0; k < 2; ++k) dst[n][k] = *(const LAS bf16x8*)(lds + PG8_SB(b, h) + boff + n * 2048 + k * 1024); } while (0)
; #define PG8_WAIT_V(n) asm volatile("s_waitcnt vmcnt(" #n ")" ::: "memory")
; #define PG8_WAIT_L(n) asm volatile("s_waitcnt lgkmcnt(" #n ")" ::: "memory")
; #define PG8_BAR __builtin_amdgcn_s_barrier()
; #define PG8_SCHED __builtin_amdgcn_sched_barrier(0)
; template <class Epi>
; __device__ __forceinline__ void gemm_phase(LAS unsigned char* lds, const bf16_t* A, int lda, const bf16_t* Bt, int ldb, int M, int N, int K, int asel, const Epi& E, const int fixed_round = -1) {
;     ...
;             PG8_WAIT_V(6); PG8_BAR; PG8_MMA(1, 1, At, B1); PG8_BAR;
;             PG8_LDB(B0, 1, 0); PG8_SCHED; PG8_LDA(At, 1, 0); PG8_STAGE(PG8_SA(0, 1), a2 + hstepA, voffA);
;             PG8_WAIT_L(8); PG8_BAR; PG8_WAIT_L(0); PG8_MMA(0, 0, At, B0); PG8_BAR; PG8_SCHED;
;             PG8_LDB(B1, 1, 1); PG8_STAGE(PG8_SB(1, 0), b3, voffB);
;             PG8_BAR; PG8_WAIT_L(0); PG8_MMA(0, 1, At, B1); PG8_BAR;
	v_mfma_f32_16x16x32_bf16 v[52:55], v[206:209], v[170:173], v[52:55]
	v_mfma_f32_16x16x32_bf16 v[44:47], v[214:217], v[170:173], v[44:47]
	v_mfma_f32_16x16x32_bf16 v[36:39], v[206:209], v[178:181], v[36:39]
	v_mfma_f32_16x16x32_bf16 v[28:31], v[214:217], v[178:181], v[28:31]
	v_mfma_f32_16x16x32_bf16 v[20:23], v[206:209], v[186:189], v[20:23]
	v_mfma_f32_16x16x32_bf16 v[12:15], v[214:217], v[186:189], v[12:15]
	v_mfma_f32_16x16x32_bf16 v[4:7], v[206:209], v[194:197], v[4:7]
	v_mfma_f32_16x16x32_bf16 v[0:3], v[214:217], v[194:197], v[0:3]
	v_mfma_f32_16x16x32_bf16 v[52:55], v[210:213], v[174:177], v[52:55]
	v_mfma_f32_16x16x32_bf16 v[44:47], v[218:221], v[174:177], v[44:47]
	v_mfma_f32_16x16x32_bf16 v[36:39], v[210:213], v[182:185], v[36:39]
	v_mfma_f32_16x16x32_bf16 v[28:31], v[218:221], v[182:185], v[28:31]
	v_mfma_f32_16x16x32_bf16 v[20:23], v[210:213], v[190:193], v[20:23]
	v_mfma_f32_16x16x32_bf16 v[12:15], v[218:221], v[190:193], v[12:15]
	v_mfma_f32_16x16x32_bf16 v[4:7], v[210:213], v[202:205], v[4:7]
	v_mfma_f32_16x16x32_bf16 v[0:3], v[218:221], v[202:205], v[0:3]
	s_barrier
	s_setprio 0
	ds_read_b128 v[146:149], v141
	ds_read_b128 v[150:153], v141 offset:1024
	ds_read_b128 v[160:163], v141 offset:2048
	ds_read_b128 v[166:169], v141 offset:3072
	s_add_u32 s24, s24, 0x80000
	s_addc_u32 s25, s25, 0
	s_mov_b32 m0, s54
	ds_read_b128 v[170:173], v139 offset:32768
	ds_read_b128 v[174:177], v139 offset:33792
	ds_read_b128 v[178:181], v139 offset:34816
	ds_read_b128 v[182:185], v139 offset:35840
	ds_read_b128 v[186:189], v139 offset:36864
	ds_read_b128 v[190:193], v139 offset:37888
	ds_read_b128 v[194:197], v139 offset:38912
	ds_read_b128 v[202:205], v139 offset:39936
	global_load_lds_dwordx4 v128, s[24:25]
	s_mov_b32 m0, s55
	s_setprio 1
	global_load_lds_dwordx4 v130, s[24:25]
	s_waitcnt lgkmcnt(8)
	s_barrier
	s_waitcnt lgkmcnt(0)
	v_mfma_f32_16x16x32_bf16 v[124:127], v[146:149], v[170:173], v[124:127]
	v_mfma_f32_16x16x32_bf16 v[120:123], v[160:163], v[170:173], v[120:123]
	v_mfma_f32_16x16x32_bf16 v[112:115], v[146:149], v[178:181], v[112:115]
	v_mfma_f32_16x16x32_bf16 v[104:107], v[160:163], v[178:181], v[104:107]
	v_mfma_f32_16x16x32_bf16 v[96:99], v[146:149], v[186:189], v[96:99]
	v_mfma_f32_16x16x32_bf16 v[88:91], v[160:163], v[186:189], v[88:91]
	v_mfma_f32_16x16x32_bf16 v[80:83], v[146:149], v[194:197], v[80:83]
	v_mfma_f32_16x16x32_bf16 v[72:75], v[160:163], v[194:197], v[72:75]
	v_mfma_f32_16x16x32_bf16 v[124:127], v[150:153], v[174:177], v[124:127]
	v_mfma_f32_16x16x32_bf16 v[120:123], v[166:169], v[174:177], v[120:123]
	v_mfma_f32_16x16x32_bf16 v[112:115], v[150:153], v[182:185], v[112:115]
	v_mfma_f32_16x16x32_bf16 v[104:107], v[166:169], v[182:185], v[104:107]
	v_mfma_f32_16x16x32_bf16 v[96:99], v[150:153], v[190:193], v[96:99]
	v_mfma_f32_16x16x32_bf16 v[88:91], v[166:169], v[190:193], v[88:91]
	v_mfma_f32_16x16x32_bf16 v[80:83], v[150:153], v[202:205], v[80:83]
	v_mfma_f32_16x16x32_bf16 v[72:75], v[166:169], v[202:205], v[72:75]
	s_barrier
	s_setprio 0
	s_mov_b32 m0, s63
	ds_read_b128 v[206:209], v142
	ds_read_b128 v[210:213], v142 offset:1024
	ds_read_b128 v[214:217], v142 offset:2048
	ds_read_b128 v[218:221], v142 offset:3072
	global_load_lds_dwordx4 v144, s[98:99]
	s_mov_b32 m0, s64
	s_setprio 1
	global_load_lds_dwordx4 v132, s[98:99]
	s_barrier
; #define PG8_STAGE(bufoff, gbase, voff) do { _Pragma("unroll") for (int _i = 0; _i < 2; ++_i) \
;         __builtin_amdgcn_global_load_lds((const unsigned*)((const char*)(gbase) + (voff)[_i]), (LAS unsigned*)(lds + (bufoff) + ldsw + _i * 8192), 16, 0, 0); } while (0)
; #define PG8_LDA(dst, b, h) do { _Pragma("unroll") for (int m = 0; m < 4; ++m) _Pragma("unroll") for (int k = 0; k < 2; ++k) dst[m][k] = *(const LAS bf16x8*)(lds + PG8_SA(b, h) + aoff + m * 2048 + k * 1024); } while (0)
; #define PG8_LDB(dst, b, h) do { _Pragma("unroll") for (int n = 0; n < 2; ++n) _Pragma("unroll") for (int k = 0; k < 2; ++k) dst[n][k] = *(const LAS bf16x8*)(lds + PG8_SB(b, h) + boff + n * 2048 + k * 1024); } while (0)
; #define PG8_WAIT_V(n) asm volatile("s_waitcnt vmcnt(" #n ")" ::: "memory")
; #define PG8_WAIT_L(n) asm volatile("s_waitcnt lgkmcnt(" #n ")" ::: "memory")
; #define PG8_BAR __builtin_amdgcn_s_barrier()
; #define PG8_SCHED __builtin_amdgcn_sched_barrier(0)
; template <class Epi>
; __device__ __forceinline__ void gemm_phase(LAS unsigned char* lds, const bf16_t* A, int lda, const bf16_t* Bt, int ldb, int M, int N, int K, int asel, const Epi& E, const int fixed_round = -1) {
;     ...
;             PG8_BAR; PG8_WAIT_L(0); PG8_MMA(1, 0, At, B0); PG8_BAR; PG8_SCHED;
;             PG8_STAGE(PG8_SB(0, 1), b2 + hstepB, voffB);
;             PG8_WAIT_V(6); PG8_BAR; PG8_MMA(1, 1, At, B1); PG8_BAR;
;             PG8_LDB(B0, 1, 0); PG8_SCHED; PG8_LDA(At, 1, 0); PG8_STAGE(PG8_SA(0, 1), a2 + hstepA, voffA);
;             PG8_WAIT_L(8); PG8_BAR; PG8_WAIT_L(0); PG8_MMA(0, 0, At, B0); PG8_BAR; PG8_SCHED;
;             PG8_LDB(B1, 1, 1); PG8_STAGE(PG8_SB(1, 0), b3, voffB);
;             PG8_BAR; PG8_WAIT_L(0); PG8_MMA(0, 1, At, B1); PG8_BAR;
;             PG8_LDA(At, 1, 1); PG8_STAGE(PG8_SA(1, 0), a3, voffA);
;             PG8_BAR; PG8_WAIT_L(0); PG8_MMA(1, 0, At, B0); PG8_BAR; PG8_SCHED;
;             PG8_STAGE(PG8_SB(1, 1), b3 + hstepB, voffB);
;             PG8_WAIT_V(6); PG8_BAR; PG8_MMA(1, 1, At, B1); PG8_BAR;
;     ...
;     PG8_WAIT_V(0);
;     if (wr == 0) PG8_BAR;
;     PG8_BAR;
	s_waitcnt lgkmcnt(0)
	v_mfma_f32_16x16x32_bf16 v[116:119], v[206:209], v[170:173], v[116:119]
	v_mfma_f32_16x16x32_bf16 v[108:111], v[214:217], v[170:173], v[108:111]
	v_mfma_f32_16x16x32_bf16 v[100:103], v[206:209], v[178:181], v[100:103]
	v_mfma_f32_16x16x32_bf16 v[92:95], v[214:217], v[178:181], v[92:95]
	v_mfma_f32_16x16x32_bf16 v[84:87], v[206:209], v[186:189], v[84:87]
	v_mfma_f32_16x16x32_bf16 v[76:79], v[214:217], v[186:189], v[76:79]
	v_mfma_f32_16x16x32_bf16 v[68:71], v[206:209], v[194:197], v[68:71]
	v_mfma_f32_16x16x32_bf16 v[64:67], v[214:217], v[194:197], v[64:67]
	v_mfma_f32_16x16x32_bf16 v[116:119], v[210:213], v[174:177], v[116:119]
	v_mfma_f32_16x16x32_bf16 v[108:111], v[218:221], v[174:177], v[108:111]
	v_mfma_f32_16x16x32_bf16 v[100:103], v[210:213], v[182:185], v[100:103]
	v_mfma_f32_16x16x32_bf16 v[92:95], v[218:221], v[182:185], v[92:95]
	v_mfma_f32_16x16x32_bf16 v[84:87], v[210:213], v[190:193], v[84:87]
	v_mfma_f32_16x16x32_bf16 v[76:79], v[218:221], v[190:193], v[76:79]
	v_mfma_f32_16x16x32_bf16 v[68:71], v[210:213], v[202:205], v[68:71]
	v_mfma_f32_16x16x32_bf16 v[64:67], v[218:221], v[202:205], v[64:67]
	s_barrier
	s_setprio 0
	s_mov_b32 m0, s56
	ds_read_b128 v[170:173], v139 offset:49152
	ds_read_b128 v[174:177], v139 offset:50176
	ds_read_b128 v[178:181], v139 offset:51200
	ds_read_b128 v[182:185], v139 offset:52224
	ds_read_b128 v[186:189], v139 offset:53248
	ds_read_b128 v[190:193], v139 offset:54272
	ds_read_b128 v[194:197], v139 offset:55296
	ds_read_b128 v[202:205], v139 offset:56320
	global_load_lds_dwordx4 v128, s[100:101]
	s_mov_b32 m0, s57
	s_setprio 1
	global_load_lds_dwordx4 v130, s[100:101]
	s_barrier
	s_waitcnt lgkmcnt(0)
	v_mfma_f32_16x16x32_bf16 v[60:63], v[146:149], v[170:173], v[60:63]
	v_mfma_f32_16x16x32_bf16 v[56:59], v[160:163], v[170:173], v[56:59]
	v_mfma_f32_16x16x32_bf16 v[48:51], v[146:149], v[178:181], v[48:51]
	v_mfma_f32_16x16x32_bf16 v[40:43], v[160:163], v[178:181], v[40:43]
	v_mfma_f32_16x16x32_bf16 v[32:35], v[146:149], v[186:189], v[32:35]
	v_mfma_f32_16x16x32_bf16 v[24:27], v[160:163], v[186:189], v[24:27]
	v_mfma_f32_16x16x32_bf16 v[16:19], v[146:149], v[194:197], v[16:19]
	v_mfma_f32_16x16x32_bf16 v[8:11], v[160:163], v[194:197], v[8:11]
	v_mfma_f32_16x16x32_bf16 v[60:63], v[150:153], v[174:177], v[60:63]
	v_mfma_f32_16x16x32_bf16 v[56:59], v[166:169], v[174:177], v[56:59]
	v_mfma_f32_16x16x32_bf16 v[48:51], v[150:153], v[182:185], v[48:51]
	v_mfma_f32_16x16x32_bf16 v[40:43], v[166:169], v[182:185], v[40:43]
	v_mfma_f32_16x16x32_bf16 v[32:35], v[150:153], v[190:193], v[32:35]
	v_mfma_f32_16x16x32_bf16 v[24:27], v[166:169], v[190:193], v[24:27]
	v_mfma_f32_16x16x32_bf16 v[16:19], v[150:153], v[202:205], v[16:19]
	v_mfma_f32_16x16x32_bf16 v[8:11], v[166:169], v[202:205], v[8:11]
	s_barrier
	s_setprio 0
	s_add_u32 s22, s22, 0x80080
	s_addc_u32 s23, s23, 0
	s_mov_b32 m0, s65
	s_nop 0
	global_load_lds_dwordx4 v144, s[22:23]
	s_mov_b32 m0, s66
	s_setprio 1
	global_load_lds_dwordx4 v132, s[22:23]
	s_waitcnt vmcnt(6)
	s_barrier
	v_mfma_f32_16x16x32_bf16 v[52:55], v[206:209], v[170:173], v[52:55]
	v_mfma_f32_16x16x32_bf16 v[44:47], v[214:217], v[170:173], v[44:47]
	v_mfma_f32_16x16x32_bf16 v[36:39], v[206:209], v[178:181], v[36:39]
	v_mfma_f32_16x16x32_bf16 v[28:31], v[214:217], v[178:181], v[28:31]
	v_mfma_f32_16x16x32_bf16 v[20:23], v[206:209], v[186:189], v[20:23]
	v_mfma_f32_16x16x32_bf16 v[12:15], v[214:217], v[186:189], v[12:15]
	v_mfma_f32_16x16x32_bf16 v[4:7], v[206:209], v[194:197], v[4:7]
	v_mfma_f32_16x16x32_bf16 v[0:3], v[214:217], v[194:197], v[0:3]
	v_mfma_f32_16x16x32_bf16 v[52:55], v[210:213], v[174:177], v[52:55]
	v_mfma_f32_16x16x32_bf16 v[44:47], v[218:221], v[174:177], v[44:47]
	v_mfma_f32_16x16x32_bf16 v[36:39], v[210:213], v[182:185], v[36:39]
	v_mfma_f32_16x16x32_bf16 v[28:31], v[218:221], v[182:185], v[28:31]
	v_mfma_f32_16x16x32_bf16 v[20:23], v[210:213], v[190:193], v[20:23]
	v_mfma_f32_16x16x32_bf16 v[12:15], v[218:221], v[190:193], v[12:15]
	v_mfma_f32_16x16x32_bf16 v[4:7], v[210:213], v[202:205], v[4:7]
	v_mfma_f32_16x16x32_bf16 v[0:3], v[218:221], v[202:205], v[0:3]
	s_setprio 0
	s_add_i32 s40, s40, 2
	s_add_u32 s6, s6, 0x100
	s_addc_u32 s7, s7, 0
	s_cmp_lt_u32 s40, 30
	s_cbranch_scc1 .Lrot_9
	s_barrier
	s_waitcnt vmcnt(0)
	s_cmpk_gt_u32 s51, 0xff
	s_cbranch_scc1 .LBB0_1123
	s_barrier

; #define PG8_STAGE(bufoff, gbase, voff) do { _Pragma("unroll") for (int _i = 0; _i < 2; ++_i) \
;         __builtin_amdgcn_global_load_lds((const unsigned*)((const char*)(gbase) + (voff)[_i]), (LAS unsigned*)(lds + (bufoff) + ldsw + _i * 8192), 16, 0, 0); } while (0)
; #define PG8_LDA(dst, b, h) do { _Pragma("unroll") for (int m = 0; m < 4; ++m) _Pragma("unroll") for (int k = 0; k < 2; ++k) dst[m][k] = *(const LAS bf16x8*)(lds + PG8_SA(b, h) + aoff + m * 2048 + k * 1024); } while (0)
; #define PG8_LDB(dst, b, h) do { _Pragma("unroll") for (int n = 0; n < 2; ++n) _Pragma("unroll") for (int k = 0; k < 2; ++k) dst[n][k] = *(const LAS bf16x8*)(lds + PG8_SB(b, h) + boff + n * 2048 + k * 1024); } while (0)
; #define PG8_WAIT_V(n) asm volatile("s_waitcnt vmcnt(" #n ")" ::: "memory")
; #define PG8_WAIT_L(n) asm volatile("s_waitcnt lgkmcnt(" #n ")" ::: "memory")
; #define PG8_BAR __builtin_amdgcn_s_barrier()
; #define PG8_SCHED __builtin_amdgcn_sched_barrier(0)
; template <class Epi>
; __device__ __forceinline__ void gemm_phase(LAS unsigned char* lds, const bf16_t* A, int lda, const bf16_t* Bt, int ldb, int M, int N, int K, int asel, const Epi& E, const int fixed_round = -1) {
;     ...
;             const bool last = (t == nt - 2);
;             const char* a1 = cA + (size_t)(t + 1) * kstep;
;             const char* a2 = last ? nA : cA + (size_t)(t + 2) * kstep; const char* b2 = last ? nB : cB + (size_t)(t + 2) * kstep;
;             const char* a3 = a2 + kstep; const char* b3 = b2 + kstep;
;             PG8_LDB(B0, 0, 0); PG8_SCHED; PG8_LDA(At, 0, 0); PG8_STAGE(PG8_SA(1, 1), a1 + hstepA, voffA);
;             PG8_WAIT_L(8); PG8_BAR; PG8_WAIT_L(0); PG8_MMA(0, 0, At, B0); PG8_BAR; PG8_SCHED;
;             PG8_LDB(B1, 0, 1); PG8_STAGE(PG8_SB(0, 0), b2, voffB);
;             PG8_BAR; PG8_WAIT_L(0); PG8_MMA(0, 1, At, B1); PG8_BAR;
;             PG8_LDA(At, 0, 1); PG8_STAGE(PG8_SA(0, 0), a2, voffA);
;             PG8_BAR; PG8_WAIT_L(0); PG8_MMA(1, 0, At, B0); PG8_BAR; PG8_SCHED;
;             PG8_STAGE(PG8_SB(0, 1), b2 + hstepB, voffB);
;             PG8_WAIT_V(6); PG8_BAR; PG8_MMA(1, 1, At, B1); PG8_BAR;
.LBB0_1223:
	ds_read_b128 v[152:155], v149
	ds_read_b128 v[156:159], v149 offset:1024
	ds_read_b128 v[160:163], v149 offset:2048
	ds_read_b128 v[164:167], v149 offset:3072
	s_add_i32 m0, s45, 0xc000
	ds_read_b128 v[168:171], v150
	ds_read_b128 v[172:175], v150 offset:1024
	ds_read_b128 v[176:179], v150 offset:2048
	ds_read_b128 v[180:183], v150 offset:3072
	ds_read_b128 v[184:187], v150 offset:4096
	ds_read_b128 v[188:191], v150 offset:5120
	ds_read_b128 v[192:195], v150 offset:6144
	ds_read_b128 v[196:199], v150 offset:7168
	global_load_lds_dwordx4 v136, s[46:47]
	s_add_i32 m0, s45, 0xe000
	s_setprio 1
	global_load_lds_dwordx4 v138, s[46:47]
	s_waitcnt lgkmcnt(8)
	s_barrier
	s_waitcnt lgkmcnt(0)
	v_mfma_f32_16x16x32_bf16 v[124:127], v[152:155], v[168:171], v[124:127]
	v_mfma_f32_16x16x32_bf16 v[120:123], v[160:163], v[168:171], v[120:123]
	v_mfma_f32_16x16x32_bf16 v[108:111], v[152:155], v[176:179], v[108:111]
	v_mfma_f32_16x16x32_bf16 v[104:107], v[160:163], v[176:179], v[104:107]
	v_mfma_f32_16x16x32_bf16 v[92:95], v[152:155], v[184:187], v[92:95]
	v_mfma_f32_16x16x32_bf16 v[88:91], v[160:163], v[184:187], v[88:91]
	v_mfma_f32_16x16x32_bf16 v[76:79], v[152:155], v[192:195], v[76:79]
	v_mfma_f32_16x16x32_bf16 v[72:75], v[160:163], v[192:195], v[72:75]
	v_mfma_f32_16x16x32_bf16 v[124:127], v[156:159], v[172:175], v[124:127]
	v_mfma_f32_16x16x32_bf16 v[120:123], v[164:167], v[172:175], v[120:123]
	v_mfma_f32_16x16x32_bf16 v[108:111], v[156:159], v[180:183], v[108:111]
	v_mfma_f32_16x16x32_bf16 v[104:107], v[164:167], v[180:183], v[104:107]
	v_mfma_f32_16x16x32_bf16 v[92:95], v[156:159], v[188:191], v[92:95]
	v_mfma_f32_16x16x32_bf16 v[88:91], v[164:167], v[188:191], v[88:91]
	v_mfma_f32_16x16x32_bf16 v[76:79], v[156:159], v[196:199], v[76:79]
	v_mfma_f32_16x16x32_bf16 v[72:75], v[164:167], v[196:199], v[72:75]
	s_barrier
	s_setprio 0
	s_add_u32 s48, s46, 0xfff80080
	s_addc_u32 s49, s47, -1
	s_cmp_eq_u32 s70, 28
	s_cselect_b32 s51, s29, s49
	s_cselect_b32 s50, s66, s48
	s_cselect_b32 s49, s25, s69
	s_cselect_b32 s48, s67, s68
	s_add_i32 s71, s81, s54
	s_add_u32 s98, s48, s2
	s_addc_u32 s99, s49, s3
	s_mov_b32 m0, s71
	ds_read_b128 v[202:205], v151
	ds_read_b128 v[206:209], v151 offset:1024
	ds_read_b128 v[210:213], v151 offset:2048
	ds_read_b128 v[214:217], v151 offset:3072
	global_load_lds_dwordx4 v130, s[48:49]
	s_add_i32 m0, s71, 0x2000
	s_setprio 1
	global_load_lds_dwordx4 v134, s[48:49]
	s_barrier
	s_waitcnt lgkmcnt(0)
	v_mfma_f32_16x16x32_bf16 v[116:119], v[202:205], v[168:171], v[116:119]
	v_mfma_f32_16x16x32_bf16 v[112:115], v[210:213], v[168:171], v[112:115]
	v_mfma_f32_16x16x32_bf16 v[100:103], v[202:205], v[176:179], v[100:103]
	v_mfma_f32_16x16x32_bf16 v[96:99], v[210:213], v[176:179], v[96:99]
	v_mfma_f32_16x16x32_bf16 v[84:87], v[202:205], v[184:187], v[84:87]
	v_mfma_f32_16x16x32_bf16 v[80:83], v[210:213], v[184:187], v[80:83]
	v_mfma_f32_16x16x32_bf16 v[68:71], v[202:205], v[192:195], v[68:71]
	v_mfma_f32_16x16x32_bf16 v[64:67], v[210:213], v[192:195], v[64:67]
	v_mfma_f32_16x16x32_bf16 v[116:119], v[206:209], v[172:175], v[116:119]
	v_mfma_f32_16x16x32_bf16 v[112:115], v[214:217], v[172:175], v[112:115]
	v_mfma_f32_16x16x32_bf16 v[100:103], v[206:209], v[180:183], v[100:103]
	v_mfma_f32_16x16x32_bf16 v[96:99], v[214:217], v[180:183], v[96:99]
	v_mfma_f32_16x16x32_bf16 v[84:87], v[206:209], v[188:191], v[84:87]
	v_mfma_f32_16x16x32_bf16 v[80:83], v[214:217], v[188:191], v[80:83]
	v_mfma_f32_16x16x32_bf16 v[68:71], v[206:209], v[196:199], v[68:71]
	v_mfma_f32_16x16x32_bf16 v[64:67], v[214:217], v[196:199], v[64:67]
	s_barrier
	s_setprio 0
	s_mov_b32 m0, s45
	s_add_u32 s100, s50, s2
	s_addc_u32 s101, s51, s3
	ds_read_b128 v[168:171], v150 offset:16384
	ds_read_b128 v[172:175], v150 offset:17408
	ds_read_b128 v[176:179], v150 offset:18432
	ds_read_b128 v[180:183], v150 offset:19456
	ds_read_b128 v[184:187], v150 offset:20480
	ds_read_b128 v[188:191], v150 offset:21504
	ds_read_b128 v[192:195], v150 offset:22528
	ds_read_b128 v[196:199], v150 offset:23552
	global_load_lds_dwordx4 v128, s[50:51]
	s_mov_b32 m0, s55
	s_setprio 1
	global_load_lds_dwordx4 v132, s[50:51]
	s_barrier
	s_waitcnt lgkmcnt(0)
	v_mfma_f32_16x16x32_bf16 v[60:63], v[152:155], v[168:171], v[60:63]
	v_mfma_f32_16x16x32_bf16 v[56:59], v[160:163], v[168:171], v[56:59]
	v_mfma_f32_16x16x32_bf16 v[44:47], v[152:155], v[176:179], v[44:47]
	v_mfma_f32_16x16x32_bf16 v[40:43], v[160:163], v[176:179], v[40:43]
	v_mfma_f32_16x16x32_bf16 v[28:31], v[152:155], v[184:187], v[28:31]
	v_mfma_f32_16x16x32_bf16 v[24:27], v[160:163], v[184:187], v[24:27]
	v_mfma_f32_16x16x32_bf16 v[12:15], v[152:155], v[192:195], v[12:15]
	v_mfma_f32_16x16x32_bf16 v[8:11], v[160:163], v[192:195], v[8:11]
	v_mfma_f32_16x16x32_bf16 v[60:63], v[156:159], v[172:175], v[60:63]
	v_mfma_f32_16x16x32_bf16 v[56:59], v[164:167], v[172:175], v[56:59]
	v_mfma_f32_16x16x32_bf16 v[44:47], v[156:159], v[180:183], v[44:47]
	v_mfma_f32_16x16x32_bf16 v[40:43], v[164:167], v[180:183], v[40:43]
	v_mfma_f32_16x16x32_bf16 v[28:31], v[156:159], v[188:191], v[28:31]
	v_mfma_f32_16x16x32_bf16 v[24:27], v[164:167], v[188:191], v[24:27]
	v_mfma_f32_16x16x32_bf16 v[12:15], v[156:159], v[196:199], v[12:15]
	v_mfma_f32_16x16x32_bf16 v[8:11], v[164:167], v[196:199], v[8:11]
	s_barrier
	s_setprio 0
	s_add_u32 s72, s48, 0x80000
	s_addc_u32 s73, s49, 0
	s_add_i32 s71, s82, s54
	s_mov_b32 m0, s71
	s_nop 0
	global_load_lds_dwordx4 v130, s[72:73]
	s_add_i32 m0, s71, 0x2000
	s_setprio 1
	global_load_lds_dwordx4 v134, s[72:73]
	s_waitcnt vmcnt(6)
	s_barrier
; #define PG8_STAGE(bufoff, gbase, voff) do { _Pragma("unroll") for (int _i = 0; _i < 2; ++_i) \
;         __builtin_amdgcn_global_load_lds((const unsigned*)((const char*)(gbase) + (voff)[_i]), (LAS unsigned*)(lds + (bufoff) + ldsw + _i * 8192), 16, 0, 0); } while (0)
; #define PG8_LDA(dst, b, h) do { _Pragma("unroll") for (int m = 0; m < 4; ++m) _Pragma("unroll") for (int k = 0; k < 2; ++k) dst[m][k] = *(const LAS bf16x8*)(lds + PG8_SA(b, h) + aoff + m * 2048 + k * 1024); } while (0)
; #define PG8_LDB(dst, b, h) do { _Pragma("unroll") for (int n = 0; n < 2; ++n) _Pragma("unroll") for (int k = 0; k < 2; ++k) dst[n][k] = *(const LAS bf16x8*)(lds + PG8_SB(b, h) + boff + n * 2048 + k * 1024); } while (0)
; #define PG8_WAIT_V(n) asm volatile("s_waitcnt vmcnt(" #n ")" ::: "memory")
; #define PG8_WAIT_L(n) asm volatile("s_waitcnt lgkmcnt(" #n ")" ::: "memory")
; #define PG8_BAR __builtin_amdgcn_s_barrier()
; #define PG8_SCHED __builtin_amdgcn_sched_barrier(0)
; template <class Epi>
; __device__ __forceinline__ void gemm_phase(LAS unsigned char* lds, const bf16_t* A, int lda, const bf16_t* Bt, int ldb, int M, int N, int K, int asel, const Epi& E, const int fixed_round = -1) {
;     ...
;             PG8_WAIT_V(6); PG8_BAR; PG8_MMA(1, 1, At, B1); PG8_BAR;
;             PG8_LDB(B0, 1, 0); PG8_SCHED; PG8_LDA(At, 1, 0); PG8_STAGE(PG8_SA(0, 1), a2 + hstepA, voffA);
;             PG8_WAIT_L(8); PG8_BAR; PG8_WAIT_L(0); PG8_MMA(0, 0, At, B0); PG8_BAR; PG8_SCHED;
;             PG8_LDB(B1, 1, 1); PG8_STAGE(PG8_SB(1, 0), b3, voffB);
;             PG8_BAR; PG8_WAIT_L(0); PG8_MMA(0, 1, At, B1); PG8_BAR;
;             PG8_LDA(At, 1, 1); PG8_STAGE(PG8_SA(1, 0), a3, voffA);
;             PG8_BAR; PG8_WAIT_L(0); PG8_MMA(1, 0, At, B0); PG8_BAR; PG8_SCHED;
	v_mfma_f32_16x16x32_bf16 v[52:55], v[202:205], v[168:171], v[52:55]
	v_mfma_f32_16x16x32_bf16 v[48:51], v[210:213], v[168:171], v[48:51]
	v_mfma_f32_16x16x32_bf16 v[36:39], v[202:205], v[176:179], v[36:39]
	v_mfma_f32_16x16x32_bf16 v[32:35], v[210:213], v[176:179], v[32:35]
	v_mfma_f32_16x16x32_bf16 v[20:23], v[202:205], v[184:187], v[20:23]
	v_mfma_f32_16x16x32_bf16 v[16:19], v[210:213], v[184:187], v[16:19]
	v_mfma_f32_16x16x32_bf16 v[4:7], v[202:205], v[192:195], v[4:7]
	v_mfma_f32_16x16x32_bf16 v[0:3], v[210:213], v[192:195], v[0:3]
	v_mfma_f32_16x16x32_bf16 v[52:55], v[206:209], v[172:175], v[52:55]
	v_mfma_f32_16x16x32_bf16 v[48:51], v[214:217], v[172:175], v[48:51]
	v_mfma_f32_16x16x32_bf16 v[36:39], v[206:209], v[180:183], v[36:39]
	v_mfma_f32_16x16x32_bf16 v[32:35], v[214:217], v[180:183], v[32:35]
	v_mfma_f32_16x16x32_bf16 v[20:23], v[206:209], v[188:191], v[20:23]
	v_mfma_f32_16x16x32_bf16 v[16:19], v[214:217], v[188:191], v[16:19]
	v_mfma_f32_16x16x32_bf16 v[4:7], v[206:209], v[196:199], v[4:7]
	v_mfma_f32_16x16x32_bf16 v[0:3], v[214:217], v[196:199], v[0:3]
	s_barrier
	s_setprio 0
	v_add_u32_e32 v164, s83, v147
	ds_read_b128 v[152:155], v164
	ds_read_b128 v[156:159], v164 offset:1024
	ds_read_b128 v[160:163], v164 offset:2048
	ds_read_b128 v[164:167], v164 offset:3072
	s_add_u32 s50, s50, 0x80000
	s_addc_u32 s51, s51, 0
	s_mov_b32 m0, s56
	ds_read_b128 v[168:171], v150 offset:32768
	ds_read_b128 v[172:175], v150 offset:33792
	ds_read_b128 v[176:179], v150 offset:34816
	ds_read_b128 v[180:183], v150 offset:35840
	ds_read_b128 v[184:187], v150 offset:36864
	ds_read_b128 v[188:191], v150 offset:37888
	ds_read_b128 v[192:195], v150 offset:38912
	ds_read_b128 v[196:199], v150 offset:39936
	global_load_lds_dwordx4 v128, s[50:51]
	s_mov_b32 m0, s57
	s_setprio 1
	global_load_lds_dwordx4 v132, s[50:51]
	s_waitcnt lgkmcnt(8)
	s_barrier
	s_waitcnt lgkmcnt(0)
	v_mfma_f32_16x16x32_bf16 v[124:127], v[152:155], v[168:171], v[124:127]
	v_mfma_f32_16x16x32_bf16 v[120:123], v[160:163], v[168:171], v[120:123]
	v_mfma_f32_16x16x32_bf16 v[108:111], v[152:155], v[176:179], v[108:111]
	v_mfma_f32_16x16x32_bf16 v[104:107], v[160:163], v[176:179], v[104:107]
	v_mfma_f32_16x16x32_bf16 v[92:95], v[152:155], v[184:187], v[92:95]
	v_mfma_f32_16x16x32_bf16 v[88:91], v[160:163], v[184:187], v[88:91]
	v_mfma_f32_16x16x32_bf16 v[76:79], v[152:155], v[192:195], v[76:79]
	v_mfma_f32_16x16x32_bf16 v[72:75], v[160:163], v[192:195], v[72:75]
	v_mfma_f32_16x16x32_bf16 v[124:127], v[156:159], v[172:175], v[124:127]
	v_mfma_f32_16x16x32_bf16 v[120:123], v[164:167], v[172:175], v[120:123]
	v_mfma_f32_16x16x32_bf16 v[108:111], v[156:159], v[180:183], v[108:111]
	v_mfma_f32_16x16x32_bf16 v[104:107], v[164:167], v[180:183], v[104:107]
	v_mfma_f32_16x16x32_bf16 v[92:95], v[156:159], v[188:191], v[92:95]
	v_mfma_f32_16x16x32_bf16 v[88:91], v[164:167], v[188:191], v[88:91]
	v_mfma_f32_16x16x32_bf16 v[76:79], v[156:159], v[196:199], v[76:79]
	v_mfma_f32_16x16x32_bf16 v[72:75], v[164:167], v[196:199], v[72:75]
	s_barrier
	s_setprio 0
	s_add_i32 s50, s83, s54
	v_add_u32_e32 v214, s84, v147
	s_mov_b32 m0, s50
	ds_read_b128 v[202:205], v214
	ds_read_b128 v[206:209], v214 offset:1024
	ds_read_b128 v[210:213], v214 offset:2048
	ds_read_b128 v[214:217], v214 offset:3072
	global_load_lds_dwordx4 v130, s[98:99]
	s_add_i32 m0, s50, 0x2000
	s_setprio 1
	global_load_lds_dwordx4 v134, s[98:99]
	s_barrier
	s_waitcnt lgkmcnt(0)
	v_mfma_f32_16x16x32_bf16 v[116:119], v[202:205], v[168:171], v[116:119]
	v_mfma_f32_16x16x32_bf16 v[112:115], v[210:213], v[168:171], v[112:115]
	v_mfma_f32_16x16x32_bf16 v[100:103], v[202:205], v[176:179], v[100:103]
	v_mfma_f32_16x16x32_bf16 v[96:99], v[210:213], v[176:179], v[96:99]
	v_mfma_f32_16x16x32_bf16 v[84:87], v[202:205], v[184:187], v[84:87]
	v_mfma_f32_16x16x32_bf16 v[80:83], v[210:213], v[184:187], v[80:83]
	v_mfma_f32_16x16x32_bf16 v[68:71], v[202:205], v[192:195], v[68:71]
	v_mfma_f32_16x16x32_bf16 v[64:67], v[210:213], v[192:195], v[64:67]
	v_mfma_f32_16x16x32_bf16 v[116:119], v[206:209], v[172:175], v[116:119]
	v_mfma_f32_16x16x32_bf16 v[112:115], v[214:217], v[172:175], v[112:115]
	v_mfma_f32_16x16x32_bf16 v[100:103], v[206:209], v[180:183], v[100:103]
	v_mfma_f32_16x16x32_bf16 v[96:99], v[214:217], v[180:183], v[96:99]
	v_mfma_f32_16x16x32_bf16 v[84:87], v[206:209], v[188:191], v[84:87]
	v_mfma_f32_16x16x32_bf16 v[80:83], v[214:217], v[188:191], v[80:83]
	v_mfma_f32_16x16x32_bf16 v[68:71], v[206:209], v[196:199], v[68:71]
	v_mfma_f32_16x16x32_bf16 v[64:67], v[214:217], v[196:199], v[64:67]
	s_barrier
	s_setprio 0
	s_mov_b32 m0, s59
	ds_read_b128 v[168:171], v150 offset:49152
	ds_read_b128 v[172:175], v150 offset:50176
	ds_read_b128 v[176:179], v150 offset:51200
	ds_read_b128 v[180:183], v150 offset:52224
	ds_read_b128 v[184:187], v150 offset:53248
	ds_read_b128 v[188:191], v150 offset:54272
	ds_read_b128 v[192:195], v150 offset:55296
	ds_read_b128 v[196:199], v150 offset:56320
	global_load_lds_dwordx4 v128, s[100:101]
	s_mov_b32 m0, s60
	s_setprio 1
	global_load_lds_dwordx4 v132, s[100:101]
	s_barrier
; __device__ __forceinline__ unsigned cvt_pk_bf16(float lo, float hi) { const bf16x2_t r = __builtin_convertvector((f32x2){lo, hi}, bf16x2_t); return __builtin_bit_cast(unsigned, r); }
; #define PG8_STAGE(bufoff, gbase, voff) do { _Pragma("unroll") for (int _i = 0; _i < 2; ++_i) \
;         __builtin_amdgcn_global_load_lds((const unsigned*)((const char*)(gbase) + (voff)[_i]), (LAS unsigned*)(lds + (bufoff) + ldsw + _i * 8192), 16, 0, 0); } while (0)
; #define PG8_WAIT_V(n) asm volatile("s_waitcnt vmcnt(" #n ")" ::: "memory")
; #define PG8_BAR __builtin_amdgcn_s_barrier()
; template <class Epi>
; __device__ __forceinline__ void gemm_phase(LAS unsigned char* lds, const bf16_t* A, int lda, const bf16_t* Bt, int ldb, int M, int N, int K, int asel, const Epi& E, const int fixed_round = -1) {
;     ...
;             PG8_STAGE(PG8_SB(1, 1), b3 + hstepB, voffB);
;             PG8_WAIT_V(6); PG8_BAR; PG8_MMA(1, 1, At, B1); PG8_BAR;
;     __device__ __forceinline__ void operator()(const AccT& acc, const Unit& u, int wr, int wc, int fr, int fq) const {
;         const int row0 = u.pm * BM + wr * 64 + fr, col0 = u.pn * BM + wc * 32 + 8 * fq;
; #pragma unroll
;         for (int ai = 0; ai < 2; ++ai)
; #pragma unroll
;             for (int m = 0; m < 4; ++m) { bf16_t* rowp = O + (size_t)(row0 + ai * HALF + m * 16) * DFF + col0;
; #pragma unroll
;                 for (int bj = 0; bj < 2; ++bj) { f32x4 v0 = acc[ai][bj][m][0], v1 = acc[ai][bj][m][1];
; #pragma unroll
;                     for (int j = 0; j < 4; ++j) { float a = fmaxf(v0[j], 0.f), b = fmaxf(v1[j], 0.f); v0[j] = a * a; v1[j] = b * b; }
;                     u32x4 w; w.x = cvt_pk_bf16(v0[0], v0[1]); w.y = cvt_pk_bf16(v0[2], v0[3]); w.z = cvt_pk_bf16(v1[0], v1[1]); w.w = cvt_pk_bf16(v1[2], v1[3]);
;                     *(u32x4*)(rowp + bj * HALF) = w; } }
;     }
	s_waitcnt lgkmcnt(0)
	v_mfma_f32_16x16x32_bf16 v[60:63], v[152:155], v[168:171], v[60:63]
	v_mfma_f32_16x16x32_bf16 v[56:59], v[160:163], v[168:171], v[56:59]
	v_mfma_f32_16x16x32_bf16 v[44:47], v[152:155], v[176:179], v[44:47]
	v_mfma_f32_16x16x32_bf16 v[40:43], v[160:163], v[176:179], v[40:43]
	v_mfma_f32_16x16x32_bf16 v[28:31], v[152:155], v[184:187], v[28:31]
	v_mfma_f32_16x16x32_bf16 v[24:27], v[160:163], v[184:187], v[24:27]
	v_mfma_f32_16x16x32_bf16 v[12:15], v[152:155], v[192:195], v[12:15]
	v_mfma_f32_16x16x32_bf16 v[8:11], v[160:163], v[192:195], v[8:11]
	v_mfma_f32_16x16x32_bf16 v[60:63], v[156:159], v[172:175], v[60:63]
	v_mfma_f32_16x16x32_bf16 v[56:59], v[164:167], v[172:175], v[56:59]
	v_mfma_f32_16x16x32_bf16 v[44:47], v[156:159], v[180:183], v[44:47]
	v_mfma_f32_16x16x32_bf16 v[40:43], v[164:167], v[180:183], v[40:43]
	v_mfma_f32_16x16x32_bf16 v[28:31], v[156:159], v[188:191], v[28:31]
	v_mfma_f32_16x16x32_bf16 v[24:27], v[164:167], v[188:191], v[24:27]
	v_mfma_f32_16x16x32_bf16 v[12:15], v[156:159], v[196:199], v[12:15]
	v_mfma_f32_16x16x32_bf16 v[8:11], v[164:167], v[196:199], v[8:11]
	s_barrier
	s_setprio 0
	s_add_u32 s48, s48, 0x80080
	s_addc_u32 s49, s49, 0
	s_add_i32 s50, s84, s54
	s_mov_b32 m0, s50
	s_nop 0
	global_load_lds_dwordx4 v130, s[48:49]
	s_add_i32 m0, s50, 0x2000
	s_setprio 1
	global_load_lds_dwordx4 v134, s[48:49]
	s_waitcnt vmcnt(6)
	s_barrier
	v_mfma_f32_16x16x32_bf16 v[52:55], v[202:205], v[168:171], v[52:55]
	v_mfma_f32_16x16x32_bf16 v[48:51], v[210:213], v[168:171], v[48:51]
	v_mfma_f32_16x16x32_bf16 v[36:39], v[202:205], v[176:179], v[36:39]
	v_mfma_f32_16x16x32_bf16 v[32:35], v[210:213], v[176:179], v[32:35]
	v_mfma_f32_16x16x32_bf16 v[20:23], v[202:205], v[184:187], v[20:23]
	v_mfma_f32_16x16x32_bf16 v[16:19], v[210:213], v[184:187], v[16:19]
	v_mfma_f32_16x16x32_bf16 v[4:7], v[202:205], v[192:195], v[4:7]
	v_mfma_f32_16x16x32_bf16 v[0:3], v[210:213], v[192:195], v[0:3]
	v_mfma_f32_16x16x32_bf16 v[52:55], v[206:209], v[172:175], v[52:55]
	v_mfma_f32_16x16x32_bf16 v[48:51], v[214:217], v[172:175], v[48:51]
	v_mfma_f32_16x16x32_bf16 v[36:39], v[206:209], v[180:183], v[36:39]
	v_mfma_f32_16x16x32_bf16 v[32:35], v[214:217], v[180:183], v[32:35]
	v_mfma_f32_16x16x32_bf16 v[20:23], v[206:209], v[188:191], v[20:23]
	v_mfma_f32_16x16x32_bf16 v[16:19], v[214:217], v[188:191], v[16:19]
	v_mfma_f32_16x16x32_bf16 v[4:7], v[206:209], v[196:199], v[4:7]
	v_mfma_f32_16x16x32_bf16 v[0:3], v[214:217], v[196:199], v[0:3]
	s_setprio 0
	s_add_i32 s70, s70, 2
	s_add_u32 s46, s46, 0x100
	s_addc_u32 s47, s47, 0
	s_add_u32 s68, s68, 0x100
	s_addc_u32 s69, s69, 0
	s_cmp_gt_u32 s70, 29
	s_cbranch_scc0 .Lrot_10
	s_barrier
	v_lshl_add_u32 v152, s44, 8, v146
	v_lshl_or_b32 v144, s65, 8, v148
	v_ashrrev_i32_e32 v153, 31, v152
	v_readlane_b32 s46, v254, 60
	v_ashrrev_i32_e32 v145, 31, v144
	v_lshlrev_b64 v[154:155], 14, v[152:153]
	v_readlane_b32 s47, v254, 61
	v_lshl_add_u64 v[154:155], s[46:47], 0, v[154:155]
	v_lshlrev_b64 v[156:157], 1, v[144:145]
	v_max_f32_e32 v120, 0, v120
	v_max_f32_e32 v121, 0, v121
	v_lshl_add_u64 v[144:145], v[154:155], 0, v[156:157]
	v_pk_mul_f32 v[154:155], v[120:121], v[120:121]
	v_max_f32_e32 v121, v122, v122
	v_max_f32_e32 v120, v126, v126
	v_max_f32_e32 v122, 0, v121
	v_max_f32_e32 v121, v127, v127
	v_max_f32_e32 v124, 0, v124
	v_max_f32_e32 v125, 0, v125
	v_max_f32_e32 v120, 0, v120
	v_max_f32_e32 v121, 0, v121
	v_max_f32_e32 v123, 0, v123
	v_pk_mul_f32 v[124:125], v[124:125], v[124:125]
	v_pk_mul_f32 v[126:127], v[120:121], v[120:121]
	v_pk_mul_f32 v[158:159], v[122:123], v[122:123]
	v_cvt_pk_bf16_f32 v120, v124, v125
	v_cvt_pk_bf16_f32 v121, v126, v127
	v_cvt_pk_bf16_f32 v122, v154, v155
	v_cvt_pk_bf16_f32 v123, v158, v159
	v_max_f32_e32 v112, 0, v112
	v_max_f32_e32 v113, 0, v113
	global_store_dwordx4 v[144:145], v[120:123], off
	s_nop 1
	v_pk_mul_f32 v[120:121], v[112:113], v[112:113]
	v_max_f32_e32 v113, v114, v114
	v_max_f32_e32 v112, v118, v118
	v_max_f32_e32 v114, 0, v113
	v_max_f32_e32 v113, v119, v119
	v_max_f32_e32 v116, 0, v116
	v_max_f32_e32 v117, 0, v117
	v_max_f32_e32 v112, 0, v112
	v_max_f32_e32 v113, 0, v113
	v_max_f32_e32 v115, 0, v115
	v_pk_mul_f32 v[116:117], v[116:117], v[116:117]
	v_pk_mul_f32 v[118:119], v[112:113], v[112:113]
	v_pk_mul_f32 v[122:123], v[114:115], v[114:115]
	v_cvt_pk_bf16_f32 v112, v116, v117
	v_cvt_pk_bf16_f32 v113, v118, v119
	v_cvt_pk_bf16_f32 v114, v120, v121
	v_cvt_pk_bf16_f32 v115, v122, v123
	v_max_f32_e32 v104, 0, v104
	v_max_f32_e32 v105, 0, v105
	global_store_dwordx4 v[144:145], v[112:115], off offset:256
	s_nop 1
	v_or_b32_e32 v112, 16, v152
	v_pk_mul_f32 v[114:115], v[104:105], v[104:105]
	v_max_f32_e32 v105, v106, v106
	v_ashrrev_i32_e32 v113, 31, v112
	v_max_f32_e32 v104, v110, v110
	v_max_f32_e32 v106, 0, v105
	v_max_f32_e32 v105, v111, v111
	v_lshlrev_b64 v[112:113], 14, v[112:113]
	v_max_f32_e32 v108, 0, v108
	v_max_f32_e32 v109, 0, v109
	v_max_f32_e32 v104, 0, v104
	v_max_f32_e32 v105, 0, v105
	v_max_f32_e32 v107, 0, v107
	v_lshl_add_u64 v[112:113], s[46:47], 0, v[112:113]
	v_pk_mul_f32 v[108:109], v[108:109], v[108:109]
	v_pk_mul_f32 v[110:111], v[104:105], v[104:105]
	v_pk_mul_f32 v[116:117], v[106:107], v[106:107]
	v_lshl_add_u64 v[112:113], v[112:113], 0, v[156:157]
	v_cvt_pk_bf16_f32 v104, v108, v109
	v_cvt_pk_bf16_f32 v105, v110, v111
	v_cvt_pk_bf16_f32 v106, v114, v115
	v_cvt_pk_bf16_f32 v107, v116, v117
	v_max_f32_e32 v96, 0, v96
	v_max_f32_e32 v97, 0, v97
	global_store_dwordx4 v[112:113], v[104:107], off
	s_nop 1
	v_pk_mul_f32 v[104:105], v[96:97], v[96:97]
	v_max_f32_e32 v97, v98, v98
	v_max_f32_e32 v96, v102, v102
; __device__ __forceinline__ unsigned cvt_pk_bf16(float lo, float hi) { const bf16x2_t r = __builtin_convertvector((f32x2){lo, hi}, bf16x2_t); return __builtin_bit_cast(unsigned, r); }
;     __device__ __forceinline__ void operator()(const AccT& acc, const Unit& u, int wr, int wc, int fr, int fq) const {
;     ...
;             for (int m = 0; m < 4; ++m) { bf16_t* rowp = O + (size_t)(row0 + ai * HALF + m * 16) * DFF + col0;
; #pragma unroll
;                 for (int bj = 0; bj < 2; ++bj) { f32x4 v0 = acc[ai][bj][m][0], v1 = acc[ai][bj][m][1];
; #pragma unroll
;                     for (int j = 0; j < 4; ++j) { float a = fmaxf(v0[j], 0.f), b = fmaxf(v1[j], 0.f); v0[j] = a * a; v1[j] = b * b; }
;                     u32x4 w; w.x = cvt_pk_bf16(v0[0], v0[1]); w.y = cvt_pk_bf16(v0[2], v0[3]); w.z = cvt_pk_bf16(v1[0], v1[1]); w.w = cvt_pk_bf16(v1[2], v1[3]);
;                     *(u32x4*)(rowp + bj * HALF) = w; } }
	v_max_f32_e32 v98, 0, v97
	v_max_f32_e32 v97, v103, v103
	v_max_f32_e32 v100, 0, v100
	v_max_f32_e32 v101, 0, v101
	v_max_f32_e32 v96, 0, v96
	v_max_f32_e32 v97, 0, v97
	v_max_f32_e32 v99, 0, v99
	v_pk_mul_f32 v[100:101], v[100:101], v[100:101]
	v_pk_mul_f32 v[102:103], v[96:97], v[96:97]
	v_pk_mul_f32 v[106:107], v[98:99], v[98:99]
	v_cvt_pk_bf16_f32 v96, v100, v101
	v_cvt_pk_bf16_f32 v97, v102, v103
	v_cvt_pk_bf16_f32 v98, v104, v105
	v_cvt_pk_bf16_f32 v99, v106, v107
	v_max_f32_e32 v88, 0, v88
	v_max_f32_e32 v89, 0, v89
	global_store_dwordx4 v[112:113], v[96:99], off offset:256
	s_nop 1
	v_or_b32_e32 v96, 32, v152
	v_pk_mul_f32 v[98:99], v[88:89], v[88:89]
	v_max_f32_e32 v89, v90, v90
	v_ashrrev_i32_e32 v97, 31, v96
	v_max_f32_e32 v88, v94, v94
	v_max_f32_e32 v90, 0, v89
	v_max_f32_e32 v89, v95, v95
	v_lshlrev_b64 v[96:97], 14, v[96:97]
	v_max_f32_e32 v92, 0, v92
	v_max_f32_e32 v93, 0, v93
	v_max_f32_e32 v88, 0, v88
	v_max_f32_e32 v89, 0, v89
	v_max_f32_e32 v91, 0, v91
	v_lshl_add_u64 v[96:97], s[46:47], 0, v[96:97]
	v_pk_mul_f32 v[92:93], v[92:93], v[92:93]
	v_pk_mul_f32 v[94:95], v[88:89], v[88:89]
	v_pk_mul_f32 v[100:101], v[90:91], v[90:91]
	v_lshl_add_u64 v[96:97], v[96:97], 0, v[156:157]
	v_cvt_pk_bf16_f32 v88, v92, v93
	v_cvt_pk_bf16_f32 v89, v94, v95
	v_cvt_pk_bf16_f32 v90, v98, v99
	v_cvt_pk_bf16_f32 v91, v100, v101
	v_max_f32_e32 v80, 0, v80
	v_max_f32_e32 v81, 0, v81
	global_store_dwordx4 v[96:97], v[88:91], off
	s_nop 1
	v_pk_mul_f32 v[88:89], v[80:81], v[80:81]
	v_max_f32_e32 v81, v82, v82
	v_max_f32_e32 v80, v86, v86
	v_max_f32_e32 v82, 0, v81
	v_max_f32_e32 v81, v87, v87
	v_max_f32_e32 v84, 0, v84
	v_max_f32_e32 v85, 0, v85
	v_max_f32_e32 v80, 0, v80
	v_max_f32_e32 v81, 0, v81
	v_max_f32_e32 v83, 0, v83
	v_pk_mul_f32 v[84:85], v[84:85], v[84:85]
	v_pk_mul_f32 v[86:87], v[80:81], v[80:81]
	v_pk_mul_f32 v[90:91], v[82:83], v[82:83]
	v_cvt_pk_bf16_f32 v80, v84, v85
	v_cvt_pk_bf16_f32 v81, v86, v87
	v_cvt_pk_bf16_f32 v82, v88, v89
	v_cvt_pk_bf16_f32 v83, v90, v91
	v_max_f32_e32 v72, 0, v72
	v_max_f32_e32 v73, 0, v73
	global_store_dwordx4 v[96:97], v[80:83], off offset:256
	s_nop 1
	v_or_b32_e32 v80, 48, v152
	v_pk_mul_f32 v[82:83], v[72:73], v[72:73]
	v_max_f32_e32 v73, v74, v74
	v_ashrrev_i32_e32 v81, 31, v80
	v_max_f32_e32 v72, v78, v78
	v_max_f32_e32 v74, 0, v73
	v_max_f32_e32 v73, v79, v79
	v_lshlrev_b64 v[80:81], 14, v[80:81]
	v_max_f32_e32 v76, 0, v76
	v_max_f32_e32 v77, 0, v77
	v_max_f32_e32 v72, 0, v72
	v_max_f32_e32 v73, 0, v73
	v_max_f32_e32 v75, 0, v75
	v_lshl_add_u64 v[80:81], s[46:47], 0, v[80:81]
	v_pk_mul_f32 v[76:77], v[76:77], v[76:77]
	v_pk_mul_f32 v[78:79], v[72:73], v[72:73]
	v_pk_mul_f32 v[84:85], v[74:75], v[74:75]
	v_lshl_add_u64 v[80:81], v[80:81], 0, v[156:157]
	v_cvt_pk_bf16_f32 v72, v76, v77
	v_cvt_pk_bf16_f32 v73, v78, v79
	v_cvt_pk_bf16_f32 v74, v82, v83
	v_cvt_pk_bf16_f32 v75, v84, v85
	v_max_f32_e32 v64, 0, v64
	v_max_f32_e32 v65, 0, v65
	global_store_dwordx4 v[80:81], v[72:75], off
	s_nop 1
	v_pk_mul_f32 v[72:73], v[64:65], v[64:65]
	v_max_f32_e32 v65, v66, v66
	v_max_f32_e32 v64, v70, v70
	v_max_f32_e32 v66, 0, v65
	v_max_f32_e32 v65, v71, v71
	v_max_f32_e32 v68, 0, v68
	v_max_f32_e32 v69, 0, v69
	v_max_f32_e32 v64, 0, v64
	v_max_f32_e32 v65, 0, v65
	v_max_f32_e32 v67, 0, v67
	v_pk_mul_f32 v[68:69], v[68:69], v[68:69]
	v_pk_mul_f32 v[70:71], v[64:65], v[64:65]
	v_pk_mul_f32 v[74:75], v[66:67], v[66:67]
	v_cvt_pk_bf16_f32 v64, v68, v69
	v_cvt_pk_bf16_f32 v65, v70, v71
	v_cvt_pk_bf16_f32 v66, v72, v73
	v_cvt_pk_bf16_f32 v67, v74, v75
	v_max_f32_e32 v56, 0, v56
	v_max_f32_e32 v57, 0, v57
	global_store_dwordx4 v[80:81], v[64:67], off offset:256
	s_nop 1
	v_pk_mul_f32 v[66:67], v[56:57], v[56:57]
	v_max_f32_e32 v57, v58, v58
	v_max_f32_e32 v60, 0, v60
	v_max_f32_e32 v61, 0, v61
	v_max_f32_e32 v56, v62, v62
	v_max_f32_e32 v58, 0, v57
	v_max_f32_e32 v57, v63, v63
	v_pk_mul_f32 v[60:61], v[60:61], v[60:61]
	v_max_f32_e32 v56, 0, v56
	v_max_f32_e32 v57, 0, v57
	v_max_f32_e32 v59, 0, v59
	v_pk_mul_f32 v[62:63], v[56:57], v[56:57]
	v_pk_mul_f32 v[68:69], v[58:59], v[58:59]
	v_cvt_pk_bf16_f32 v56, v60, v61
	v_add_co_u32_e32 v60, vcc, s61, v144
	v_cvt_pk_bf16_f32 v57, v62, v63
	v_cvt_pk_bf16_f32 v58, v66, v67
	v_cvt_pk_bf16_f32 v59, v68, v69
	v_addc_co_u32_e32 v61, vcc, 0, v145, vcc
	v_max_f32_e32 v48, 0, v48
	v_max_f32_e32 v49, 0, v49
	global_store_dwordx4 v[60:61], v[56:59], off
	s_nop 1
	v_pk_mul_f32 v[56:57], v[48:49], v[48:49]
	v_max_f32_e32 v49, v50, v50
	v_max_f32_e32 v48, v54, v54
	v_max_f32_e32 v50, 0, v49
	v_max_f32_e32 v49, v55, v55
	v_max_f32_e32 v52, 0, v52
	v_max_f32_e32 v53, 0, v53
	v_max_f32_e32 v48, 0, v48
	v_max_f32_e32 v49, 0, v49
	v_max_f32_e32 v51, 0, v51
	s_mov_b64 s[46:47], 0x200000
	v_pk_mul_f32 v[52:53], v[52:53], v[52:53]
	v_pk_mul_f32 v[54:55], v[48:49], v[48:49]
	v_pk_mul_f32 v[58:59], v[50:51], v[50:51]
; __device__ __forceinline__ unsigned cvt_pk_bf16(float lo, float hi) { const bf16x2_t r = __builtin_convertvector((f32x2){lo, hi}, bf16x2_t); return __builtin_bit_cast(unsigned, r); }
; #define PG8_WAIT_V(n) asm volatile("s_waitcnt vmcnt(" #n ")" ::: "memory")
; #define PG8_BAR __builtin_amdgcn_s_barrier()
; template <class Epi>
; __device__ __forceinline__ void gemm_phase(LAS unsigned char* lds, const bf16_t* A, int lda, const bf16_t* Bt, int ldb, int M, int N, int K, int asel, const Epi& E, const int fixed_round = -1) {
;     ...
;         if (!has_next) break;
; #pragma unroll
;         for (int a = 0; a < 2; ++a)
; #pragma unroll
;             for (int b = 0; b < 2; ++b)
; #pragma unroll
;                 for (int m = 0; m < 4; ++m)
; #pragma unroll
;                     for (int n = 0; n < 2; ++n) acc[a][b][m][n] = (f32x4){0.f, 0.f, 0.f, 0.f};
;         cur = nxt; cA = nA; cB = nB; ++ui;
;     }
;     PG8_WAIT_V(0);
;     if (wr == 0) PG8_BAR;
;     PG8_BAR;
;     __device__ __forceinline__ void operator()(const AccT& acc, const Unit& u, int wr, int wc, int fr, int fq) const {
;     ...
;             for (int m = 0; m < 4; ++m) { bf16_t* rowp = O + (size_t)(row0 + ai * HALF + m * 16) * DFF + col0;
; #pragma unroll
;                 for (int bj = 0; bj < 2; ++bj) { f32x4 v0 = acc[ai][bj][m][0], v1 = acc[ai][bj][m][1];
; #pragma unroll
;                     for (int j = 0; j < 4; ++j) { float a = fmaxf(v0[j], 0.f), b = fmaxf(v1[j], 0.f); v0[j] = a * a; v1[j] = b * b; }
;                     u32x4 w; w.x = cvt_pk_bf16(v0[0], v0[1]); w.y = cvt_pk_bf16(v0[2], v0[3]); w.z = cvt_pk_bf16(v1[0], v1[1]); w.w = cvt_pk_bf16(v1[2], v1[3]);
;                     *(u32x4*)(rowp + bj * HALF) = w; } }
;     }
	v_lshl_add_u64 v[64:65], v[144:145], 0, s[46:47]
	v_cvt_pk_bf16_f32 v48, v52, v53
	v_cvt_pk_bf16_f32 v49, v54, v55
	v_cvt_pk_bf16_f32 v50, v56, v57
	v_cvt_pk_bf16_f32 v51, v58, v59
	v_max_f32_e32 v40, 0, v40
	v_max_f32_e32 v41, 0, v41
	global_store_dwordx4 v[64:65], v[48:51], off offset:256
	s_nop 1
	v_pk_mul_f32 v[50:51], v[40:41], v[40:41]
	v_max_f32_e32 v41, v42, v42
	v_max_f32_e32 v44, 0, v44
	v_max_f32_e32 v45, 0, v45
	v_max_f32_e32 v40, v46, v46
	v_max_f32_e32 v42, 0, v41
	v_max_f32_e32 v41, v47, v47
	v_pk_mul_f32 v[44:45], v[44:45], v[44:45]
	v_max_f32_e32 v40, 0, v40
	v_max_f32_e32 v41, 0, v41
	v_max_f32_e32 v43, 0, v43
	v_pk_mul_f32 v[46:47], v[40:41], v[40:41]
	v_pk_mul_f32 v[52:53], v[42:43], v[42:43]
	v_cvt_pk_bf16_f32 v40, v44, v45
	v_add_co_u32_e32 v44, vcc, s62, v144
	v_cvt_pk_bf16_f32 v41, v46, v47
	v_cvt_pk_bf16_f32 v42, v50, v51
	v_cvt_pk_bf16_f32 v43, v52, v53
	v_addc_co_u32_e32 v45, vcc, 0, v145, vcc
	v_max_f32_e32 v32, 0, v32
	v_max_f32_e32 v33, 0, v33
	global_store_dwordx4 v[44:45], v[40:43], off
	s_nop 1
	v_pk_mul_f32 v[40:41], v[32:33], v[32:33]
	v_max_f32_e32 v33, v34, v34
	v_max_f32_e32 v32, v38, v38
	v_max_f32_e32 v34, 0, v33
	v_max_f32_e32 v33, v39, v39
	v_max_f32_e32 v36, 0, v36
	v_max_f32_e32 v37, 0, v37
	v_max_f32_e32 v32, 0, v32
	v_max_f32_e32 v33, 0, v33
	v_max_f32_e32 v35, 0, v35
	v_pk_mul_f32 v[36:37], v[36:37], v[36:37]
	v_pk_mul_f32 v[38:39], v[32:33], v[32:33]
	v_pk_mul_f32 v[42:43], v[34:35], v[34:35]
	v_lshl_add_u64 v[48:49], v[144:145], 0, s[4:5]
	v_cvt_pk_bf16_f32 v32, v36, v37
	v_cvt_pk_bf16_f32 v33, v38, v39
	v_cvt_pk_bf16_f32 v34, v40, v41
	v_cvt_pk_bf16_f32 v35, v42, v43
	v_max_f32_e32 v24, 0, v24
	v_max_f32_e32 v25, 0, v25
	global_store_dwordx4 v[48:49], v[32:35], off offset:256
	s_nop 1
	v_pk_mul_f32 v[34:35], v[24:25], v[24:25]
	v_max_f32_e32 v25, v26, v26
	v_max_f32_e32 v28, 0, v28
	v_max_f32_e32 v29, 0, v29
	v_max_f32_e32 v24, v30, v30
	v_max_f32_e32 v26, 0, v25
	v_max_f32_e32 v25, v31, v31
	v_pk_mul_f32 v[28:29], v[28:29], v[28:29]
	v_max_f32_e32 v24, 0, v24
	v_max_f32_e32 v25, 0, v25
	v_max_f32_e32 v27, 0, v27
	v_pk_mul_f32 v[30:31], v[24:25], v[24:25]
	v_pk_mul_f32 v[36:37], v[26:27], v[26:27]
	v_cvt_pk_bf16_f32 v24, v28, v29
	v_add_co_u32_e32 v28, vcc, s63, v144
	v_cvt_pk_bf16_f32 v25, v30, v31
	v_cvt_pk_bf16_f32 v26, v34, v35
	v_cvt_pk_bf16_f32 v27, v36, v37
	v_addc_co_u32_e32 v29, vcc, 0, v145, vcc
	v_max_f32_e32 v16, 0, v16
	v_max_f32_e32 v17, 0, v17
	global_store_dwordx4 v[28:29], v[24:27], off
	s_nop 1
	v_pk_mul_f32 v[24:25], v[16:17], v[16:17]
	v_max_f32_e32 v17, v18, v18
	v_max_f32_e32 v16, v22, v22
	v_max_f32_e32 v18, 0, v17
	v_max_f32_e32 v17, v23, v23
	v_max_f32_e32 v20, 0, v20
	v_max_f32_e32 v21, 0, v21
	v_max_f32_e32 v16, 0, v16
	v_max_f32_e32 v17, 0, v17
	v_max_f32_e32 v19, 0, v19
	v_pk_mul_f32 v[20:21], v[20:21], v[20:21]
	v_pk_mul_f32 v[22:23], v[16:17], v[16:17]
	v_pk_mul_f32 v[26:27], v[18:19], v[18:19]
	v_lshl_add_u64 v[32:33], v[144:145], 0, s[6:7]
	v_cvt_pk_bf16_f32 v16, v20, v21
	v_cvt_pk_bf16_f32 v17, v22, v23
	v_cvt_pk_bf16_f32 v18, v24, v25
	v_cvt_pk_bf16_f32 v19, v26, v27
	v_max_f32_e32 v8, 0, v8
	v_max_f32_e32 v9, 0, v9
	global_store_dwordx4 v[32:33], v[16:19], off offset:256
	s_nop 1
	v_pk_mul_f32 v[18:19], v[8:9], v[8:9]
	v_max_f32_e32 v9, v10, v10
	v_max_f32_e32 v12, 0, v12
	v_max_f32_e32 v13, 0, v13
	v_max_f32_e32 v8, v14, v14
	v_max_f32_e32 v10, 0, v9
	v_max_f32_e32 v9, v15, v15
	v_pk_mul_f32 v[12:13], v[12:13], v[12:13]
	v_max_f32_e32 v8, 0, v8
	v_max_f32_e32 v9, 0, v9
	v_max_f32_e32 v11, 0, v11
	v_pk_mul_f32 v[14:15], v[8:9], v[8:9]
	v_pk_mul_f32 v[20:21], v[10:11], v[10:11]
	v_cvt_pk_bf16_f32 v8, v12, v13
	v_add_co_u32_e32 v12, vcc, s64, v144
	v_cvt_pk_bf16_f32 v9, v14, v15
	v_cvt_pk_bf16_f32 v10, v18, v19
	v_cvt_pk_bf16_f32 v11, v20, v21
	v_addc_co_u32_e32 v13, vcc, 0, v145, vcc
	v_max_f32_e32 v0, 0, v0
	v_max_f32_e32 v1, 0, v1
	global_store_dwordx4 v[12:13], v[8:11], off
	s_nop 1
	v_pk_mul_f32 v[8:9], v[0:1], v[0:1]
	v_max_f32_e32 v1, v2, v2
	v_max_f32_e32 v0, v6, v6
	v_max_f32_e32 v2, 0, v1
	v_max_f32_e32 v1, v7, v7
	v_max_f32_e32 v4, 0, v4
	v_max_f32_e32 v5, 0, v5
	v_max_f32_e32 v0, 0, v0
	v_max_f32_e32 v1, 0, v1
	v_max_f32_e32 v3, 0, v3
	v_pk_mul_f32 v[4:5], v[4:5], v[4:5]
	v_pk_mul_f32 v[6:7], v[0:1], v[0:1]
	v_pk_mul_f32 v[10:11], v[2:3], v[2:3]
	v_lshl_add_u64 v[16:17], v[144:145], 0, s[22:23]
	v_cvt_pk_bf16_f32 v0, v4, v5
	v_cvt_pk_bf16_f32 v1, v6, v7
	v_cvt_pk_bf16_f32 v2, v8, v9
	v_cvt_pk_bf16_f32 v3, v10, v11
	s_and_b64 vcc, exec, s[0:1]
	s_mov_b32 s65, s24
	s_mov_b32 s44, s28
	s_mov_b64 s[48:49], s[42:43]
	s_mov_b64 s[46:47], s[40:41]
	s_mov_b64 s[70:71], s[26:27]
	global_store_dwordx4 v[16:17], v[0:3], off offset:256
	s_cbranch_vccz .LBB0_1216
	s_waitcnt vmcnt(0)
	s_cmpk_gt_u32 s33, 0xff
	s_cbranch_scc1 .LBB0_1227
	s_barrier

; #define PG8_STAGE(bufoff, gbase, voff) do { _Pragma("unroll") for (int _i = 0; _i < 2; ++_i) \
;         __builtin_amdgcn_global_load_lds((const unsigned*)((const char*)(gbase) + (voff)[_i]), (LAS unsigned*)(lds + (bufoff) + ldsw + _i * 8192), 16, 0, 0); } while (0)
; #define PG8_LDA(dst, b, h) do { _Pragma("unroll") for (int m = 0; m < 4; ++m) _Pragma("unroll") for (int k = 0; k < 2; ++k) dst[m][k] = *(const LAS bf16x8*)(lds + PG8_SA(b, h) + aoff + m * 2048 + k * 1024); } while (0)
; #define PG8_LDB(dst, b, h) do { _Pragma("unroll") for (int n = 0; n < 2; ++n) _Pragma("unroll") for (int k = 0; k < 2; ++k) dst[n][k] = *(const LAS bf16x8*)(lds + PG8_SB(b, h) + boff + n * 2048 + k * 1024); } while (0)
; #define PG8_WAIT_V(n) asm volatile("s_waitcnt vmcnt(" #n ")" ::: "memory")
; #define PG8_WAIT_L(n) asm volatile("s_waitcnt lgkmcnt(" #n ")" ::: "memory")
; #define PG8_BAR __builtin_amdgcn_s_barrier()
; #define PG8_SCHED __builtin_amdgcn_sched_barrier(0)
; template <class Epi>
; __device__ __forceinline__ void gemm_phase(LAS unsigned char* lds, const bf16_t* A, int lda, const bf16_t* Bt, int ldb, int M, int N, int K, int asel, const Epi& E, const int fixed_round = -1) {
;     ...
;             const bool last = (t == nt - 2);
;             const char* a1 = cA + (size_t)(t + 1) * kstep;
;             const char* a2 = last ? nA : cA + (size_t)(t + 2) * kstep; const char* b2 = last ? nB : cB + (size_t)(t + 2) * kstep;
;             const char* a3 = a2 + kstep; const char* b3 = b2 + kstep;
;             PG8_LDB(B0, 0, 0); PG8_SCHED; PG8_LDA(At, 0, 0); PG8_STAGE(PG8_SA(1, 1), a1 + hstepA, voffA);
;             PG8_WAIT_L(8); PG8_BAR; PG8_WAIT_L(0); PG8_MMA(0, 0, At, B0); PG8_BAR; PG8_SCHED;
;             PG8_LDB(B1, 0, 1); PG8_STAGE(PG8_SB(0, 0), b2, voffB);
;             PG8_BAR; PG8_WAIT_L(0); PG8_MMA(0, 1, At, B1); PG8_BAR;
;             PG8_LDA(At, 0, 1); PG8_STAGE(PG8_SA(0, 0), a2, voffA);
;             PG8_BAR; PG8_WAIT_L(0); PG8_MMA(1, 0, At, B0); PG8_BAR; PG8_SCHED;
;             PG8_STAGE(PG8_SB(0, 1), b2 + hstepB, voffB);
;             PG8_WAIT_V(6); PG8_BAR; PG8_MMA(1, 1, At, B1); PG8_BAR;
.LBB0_1283:
	ds_read_b128 v[146:149], v124
	ds_read_b128 v[150:153], v124 offset:1024
	ds_read_b128 v[154:157], v124 offset:2048
	ds_read_b128 v[158:161], v124 offset:3072
	s_mov_b32 m0, s47
	v_lshl_add_u64 v[194:195], v[120:121], 0, s[22:23]
	ds_read_b128 v[162:165], v125
	ds_read_b128 v[166:169], v125 offset:1024
	ds_read_b128 v[170:173], v125 offset:2048
	ds_read_b128 v[174:177], v125 offset:3072
	ds_read_b128 v[178:181], v125 offset:4096
	ds_read_b128 v[182:185], v125 offset:5120
	ds_read_b128 v[186:189], v125 offset:6144
	ds_read_b128 v[190:193], v125 offset:7168
	global_load_lds_dwordx4 v[194:195], off
	v_lshl_add_u64 v[194:195], v[122:123], 0, s[22:23]
	s_mov_b32 m0, s48
	s_setprio 1
	global_load_lds_dwordx4 v[194:195], off
	s_waitcnt lgkmcnt(8)
	s_barrier
	s_waitcnt lgkmcnt(0)
	v_mfma_f32_16x16x32_bf16 v[140:143], v[146:149], v[162:165], v[140:143]
	v_mfma_f32_16x16x32_bf16 v[136:139], v[154:157], v[162:165], v[136:139]
	v_mfma_f32_16x16x32_bf16 v[108:111], v[146:149], v[170:173], v[108:111]
	v_mfma_f32_16x16x32_bf16 v[104:107], v[154:157], v[170:173], v[104:107]
	v_mfma_f32_16x16x32_bf16 v[92:95], v[146:149], v[178:181], v[92:95]
	v_mfma_f32_16x16x32_bf16 v[88:91], v[154:157], v[178:181], v[88:91]
	v_mfma_f32_16x16x32_bf16 v[76:79], v[146:149], v[186:189], v[76:79]
	v_mfma_f32_16x16x32_bf16 v[72:75], v[154:157], v[186:189], v[72:75]
	v_mfma_f32_16x16x32_bf16 v[140:143], v[150:153], v[166:169], v[140:143]
	v_mfma_f32_16x16x32_bf16 v[136:139], v[158:161], v[166:169], v[136:139]
	v_mfma_f32_16x16x32_bf16 v[108:111], v[150:153], v[174:177], v[108:111]
	v_mfma_f32_16x16x32_bf16 v[104:107], v[158:161], v[174:177], v[104:107]
	v_mfma_f32_16x16x32_bf16 v[92:95], v[150:153], v[182:185], v[92:95]
	v_mfma_f32_16x16x32_bf16 v[88:91], v[158:161], v[182:185], v[88:91]
	v_mfma_f32_16x16x32_bf16 v[76:79], v[150:153], v[190:193], v[76:79]
	v_mfma_f32_16x16x32_bf16 v[72:75], v[158:161], v[190:193], v[72:75]
	s_barrier
	s_setprio 0
	s_add_u32 s24, s16, s22
	s_addc_u32 s25, s17, s23
	s_add_u32 s24, s24, 0x18500100
	s_addc_u32 s25, s25, 0
	s_add_u32 s57, s28, s22
	s_addc_u32 s58, s29, s23
	s_cmpk_eq_i32 s22, 0x3f00
	s_cselect_b32 s27, s87, s25
	s_cselect_b32 s26, s86, s24
	s_cselect_b32 s25, s3, s58
	s_cselect_b32 s24, s2, s57
	s_mov_b32 m0, s49
	s_add_u32 s98, s24, s0
	s_addc_u32 s99, s25, s1
	ds_read_b128 v[194:197], v126
	ds_read_b128 v[204:207], v126 offset:1024
	ds_read_b128 v[208:211], v126 offset:2048
	ds_read_b128 v[212:215], v126 offset:3072
	global_load_lds_dwordx4 v114, s[24:25]
	s_mov_b32 m0, s50
	s_setprio 1
	global_load_lds_dwordx4 v118, s[24:25]
	s_barrier
	s_waitcnt lgkmcnt(0)
	v_mfma_f32_16x16x32_bf16 v[132:135], v[194:197], v[162:165], v[132:135]
	v_mfma_f32_16x16x32_bf16 v[128:131], v[208:211], v[162:165], v[128:131]
	v_mfma_f32_16x16x32_bf16 v[100:103], v[194:197], v[170:173], v[100:103]
	v_mfma_f32_16x16x32_bf16 v[96:99], v[208:211], v[170:173], v[96:99]
	v_mfma_f32_16x16x32_bf16 v[84:87], v[194:197], v[178:181], v[84:87]
	v_mfma_f32_16x16x32_bf16 v[80:83], v[208:211], v[178:181], v[80:83]
	v_mfma_f32_16x16x32_bf16 v[68:71], v[194:197], v[186:189], v[68:71]
	v_mfma_f32_16x16x32_bf16 v[64:67], v[208:211], v[186:189], v[64:67]
	v_mfma_f32_16x16x32_bf16 v[132:135], v[204:207], v[166:169], v[132:135]
	v_mfma_f32_16x16x32_bf16 v[128:131], v[212:215], v[166:169], v[128:131]
	v_mfma_f32_16x16x32_bf16 v[100:103], v[204:207], v[174:177], v[100:103]
	v_mfma_f32_16x16x32_bf16 v[96:99], v[212:215], v[174:177], v[96:99]
	v_mfma_f32_16x16x32_bf16 v[84:87], v[204:207], v[182:185], v[84:87]
	v_mfma_f32_16x16x32_bf16 v[80:83], v[212:215], v[182:185], v[80:83]
	v_mfma_f32_16x16x32_bf16 v[68:71], v[204:207], v[190:193], v[68:71]
	v_mfma_f32_16x16x32_bf16 v[64:67], v[212:215], v[190:193], v[64:67]
	s_barrier
	s_setprio 0
	s_mov_b32 m0, s40
	s_add_u32 s100, s26, s0
	s_addc_u32 s101, s27, s1
	ds_read_b128 v[162:165], v125 offset:16384
	ds_read_b128 v[166:169], v125 offset:17408
	ds_read_b128 v[170:173], v125 offset:18432
	ds_read_b128 v[174:177], v125 offset:19456
	ds_read_b128 v[178:181], v125 offset:20480
	ds_read_b128 v[182:185], v125 offset:21504
	ds_read_b128 v[186:189], v125 offset:22528
	ds_read_b128 v[190:193], v125 offset:23552
	global_load_lds_dwordx4 v112, s[26:27]
	s_mov_b32 m0, s41
	s_setprio 1
	global_load_lds_dwordx4 v116, s[26:27]
	s_barrier
	s_waitcnt lgkmcnt(0)
	v_mfma_f32_16x16x32_bf16 v[60:63], v[146:149], v[162:165], v[60:63]
	v_mfma_f32_16x16x32_bf16 v[56:59], v[154:157], v[162:165], v[56:59]
	v_mfma_f32_16x16x32_bf16 v[44:47], v[146:149], v[170:173], v[44:47]
	v_mfma_f32_16x16x32_bf16 v[40:43], v[154:157], v[170:173], v[40:43]
	v_mfma_f32_16x16x32_bf16 v[28:31], v[146:149], v[178:181], v[28:31]
	v_mfma_f32_16x16x32_bf16 v[24:27], v[154:157], v[178:181], v[24:27]
	v_mfma_f32_16x16x32_bf16 v[12:15], v[146:149], v[186:189], v[12:15]
	v_mfma_f32_16x16x32_bf16 v[8:11], v[154:157], v[186:189], v[8:11]
	v_mfma_f32_16x16x32_bf16 v[60:63], v[150:153], v[166:169], v[60:63]
	v_mfma_f32_16x16x32_bf16 v[56:59], v[158:161], v[166:169], v[56:59]
	v_mfma_f32_16x16x32_bf16 v[44:47], v[150:153], v[174:177], v[44:47]
	v_mfma_f32_16x16x32_bf16 v[40:43], v[158:161], v[174:177], v[40:43]
	v_mfma_f32_16x16x32_bf16 v[28:31], v[150:153], v[182:185], v[28:31]
	v_mfma_f32_16x16x32_bf16 v[24:27], v[158:161], v[182:185], v[24:27]
	v_mfma_f32_16x16x32_bf16 v[12:15], v[150:153], v[190:193], v[12:15]
	v_mfma_f32_16x16x32_bf16 v[8:11], v[158:161], v[190:193], v[8:11]
	s_barrier
	s_setprio 0
	s_add_u32 s58, s24, 0x200000
	s_addc_u32 s59, s25, 0
	s_mov_b32 m0, s51
	s_nop 0
	global_load_lds_dwordx4 v114, s[58:59]
	s_mov_b32 m0, s52
	s_setprio 1
	global_load_lds_dwordx4 v118, s[58:59]
	s_waitcnt vmcnt(6)
	s_barrier
; #define PG8_STAGE(bufoff, gbase, voff) do { _Pragma("unroll") for (int _i = 0; _i < 2; ++_i) \
;         __builtin_amdgcn_global_load_lds((const unsigned*)((const char*)(gbase) + (voff)[_i]), (LAS unsigned*)(lds + (bufoff) + ldsw + _i * 8192), 16, 0, 0); } while (0)
; #define PG8_LDA(dst, b, h) do { _Pragma("unroll") for (int m = 0; m < 4; ++m) _Pragma("unroll") for (int k = 0; k < 2; ++k) dst[m][k] = *(const LAS bf16x8*)(lds + PG8_SA(b, h) + aoff + m * 2048 + k * 1024); } while (0)
; #define PG8_LDB(dst, b, h) do { _Pragma("unroll") for (int n = 0; n < 2; ++n) _Pragma("unroll") for (int k = 0; k < 2; ++k) dst[n][k] = *(const LAS bf16x8*)(lds + PG8_SB(b, h) + boff + n * 2048 + k * 1024); } while (0)
; #define PG8_WAIT_V(n) asm volatile("s_waitcnt vmcnt(" #n ")" ::: "memory")
; #define PG8_WAIT_L(n) asm volatile("s_waitcnt lgkmcnt(" #n ")" ::: "memory")
; #define PG8_BAR __builtin_amdgcn_s_barrier()
; #define PG8_SCHED __builtin_amdgcn_sched_barrier(0)
; template <class Epi>
; __device__ __forceinline__ void gemm_phase(LAS unsigned char* lds, const bf16_t* A, int lda, const bf16_t* Bt, int ldb, int M, int N, int K, int asel, const Epi& E, const int fixed_round = -1) {
;     ...
;             PG8_WAIT_V(6); PG8_BAR; PG8_MMA(1, 1, At, B1); PG8_BAR;
;             PG8_LDB(B0, 1, 0); PG8_SCHED; PG8_LDA(At, 1, 0); PG8_STAGE(PG8_SA(0, 1), a2 + hstepA, voffA);
;             PG8_WAIT_L(8); PG8_BAR; PG8_WAIT_L(0); PG8_MMA(0, 0, At, B0); PG8_BAR; PG8_SCHED;
;             PG8_LDB(B1, 1, 1); PG8_STAGE(PG8_SB(1, 0), b3, voffB);
;             PG8_BAR; PG8_WAIT_L(0); PG8_MMA(0, 1, At, B1); PG8_BAR;
;             PG8_LDA(At, 1, 1); PG8_STAGE(PG8_SA(1, 0), a3, voffA);
;             PG8_BAR; PG8_WAIT_L(0); PG8_MMA(1, 0, At, B0); PG8_BAR; PG8_SCHED;
	v_mfma_f32_16x16x32_bf16 v[52:55], v[194:197], v[162:165], v[52:55]
	v_mfma_f32_16x16x32_bf16 v[48:51], v[208:211], v[162:165], v[48:51]
	v_mfma_f32_16x16x32_bf16 v[36:39], v[194:197], v[170:173], v[36:39]
	v_mfma_f32_16x16x32_bf16 v[32:35], v[208:211], v[170:173], v[32:35]
	v_mfma_f32_16x16x32_bf16 v[20:23], v[194:197], v[178:181], v[20:23]
	v_mfma_f32_16x16x32_bf16 v[16:19], v[208:211], v[178:181], v[16:19]
	v_mfma_f32_16x16x32_bf16 v[4:7], v[194:197], v[186:189], v[4:7]
	v_mfma_f32_16x16x32_bf16 v[0:3], v[208:211], v[186:189], v[0:3]
	v_mfma_f32_16x16x32_bf16 v[52:55], v[204:207], v[166:169], v[52:55]
	v_mfma_f32_16x16x32_bf16 v[48:51], v[212:215], v[166:169], v[48:51]
	v_mfma_f32_16x16x32_bf16 v[36:39], v[204:207], v[174:177], v[36:39]
	v_mfma_f32_16x16x32_bf16 v[32:35], v[212:215], v[174:177], v[32:35]
	v_mfma_f32_16x16x32_bf16 v[20:23], v[204:207], v[182:185], v[20:23]
	v_mfma_f32_16x16x32_bf16 v[16:19], v[212:215], v[182:185], v[16:19]
	v_mfma_f32_16x16x32_bf16 v[4:7], v[204:207], v[190:193], v[4:7]
	v_mfma_f32_16x16x32_bf16 v[0:3], v[212:215], v[190:193], v[0:3]
	s_barrier
	s_setprio 0
	ds_read_b128 v[146:149], v127
	ds_read_b128 v[150:153], v127 offset:1024
	ds_read_b128 v[154:157], v127 offset:2048
	ds_read_b128 v[158:161], v127 offset:3072
	s_add_u32 s26, s26, 0x200000
	s_addc_u32 s27, s27, 0
	s_mov_b32 m0, s42
	ds_read_b128 v[162:165], v125 offset:32768
	ds_read_b128 v[166:169], v125 offset:33792
	ds_read_b128 v[170:173], v125 offset:34816
	ds_read_b128 v[174:177], v125 offset:35840
	ds_read_b128 v[178:181], v125 offset:36864
	ds_read_b128 v[182:185], v125 offset:37888
	ds_read_b128 v[186:189], v125 offset:38912
	ds_read_b128 v[190:193], v125 offset:39936
	global_load_lds_dwordx4 v112, s[26:27]
	s_mov_b32 m0, s43
	s_setprio 1
	global_load_lds_dwordx4 v116, s[26:27]
	s_waitcnt lgkmcnt(8)
	s_barrier
	s_waitcnt lgkmcnt(0)
	v_mfma_f32_16x16x32_bf16 v[140:143], v[146:149], v[162:165], v[140:143]
	v_mfma_f32_16x16x32_bf16 v[136:139], v[154:157], v[162:165], v[136:139]
	v_mfma_f32_16x16x32_bf16 v[108:111], v[146:149], v[170:173], v[108:111]
	v_mfma_f32_16x16x32_bf16 v[104:107], v[154:157], v[170:173], v[104:107]
	v_mfma_f32_16x16x32_bf16 v[92:95], v[146:149], v[178:181], v[92:95]
	v_mfma_f32_16x16x32_bf16 v[88:91], v[154:157], v[178:181], v[88:91]
	v_mfma_f32_16x16x32_bf16 v[76:79], v[146:149], v[186:189], v[76:79]
	v_mfma_f32_16x16x32_bf16 v[72:75], v[154:157], v[186:189], v[72:75]
	v_mfma_f32_16x16x32_bf16 v[140:143], v[150:153], v[166:169], v[140:143]
	v_mfma_f32_16x16x32_bf16 v[136:139], v[158:161], v[166:169], v[136:139]
	v_mfma_f32_16x16x32_bf16 v[108:111], v[150:153], v[174:177], v[108:111]
	v_mfma_f32_16x16x32_bf16 v[104:107], v[158:161], v[174:177], v[104:107]
	v_mfma_f32_16x16x32_bf16 v[92:95], v[150:153], v[182:185], v[92:95]
	v_mfma_f32_16x16x32_bf16 v[88:91], v[158:161], v[182:185], v[88:91]
	v_mfma_f32_16x16x32_bf16 v[76:79], v[150:153], v[190:193], v[76:79]
	v_mfma_f32_16x16x32_bf16 v[72:75], v[158:161], v[190:193], v[72:75]
	s_barrier
	s_setprio 0
	s_mov_b32 m0, s53
	ds_read_b128 v[194:197], v144
	ds_read_b128 v[204:207], v144 offset:1024
	ds_read_b128 v[208:211], v144 offset:2048
	ds_read_b128 v[212:215], v144 offset:3072
	global_load_lds_dwordx4 v114, s[98:99]
	s_mov_b32 m0, s54
	s_setprio 1
	global_load_lds_dwordx4 v118, s[98:99]
	s_barrier
	s_waitcnt lgkmcnt(0)
	v_mfma_f32_16x16x32_bf16 v[132:135], v[194:197], v[162:165], v[132:135]
	v_mfma_f32_16x16x32_bf16 v[128:131], v[208:211], v[162:165], v[128:131]
	v_mfma_f32_16x16x32_bf16 v[100:103], v[194:197], v[170:173], v[100:103]
	v_mfma_f32_16x16x32_bf16 v[96:99], v[208:211], v[170:173], v[96:99]
	v_mfma_f32_16x16x32_bf16 v[84:87], v[194:197], v[178:181], v[84:87]
	v_mfma_f32_16x16x32_bf16 v[80:83], v[208:211], v[178:181], v[80:83]
	v_mfma_f32_16x16x32_bf16 v[68:71], v[194:197], v[186:189], v[68:71]
	v_mfma_f32_16x16x32_bf16 v[64:67], v[208:211], v[186:189], v[64:67]
	v_mfma_f32_16x16x32_bf16 v[132:135], v[204:207], v[166:169], v[132:135]
	v_mfma_f32_16x16x32_bf16 v[128:131], v[212:215], v[166:169], v[128:131]
	v_mfma_f32_16x16x32_bf16 v[100:103], v[204:207], v[174:177], v[100:103]
	v_mfma_f32_16x16x32_bf16 v[96:99], v[212:215], v[174:177], v[96:99]
	v_mfma_f32_16x16x32_bf16 v[84:87], v[204:207], v[182:185], v[84:87]
	v_mfma_f32_16x16x32_bf16 v[80:83], v[212:215], v[182:185], v[80:83]
	v_mfma_f32_16x16x32_bf16 v[68:71], v[204:207], v[190:193], v[68:71]
	v_mfma_f32_16x16x32_bf16 v[64:67], v[212:215], v[190:193], v[64:67]
	s_barrier
; #define PG8_STAGE(bufoff, gbase, voff) do { _Pragma("unroll") for (int _i = 0; _i < 2; ++_i) \
;         __builtin_amdgcn_global_load_lds((const unsigned*)((const char*)(gbase) + (voff)[_i]), (LAS unsigned*)(lds + (bufoff) + ldsw + _i * 8192), 16, 0, 0); } while (0)
; #define PG8_WAIT_V(n) asm volatile("s_waitcnt vmcnt(" #n ")" ::: "memory")
; #define PG8_WAIT_L(n) asm volatile("s_waitcnt lgkmcnt(" #n ")" ::: "memory")
; #define PG8_BAR __builtin_amdgcn_s_barrier()
; #define PG8_SCHED __builtin_amdgcn_sched_barrier(0)
; template <class Epi>
; __device__ __forceinline__ void gemm_phase(LAS unsigned char* lds, const bf16_t* A, int lda, const bf16_t* Bt, int ldb, int M, int N, int K, int asel, const Epi& E, const int fixed_round = -1) {
;     ...
;             PG8_BAR; PG8_WAIT_L(0); PG8_MMA(1, 0, At, B0); PG8_BAR; PG8_SCHED;
;             PG8_STAGE(PG8_SB(1, 1), b3 + hstepB, voffB);
;             PG8_WAIT_V(6); PG8_BAR; PG8_MMA(1, 1, At, B1); PG8_BAR;
;     ...
;     PG8_WAIT_V(0);
;     if (wr == 0) PG8_BAR;
;     PG8_BAR;
	s_setprio 0
	s_mov_b32 m0, s44
	ds_read_b128 v[162:165], v125 offset:49152
	ds_read_b128 v[166:169], v125 offset:50176
	ds_read_b128 v[170:173], v125 offset:51200
	ds_read_b128 v[174:177], v125 offset:52224
	ds_read_b128 v[178:181], v125 offset:53248
	ds_read_b128 v[182:185], v125 offset:54272
	ds_read_b128 v[186:189], v125 offset:55296
	ds_read_b128 v[190:193], v125 offset:56320
	global_load_lds_dwordx4 v112, s[100:101]
	s_mov_b32 m0, s45
	s_setprio 1
	global_load_lds_dwordx4 v116, s[100:101]
	s_barrier
	s_waitcnt lgkmcnt(0)
	v_mfma_f32_16x16x32_bf16 v[60:63], v[146:149], v[162:165], v[60:63]
	v_mfma_f32_16x16x32_bf16 v[56:59], v[154:157], v[162:165], v[56:59]
	v_mfma_f32_16x16x32_bf16 v[44:47], v[146:149], v[170:173], v[44:47]
	v_mfma_f32_16x16x32_bf16 v[40:43], v[154:157], v[170:173], v[40:43]
	v_mfma_f32_16x16x32_bf16 v[28:31], v[146:149], v[178:181], v[28:31]
	v_mfma_f32_16x16x32_bf16 v[24:27], v[154:157], v[178:181], v[24:27]
	v_mfma_f32_16x16x32_bf16 v[12:15], v[146:149], v[186:189], v[12:15]
	v_mfma_f32_16x16x32_bf16 v[8:11], v[154:157], v[186:189], v[8:11]
	v_mfma_f32_16x16x32_bf16 v[60:63], v[150:153], v[166:169], v[60:63]
	v_mfma_f32_16x16x32_bf16 v[56:59], v[158:161], v[166:169], v[56:59]
	v_mfma_f32_16x16x32_bf16 v[44:47], v[150:153], v[174:177], v[44:47]
	v_mfma_f32_16x16x32_bf16 v[40:43], v[158:161], v[174:177], v[40:43]
	v_mfma_f32_16x16x32_bf16 v[28:31], v[150:153], v[182:185], v[28:31]
	v_mfma_f32_16x16x32_bf16 v[24:27], v[158:161], v[182:185], v[24:27]
	v_mfma_f32_16x16x32_bf16 v[12:15], v[150:153], v[190:193], v[12:15]
	v_mfma_f32_16x16x32_bf16 v[8:11], v[158:161], v[190:193], v[8:11]
	s_barrier
	s_setprio 0
	s_add_u32 s24, s24, 0x200080
	s_addc_u32 s25, s25, 0
	s_mov_b32 m0, s55
	s_nop 0
	global_load_lds_dwordx4 v114, s[24:25]
	s_mov_b32 m0, s56
	s_setprio 1
	global_load_lds_dwordx4 v118, s[24:25]
	s_waitcnt vmcnt(6)
	s_barrier
	v_mfma_f32_16x16x32_bf16 v[52:55], v[194:197], v[162:165], v[52:55]
	v_mfma_f32_16x16x32_bf16 v[48:51], v[208:211], v[162:165], v[48:51]
	v_mfma_f32_16x16x32_bf16 v[36:39], v[194:197], v[170:173], v[36:39]
	v_mfma_f32_16x16x32_bf16 v[32:35], v[208:211], v[170:173], v[32:35]
	v_mfma_f32_16x16x32_bf16 v[20:23], v[194:197], v[178:181], v[20:23]
	v_mfma_f32_16x16x32_bf16 v[16:19], v[208:211], v[178:181], v[16:19]
	v_mfma_f32_16x16x32_bf16 v[4:7], v[194:197], v[186:189], v[4:7]
	v_mfma_f32_16x16x32_bf16 v[0:3], v[208:211], v[186:189], v[0:3]
	v_mfma_f32_16x16x32_bf16 v[52:55], v[204:207], v[166:169], v[52:55]
	v_mfma_f32_16x16x32_bf16 v[48:51], v[212:215], v[166:169], v[48:51]
	v_mfma_f32_16x16x32_bf16 v[36:39], v[204:207], v[174:177], v[36:39]
	v_mfma_f32_16x16x32_bf16 v[32:35], v[212:215], v[174:177], v[32:35]
	v_mfma_f32_16x16x32_bf16 v[20:23], v[204:207], v[182:185], v[20:23]
	v_mfma_f32_16x16x32_bf16 v[16:19], v[212:215], v[182:185], v[16:19]
	v_mfma_f32_16x16x32_bf16 v[4:7], v[204:207], v[190:193], v[4:7]
	v_mfma_f32_16x16x32_bf16 v[0:3], v[212:215], v[190:193], v[0:3]
	s_setprio 0
	s_add_i32 s46, s46, 2
	s_add_u32 s22, s22, 0x100
	s_addc_u32 s23, s23, 0
	s_cmpk_lt_u32 s46, 0x7e
	s_cbranch_scc1 .Lrot_11
	s_barrier
	s_waitcnt vmcnt(0)
	v_readlane_b32 s48, v254, 0
	s_cmpk_gt_u32 s33, 0xff
	v_readlane_b32 s54, v254, 6
	v_readlane_b32 s55, v254, 7
	v_readlane_b32 s49, v254, 1
	v_readlane_b32 s50, v254, 2
	v_readlane_b32 s51, v254, 3
	v_readlane_b32 s52, v254, 4
	v_readlane_b32 s53, v254, 5
	s_cbranch_scc1 .LBB0_1286
	s_barrier

; #define PG8_STAGE(bufoff, gbase, voff) do { _Pragma("unroll") for (int _i = 0; _i < 2; ++_i) \
;         __builtin_amdgcn_global_load_lds((const unsigned*)((const char*)(gbase) + (voff)[_i]), (LAS unsigned*)(lds + (bufoff) + ldsw + _i * 8192), 16, 0, 0); } while (0)
; #define PG8_LDA(dst, b, h) do { _Pragma("unroll") for (int m = 0; m < 4; ++m) _Pragma("unroll") for (int k = 0; k < 2; ++k) dst[m][k] = *(const LAS bf16x8*)(lds + PG8_SA(b, h) + aoff + m * 2048 + k * 1024); } while (0)
; #define PG8_LDB(dst, b, h) do { _Pragma("unroll") for (int n = 0; n < 2; ++n) _Pragma("unroll") for (int k = 0; k < 2; ++k) dst[n][k] = *(const LAS bf16x8*)(lds + PG8_SB(b, h) + boff + n * 2048 + k * 1024); } while (0)
; #define PG8_WAIT_V(n) asm volatile("s_waitcnt vmcnt(" #n ")" ::: "memory")
; #define PG8_WAIT_L(n) asm volatile("s_waitcnt lgkmcnt(" #n ")" ::: "memory")
; #define PG8_BAR __builtin_amdgcn_s_barrier()
; #define PG8_SCHED __builtin_amdgcn_sched_barrier(0)
; template <class Epi>
; __device__ __forceinline__ void gemm_phase(LAS unsigned char* lds, const bf16_t* A, int lda, const bf16_t* Bt, int ldb, int M, int N, int K, int asel, const Epi& E, const int fixed_round = -1) {
;     ...
;             const bool last = (t == nt - 2);
;             const char* a1 = cA + (size_t)(t + 1) * kstep;
;             const char* a2 = last ? nA : cA + (size_t)(t + 2) * kstep; const char* b2 = last ? nB : cB + (size_t)(t + 2) * kstep;
;             const char* a3 = a2 + kstep; const char* b3 = b2 + kstep;
;             PG8_LDB(B0, 0, 0); PG8_SCHED; PG8_LDA(At, 0, 0); PG8_STAGE(PG8_SA(1, 1), a1 + hstepA, voffA);
;             PG8_WAIT_L(8); PG8_BAR; PG8_WAIT_L(0); PG8_MMA(0, 0, At, B0); PG8_BAR; PG8_SCHED;
;             PG8_LDB(B1, 0, 1); PG8_STAGE(PG8_SB(0, 0), b2, voffB);
;             PG8_BAR; PG8_WAIT_L(0); PG8_MMA(0, 1, At, B1); PG8_BAR;
;             PG8_LDA(At, 0, 1); PG8_STAGE(PG8_SA(0, 0), a2, voffA);
;             PG8_BAR; PG8_WAIT_L(0); PG8_MMA(1, 0, At, B0); PG8_BAR; PG8_SCHED;
;             PG8_STAGE(PG8_SB(0, 1), b2 + hstepB, voffB);
;             PG8_WAIT_V(6); PG8_BAR; PG8_MMA(1, 1, At, B1); PG8_BAR;
.LBB0_1322:
	ds_read_b128 v[144:147], v122
	ds_read_b128 v[148:151], v122 offset:1024
	ds_read_b128 v[152:155], v122 offset:2048
	ds_read_b128 v[156:159], v122 offset:3072
	s_mov_b32 m0, s35
	v_lshl_add_u64 v[192:193], v[118:119], 0, s[6:7]
	ds_read_b128 v[160:163], v123
	ds_read_b128 v[164:167], v123 offset:1024
	ds_read_b128 v[168:171], v123 offset:2048
	ds_read_b128 v[172:175], v123 offset:3072
	ds_read_b128 v[176:179], v123 offset:4096
	ds_read_b128 v[180:183], v123 offset:5120
	ds_read_b128 v[184:187], v123 offset:6144
	ds_read_b128 v[188:191], v123 offset:7168
	global_load_lds_dwordx4 v[192:193], off
	v_lshl_add_u64 v[192:193], v[120:121], 0, s[6:7]
	s_mov_b32 m0, s40
	s_setprio 1
	global_load_lds_dwordx4 v[192:193], off
	s_waitcnt lgkmcnt(8)
	s_barrier
	s_waitcnt lgkmcnt(0)
	v_mfma_f32_16x16x32_bf16 v[140:143], v[144:147], v[160:163], v[140:143]
	v_mfma_f32_16x16x32_bf16 v[136:139], v[152:155], v[160:163], v[136:139]
	v_mfma_f32_16x16x32_bf16 v[108:111], v[144:147], v[168:171], v[108:111]
	v_mfma_f32_16x16x32_bf16 v[104:107], v[152:155], v[168:171], v[104:107]
	v_mfma_f32_16x16x32_bf16 v[92:95], v[144:147], v[176:179], v[92:95]
	v_mfma_f32_16x16x32_bf16 v[88:91], v[152:155], v[176:179], v[88:91]
	v_mfma_f32_16x16x32_bf16 v[76:79], v[144:147], v[184:187], v[76:79]
	v_mfma_f32_16x16x32_bf16 v[72:75], v[152:155], v[184:187], v[72:75]
	v_mfma_f32_16x16x32_bf16 v[140:143], v[148:151], v[164:167], v[140:143]
	v_mfma_f32_16x16x32_bf16 v[136:139], v[156:159], v[164:167], v[136:139]
	v_mfma_f32_16x16x32_bf16 v[108:111], v[148:151], v[172:175], v[108:111]
	v_mfma_f32_16x16x32_bf16 v[104:107], v[156:159], v[172:175], v[104:107]
	v_mfma_f32_16x16x32_bf16 v[92:95], v[148:151], v[180:183], v[92:95]
	v_mfma_f32_16x16x32_bf16 v[88:91], v[156:159], v[180:183], v[88:91]
	v_mfma_f32_16x16x32_bf16 v[76:79], v[148:151], v[188:191], v[76:79]
	v_mfma_f32_16x16x32_bf16 v[72:75], v[156:159], v[188:191], v[72:75]
	s_barrier
	s_setprio 0
	s_add_u32 s8, s4, s6
	s_addc_u32 s9, s5, s7
	s_add_u32 s8, s8, 0x18500100
	s_addc_u32 s9, s9, 0
	s_add_u32 s49, s28, s6
	s_addc_u32 s50, s29, s7
	s_cmpk_eq_i32 s6, 0x3f00
	s_cselect_b32 s13, s11, s9
	s_cselect_b32 s12, s10, s8
	s_cselect_b32 s9, s3, s50
	s_cselect_b32 s8, s2, s49
	s_mov_b32 m0, s41
	s_add_u32 s98, s8, s0
	s_addc_u32 s99, s9, s1
	ds_read_b128 v[192:195], v124
	ds_read_b128 v[196:199], v124 offset:1024
	ds_read_b128 v[204:207], v124 offset:2048
	ds_read_b128 v[208:211], v124 offset:3072
	global_load_lds_dwordx4 v202, s[8:9]
	s_mov_b32 m0, s42
	s_setprio 1
	global_load_lds_dwordx4 v116, s[8:9]
	s_barrier
	s_waitcnt lgkmcnt(0)
	v_mfma_f32_16x16x32_bf16 v[132:135], v[192:195], v[160:163], v[132:135]
	v_mfma_f32_16x16x32_bf16 v[128:131], v[204:207], v[160:163], v[128:131]
	v_mfma_f32_16x16x32_bf16 v[100:103], v[192:195], v[168:171], v[100:103]
	v_mfma_f32_16x16x32_bf16 v[96:99], v[204:207], v[168:171], v[96:99]
	v_mfma_f32_16x16x32_bf16 v[84:87], v[192:195], v[176:179], v[84:87]
	v_mfma_f32_16x16x32_bf16 v[80:83], v[204:207], v[176:179], v[80:83]
	v_mfma_f32_16x16x32_bf16 v[68:71], v[192:195], v[184:187], v[68:71]
	v_mfma_f32_16x16x32_bf16 v[64:67], v[204:207], v[184:187], v[64:67]
	v_mfma_f32_16x16x32_bf16 v[132:135], v[196:199], v[164:167], v[132:135]
	v_mfma_f32_16x16x32_bf16 v[128:131], v[208:211], v[164:167], v[128:131]
	v_mfma_f32_16x16x32_bf16 v[100:103], v[196:199], v[172:175], v[100:103]
	v_mfma_f32_16x16x32_bf16 v[96:99], v[208:211], v[172:175], v[96:99]
	v_mfma_f32_16x16x32_bf16 v[84:87], v[196:199], v[180:183], v[84:87]
	v_mfma_f32_16x16x32_bf16 v[80:83], v[208:211], v[180:183], v[80:83]
	v_mfma_f32_16x16x32_bf16 v[68:71], v[196:199], v[188:191], v[68:71]
	v_mfma_f32_16x16x32_bf16 v[64:67], v[208:211], v[188:191], v[64:67]
	s_barrier
	s_setprio 0
	s_mov_b32 m0, s19
	s_add_u32 s100, s12, s0
	s_addc_u32 s101, s13, s1
	ds_read_b128 v[160:163], v123 offset:16384
	ds_read_b128 v[164:167], v123 offset:17408
	ds_read_b128 v[168:171], v123 offset:18432
	ds_read_b128 v[172:175], v123 offset:19456
	ds_read_b128 v[176:179], v123 offset:20480
	ds_read_b128 v[180:183], v123 offset:21504
	ds_read_b128 v[184:187], v123 offset:22528
	ds_read_b128 v[188:191], v123 offset:23552
	global_load_lds_dwordx4 v112, s[12:13]
	s_mov_b32 m0, s30
	s_setprio 1
	global_load_lds_dwordx4 v114, s[12:13]
	s_barrier
	s_waitcnt lgkmcnt(0)
	v_mfma_f32_16x16x32_bf16 v[60:63], v[144:147], v[160:163], v[60:63]
	v_mfma_f32_16x16x32_bf16 v[56:59], v[152:155], v[160:163], v[56:59]
	v_mfma_f32_16x16x32_bf16 v[44:47], v[144:147], v[168:171], v[44:47]
	v_mfma_f32_16x16x32_bf16 v[40:43], v[152:155], v[168:171], v[40:43]
	v_mfma_f32_16x16x32_bf16 v[28:31], v[144:147], v[176:179], v[28:31]
	v_mfma_f32_16x16x32_bf16 v[24:27], v[152:155], v[176:179], v[24:27]
	v_mfma_f32_16x16x32_bf16 v[12:15], v[144:147], v[184:187], v[12:15]
	v_mfma_f32_16x16x32_bf16 v[8:11], v[152:155], v[184:187], v[8:11]
	v_mfma_f32_16x16x32_bf16 v[60:63], v[148:151], v[164:167], v[60:63]
	v_mfma_f32_16x16x32_bf16 v[56:59], v[156:159], v[164:167], v[56:59]
	v_mfma_f32_16x16x32_bf16 v[44:47], v[148:151], v[172:175], v[44:47]
	v_mfma_f32_16x16x32_bf16 v[40:43], v[156:159], v[172:175], v[40:43]
	v_mfma_f32_16x16x32_bf16 v[28:31], v[148:151], v[180:183], v[28:31]
	v_mfma_f32_16x16x32_bf16 v[24:27], v[156:159], v[180:183], v[24:27]
	v_mfma_f32_16x16x32_bf16 v[12:15], v[148:151], v[188:191], v[12:15]
	v_mfma_f32_16x16x32_bf16 v[8:11], v[156:159], v[188:191], v[8:11]
	s_barrier
	s_setprio 0
	s_add_u32 s50, s8, 0x200000
	s_addc_u32 s51, s9, 0
	s_mov_b32 m0, s43
	s_nop 0
	global_load_lds_dwordx4 v202, s[50:51]
	s_mov_b32 m0, s44
	s_setprio 1
	global_load_lds_dwordx4 v116, s[50:51]
	s_waitcnt vmcnt(6)
	s_barrier
; #define PG8_STAGE(bufoff, gbase, voff) do { _Pragma("unroll") for (int _i = 0; _i < 2; ++_i) \
;         __builtin_amdgcn_global_load_lds((const unsigned*)((const char*)(gbase) + (voff)[_i]), (LAS unsigned*)(lds + (bufoff) + ldsw + _i * 8192), 16, 0, 0); } while (0)
; #define PG8_LDA(dst, b, h) do { _Pragma("unroll") for (int m = 0; m < 4; ++m) _Pragma("unroll") for (int k = 0; k < 2; ++k) dst[m][k] = *(const LAS bf16x8*)(lds + PG8_SA(b, h) + aoff + m * 2048 + k * 1024); } while (0)
; #define PG8_LDB(dst, b, h) do { _Pragma("unroll") for (int n = 0; n < 2; ++n) _Pragma("unroll") for (int k = 0; k < 2; ++k) dst[n][k] = *(const LAS bf16x8*)(lds + PG8_SB(b, h) + boff + n * 2048 + k * 1024); } while (0)
; #define PG8_WAIT_V(n) asm volatile("s_waitcnt vmcnt(" #n ")" ::: "memory")
; #define PG8_WAIT_L(n) asm volatile("s_waitcnt lgkmcnt(" #n ")" ::: "memory")
; #define PG8_BAR __builtin_amdgcn_s_barrier()
; #define PG8_SCHED __builtin_amdgcn_sched_barrier(0)
; template <class Epi>
; __device__ __forceinline__ void gemm_phase(LAS unsigned char* lds, const bf16_t* A, int lda, const bf16_t* Bt, int ldb, int M, int N, int K, int asel, const Epi& E, const int fixed_round = -1) {
;     ...
;             PG8_WAIT_V(6); PG8_BAR; PG8_MMA(1, 1, At, B1); PG8_BAR;
;             PG8_LDB(B0, 1, 0); PG8_SCHED; PG8_LDA(At, 1, 0); PG8_STAGE(PG8_SA(0, 1), a2 + hstepA, voffA);
;             PG8_WAIT_L(8); PG8_BAR; PG8_WAIT_L(0); PG8_MMA(0, 0, At, B0); PG8_BAR; PG8_SCHED;
;             PG8_LDB(B1, 1, 1); PG8_STAGE(PG8_SB(1, 0), b3, voffB);
;             PG8_BAR; PG8_WAIT_L(0); PG8_MMA(0, 1, At, B1); PG8_BAR;
;             PG8_LDA(At, 1, 1); PG8_STAGE(PG8_SA(1, 0), a3, voffA);
	v_mfma_f32_16x16x32_bf16 v[52:55], v[192:195], v[160:163], v[52:55]
	v_mfma_f32_16x16x32_bf16 v[48:51], v[204:207], v[160:163], v[48:51]
	v_mfma_f32_16x16x32_bf16 v[36:39], v[192:195], v[168:171], v[36:39]
	v_mfma_f32_16x16x32_bf16 v[32:35], v[204:207], v[168:171], v[32:35]
	v_mfma_f32_16x16x32_bf16 v[20:23], v[192:195], v[176:179], v[20:23]
	v_mfma_f32_16x16x32_bf16 v[16:19], v[204:207], v[176:179], v[16:19]
	v_mfma_f32_16x16x32_bf16 v[4:7], v[192:195], v[184:187], v[4:7]
	v_mfma_f32_16x16x32_bf16 v[0:3], v[204:207], v[184:187], v[0:3]
	v_mfma_f32_16x16x32_bf16 v[52:55], v[196:199], v[164:167], v[52:55]
	v_mfma_f32_16x16x32_bf16 v[48:51], v[208:211], v[164:167], v[48:51]
	v_mfma_f32_16x16x32_bf16 v[36:39], v[196:199], v[172:175], v[36:39]
	v_mfma_f32_16x16x32_bf16 v[32:35], v[208:211], v[172:175], v[32:35]
	v_mfma_f32_16x16x32_bf16 v[20:23], v[196:199], v[180:183], v[20:23]
	v_mfma_f32_16x16x32_bf16 v[16:19], v[208:211], v[180:183], v[16:19]
	v_mfma_f32_16x16x32_bf16 v[4:7], v[196:199], v[188:191], v[4:7]
	v_mfma_f32_16x16x32_bf16 v[0:3], v[208:211], v[188:191], v[0:3]
	s_barrier
	s_setprio 0
	ds_read_b128 v[144:147], v125
	ds_read_b128 v[148:151], v125 offset:1024
	ds_read_b128 v[152:155], v125 offset:2048
	ds_read_b128 v[156:159], v125 offset:3072
	s_add_u32 s12, s12, 0x200000
	s_addc_u32 s13, s13, 0
	s_mov_b32 m0, s31
	ds_read_b128 v[160:163], v123 offset:32768
	ds_read_b128 v[164:167], v123 offset:33792
	ds_read_b128 v[168:171], v123 offset:34816
	ds_read_b128 v[172:175], v123 offset:35840
	ds_read_b128 v[176:179], v123 offset:36864
	ds_read_b128 v[180:183], v123 offset:37888
	ds_read_b128 v[184:187], v123 offset:38912
	ds_read_b128 v[188:191], v123 offset:39936
	global_load_lds_dwordx4 v112, s[12:13]
	s_mov_b32 m0, s33
	s_setprio 1
	global_load_lds_dwordx4 v114, s[12:13]
	s_waitcnt lgkmcnt(8)
	s_barrier
	s_waitcnt lgkmcnt(0)
	v_mfma_f32_16x16x32_bf16 v[140:143], v[144:147], v[160:163], v[140:143]
	v_mfma_f32_16x16x32_bf16 v[136:139], v[152:155], v[160:163], v[136:139]
	v_mfma_f32_16x16x32_bf16 v[108:111], v[144:147], v[168:171], v[108:111]
	v_mfma_f32_16x16x32_bf16 v[104:107], v[152:155], v[168:171], v[104:107]
	v_mfma_f32_16x16x32_bf16 v[92:95], v[144:147], v[176:179], v[92:95]
	v_mfma_f32_16x16x32_bf16 v[88:91], v[152:155], v[176:179], v[88:91]
	v_mfma_f32_16x16x32_bf16 v[76:79], v[144:147], v[184:187], v[76:79]
	v_mfma_f32_16x16x32_bf16 v[72:75], v[152:155], v[184:187], v[72:75]
	v_mfma_f32_16x16x32_bf16 v[140:143], v[148:151], v[164:167], v[140:143]
	v_mfma_f32_16x16x32_bf16 v[136:139], v[156:159], v[164:167], v[136:139]
	v_mfma_f32_16x16x32_bf16 v[108:111], v[148:151], v[172:175], v[108:111]
	v_mfma_f32_16x16x32_bf16 v[104:107], v[156:159], v[172:175], v[104:107]
	v_mfma_f32_16x16x32_bf16 v[92:95], v[148:151], v[180:183], v[92:95]
	v_mfma_f32_16x16x32_bf16 v[88:91], v[156:159], v[180:183], v[88:91]
	v_mfma_f32_16x16x32_bf16 v[76:79], v[148:151], v[188:191], v[76:79]
	v_mfma_f32_16x16x32_bf16 v[72:75], v[156:159], v[188:191], v[72:75]
	s_barrier
	s_setprio 0
	s_mov_b32 m0, s45
	ds_read_b128 v[192:195], v126
	ds_read_b128 v[196:199], v126 offset:1024
	ds_read_b128 v[204:207], v126 offset:2048
	ds_read_b128 v[208:211], v126 offset:3072
	global_load_lds_dwordx4 v202, s[98:99]
	s_mov_b32 m0, s46
	s_setprio 1
	global_load_lds_dwordx4 v116, s[98:99]
	s_barrier
; #define PG8_STAGE(bufoff, gbase, voff) do { _Pragma("unroll") for (int _i = 0; _i < 2; ++_i) \
;         __builtin_amdgcn_global_load_lds((const unsigned*)((const char*)(gbase) + (voff)[_i]), (LAS unsigned*)(lds + (bufoff) + ldsw + _i * 8192), 16, 0, 0); } while (0)
; #define PG8_WAIT_V(n) asm volatile("s_waitcnt vmcnt(" #n ")" ::: "memory")
; #define PG8_WAIT_L(n) asm volatile("s_waitcnt lgkmcnt(" #n ")" ::: "memory")
; #define PG8_BAR __builtin_amdgcn_s_barrier()
; #define PG8_SCHED __builtin_amdgcn_sched_barrier(0)
; template <class Epi>
; __device__ __forceinline__ void gemm_phase(LAS unsigned char* lds, const bf16_t* A, int lda, const bf16_t* Bt, int ldb, int M, int N, int K, int asel, const Epi& E, const int fixed_round = -1) {
;     ...
;             PG8_BAR; PG8_WAIT_L(0); PG8_MMA(1, 0, At, B0); PG8_BAR; PG8_SCHED;
;             PG8_STAGE(PG8_SB(1, 1), b3 + hstepB, voffB);
;             PG8_WAIT_V(6); PG8_BAR; PG8_MMA(1, 1, At, B1); PG8_BAR;
;     ...
;     PG8_WAIT_V(0);
;     if (wr == 0) PG8_BAR;
;     PG8_BAR;
	s_waitcnt lgkmcnt(0)
	v_mfma_f32_16x16x32_bf16 v[132:135], v[192:195], v[160:163], v[132:135]
	v_mfma_f32_16x16x32_bf16 v[128:131], v[204:207], v[160:163], v[128:131]
	v_mfma_f32_16x16x32_bf16 v[100:103], v[192:195], v[168:171], v[100:103]
	v_mfma_f32_16x16x32_bf16 v[96:99], v[204:207], v[168:171], v[96:99]
	v_mfma_f32_16x16x32_bf16 v[84:87], v[192:195], v[176:179], v[84:87]
	v_mfma_f32_16x16x32_bf16 v[80:83], v[204:207], v[176:179], v[80:83]
	v_mfma_f32_16x16x32_bf16 v[68:71], v[192:195], v[184:187], v[68:71]
	v_mfma_f32_16x16x32_bf16 v[64:67], v[204:207], v[184:187], v[64:67]
	v_mfma_f32_16x16x32_bf16 v[132:135], v[196:199], v[164:167], v[132:135]
	v_mfma_f32_16x16x32_bf16 v[128:131], v[208:211], v[164:167], v[128:131]
	v_mfma_f32_16x16x32_bf16 v[100:103], v[196:199], v[172:175], v[100:103]
	v_mfma_f32_16x16x32_bf16 v[96:99], v[208:211], v[172:175], v[96:99]
	v_mfma_f32_16x16x32_bf16 v[84:87], v[196:199], v[180:183], v[84:87]
	v_mfma_f32_16x16x32_bf16 v[80:83], v[208:211], v[180:183], v[80:83]
	v_mfma_f32_16x16x32_bf16 v[68:71], v[196:199], v[188:191], v[68:71]
	v_mfma_f32_16x16x32_bf16 v[64:67], v[208:211], v[188:191], v[64:67]
	s_barrier
	s_setprio 0
	s_mov_b32 m0, s36
	ds_read_b128 v[160:163], v123 offset:49152
	ds_read_b128 v[164:167], v123 offset:50176
	ds_read_b128 v[168:171], v123 offset:51200
	ds_read_b128 v[172:175], v123 offset:52224
	ds_read_b128 v[176:179], v123 offset:53248
	ds_read_b128 v[180:183], v123 offset:54272
	ds_read_b128 v[184:187], v123 offset:55296
	ds_read_b128 v[188:191], v123 offset:56320
	global_load_lds_dwordx4 v112, s[100:101]
	s_mov_b32 m0, s37
	s_setprio 1
	global_load_lds_dwordx4 v114, s[100:101]
	s_barrier
	s_waitcnt lgkmcnt(0)
	v_mfma_f32_16x16x32_bf16 v[60:63], v[144:147], v[160:163], v[60:63]
	v_mfma_f32_16x16x32_bf16 v[56:59], v[152:155], v[160:163], v[56:59]
	v_mfma_f32_16x16x32_bf16 v[44:47], v[144:147], v[168:171], v[44:47]
	v_mfma_f32_16x16x32_bf16 v[40:43], v[152:155], v[168:171], v[40:43]
	v_mfma_f32_16x16x32_bf16 v[28:31], v[144:147], v[176:179], v[28:31]
	v_mfma_f32_16x16x32_bf16 v[24:27], v[152:155], v[176:179], v[24:27]
	v_mfma_f32_16x16x32_bf16 v[12:15], v[144:147], v[184:187], v[12:15]
	v_mfma_f32_16x16x32_bf16 v[8:11], v[152:155], v[184:187], v[8:11]
	v_mfma_f32_16x16x32_bf16 v[60:63], v[148:151], v[164:167], v[60:63]
	v_mfma_f32_16x16x32_bf16 v[56:59], v[156:159], v[164:167], v[56:59]
	v_mfma_f32_16x16x32_bf16 v[44:47], v[148:151], v[172:175], v[44:47]
	v_mfma_f32_16x16x32_bf16 v[40:43], v[156:159], v[172:175], v[40:43]
	v_mfma_f32_16x16x32_bf16 v[28:31], v[148:151], v[180:183], v[28:31]
	v_mfma_f32_16x16x32_bf16 v[24:27], v[156:159], v[180:183], v[24:27]
	v_mfma_f32_16x16x32_bf16 v[12:15], v[148:151], v[188:191], v[12:15]
	v_mfma_f32_16x16x32_bf16 v[8:11], v[156:159], v[188:191], v[8:11]
	s_barrier
	s_setprio 0
	s_add_u32 s8, s8, 0x200080
	s_addc_u32 s9, s9, 0
	s_mov_b32 m0, s47
	s_nop 0
	global_load_lds_dwordx4 v202, s[8:9]
	s_mov_b32 m0, s48
	s_setprio 1
	global_load_lds_dwordx4 v116, s[8:9]
	s_waitcnt vmcnt(6)
	s_barrier
	v_mfma_f32_16x16x32_bf16 v[52:55], v[192:195], v[160:163], v[52:55]
	v_mfma_f32_16x16x32_bf16 v[48:51], v[204:207], v[160:163], v[48:51]
	v_mfma_f32_16x16x32_bf16 v[36:39], v[192:195], v[168:171], v[36:39]
	v_mfma_f32_16x16x32_bf16 v[32:35], v[204:207], v[168:171], v[32:35]
	v_mfma_f32_16x16x32_bf16 v[20:23], v[192:195], v[176:179], v[20:23]
	v_mfma_f32_16x16x32_bf16 v[16:19], v[204:207], v[176:179], v[16:19]
	v_mfma_f32_16x16x32_bf16 v[4:7], v[192:195], v[184:187], v[4:7]
	v_mfma_f32_16x16x32_bf16 v[0:3], v[204:207], v[184:187], v[0:3]
	v_mfma_f32_16x16x32_bf16 v[52:55], v[196:199], v[164:167], v[52:55]
	v_mfma_f32_16x16x32_bf16 v[48:51], v[208:211], v[164:167], v[48:51]
	v_mfma_f32_16x16x32_bf16 v[36:39], v[196:199], v[172:175], v[36:39]
	v_mfma_f32_16x16x32_bf16 v[32:35], v[208:211], v[172:175], v[32:35]
	v_mfma_f32_16x16x32_bf16 v[20:23], v[196:199], v[180:183], v[20:23]
	v_mfma_f32_16x16x32_bf16 v[16:19], v[208:211], v[180:183], v[16:19]
	v_mfma_f32_16x16x32_bf16 v[4:7], v[196:199], v[188:191], v[4:7]
	v_mfma_f32_16x16x32_bf16 v[0:3], v[208:211], v[188:191], v[0:3]
	s_setprio 0
	s_add_i32 s34, s34, 2
	s_add_u32 s6, s6, 0x100
	s_addc_u32 s7, s7, 0
	s_cmpk_lt_u32 s34, 0x7e
	s_cbranch_scc1 .Lrot_12
	s_barrier
	s_waitcnt vmcnt(0)
	s_cmpk_gt_u32 s18, 0xff
	s_cbranch_scc1 .LBB0_1325
	s_barrier
